# 16-byte global stores issued write-through (sc1): no dirty-L2 writeback burst at the grid barriers
# speedup vs baseline: 1.0066x; 1.0066x over previous
.Lwt_cvdone:
	s_waitcnt lgkmcnt(0)
	s_barrier
	s_cmp_lt_u32 s76, 1
	s_cbranch_scc1 .Lwt_stdone
	v_add_u32_e32 v0, s65, v11
	v_cmp_gt_i32_e32 vcc, s34, v0
	s_and_saveexec_b64 s[6:7], vcc
	s_cbranch_execz .Lwt_skipst0
	s_mov_b32 s24, s64
	v_sub_u32_e32 v2, 0, v0
	v_max_i32_e32 v2, v0, v2
	v_mul_hi_u32 v3, v2, v15
	v_mul_lo_u32 v4, v3, s38
	v_sub_u32_e32 v2, v2, v4
	v_add_u32_e32 v4, 1, v3
	v_cmp_le_u32_e32 vcc, s38, v2
	v_ashrrev_i32_e32 v1, 31, v0
	s_ashr_i32 s25, s24, 31
	v_cndmask_b32_e32 v3, v3, v4, vcc
	v_subrev_u32_e32 v4, s38, v2
	v_cndmask_b32_e32 v2, v2, v4, vcc
	v_add_u32_e32 v4, 1, v3
	v_cmp_le_u32_e32 vcc, s38, v2
	s_nop 1
	v_cndmask_b32_e32 v2, v3, v4, vcc
	v_xor_b32_e32 v2, v2, v1
	v_sub_u32_e32 v1, v2, v1
	v_mul_lo_u32 v2, v1, s37
	v_mul_lo_u32 v1, v1, s38
	v_sub_u32_e32 v0, v0, v1
	v_add3_u32 v4, v2, s31, v0
	v_ashrrev_i32_e32 v7, 31, v4
	v_mad_u64_u32 v[4:5], s[26:27], v4, s36, 0
	v_mov_b32_e32 v6, v5
	ds_read_b128 v[0:3], v18
	v_mad_u64_u32 v[6:7], s[26:27], v7, s36, v[6:7]
	v_mov_b32_e32 v5, v6
	v_lshl_add_u64 v[4:5], v[4:5], 1, s[8:9]
	v_lshl_add_u64 v[4:5], s[24:25], 1, v[4:5]
	v_lshl_add_u64 v[4:5], v[4:5], 0, v[12:13]
	s_waitcnt lgkmcnt(0)
	global_store_dwordx4 v[4:5], v[0:3], off sc1
.Lwt_skipst0:
	s_or_b64 exec, exec, s[6:7]
	s_cmp_lt_u32 s76, 2
	s_cbranch_scc1 .Lwt_stdone
	v_add_u32_e32 v0, s67, v11
	v_cmp_gt_i32_e32 vcc, s34, v0
	s_and_saveexec_b64 s[6:7], vcc
	s_cbranch_execz .Lwt_skipst1
	s_mov_b32 s24, s66
	v_sub_u32_e32 v2, 0, v0
	v_max_i32_e32 v2, v0, v2
	v_mul_hi_u32 v3, v2, v15
	v_mul_lo_u32 v4, v3, s38
	v_sub_u32_e32 v2, v2, v4
	v_add_u32_e32 v4, 1, v3
	v_cmp_le_u32_e32 vcc, s38, v2
	v_ashrrev_i32_e32 v1, 31, v0
	s_ashr_i32 s25, s24, 31
	v_cndmask_b32_e32 v3, v3, v4, vcc
	v_subrev_u32_e32 v4, s38, v2
	v_cndmask_b32_e32 v2, v2, v4, vcc
	v_add_u32_e32 v4, 1, v3
	v_cmp_le_u32_e32 vcc, s38, v2
	s_nop 1
	v_cndmask_b32_e32 v2, v3, v4, vcc
	v_xor_b32_e32 v2, v2, v1
	v_sub_u32_e32 v1, v2, v1
	v_mul_lo_u32 v2, v1, s37
	v_mul_lo_u32 v1, v1, s38
	v_sub_u32_e32 v0, v0, v1
	v_add3_u32 v4, v2, s31, v0
	v_ashrrev_i32_e32 v7, 31, v4
	v_mad_u64_u32 v[4:5], s[26:27], v4, s36, 0
	v_mov_b32_e32 v6, v5
	ds_read_b128 v[0:3], v18 offset:9216
	v_mad_u64_u32 v[6:7], s[26:27], v7, s36, v[6:7]
	v_mov_b32_e32 v5, v6
	v_lshl_add_u64 v[4:5], v[4:5], 1, s[8:9]
	v_lshl_add_u64 v[4:5], s[24:25], 1, v[4:5]
	v_lshl_add_u64 v[4:5], v[4:5], 0, v[12:13]
	s_waitcnt lgkmcnt(0)
	global_store_dwordx4 v[4:5], v[0:3], off sc1
.Lwt_skipst1:
	s_or_b64 exec, exec, s[6:7]
	s_cmp_lt_u32 s76, 3
	s_cbranch_scc1 .Lwt_stdone
	v_add_u32_e32 v0, s69, v11
	v_cmp_gt_i32_e32 vcc, s34, v0
	s_and_saveexec_b64 s[6:7], vcc
	s_cbranch_execz .Lwt_skipst2
	s_mov_b32 s24, s68
	v_sub_u32_e32 v2, 0, v0
	v_max_i32_e32 v2, v0, v2
	v_mul_hi_u32 v3, v2, v15
	v_mul_lo_u32 v4, v3, s38
	v_sub_u32_e32 v2, v2, v4
	v_add_u32_e32 v4, 1, v3
	v_cmp_le_u32_e32 vcc, s38, v2
	v_ashrrev_i32_e32 v1, 31, v0
	s_ashr_i32 s25, s24, 31
	v_cndmask_b32_e32 v3, v3, v4, vcc
	v_subrev_u32_e32 v4, s38, v2
	v_cndmask_b32_e32 v2, v2, v4, vcc
	v_add_u32_e32 v4, 1, v3
	v_cmp_le_u32_e32 vcc, s38, v2
	s_nop 1
	v_cndmask_b32_e32 v2, v3, v4, vcc
	v_xor_b32_e32 v2, v2, v1
	v_sub_u32_e32 v1, v2, v1
	v_mul_lo_u32 v2, v1, s37
	v_mul_lo_u32 v1, v1, s38
	v_sub_u32_e32 v0, v0, v1
	v_add3_u32 v4, v2, s31, v0
	v_ashrrev_i32_e32 v7, 31, v4
	v_mad_u64_u32 v[4:5], s[26:27], v4, s36, 0
	v_mov_b32_e32 v6, v5
	ds_read_b128 v[0:3], v18 offset:18432
	v_mad_u64_u32 v[6:7], s[26:27], v7, s36, v[6:7]
	v_mov_b32_e32 v5, v6
	v_lshl_add_u64 v[4:5], v[4:5], 1, s[8:9]
	v_lshl_add_u64 v[4:5], s[24:25], 1, v[4:5]
	v_lshl_add_u64 v[4:5], v[4:5], 0, v[12:13]
	s_waitcnt lgkmcnt(0)
	global_store_dwordx4 v[4:5], v[0:3], off sc1

.LBB0_116:
	v_ashrrev_i32_e32 v5, 31, v4
	v_lshl_add_u64 v[6:7], v[4:5], 4, s[12:13]
	v_add_u32_e32 v4, s3, v4
	v_cmp_lt_i32_e32 vcc, s14, v4
	s_or_b64 s[8:9], vcc, s[8:9]
	global_store_dwordx4 v[6:7], v[0:3], off sc1
	s_andn2_b64 exec, exec, s[8:9]
	s_cbranch_execnz .LBB0_116

.Lwc_last:
	s_waitcnt vmcnt(0)
	v_fmac_f32_e32 v10, v62, v70
	v_fmac_f32_e32 v11, v62, v74
	v_fmac_f32_e32 v12, v62, v78
	v_fmac_f32_e32 v13, v62, v82
	v_fmac_f32_e32 v14, v62, v86
	v_fmac_f32_e32 v15, v62, v90
	v_fmac_f32_e32 v8, v62, v94
	v_fmac_f32_e32 v9, v62, v98
	v_fmac_f32_e32 v10, v64, v71
	v_fmac_f32_e32 v11, v64, v75
	v_fmac_f32_e32 v12, v64, v79
	v_fmac_f32_e32 v13, v64, v83
	v_fmac_f32_e32 v14, v64, v87
	v_fmac_f32_e32 v15, v64, v91
	v_fmac_f32_e32 v8, v64, v95
	v_fmac_f32_e32 v9, v64, v99
	v_fmac_f32_e32 v10, v66, v72
	v_fmac_f32_e32 v11, v66, v76
	v_fmac_f32_e32 v12, v66, v80
	v_fmac_f32_e32 v13, v66, v84
	v_fmac_f32_e32 v14, v66, v88
	v_fmac_f32_e32 v15, v66, v92
	v_fmac_f32_e32 v8, v66, v96
	v_fmac_f32_e32 v9, v66, v100
	v_fmac_f32_e32 v10, v68, v73
	v_fmac_f32_e32 v11, v68, v77
	v_fmac_f32_e32 v12, v68, v81
	v_fmac_f32_e32 v13, v68, v85
	v_fmac_f32_e32 v14, v68, v89
	v_fmac_f32_e32 v15, v68, v93
	v_fmac_f32_e32 v8, v68, v97
	v_fmac_f32_e32 v9, v68, v101
	v_and_b32_e32 v0, 0x3ff, v16
	v_lshlrev_b32_e32 v0, 12, v0
	v_lshlrev_b32_e32 v2, 7, v2
	v_cvt_pk_bf16_f32 v7, v8, v9
	v_lshl_add_u64 v[8:9], s[10:11], 0, v[0:1]
	v_ashrrev_i32_e32 v3, 31, v2
	v_lshrrev_b32_e32 v0, 6, v16
	v_add_u32_e32 v16, s3, v16
	v_lshl_add_u64 v[2:3], v[2:3], 1, v[8:9]
	v_and_b32_e32 v0, 0xf0, v0
	v_cmp_lt_i32_e32 vcc, s29, v16
	v_cvt_pk_bf16_f32 v4, v10, v11
	v_cvt_pk_bf16_f32 v5, v12, v13
	v_cvt_pk_bf16_f32 v6, v14, v15
	v_lshl_add_u64 v[2:3], v[2:3], 0, v[0:1]
	s_or_b64 s[14:15], vcc, s[14:15]
	v_subrev_u16_e32 v17, s3, v17
	global_store_dwordx4 v[2:3], v[4:7], off sc1
	s_andn2_b64 exec, exec, s[14:15]
	s_cbranch_execnz .LBB0_122

.LBB0_184:
	ds_read2_b32 v[164:165], v155 offset1:16
	ds_read2_b32 v[150:151], v155 offset0:32 offset1:48
	ds_read2_b32 v[148:149], v155 offset0:64 offset1:80
	ds_read2_b32 v[146:147], v155 offset0:96 offset1:112
	v_pk_mul_f32 v[120:121], v[124:125], v[120:121]
	s_waitcnt lgkmcnt(0)
	v_mul_f32_e32 v166, 0xbfb8aa3b, v164
	v_pk_mul_f32 v[168:169], v[124:125], v[166:167] op_sel_hi:[1,0]
	v_pk_mul_f32 v[170:171], v[126:127], v[166:167] op_sel_hi:[1,0]
	v_exp_f32_e32 v167, v169
	v_exp_f32_e32 v161, v168
	v_pk_mul_f32 v[122:123], v[126:127], v[122:123]
	v_exp_f32_e32 v171, v171
	v_add_f32_e32 v167, 1.0, v167
	v_pk_mul_f32 v[124:125], v[116:117], v[166:167] op_sel_hi:[1,0]
	v_add_f32_e32 v161, 1.0, v161
	v_exp_f32_e32 v124, v124
	v_pk_mul_f32 v[126:127], v[118:119], v[166:167] op_sel_hi:[1,0]
	v_exp_f32_e32 v125, v125
	v_rcp_f32_e32 v168, v161
	v_exp_f32_e32 v161, v170
	v_exp_f32_e32 v126, v126
	v_exp_f32_e32 v127, v127
	v_add_f32_e32 v124, 1.0, v124
	v_add_f32_e32 v125, 1.0, v125
	v_add_f32_e32 v161, 1.0, v161
	v_rcp_f32_e32 v124, v124
	v_rcp_f32_e32 v125, v125
	v_add_f32_e32 v126, 1.0, v126
	v_add_f32_e32 v127, 1.0, v127
	v_rcp_f32_e32 v169, v167
	v_rcp_f32_e32 v170, v161
	v_add_f32_e32 v161, 1.0, v171
	v_rcp_f32_e32 v126, v126
	v_rcp_f32_e32 v127, v127
	v_mul_f32_e32 v164, v164, v164
	v_rcp_f32_e32 v171, v161
	v_pk_mul_f32 v[112:113], v[116:117], v[112:113]
	v_pk_mul_f32 v[114:115], v[118:119], v[114:115]
	v_pk_mul_f32 v[112:113], v[112:113], v[164:165] op_sel_hi:[1,0]
	v_lshl_or_b32 v162, s64, 7, v156
	v_pk_mul_f32 v[120:121], v[120:121], v[164:165] op_sel_hi:[1,0]
	v_pk_mul_f32 v[112:113], v[112:113], v[124:125]
	v_pk_mul_f32 v[114:115], v[114:115], v[164:165] op_sel_hi:[1,0]
	v_add_u32_e32 v160, s25, v145
	v_ashrrev_i32_e32 v163, 31, v162
	v_pk_mul_f32 v[120:121], v[120:121], v[168:169]
	v_pk_mul_f32 v[122:123], v[122:123], v[164:165] op_sel_hi:[1,0]
	v_pk_mul_f32 v[114:115], v[114:115], v[126:127]
	v_cvt_pk_bf16_f32 v118, v112, v113
	v_mov_b64_e32 v[112:113], s[10:11]
	v_pk_mul_f32 v[122:123], v[122:123], v[170:171]
	v_cvt_pk_bf16_f32 v116, v120, v121
	v_cvt_pk_bf16_f32 v119, v114, v115
	v_mad_i64_i32 v[120:121], s[8:9], v160, s58, v[112:113]
	v_lshlrev_b64 v[114:115], 1, v[162:163]
	v_cvt_pk_bf16_f32 v117, v122, v123
	v_lshl_add_u64 v[120:121], v[120:121], 0, v[114:115]
	global_store_dwordx4 v[120:121], v[116:119], off sc1
	v_pk_mul_f32 v[104:105], v[108:109], v[104:105]
	v_pk_mul_f32 v[106:107], v[110:111], v[106:107]
	v_mul_f32_e32 v116, 0xbfb8aa3b, v165
	v_pk_mul_f32 v[118:119], v[108:109], v[116:117] op_sel_hi:[1,0]
	v_pk_mul_f32 v[96:97], v[100:101], v[96:97]
	v_exp_f32_e32 v117, v118
	v_exp_f32_e32 v119, v119
	v_mul_f32_e32 v118, v165, v165
	v_pk_mul_f32 v[98:99], v[102:103], v[98:99]
	v_pk_mul_f32 v[120:121], v[110:111], v[116:117] op_sel_hi:[1,0]
	v_add_f32_e32 v117, 1.0, v117
	v_rcp_f32_e32 v122, v117
	v_exp_f32_e32 v117, v120
	v_exp_f32_e32 v121, v121
	v_add_f32_e32 v119, 1.0, v119
	v_rcp_f32_e32 v123, v119
	v_add_f32_e32 v117, 1.0, v117
	v_rcp_f32_e32 v120, v117
	v_add_f32_e32 v117, 1.0, v121
	v_pk_mul_f32 v[108:109], v[100:101], v[116:117] op_sel_hi:[1,0]
	v_pk_mul_f32 v[110:111], v[102:103], v[116:117] op_sel_hi:[1,0]
	v_exp_f32_e32 v108, v108
	v_exp_f32_e32 v109, v109
	v_exp_f32_e32 v110, v110
	v_exp_f32_e32 v111, v111
	v_add_f32_e32 v108, 1.0, v108
	v_add_f32_e32 v109, 1.0, v109
	v_rcp_f32_e32 v108, v108
	v_rcp_f32_e32 v109, v109
	v_add_f32_e32 v110, 1.0, v110
	v_add_f32_e32 v111, 1.0, v111
	v_rcp_f32_e32 v121, v117
	v_rcp_f32_e32 v110, v110
	v_rcp_f32_e32 v111, v111
	v_pk_mul_f32 v[96:97], v[96:97], v[118:119] op_sel_hi:[1,0]
	v_pk_mul_f32 v[104:105], v[104:105], v[118:119] op_sel_hi:[1,0]
	v_pk_mul_f32 v[106:107], v[106:107], v[118:119] op_sel_hi:[1,0]
	v_pk_mul_f32 v[100:101], v[96:97], v[108:109]
	v_pk_mul_f32 v[96:97], v[98:99], v[118:119] op_sel_hi:[1,0]
	v_or_b32_e32 v108, 16, v160
	v_pk_mul_f32 v[104:105], v[104:105], v[122:123]
	v_pk_mul_f32 v[106:107], v[106:107], v[120:121]
	v_pk_mul_f32 v[102:103], v[96:97], v[110:111]
	v_cvt_pk_bf16_f32 v98, v100, v101
	v_mad_i64_i32 v[100:101], s[8:9], v108, s58, v[112:113]
	v_cvt_pk_bf16_f32 v96, v104, v105
	v_cvt_pk_bf16_f32 v97, v106, v107
	v_cvt_pk_bf16_f32 v99, v102, v103
	v_lshl_add_u64 v[100:101], v[100:101], 0, v[114:115]
	global_store_dwordx4 v[100:101], v[96:99], off sc1
	v_pk_mul_f32 v[88:89], v[92:93], v[88:89]
	v_pk_mul_f32 v[90:91], v[94:95], v[90:91]
	v_mul_f32_e32 v96, 0xbfb8aa3b, v150
	v_pk_mul_f32 v[98:99], v[92:93], v[96:97] op_sel_hi:[1,0]
	v_pk_mul_f32 v[80:81], v[84:85], v[80:81]
	v_exp_f32_e32 v97, v98
	v_exp_f32_e32 v99, v99
	v_mul_f32_e32 v98, v150, v150
	v_pk_mul_f32 v[82:83], v[86:87], v[82:83]
	v_pk_mul_f32 v[100:101], v[94:95], v[96:97] op_sel_hi:[1,0]
	v_add_f32_e32 v97, 1.0, v97
	v_rcp_f32_e32 v102, v97
	v_exp_f32_e32 v97, v100
	v_exp_f32_e32 v101, v101
	v_add_f32_e32 v99, 1.0, v99
	v_rcp_f32_e32 v103, v99
	v_add_f32_e32 v97, 1.0, v97
	v_rcp_f32_e32 v100, v97
	v_add_f32_e32 v97, 1.0, v101
	v_pk_mul_f32 v[92:93], v[84:85], v[96:97] op_sel_hi:[1,0]
	v_pk_mul_f32 v[94:95], v[86:87], v[96:97] op_sel_hi:[1,0]
	v_exp_f32_e32 v92, v92
	v_exp_f32_e32 v93, v93
	v_exp_f32_e32 v94, v94
	v_exp_f32_e32 v95, v95
	v_add_f32_e32 v92, 1.0, v92
	v_add_f32_e32 v93, 1.0, v93
	v_rcp_f32_e32 v92, v92
	v_rcp_f32_e32 v93, v93
	v_add_f32_e32 v94, 1.0, v94
	v_add_f32_e32 v95, 1.0, v95
	v_rcp_f32_e32 v101, v97
	v_rcp_f32_e32 v94, v94
	v_rcp_f32_e32 v95, v95
	v_pk_mul_f32 v[80:81], v[80:81], v[98:99] op_sel_hi:[1,0]
	v_pk_mul_f32 v[88:89], v[88:89], v[98:99] op_sel_hi:[1,0]
	v_pk_mul_f32 v[90:91], v[90:91], v[98:99] op_sel_hi:[1,0]
	v_pk_mul_f32 v[84:85], v[80:81], v[92:93]
	v_pk_mul_f32 v[80:81], v[82:83], v[98:99] op_sel_hi:[1,0]
	v_or_b32_e32 v92, 32, v160
	v_pk_mul_f32 v[88:89], v[88:89], v[102:103]
	v_pk_mul_f32 v[90:91], v[90:91], v[100:101]
	v_pk_mul_f32 v[86:87], v[80:81], v[94:95]
	v_cvt_pk_bf16_f32 v82, v84, v85
	v_mad_i64_i32 v[84:85], s[8:9], v92, s58, v[112:113]
	v_cvt_pk_bf16_f32 v80, v88, v89
	v_cvt_pk_bf16_f32 v81, v90, v91
	v_cvt_pk_bf16_f32 v83, v86, v87
	v_lshl_add_u64 v[84:85], v[84:85], 0, v[114:115]
	global_store_dwordx4 v[84:85], v[80:83], off sc1
	v_pk_mul_f32 v[72:73], v[76:77], v[72:73]
	v_pk_mul_f32 v[74:75], v[78:79], v[74:75]
	v_mul_f32_e32 v80, 0xbfb8aa3b, v151
	v_pk_mul_f32 v[82:83], v[76:77], v[80:81] op_sel_hi:[1,0]
	v_pk_mul_f32 v[64:65], v[68:69], v[64:65]
	v_exp_f32_e32 v81, v82
	v_exp_f32_e32 v83, v83
	v_mul_f32_e32 v82, v151, v151
	v_pk_mul_f32 v[66:67], v[70:71], v[66:67]
	v_pk_mul_f32 v[84:85], v[78:79], v[80:81] op_sel_hi:[1,0]
	v_add_f32_e32 v81, 1.0, v81
	v_rcp_f32_e32 v86, v81
	v_exp_f32_e32 v81, v84
	v_exp_f32_e32 v85, v85
	v_add_f32_e32 v83, 1.0, v83
	v_rcp_f32_e32 v87, v83
	v_add_f32_e32 v81, 1.0, v81
	v_rcp_f32_e32 v84, v81
	v_add_f32_e32 v81, 1.0, v85
	v_pk_mul_f32 v[76:77], v[68:69], v[80:81] op_sel_hi:[1,0]
	v_pk_mul_f32 v[78:79], v[70:71], v[80:81] op_sel_hi:[1,0]
	v_exp_f32_e32 v76, v76
	v_exp_f32_e32 v77, v77
	v_exp_f32_e32 v78, v78
	v_exp_f32_e32 v79, v79
	v_add_f32_e32 v76, 1.0, v76
	v_add_f32_e32 v77, 1.0, v77
	v_rcp_f32_e32 v76, v76
	v_rcp_f32_e32 v77, v77
	v_add_f32_e32 v78, 1.0, v78
	v_add_f32_e32 v79, 1.0, v79
	v_rcp_f32_e32 v85, v81
	v_rcp_f32_e32 v78, v78
	v_rcp_f32_e32 v79, v79
	v_pk_mul_f32 v[64:65], v[64:65], v[82:83] op_sel_hi:[1,0]
	v_pk_mul_f32 v[72:73], v[72:73], v[82:83] op_sel_hi:[1,0]
	v_pk_mul_f32 v[74:75], v[74:75], v[82:83] op_sel_hi:[1,0]
	v_pk_mul_f32 v[68:69], v[64:65], v[76:77]
	v_pk_mul_f32 v[64:65], v[66:67], v[82:83] op_sel_hi:[1,0]
	v_or_b32_e32 v76, 48, v160
	v_pk_mul_f32 v[72:73], v[72:73], v[86:87]
	v_pk_mul_f32 v[74:75], v[74:75], v[84:85]
	v_pk_mul_f32 v[70:71], v[64:65], v[78:79]
	v_cvt_pk_bf16_f32 v66, v68, v69
	v_mad_i64_i32 v[68:69], s[8:9], v76, s58, v[112:113]
	v_cvt_pk_bf16_f32 v64, v72, v73
	v_cvt_pk_bf16_f32 v65, v74, v75
	v_cvt_pk_bf16_f32 v67, v70, v71
	v_lshl_add_u64 v[68:69], v[68:69], 0, v[114:115]
	global_store_dwordx4 v[68:69], v[64:67], off sc1
	v_pk_mul_f32 v[56:57], v[60:61], v[56:57]
	v_pk_mul_f32 v[58:59], v[62:63], v[58:59]
	v_add_u32_e32 v65, 0x80, v160
	v_mul_f32_e32 v64, 0xbfb8aa3b, v148
	v_pk_mul_f32 v[66:67], v[60:61], v[64:65] op_sel_hi:[1,0]
	v_pk_mul_f32 v[68:69], v[62:63], v[64:65] op_sel_hi:[1,0]
	v_exp_f32_e32 v67, v67
	v_pk_mul_f32 v[60:61], v[52:53], v[64:65] op_sel_hi:[1,0]
	v_exp_f32_e32 v68, v68
	v_exp_f32_e32 v60, v60
	v_pk_mul_f32 v[62:63], v[54:55], v[64:65] op_sel_hi:[1,0]
	v_exp_f32_e32 v61, v61
	v_exp_f32_e32 v70, v66
	v_exp_f32_e32 v69, v69
	v_exp_f32_e32 v62, v62
	v_exp_f32_e32 v63, v63
	v_add_f32_e32 v67, 1.0, v67
	v_rcp_f32_e32 v71, v67
	v_add_f32_e32 v67, 1.0, v68
	v_add_f32_e32 v60, 1.0, v60
	v_add_f32_e32 v61, 1.0, v61
	v_add_f32_e32 v70, 1.0, v70
	v_rcp_f32_e32 v68, v67
	v_add_f32_e32 v67, 1.0, v69
	v_rcp_f32_e32 v60, v60
	v_rcp_f32_e32 v61, v61
	v_add_f32_e32 v62, 1.0, v62
	v_add_f32_e32 v63, 1.0, v63
	v_rcp_f32_e32 v70, v70
	v_rcp_f32_e32 v69, v67
	v_rcp_f32_e32 v62, v62
	v_rcp_f32_e32 v63, v63
	v_mul_f32_e32 v66, v148, v148
	v_pk_mul_f32 v[48:49], v[52:53], v[48:49]
	v_pk_mul_f32 v[50:51], v[54:55], v[50:51]
	v_pk_mul_f32 v[48:49], v[48:49], v[66:67] op_sel_hi:[1,0]
	v_pk_mul_f32 v[56:57], v[56:57], v[66:67] op_sel_hi:[1,0]
	v_pk_mul_f32 v[58:59], v[58:59], v[66:67] op_sel_hi:[1,0]
	v_pk_mul_f32 v[52:53], v[48:49], v[60:61]
	v_pk_mul_f32 v[48:49], v[50:51], v[66:67] op_sel_hi:[1,0]
	v_pk_mul_f32 v[56:57], v[56:57], v[70:71]
	v_pk_mul_f32 v[58:59], v[58:59], v[68:69]
	v_pk_mul_f32 v[54:55], v[48:49], v[62:63]
	v_cvt_pk_bf16_f32 v50, v52, v53
	v_mad_i64_i32 v[52:53], s[8:9], v65, s58, v[112:113]
	v_cvt_pk_bf16_f32 v48, v56, v57
	v_cvt_pk_bf16_f32 v49, v58, v59
	v_cvt_pk_bf16_f32 v51, v54, v55
	v_lshl_add_u64 v[52:53], v[52:53], 0, v[114:115]
	global_store_dwordx4 v[52:53], v[48:51], off sc1
	v_pk_mul_f32 v[40:41], v[44:45], v[40:41]
	v_pk_mul_f32 v[42:43], v[46:47], v[42:43]
	v_mul_f32_e32 v48, 0xbfb8aa3b, v149
	v_pk_mul_f32 v[50:51], v[44:45], v[48:49] op_sel_hi:[1,0]
	v_pk_mul_f32 v[32:33], v[36:37], v[32:33]
	v_exp_f32_e32 v49, v50
	v_exp_f32_e32 v51, v51
	v_mul_f32_e32 v50, v149, v149
	v_pk_mul_f32 v[34:35], v[38:39], v[34:35]
	v_pk_mul_f32 v[52:53], v[46:47], v[48:49] op_sel_hi:[1,0]
	v_add_f32_e32 v49, 1.0, v49
	v_rcp_f32_e32 v54, v49
	v_exp_f32_e32 v49, v52
	v_exp_f32_e32 v53, v53
	v_add_f32_e32 v51, 1.0, v51
	v_rcp_f32_e32 v55, v51
	v_add_f32_e32 v49, 1.0, v49
	v_rcp_f32_e32 v52, v49
	v_add_f32_e32 v49, 1.0, v53
	v_pk_mul_f32 v[44:45], v[36:37], v[48:49] op_sel_hi:[1,0]
	v_pk_mul_f32 v[46:47], v[38:39], v[48:49] op_sel_hi:[1,0]
	v_exp_f32_e32 v44, v44
	v_exp_f32_e32 v45, v45
	v_exp_f32_e32 v46, v46
	v_exp_f32_e32 v47, v47
	v_add_f32_e32 v44, 1.0, v44
	v_add_f32_e32 v45, 1.0, v45
	v_rcp_f32_e32 v44, v44
	v_rcp_f32_e32 v45, v45
	v_add_f32_e32 v46, 1.0, v46
	v_add_f32_e32 v47, 1.0, v47
	v_rcp_f32_e32 v53, v49
	v_rcp_f32_e32 v46, v46
	v_rcp_f32_e32 v47, v47
	v_pk_mul_f32 v[32:33], v[32:33], v[50:51] op_sel_hi:[1,0]
	v_pk_mul_f32 v[40:41], v[40:41], v[50:51] op_sel_hi:[1,0]
	v_pk_mul_f32 v[42:43], v[42:43], v[50:51] op_sel_hi:[1,0]
	v_pk_mul_f32 v[36:37], v[32:33], v[44:45]
	v_pk_mul_f32 v[32:33], v[34:35], v[50:51] op_sel_hi:[1,0]
	v_add_u32_e32 v44, 0x90, v160
	v_pk_mul_f32 v[40:41], v[40:41], v[54:55]
	v_pk_mul_f32 v[42:43], v[42:43], v[52:53]
	v_pk_mul_f32 v[38:39], v[32:33], v[46:47]
	v_cvt_pk_bf16_f32 v34, v36, v37
	v_mad_i64_i32 v[36:37], s[8:9], v44, s58, v[112:113]
	v_cvt_pk_bf16_f32 v32, v40, v41
	v_cvt_pk_bf16_f32 v33, v42, v43
	v_cvt_pk_bf16_f32 v35, v38, v39
	v_lshl_add_u64 v[36:37], v[36:37], 0, v[114:115]
	global_store_dwordx4 v[36:37], v[32:35], off sc1
	v_pk_mul_f32 v[24:25], v[28:29], v[24:25]
	v_pk_mul_f32 v[26:27], v[30:31], v[26:27]
	v_mul_f32_e32 v32, 0xbfb8aa3b, v146
	v_pk_mul_f32 v[34:35], v[28:29], v[32:33] op_sel_hi:[1,0]
	v_pk_mul_f32 v[16:17], v[20:21], v[16:17]
	v_exp_f32_e32 v33, v34
	v_exp_f32_e32 v35, v35
	v_mul_f32_e32 v34, v146, v146
	v_pk_mul_f32 v[18:19], v[22:23], v[18:19]
	v_pk_mul_f32 v[36:37], v[30:31], v[32:33] op_sel_hi:[1,0]
	v_add_f32_e32 v33, 1.0, v33
	v_rcp_f32_e32 v38, v33
	v_exp_f32_e32 v33, v36
	v_exp_f32_e32 v37, v37
	v_add_f32_e32 v35, 1.0, v35
	v_rcp_f32_e32 v39, v35
	v_add_f32_e32 v33, 1.0, v33
	v_rcp_f32_e32 v36, v33
	v_add_f32_e32 v33, 1.0, v37
	v_pk_mul_f32 v[28:29], v[20:21], v[32:33] op_sel_hi:[1,0]
	v_pk_mul_f32 v[30:31], v[22:23], v[32:33] op_sel_hi:[1,0]
	v_exp_f32_e32 v28, v28
	v_exp_f32_e32 v29, v29
	v_exp_f32_e32 v30, v30
	v_exp_f32_e32 v31, v31
	v_add_f32_e32 v28, 1.0, v28
	v_add_f32_e32 v29, 1.0, v29
	v_rcp_f32_e32 v28, v28
	v_rcp_f32_e32 v29, v29
	v_add_f32_e32 v30, 1.0, v30
	v_add_f32_e32 v31, 1.0, v31
	v_rcp_f32_e32 v37, v33
	v_rcp_f32_e32 v30, v30
	v_rcp_f32_e32 v31, v31
	v_pk_mul_f32 v[16:17], v[16:17], v[34:35] op_sel_hi:[1,0]
	v_pk_mul_f32 v[24:25], v[24:25], v[34:35] op_sel_hi:[1,0]
	v_pk_mul_f32 v[26:27], v[26:27], v[34:35] op_sel_hi:[1,0]
	v_pk_mul_f32 v[20:21], v[16:17], v[28:29]
	v_pk_mul_f32 v[16:17], v[18:19], v[34:35] op_sel_hi:[1,0]
	v_add_u32_e32 v28, 0xa0, v160
	v_pk_mul_f32 v[24:25], v[24:25], v[38:39]
	v_pk_mul_f32 v[26:27], v[26:27], v[36:37]
	v_pk_mul_f32 v[22:23], v[16:17], v[30:31]
	v_cvt_pk_bf16_f32 v18, v20, v21
	v_mad_i64_i32 v[20:21], s[8:9], v28, s58, v[112:113]
	v_cvt_pk_bf16_f32 v16, v24, v25
	v_cvt_pk_bf16_f32 v17, v26, v27
	v_cvt_pk_bf16_f32 v19, v22, v23
	v_lshl_add_u64 v[20:21], v[20:21], 0, v[114:115]
	global_store_dwordx4 v[20:21], v[16:19], off sc1
	v_pk_mul_f32 v[8:9], v[12:13], v[8:9]
	v_pk_mul_f32 v[10:11], v[14:15], v[10:11]
	v_mul_f32_e32 v16, 0xbfb8aa3b, v147
	v_pk_mul_f32 v[18:19], v[12:13], v[16:17] op_sel_hi:[1,0]
	v_pk_mul_f32 v[0:1], v[4:5], v[0:1]
	v_exp_f32_e32 v17, v18
	v_exp_f32_e32 v19, v19
	v_mul_f32_e32 v18, v147, v147
	v_pk_mul_f32 v[2:3], v[6:7], v[2:3]
	v_pk_mul_f32 v[20:21], v[14:15], v[16:17] op_sel_hi:[1,0]
	v_add_f32_e32 v17, 1.0, v17
	v_rcp_f32_e32 v22, v17
	v_exp_f32_e32 v17, v20
	v_exp_f32_e32 v21, v21
	v_add_f32_e32 v19, 1.0, v19
	v_rcp_f32_e32 v23, v19
	v_add_f32_e32 v17, 1.0, v17
	v_rcp_f32_e32 v20, v17
	v_add_f32_e32 v17, 1.0, v21
	v_pk_mul_f32 v[12:13], v[4:5], v[16:17] op_sel_hi:[1,0]
	v_pk_mul_f32 v[14:15], v[6:7], v[16:17] op_sel_hi:[1,0]
	v_exp_f32_e32 v12, v12
	v_exp_f32_e32 v13, v13
	v_exp_f32_e32 v14, v14
	v_exp_f32_e32 v15, v15
	v_add_f32_e32 v12, 1.0, v12
	v_add_f32_e32 v13, 1.0, v13
	v_rcp_f32_e32 v12, v12
	v_rcp_f32_e32 v13, v13
	v_add_f32_e32 v14, 1.0, v14
	v_add_f32_e32 v15, 1.0, v15
	v_rcp_f32_e32 v21, v17
	v_rcp_f32_e32 v14, v14
	v_rcp_f32_e32 v15, v15
	v_pk_mul_f32 v[0:1], v[0:1], v[18:19] op_sel_hi:[1,0]
	v_pk_mul_f32 v[8:9], v[8:9], v[18:19] op_sel_hi:[1,0]
	v_pk_mul_f32 v[10:11], v[10:11], v[18:19] op_sel_hi:[1,0]
	v_pk_mul_f32 v[4:5], v[0:1], v[12:13]
	v_pk_mul_f32 v[0:1], v[2:3], v[18:19] op_sel_hi:[1,0]
	v_add_u32_e32 v12, 0xb0, v160
	v_pk_mul_f32 v[8:9], v[8:9], v[22:23]
	v_pk_mul_f32 v[10:11], v[10:11], v[20:21]
	v_pk_mul_f32 v[6:7], v[0:1], v[14:15]
	v_cvt_pk_bf16_f32 v2, v4, v5
	v_mad_i64_i32 v[4:5], s[8:9], v12, s58, v[112:113]
	v_cvt_pk_bf16_f32 v0, v8, v9
	v_cvt_pk_bf16_f32 v1, v10, v11
	v_cvt_pk_bf16_f32 v3, v6, v7
	v_lshl_add_u64 v[4:5], v[4:5], 0, v[114:115]
	s_and_b64 vcc, exec, s[6:7]
	s_mov_b32 s64, s24
	s_mov_b32 s34, s26
	s_mov_b64 s[36:37], s[30:31]
	s_mov_b64 s[8:9], s[28:29]
	global_store_dwordx4 v[4:5], v[0:3], off sc1
	s_cbranch_vccnz .LBB0_191

.LBB0_268:
	s_waitcnt lgkmcnt(0)
	ds_read_b128 v[128:131], v244
	ds_read_b128 v[132:135], v244 offset:1024
	ds_read_b128 v[136:139], v244 offset:2048
	ds_read_b128 v[140:143], v244 offset:3072
	s_add_u32 s38, s36, 0xfff50080
	s_addc_u32 s39, s37, -1
	s_cmp_eq_u32 s67, 40
	s_cselect_b32 s41, s9, s39
	s_cselect_b32 s40, s8, s38
	s_cselect_b32 s39, s11, s66
	s_cselect_b32 s38, s10, s16
	v_lshl_add_u64 v[176:177], s[36:37], 0, v[202:203]
	s_add_i32 m0, s45, 0xc000
	ds_read_b128 v[144:147], v245
	ds_read_b128 v[148:151], v245 offset:1024
	ds_read_b128 v[152:155], v245 offset:2048
	ds_read_b128 v[156:159], v245 offset:3072
	ds_read_b128 v[160:163], v245 offset:4096
	ds_read_b128 v[164:167], v245 offset:5120
	ds_read_b128 v[168:171], v245 offset:6144
	ds_read_b128 v[172:175], v245 offset:7168
	global_load_lds_dwordx4 v[176:177], off
	v_lshl_add_u64 v[176:177], s[36:37], 0, v[204:205]
	s_add_i32 m0, s45, 0xe000
	s_nop 0
	global_load_lds_dwordx4 v[176:177], off
	s_waitcnt lgkmcnt(8)
	s_barrier
	s_waitcnt lgkmcnt(0)
	s_setprio 1
	s_waitcnt lgkmcnt(0)
	v_mfma_f32_16x16x32_bf16 v[124:127], v[128:131], v[144:147], v[124:127]
	v_mfma_f32_16x16x32_bf16 v[120:123], v[136:139], v[144:147], v[120:123]
	v_mfma_f32_16x16x32_bf16 v[108:111], v[128:131], v[152:155], v[108:111]
	v_mfma_f32_16x16x32_bf16 v[104:107], v[136:139], v[152:155], v[104:107]
	v_mfma_f32_16x16x32_bf16 v[92:95], v[128:131], v[160:163], v[92:95]
	v_mfma_f32_16x16x32_bf16 v[88:91], v[136:139], v[160:163], v[88:91]
	v_mfma_f32_16x16x32_bf16 v[76:79], v[128:131], v[168:171], v[76:79]
	v_mfma_f32_16x16x32_bf16 v[72:75], v[136:139], v[168:171], v[72:75]
	v_mfma_f32_16x16x32_bf16 v[124:127], v[132:135], v[148:151], v[124:127]
	v_mfma_f32_16x16x32_bf16 v[120:123], v[140:143], v[148:151], v[120:123]
	v_mfma_f32_16x16x32_bf16 v[108:111], v[132:135], v[156:159], v[108:111]
	v_mfma_f32_16x16x32_bf16 v[104:107], v[140:143], v[156:159], v[104:107]
	v_mfma_f32_16x16x32_bf16 v[92:95], v[132:135], v[164:167], v[92:95]
	v_mfma_f32_16x16x32_bf16 v[88:91], v[140:143], v[164:167], v[88:91]
	v_mfma_f32_16x16x32_bf16 v[76:79], v[132:135], v[172:175], v[76:79]
	v_mfma_f32_16x16x32_bf16 v[72:75], v[140:143], v[172:175], v[72:75]
	s_setprio 0
	s_barrier
	s_add_i32 s68, s55, s44
	v_lshl_add_u64 v[206:207], s[38:39], 0, v[196:197]
	s_mov_b32 m0, s68
	ds_read_b128 v[176:179], v246
	ds_read_b128 v[180:183], v246 offset:1024
	ds_read_b128 v[184:187], v246 offset:2048
	ds_read_b128 v[188:191], v246 offset:3072
	global_load_lds_dwordx4 v[206:207], off
	v_lshl_add_u64 v[208:209], s[38:39], 0, v[200:201]
	s_add_i32 m0, s68, 0x2000
	s_nop 0
	global_load_lds_dwordx4 v[208:209], off
	s_barrier
	s_waitcnt lgkmcnt(0)
	s_setprio 1
	s_waitcnt lgkmcnt(0)
	v_mfma_f32_16x16x32_bf16 v[116:119], v[176:179], v[144:147], v[116:119]
	v_mfma_f32_16x16x32_bf16 v[112:115], v[184:187], v[144:147], v[112:115]
	v_mfma_f32_16x16x32_bf16 v[100:103], v[176:179], v[152:155], v[100:103]
	v_mfma_f32_16x16x32_bf16 v[96:99], v[184:187], v[152:155], v[96:99]
	v_mfma_f32_16x16x32_bf16 v[84:87], v[176:179], v[160:163], v[84:87]
	v_mfma_f32_16x16x32_bf16 v[80:83], v[184:187], v[160:163], v[80:83]
	v_mfma_f32_16x16x32_bf16 v[68:71], v[176:179], v[168:171], v[68:71]
	v_mfma_f32_16x16x32_bf16 v[64:67], v[184:187], v[168:171], v[64:67]
	v_mfma_f32_16x16x32_bf16 v[116:119], v[180:183], v[148:151], v[116:119]
	v_mfma_f32_16x16x32_bf16 v[112:115], v[188:191], v[148:151], v[112:115]
	v_mfma_f32_16x16x32_bf16 v[100:103], v[180:183], v[156:159], v[100:103]
	v_mfma_f32_16x16x32_bf16 v[96:99], v[188:191], v[156:159], v[96:99]
	v_mfma_f32_16x16x32_bf16 v[84:87], v[180:183], v[164:167], v[84:87]
	v_mfma_f32_16x16x32_bf16 v[80:83], v[188:191], v[164:167], v[80:83]
	v_mfma_f32_16x16x32_bf16 v[68:71], v[180:183], v[172:175], v[68:71]
	v_mfma_f32_16x16x32_bf16 v[64:67], v[188:191], v[172:175], v[64:67]
	s_setprio 0
	s_mov_b32 m0, s45
	v_lshl_add_u64 v[210:211], s[40:41], 0, v[194:195]
	s_barrier
	ds_read_b128 v[144:147], v245 offset:16384
	ds_read_b128 v[148:151], v245 offset:17408
	ds_read_b128 v[152:155], v245 offset:18432
	ds_read_b128 v[156:159], v245 offset:19456
	ds_read_b128 v[160:163], v245 offset:20480
	ds_read_b128 v[164:167], v245 offset:21504
	ds_read_b128 v[168:171], v245 offset:22528
	ds_read_b128 v[172:175], v245 offset:23552
	global_load_lds_dwordx4 v[210:211], off
	v_lshl_add_u64 v[212:213], s[40:41], 0, v[198:199]
	s_mov_b32 m0, s46
	s_nop 0
	global_load_lds_dwordx4 v[212:213], off
	s_barrier
	s_waitcnt lgkmcnt(0)
	s_setprio 1
	s_waitcnt lgkmcnt(0)
	v_mfma_f32_16x16x32_bf16 v[60:63], v[128:131], v[144:147], v[60:63]
	v_mfma_f32_16x16x32_bf16 v[56:59], v[136:139], v[144:147], v[56:59]
	v_mfma_f32_16x16x32_bf16 v[44:47], v[128:131], v[152:155], v[44:47]
	v_mfma_f32_16x16x32_bf16 v[40:43], v[136:139], v[152:155], v[40:43]
	v_mfma_f32_16x16x32_bf16 v[28:31], v[128:131], v[160:163], v[28:31]
	v_mfma_f32_16x16x32_bf16 v[24:27], v[136:139], v[160:163], v[24:27]
	v_mfma_f32_16x16x32_bf16 v[12:15], v[128:131], v[168:171], v[12:15]
	v_mfma_f32_16x16x32_bf16 v[8:11], v[136:139], v[168:171], v[8:11]
	v_mfma_f32_16x16x32_bf16 v[60:63], v[132:135], v[148:151], v[60:63]
	v_mfma_f32_16x16x32_bf16 v[56:59], v[140:143], v[148:151], v[56:59]
	v_mfma_f32_16x16x32_bf16 v[44:47], v[132:135], v[156:159], v[44:47]
	v_mfma_f32_16x16x32_bf16 v[40:43], v[140:143], v[156:159], v[40:43]
	v_mfma_f32_16x16x32_bf16 v[28:31], v[132:135], v[164:167], v[28:31]
	v_mfma_f32_16x16x32_bf16 v[24:27], v[140:143], v[164:167], v[24:27]
	v_mfma_f32_16x16x32_bf16 v[12:15], v[132:135], v[172:175], v[12:15]
	v_mfma_f32_16x16x32_bf16 v[8:11], v[140:143], v[172:175], v[8:11]
	s_setprio 0
	s_barrier
	s_add_u32 s68, s38, 0xb0000
	s_addc_u32 s69, s39, 0
	s_add_i32 s70, s56, s44
	v_lshl_add_u64 v[128:129], s[68:69], 0, v[196:197]
	s_mov_b32 m0, s70
	s_nop 0
	global_load_lds_dwordx4 v[128:129], off
	v_lshl_add_u64 v[128:129], s[68:69], 0, v[200:201]
	s_add_i32 m0, s70, 0x2000
	s_nop 0
	global_load_lds_dwordx4 v[128:129], off
	s_waitcnt vmcnt(6)
	s_barrier
	s_setprio 1
	v_mfma_f32_16x16x32_bf16 v[52:55], v[176:179], v[144:147], v[52:55]
	v_mfma_f32_16x16x32_bf16 v[48:51], v[184:187], v[144:147], v[48:51]
	v_mfma_f32_16x16x32_bf16 v[36:39], v[176:179], v[152:155], v[36:39]
	v_mfma_f32_16x16x32_bf16 v[32:35], v[184:187], v[152:155], v[32:35]
	v_mfma_f32_16x16x32_bf16 v[20:23], v[176:179], v[160:163], v[20:23]
	v_mfma_f32_16x16x32_bf16 v[16:19], v[184:187], v[160:163], v[16:19]
	v_mfma_f32_16x16x32_bf16 v[4:7], v[176:179], v[168:171], v[4:7]
	v_mfma_f32_16x16x32_bf16 v[0:3], v[184:187], v[168:171], v[0:3]
	v_mfma_f32_16x16x32_bf16 v[52:55], v[180:183], v[148:151], v[52:55]
	v_mfma_f32_16x16x32_bf16 v[48:51], v[188:191], v[148:151], v[48:51]
	v_mfma_f32_16x16x32_bf16 v[36:39], v[180:183], v[156:159], v[36:39]
	v_mfma_f32_16x16x32_bf16 v[32:35], v[188:191], v[156:159], v[32:35]
	v_mfma_f32_16x16x32_bf16 v[20:23], v[180:183], v[164:167], v[20:23]
	v_mfma_f32_16x16x32_bf16 v[16:19], v[188:191], v[164:167], v[16:19]
	v_mfma_f32_16x16x32_bf16 v[4:7], v[180:183], v[172:175], v[4:7]
	v_mfma_f32_16x16x32_bf16 v[0:3], v[188:191], v[172:175], v[0:3]
	s_setprio 0
	s_add_i32 s68, 0, 0x18000
	v_add_u32_e32 v140, s68, v242
	s_barrier
	ds_read_b128 v[128:131], v140
	ds_read_b128 v[132:135], v140 offset:1024
	ds_read_b128 v[136:139], v140 offset:2048
	ds_read_b128 v[140:143], v140 offset:3072
	s_add_u32 s40, s40, 0xb0000
	s_addc_u32 s41, s41, 0
	s_mov_b32 m0, s47
	v_lshl_add_u64 v[176:177], s[40:41], 0, v[194:195]
	ds_read_b128 v[144:147], v245 offset:32768
	ds_read_b128 v[148:151], v245 offset:33792
	ds_read_b128 v[152:155], v245 offset:34816
	ds_read_b128 v[156:159], v245 offset:35840
	ds_read_b128 v[160:163], v245 offset:36864
	ds_read_b128 v[164:167], v245 offset:37888
	ds_read_b128 v[168:171], v245 offset:38912
	ds_read_b128 v[172:175], v245 offset:39936
	global_load_lds_dwordx4 v[176:177], off
	v_lshl_add_u64 v[176:177], s[40:41], 0, v[198:199]
	s_mov_b32 m0, s48
	s_nop 0
	global_load_lds_dwordx4 v[176:177], off
	s_waitcnt lgkmcnt(8)
	s_barrier
	s_waitcnt lgkmcnt(0)
	s_setprio 1
	s_waitcnt lgkmcnt(0)
	v_mfma_f32_16x16x32_bf16 v[124:127], v[128:131], v[144:147], v[124:127]
	v_mfma_f32_16x16x32_bf16 v[120:123], v[136:139], v[144:147], v[120:123]
	v_mfma_f32_16x16x32_bf16 v[108:111], v[128:131], v[152:155], v[108:111]
	v_mfma_f32_16x16x32_bf16 v[104:107], v[136:139], v[152:155], v[104:107]
	v_mfma_f32_16x16x32_bf16 v[92:95], v[128:131], v[160:163], v[92:95]
	v_mfma_f32_16x16x32_bf16 v[88:91], v[136:139], v[160:163], v[88:91]
	v_mfma_f32_16x16x32_bf16 v[76:79], v[128:131], v[168:171], v[76:79]
	v_mfma_f32_16x16x32_bf16 v[72:75], v[136:139], v[168:171], v[72:75]
	v_mfma_f32_16x16x32_bf16 v[124:127], v[132:135], v[148:151], v[124:127]
	v_mfma_f32_16x16x32_bf16 v[120:123], v[140:143], v[148:151], v[120:123]
	v_mfma_f32_16x16x32_bf16 v[108:111], v[132:135], v[156:159], v[108:111]
	v_mfma_f32_16x16x32_bf16 v[104:107], v[140:143], v[156:159], v[104:107]
	v_mfma_f32_16x16x32_bf16 v[92:95], v[132:135], v[164:167], v[92:95]
	v_mfma_f32_16x16x32_bf16 v[88:91], v[140:143], v[164:167], v[88:91]
	v_mfma_f32_16x16x32_bf16 v[76:79], v[132:135], v[172:175], v[76:79]
	v_mfma_f32_16x16x32_bf16 v[72:75], v[140:143], v[172:175], v[72:75]
	s_setprio 0
	s_barrier
	s_add_i32 s40, 0, 0x1c000
	s_add_i32 s41, s68, s44
	v_add_u32_e32 v188, s40, v242
	v_lshl_add_u64 v[206:207], v[206:207], 0, s[28:29]
	s_mov_b32 m0, s41
	ds_read_b128 v[176:179], v188
	ds_read_b128 v[180:183], v188 offset:1024
	ds_read_b128 v[184:187], v188 offset:2048
	ds_read_b128 v[188:191], v188 offset:3072
	global_load_lds_dwordx4 v[206:207], off
	v_lshl_add_u64 v[206:207], v[208:209], 0, s[28:29]
	s_add_i32 m0, s41, 0x2000
	s_nop 0
	global_load_lds_dwordx4 v[206:207], off
	s_barrier
	s_waitcnt lgkmcnt(0)
	s_setprio 1
	s_waitcnt lgkmcnt(0)
	v_mfma_f32_16x16x32_bf16 v[116:119], v[176:179], v[144:147], v[116:119]
	v_mfma_f32_16x16x32_bf16 v[112:115], v[184:187], v[144:147], v[112:115]
	v_mfma_f32_16x16x32_bf16 v[100:103], v[176:179], v[152:155], v[100:103]
	v_mfma_f32_16x16x32_bf16 v[96:99], v[184:187], v[152:155], v[96:99]
	v_mfma_f32_16x16x32_bf16 v[84:87], v[176:179], v[160:163], v[84:87]
	v_mfma_f32_16x16x32_bf16 v[80:83], v[184:187], v[160:163], v[80:83]
	v_mfma_f32_16x16x32_bf16 v[68:71], v[176:179], v[168:171], v[68:71]
	v_mfma_f32_16x16x32_bf16 v[64:67], v[184:187], v[168:171], v[64:67]
	v_mfma_f32_16x16x32_bf16 v[116:119], v[180:183], v[148:151], v[116:119]
	v_mfma_f32_16x16x32_bf16 v[112:115], v[188:191], v[148:151], v[112:115]
	v_mfma_f32_16x16x32_bf16 v[100:103], v[180:183], v[156:159], v[100:103]
	v_mfma_f32_16x16x32_bf16 v[96:99], v[188:191], v[156:159], v[96:99]
	v_mfma_f32_16x16x32_bf16 v[84:87], v[180:183], v[164:167], v[84:87]
	v_mfma_f32_16x16x32_bf16 v[80:83], v[188:191], v[164:167], v[80:83]
	v_mfma_f32_16x16x32_bf16 v[68:71], v[180:183], v[172:175], v[68:71]
	v_mfma_f32_16x16x32_bf16 v[64:67], v[188:191], v[172:175], v[64:67]
	s_setprio 0
	s_mov_b32 m0, s50
	v_lshl_add_u64 v[206:207], v[210:211], 0, s[28:29]
	s_barrier
	ds_read_b128 v[144:147], v245 offset:49152
	ds_read_b128 v[148:151], v245 offset:50176
	ds_read_b128 v[152:155], v245 offset:51200
	ds_read_b128 v[156:159], v245 offset:52224
	ds_read_b128 v[160:163], v245 offset:53248
	ds_read_b128 v[164:167], v245 offset:54272
	ds_read_b128 v[168:171], v245 offset:55296
	ds_read_b128 v[172:175], v245 offset:56320
	global_load_lds_dwordx4 v[206:207], off
	v_lshl_add_u64 v[206:207], v[212:213], 0, s[28:29]
	s_mov_b32 m0, s51
	s_nop 0
	global_load_lds_dwordx4 v[206:207], off
	s_barrier
	s_waitcnt lgkmcnt(0)
	s_setprio 1
	s_waitcnt lgkmcnt(0)
	v_mfma_f32_16x16x32_bf16 v[60:63], v[128:131], v[144:147], v[60:63]
	v_mfma_f32_16x16x32_bf16 v[56:59], v[136:139], v[144:147], v[56:59]
	v_mfma_f32_16x16x32_bf16 v[44:47], v[128:131], v[152:155], v[44:47]
	v_mfma_f32_16x16x32_bf16 v[40:43], v[136:139], v[152:155], v[40:43]
	v_mfma_f32_16x16x32_bf16 v[28:31], v[128:131], v[160:163], v[28:31]
	v_mfma_f32_16x16x32_bf16 v[24:27], v[136:139], v[160:163], v[24:27]
	v_mfma_f32_16x16x32_bf16 v[12:15], v[128:131], v[168:171], v[12:15]
	v_mfma_f32_16x16x32_bf16 v[8:11], v[136:139], v[168:171], v[8:11]
	v_mfma_f32_16x16x32_bf16 v[60:63], v[132:135], v[148:151], v[60:63]
	v_mfma_f32_16x16x32_bf16 v[56:59], v[140:143], v[148:151], v[56:59]
	v_mfma_f32_16x16x32_bf16 v[44:47], v[132:135], v[156:159], v[44:47]
	v_mfma_f32_16x16x32_bf16 v[40:43], v[140:143], v[156:159], v[40:43]
	v_mfma_f32_16x16x32_bf16 v[28:31], v[132:135], v[164:167], v[28:31]
	v_mfma_f32_16x16x32_bf16 v[24:27], v[140:143], v[164:167], v[24:27]
	v_mfma_f32_16x16x32_bf16 v[12:15], v[132:135], v[172:175], v[12:15]
	v_mfma_f32_16x16x32_bf16 v[8:11], v[140:143], v[172:175], v[8:11]
	s_setprio 0
	s_barrier
	s_add_u32 s38, s38, 0xb0080
	s_addc_u32 s39, s39, 0
	s_add_i32 s40, s40, s44
	v_lshl_add_u64 v[128:129], s[38:39], 0, v[196:197]
	s_mov_b32 m0, s40
	s_nop 0
	global_load_lds_dwordx4 v[128:129], off
	v_lshl_add_u64 v[128:129], s[38:39], 0, v[200:201]
	s_add_i32 m0, s40, 0x2000
	s_nop 0
	global_load_lds_dwordx4 v[128:129], off
	s_waitcnt vmcnt(6)
	s_barrier
	s_setprio 1
	v_mfma_f32_16x16x32_bf16 v[52:55], v[176:179], v[144:147], v[52:55]
	v_mfma_f32_16x16x32_bf16 v[48:51], v[184:187], v[144:147], v[48:51]
	v_mfma_f32_16x16x32_bf16 v[36:39], v[176:179], v[152:155], v[36:39]
	v_mfma_f32_16x16x32_bf16 v[32:35], v[184:187], v[152:155], v[32:35]
	v_mfma_f32_16x16x32_bf16 v[20:23], v[176:179], v[160:163], v[20:23]
	v_mfma_f32_16x16x32_bf16 v[16:19], v[184:187], v[160:163], v[16:19]
	v_mfma_f32_16x16x32_bf16 v[4:7], v[176:179], v[168:171], v[4:7]
	v_mfma_f32_16x16x32_bf16 v[0:3], v[184:187], v[168:171], v[0:3]
	v_mfma_f32_16x16x32_bf16 v[52:55], v[180:183], v[148:151], v[52:55]
	v_mfma_f32_16x16x32_bf16 v[48:51], v[188:191], v[148:151], v[48:51]
	v_mfma_f32_16x16x32_bf16 v[36:39], v[180:183], v[156:159], v[36:39]
	v_mfma_f32_16x16x32_bf16 v[32:35], v[188:191], v[156:159], v[32:35]
	v_mfma_f32_16x16x32_bf16 v[20:23], v[180:183], v[164:167], v[20:23]
	v_mfma_f32_16x16x32_bf16 v[16:19], v[188:191], v[164:167], v[16:19]
	v_mfma_f32_16x16x32_bf16 v[4:7], v[180:183], v[172:175], v[4:7]
	v_mfma_f32_16x16x32_bf16 v[0:3], v[188:191], v[172:175], v[0:3]
	s_setprio 0
	s_add_i32 s67, s67, 2
	s_add_u32 s36, s36, 0x100
	s_addc_u32 s37, s37, 0
	s_add_u32 s16, s16, 0x100
	s_addc_u32 s66, s66, 0
	s_cmp_gt_u32 s67, 41
	s_barrier
	s_cbranch_scc0 .LBB0_268
	v_lshl_add_u32 v216, s65, 8, v193
	v_lshl_or_b32 v206, s64, 8, v243
	v_or_b32_e32 v214, 16, v216
	v_or_b32_e32 v210, 32, v216
	v_or_b32_e32 v208, 48, v216
	v_ashrrev_i32_e32 v207, 31, v206
	s_andn2_b64 vcc, exec, s[34:35]
	v_ashrrev_i32_e32 v217, 31, v216
	v_ashrrev_i32_e32 v215, 31, v214
	v_ashrrev_i32_e32 v211, 31, v210
	v_ashrrev_i32_e32 v209, 31, v208
	s_cbranch_vccnz .LBB0_300
	v_lshl_add_u64 v[176:177], v[206:207], 2, s[12:13]
	v_lshlrev_b64 v[128:129], 12, v[216:217]
	v_lshl_add_u64 v[128:129], v[176:177], 0, v[128:129]
	global_load_dwordx4 v[178:181], v[128:129], off
	global_load_dwordx4 v[186:189], v[128:129], off offset:16
	global_load_dwordx4 v[218:221], v[128:129], off offset:512
	global_load_dwordx4 v[222:225], v[128:129], off offset:528
	v_lshlrev_b64 v[128:129], 12, v[214:215]
	v_lshlrev_b64 v[130:131], 12, v[210:211]
	v_lshlrev_b64 v[132:133], 12, v[208:209]
	v_lshl_add_u64 v[128:129], v[176:177], 0, v[128:129]
	v_lshl_add_u64 v[130:131], v[176:177], 0, v[130:131]
	v_lshl_add_u64 v[132:133], v[176:177], 0, v[132:133]
	global_load_dwordx4 v[168:171], v[128:129], off offset:16
	global_load_dwordx4 v[172:175], v[128:129], off
	global_load_dwordx4 v[160:163], v[128:129], off offset:528
	global_load_dwordx4 v[164:167], v[128:129], off offset:512
	global_load_dwordx4 v[152:155], v[130:131], off offset:16
	global_load_dwordx4 v[156:159], v[130:131], off
	global_load_dwordx4 v[144:147], v[130:131], off offset:528
	global_load_dwordx4 v[148:151], v[130:131], off offset:512
	global_load_dwordx4 v[136:139], v[132:133], off offset:16
	global_load_dwordx4 v[140:143], v[132:133], off
	s_nop 0
	global_load_dwordx4 v[128:131], v[132:133], off offset:528
	s_nop 0
	global_load_dwordx4 v[132:135], v[132:133], off offset:512
	v_and_b32_e32 v185, 64, v247
	v_xor_b32_e32 v184, 16, v247
	v_add_u32_e32 v185, 64, v185
	v_xor_b32_e32 v190, 32, v247
	v_cmp_lt_i32_e32 vcc, v184, v185
	v_lshlrev_b64 v[182:183], 11, v[216:217]
	v_lshl_add_u64 v[182:183], s[24:25], 0, v[182:183]
	v_cndmask_b32_e32 v184, v247, v184, vcc
	v_cmp_lt_i32_e32 vcc, v190, v185
	v_lshlrev_b32_e32 v185, 2, v184
	s_lshl_b32 s36, s64, 2
	v_cndmask_b32_e32 v190, v247, v190, vcc
	v_lshlrev_b32_e32 v184, 2, v190
	s_ashr_i32 s37, s36, 31
	s_waitcnt vmcnt(0)
	v_pk_add_f32 v[190:191], v[126:127], v[180:181]
	v_pk_add_f32 v[212:213], v[124:125], v[178:179]
	v_pk_add_f32 v[188:189], v[122:123], v[188:189]
	v_pk_add_f32 v[186:187], v[120:121], v[186:187]
	v_pk_add_f32 v[220:221], v[118:119], v[220:221]
	v_pk_add_f32 v[218:219], v[116:117], v[218:219]
	v_pk_add_f32 v[224:225], v[114:115], v[224:225]
	v_pk_add_f32 v[222:223], v[112:113], v[222:223]
	v_mul_f32_e32 v226, v213, v213
	v_mul_f32_e32 v227, v191, v191
	v_mul_f32_e32 v228, v187, v187
	v_mul_f32_e32 v229, v189, v189
	v_cvt_pk_bf16_f32 v178, v212, v213
	v_cvt_pk_bf16_f32 v179, v190, v191
	v_cvt_pk_bf16_f32 v180, v186, v187
	v_cvt_pk_bf16_f32 v181, v188, v189
	v_mul_f32_e32 v187, v219, v219
	v_mul_f32_e32 v189, v221, v221
	v_mul_f32_e32 v191, v223, v223
	v_mul_f32_e32 v213, v225, v225
	v_fmac_f32_e32 v226, v212, v212
	v_fmac_f32_e32 v227, v190, v190
	v_fmac_f32_e32 v228, v186, v186
	v_fmac_f32_e32 v229, v188, v188
	v_fmac_f32_e32 v187, v218, v218
	v_fmac_f32_e32 v189, v220, v220
	v_fmac_f32_e32 v191, v222, v222
	v_fmac_f32_e32 v213, v224, v224
	v_add_f32_e32 v186, v226, v227
	v_add_f32_e32 v188, v228, v229
	v_add_f32_e32 v187, v187, v189
	v_add_f32_e32 v189, v191, v213
	v_add_f32_e32 v186, v186, v188
	v_add_f32_e32 v187, v187, v189
	v_add_f32_e32 v188, v186, v187
	ds_bpermute_b32 v189, v185, v188
	v_lshl_add_u64 v[186:187], v[206:207], 1, v[182:183]
	global_store_dwordx4 v[186:187], v[178:181], off sc1
	v_cvt_pk_bf16_f32 v182, v222, v223
	v_cvt_pk_bf16_f32 v183, v224, v225
	s_waitcnt lgkmcnt(0)
	v_add_f32_e32 v178, v188, v189
	ds_bpermute_b32 v179, v184, v178
	v_cvt_pk_bf16_f32 v180, v218, v219
	v_cvt_pk_bf16_f32 v181, v220, v221
	global_store_dwordx4 v[186:187], v[180:183], off offset:256 sc1
	s_and_saveexec_b64 s[38:39], s[30:31]
	s_cbranch_execz .LBB0_272
	v_lshlrev_b64 v[180:181], 6, v[216:217]
	v_lshl_add_u64 v[180:181], s[26:27], 0, v[180:181]
	v_lshl_add_u64 v[180:181], s[36:37], 2, v[180:181]
	s_lshl_b32 s16, s49, 2
	v_lshl_add_u64 v[180:181], v[180:181], 0, s[16:17]
	s_waitcnt lgkmcnt(0)
	v_add_f32_e32 v178, v178, v179
	global_store_dword v[180:181], v178, off
.LBB0_272:
	s_or_b64 exec, exec, s[38:39]
	v_pk_add_f32 v[174:175], v[110:111], v[174:175]
	v_pk_add_f32 v[172:173], v[108:109], v[172:173]
	v_pk_add_f32 v[180:181], v[106:107], v[170:171]
	v_pk_add_f32 v[170:171], v[104:105], v[168:169]
	v_mul_f32_e32 v168, v173, v173
	v_mul_f32_e32 v169, v175, v175
	v_fmac_f32_e32 v168, v172, v172
	v_fmac_f32_e32 v169, v174, v174
	v_add_f32_e32 v168, v168, v169
	v_mul_f32_e32 v169, v171, v171
	v_mul_f32_e32 v182, v181, v181
	v_fmac_f32_e32 v169, v170, v170
	v_fmac_f32_e32 v182, v180, v180
	v_add_f32_e32 v169, v169, v182
	v_pk_add_f32 v[166:167], v[102:103], v[166:167]
	v_pk_add_f32 v[164:165], v[100:101], v[164:165]
	v_add_f32_e32 v182, v168, v169
	v_cvt_pk_bf16_f32 v169, v174, v175
	v_pk_add_f32 v[174:175], v[96:97], v[160:161]
	v_mul_f32_e32 v160, v165, v165
	v_mul_f32_e32 v161, v167, v167
	v_cvt_pk_bf16_f32 v168, v172, v173
	v_pk_add_f32 v[172:173], v[98:99], v[162:163]
	v_fmac_f32_e32 v160, v164, v164
	v_fmac_f32_e32 v161, v166, v166
	v_add_f32_e32 v160, v160, v161
	v_mul_f32_e32 v161, v175, v175
	v_mul_f32_e32 v162, v173, v173
	v_fmac_f32_e32 v161, v174, v174
	v_fmac_f32_e32 v162, v172, v172
	v_add_f32_e32 v161, v161, v162
	v_add_f32_e32 v160, v160, v161
	v_add_f32_e32 v163, v182, v160
	v_cvt_pk_bf16_f32 v170, v170, v171
	v_cvt_pk_bf16_f32 v171, v180, v181
	ds_bpermute_b32 v180, v185, v163
	s_waitcnt lgkmcnt(1)
	v_lshlrev_b64 v[178:179], 11, v[214:215]
	v_lshl_add_u64 v[160:161], s[24:25], 0, v[178:179]
	v_lshl_add_u64 v[178:179], v[206:207], 1, v[160:161]
	v_cvt_pk_bf16_f32 v162, v164, v165
	s_waitcnt lgkmcnt(0)
	v_add_f32_e32 v160, v163, v180
	ds_bpermute_b32 v161, v184, v160
	v_cvt_pk_bf16_f32 v163, v166, v167
	v_cvt_pk_bf16_f32 v164, v174, v175
	v_cvt_pk_bf16_f32 v165, v172, v173
	global_store_dwordx4 v[178:179], v[168:171], off sc1
	global_store_dwordx4 v[178:179], v[162:165], off offset:256 sc1
	s_and_saveexec_b64 s[38:39], s[30:31]
	s_cbranch_execz .LBB0_274
	v_lshlrev_b64 v[162:163], 6, v[214:215]
	v_lshl_add_u64 v[162:163], s[26:27], 0, v[162:163]
	v_lshl_add_u64 v[162:163], s[36:37], 2, v[162:163]
	s_lshl_b32 s16, s49, 2
	v_lshl_add_u64 v[162:163], v[162:163], 0, s[16:17]
	s_waitcnt lgkmcnt(0)
	v_add_f32_e32 v160, v160, v161
	global_store_dword v[162:163], v160, off
.LBB0_274:
	s_or_b64 exec, exec, s[38:39]
	v_pk_add_f32 v[158:159], v[94:95], v[158:159]
	v_pk_add_f32 v[156:157], v[92:93], v[156:157]
	v_pk_add_f32 v[162:163], v[90:91], v[154:155]
	v_pk_add_f32 v[154:155], v[88:89], v[152:153]
	v_mul_f32_e32 v152, v157, v157
	v_mul_f32_e32 v153, v159, v159
	v_fmac_f32_e32 v152, v156, v156
	v_fmac_f32_e32 v153, v158, v158
	v_add_f32_e32 v152, v152, v153
	v_mul_f32_e32 v153, v155, v155
	v_mul_f32_e32 v164, v163, v163
	v_fmac_f32_e32 v153, v154, v154
	v_fmac_f32_e32 v164, v162, v162
	v_add_f32_e32 v153, v153, v164
	v_pk_add_f32 v[150:151], v[86:87], v[150:151]
	v_pk_add_f32 v[148:149], v[84:85], v[148:149]
	v_add_f32_e32 v164, v152, v153
	v_cvt_pk_bf16_f32 v153, v158, v159
	v_pk_add_f32 v[158:159], v[80:81], v[144:145]
	v_mul_f32_e32 v144, v149, v149
	v_mul_f32_e32 v145, v151, v151
	v_cvt_pk_bf16_f32 v152, v156, v157
	v_pk_add_f32 v[156:157], v[82:83], v[146:147]
	v_fmac_f32_e32 v144, v148, v148
	v_fmac_f32_e32 v145, v150, v150
	v_add_f32_e32 v144, v144, v145
	v_mul_f32_e32 v145, v159, v159
	v_mul_f32_e32 v146, v157, v157
	v_fmac_f32_e32 v145, v158, v158
	v_fmac_f32_e32 v146, v156, v156
	v_add_f32_e32 v145, v145, v146
	v_add_f32_e32 v144, v144, v145
	v_add_f32_e32 v147, v164, v144
	v_cvt_pk_bf16_f32 v154, v154, v155
	v_cvt_pk_bf16_f32 v155, v162, v163
	ds_bpermute_b32 v162, v185, v147
	s_waitcnt lgkmcnt(1)
	v_lshlrev_b64 v[160:161], 11, v[210:211]
	v_lshl_add_u64 v[144:145], s[24:25], 0, v[160:161]
	v_lshl_add_u64 v[160:161], v[206:207], 1, v[144:145]
	v_cvt_pk_bf16_f32 v146, v148, v149
	s_waitcnt lgkmcnt(0)
	v_add_f32_e32 v144, v147, v162
	ds_bpermute_b32 v145, v184, v144
	v_cvt_pk_bf16_f32 v147, v150, v151
	v_cvt_pk_bf16_f32 v148, v158, v159
	v_cvt_pk_bf16_f32 v149, v156, v157
	global_store_dwordx4 v[160:161], v[152:155], off sc1
	global_store_dwordx4 v[160:161], v[146:149], off offset:256 sc1
	s_and_saveexec_b64 s[38:39], s[30:31]
	s_cbranch_execz .LBB0_276
	v_lshlrev_b64 v[146:147], 6, v[210:211]
	v_lshl_add_u64 v[146:147], s[26:27], 0, v[146:147]
	v_lshl_add_u64 v[146:147], s[36:37], 2, v[146:147]
	s_lshl_b32 s16, s49, 2
	v_lshl_add_u64 v[146:147], v[146:147], 0, s[16:17]
	s_waitcnt lgkmcnt(0)
	v_add_f32_e32 v144, v144, v145
	global_store_dword v[146:147], v144, off
.LBB0_276:
	s_or_b64 exec, exec, s[38:39]
	v_pk_add_f32 v[142:143], v[78:79], v[142:143]
	v_pk_add_f32 v[140:141], v[76:77], v[140:141]
	v_pk_add_f32 v[146:147], v[74:75], v[138:139]
	v_pk_add_f32 v[138:139], v[72:73], v[136:137]
	v_mul_f32_e32 v136, v141, v141
	v_mul_f32_e32 v137, v143, v143
	v_fmac_f32_e32 v136, v140, v140
	v_fmac_f32_e32 v137, v142, v142
	v_add_f32_e32 v136, v136, v137
	v_mul_f32_e32 v137, v139, v139
	v_mul_f32_e32 v148, v147, v147
	v_fmac_f32_e32 v137, v138, v138
	v_fmac_f32_e32 v148, v146, v146
	v_add_f32_e32 v137, v137, v148
	v_pk_add_f32 v[134:135], v[70:71], v[134:135]
	v_pk_add_f32 v[132:133], v[68:69], v[132:133]
	v_add_f32_e32 v148, v136, v137
	v_cvt_pk_bf16_f32 v137, v142, v143
	v_pk_add_f32 v[142:143], v[64:65], v[128:129]
	v_mul_f32_e32 v128, v133, v133
	v_mul_f32_e32 v129, v135, v135
	v_cvt_pk_bf16_f32 v136, v140, v141
	v_pk_add_f32 v[140:141], v[66:67], v[130:131]
	v_fmac_f32_e32 v128, v132, v132
	v_fmac_f32_e32 v129, v134, v134
	v_add_f32_e32 v128, v128, v129
	v_mul_f32_e32 v129, v143, v143
	v_mul_f32_e32 v130, v141, v141
	v_fmac_f32_e32 v129, v142, v142
	v_fmac_f32_e32 v130, v140, v140
	v_add_f32_e32 v129, v129, v130
	v_add_f32_e32 v128, v128, v129
	v_add_f32_e32 v131, v148, v128
	v_cvt_pk_bf16_f32 v138, v138, v139
	v_cvt_pk_bf16_f32 v139, v146, v147
	ds_bpermute_b32 v146, v185, v131
	s_waitcnt lgkmcnt(1)
	v_lshlrev_b64 v[144:145], 11, v[208:209]
	v_lshl_add_u64 v[128:129], s[24:25], 0, v[144:145]
	v_lshl_add_u64 v[144:145], v[206:207], 1, v[128:129]
	v_cvt_pk_bf16_f32 v130, v132, v133
	s_waitcnt lgkmcnt(0)
	v_add_f32_e32 v128, v131, v146
	ds_bpermute_b32 v129, v184, v128
	v_cvt_pk_bf16_f32 v131, v134, v135
	v_cvt_pk_bf16_f32 v132, v142, v143
	v_cvt_pk_bf16_f32 v133, v140, v141
	global_store_dwordx4 v[144:145], v[136:139], off sc1
	global_store_dwordx4 v[144:145], v[130:133], off offset:256 sc1
	s_and_saveexec_b64 s[38:39], s[30:31]
	s_cbranch_execz .LBB0_278
	v_lshlrev_b64 v[130:131], 6, v[208:209]
	v_lshl_add_u64 v[130:131], s[26:27], 0, v[130:131]
	v_lshl_add_u64 v[130:131], s[36:37], 2, v[130:131]
	s_lshl_b32 s16, s49, 2
	v_lshl_add_u64 v[130:131], v[130:131], 0, s[16:17]
	s_waitcnt lgkmcnt(0)
	v_add_f32_e32 v128, v128, v129
	global_store_dword v[130:131], v128, off
.LBB0_278:
	s_or_b64 exec, exec, s[38:39]
	v_add_u32_e32 v182, 0x80, v216
	v_ashrrev_i32_e32 v183, 31, v182
	s_waitcnt lgkmcnt(0)
	v_lshlrev_b64 v[128:129], 12, v[182:183]
	v_lshl_add_u64 v[128:129], v[176:177], 0, v[128:129]
	global_load_dwordx4 v[186:189], v[128:129], off
	global_load_dwordx4 v[218:221], v[128:129], off offset:16
	global_load_dwordx4 v[222:225], v[128:129], off offset:512
	global_load_dwordx4 v[226:229], v[128:129], off offset:528
	v_add_u32_e32 v180, 0x90, v216
	v_add_u32_e32 v178, 0xa0, v216
	v_add_u32_e32 v212, 0xb0, v216
	v_ashrrev_i32_e32 v181, 31, v180
	v_ashrrev_i32_e32 v179, 31, v178
	v_ashrrev_i32_e32 v213, 31, v212
	v_lshlrev_b64 v[128:129], 12, v[180:181]
	v_lshlrev_b64 v[130:131], 12, v[178:179]
	v_lshlrev_b64 v[132:133], 12, v[212:213]
	v_lshl_add_u64 v[128:129], v[176:177], 0, v[128:129]
	v_lshl_add_u64 v[130:131], v[176:177], 0, v[130:131]
	v_lshl_add_u64 v[132:133], v[176:177], 0, v[132:133]
	global_load_dwordx4 v[168:171], v[128:129], off offset:16
	global_load_dwordx4 v[172:175], v[128:129], off
	global_load_dwordx4 v[160:163], v[128:129], off offset:528
	global_load_dwordx4 v[164:167], v[128:129], off offset:512
	global_load_dwordx4 v[152:155], v[130:131], off offset:16
	global_load_dwordx4 v[156:159], v[130:131], off
	global_load_dwordx4 v[144:147], v[130:131], off offset:528
	global_load_dwordx4 v[148:151], v[130:131], off offset:512
	global_load_dwordx4 v[136:139], v[132:133], off offset:16
	global_load_dwordx4 v[140:143], v[132:133], off
	s_nop 0
	global_load_dwordx4 v[128:131], v[132:133], off offset:528
	s_nop 0
	global_load_dwordx4 v[132:135], v[132:133], off offset:512
	v_lshlrev_b64 v[176:177], 11, v[182:183]
	v_lshl_add_u64 v[176:177], s[24:25], 0, v[176:177]
	s_waitcnt vmcnt(15)
	v_pk_add_f32 v[190:191], v[62:63], v[188:189]
	v_pk_add_f32 v[230:231], v[60:61], v[186:187]
	s_waitcnt vmcnt(14)
	v_pk_add_f32 v[220:221], v[58:59], v[220:221]
	v_pk_add_f32 v[218:219], v[56:57], v[218:219]
	s_waitcnt vmcnt(13)
	v_pk_add_f32 v[224:225], v[54:55], v[224:225]
	v_pk_add_f32 v[222:223], v[52:53], v[222:223]
	s_waitcnt vmcnt(12)
	v_pk_add_f32 v[228:229], v[50:51], v[228:229]
	v_pk_add_f32 v[226:227], v[48:49], v[226:227]
	v_mul_f32_e32 v232, v231, v231
	v_mul_f32_e32 v233, v191, v191
	v_mul_f32_e32 v234, v219, v219
	v_mul_f32_e32 v235, v221, v221
	v_cvt_pk_bf16_f32 v186, v230, v231
	v_cvt_pk_bf16_f32 v187, v190, v191
	v_cvt_pk_bf16_f32 v188, v218, v219
	v_cvt_pk_bf16_f32 v189, v220, v221
	v_mul_f32_e32 v191, v223, v223
	v_mul_f32_e32 v219, v225, v225
	v_mul_f32_e32 v221, v227, v227
	v_mul_f32_e32 v231, v229, v229
	v_fmac_f32_e32 v232, v230, v230
	v_fmac_f32_e32 v233, v190, v190
	v_fmac_f32_e32 v234, v218, v218
	v_fmac_f32_e32 v235, v220, v220
	v_fmac_f32_e32 v191, v222, v222
	v_fmac_f32_e32 v219, v224, v224
	v_fmac_f32_e32 v221, v226, v226
	v_fmac_f32_e32 v231, v228, v228
	v_add_f32_e32 v190, v232, v233
	v_add_f32_e32 v218, v234, v235
	v_add_f32_e32 v191, v191, v219
	v_add_f32_e32 v219, v221, v231
	v_add_f32_e32 v190, v190, v218
	v_add_f32_e32 v191, v191, v219
	v_add_f32_e32 v218, v190, v191
	ds_bpermute_b32 v219, v185, v218
	v_lshl_add_u64 v[190:191], v[206:207], 1, v[176:177]
	global_store_dwordx4 v[190:191], v[186:189], off sc1
	s_waitcnt lgkmcnt(0)
	v_add_f32_e32 v176, v218, v219
	ds_bpermute_b32 v177, v184, v176
	v_cvt_pk_bf16_f32 v186, v222, v223
	v_cvt_pk_bf16_f32 v187, v224, v225
	v_cvt_pk_bf16_f32 v188, v226, v227
	v_cvt_pk_bf16_f32 v189, v228, v229
	global_store_dwordx4 v[190:191], v[186:189], off offset:256 sc1
	s_and_saveexec_b64 s[38:39], s[30:31]
	s_cbranch_execz .LBB0_280
	v_lshlrev_b64 v[182:183], 6, v[182:183]
	v_lshl_add_u64 v[182:183], s[26:27], 0, v[182:183]
	v_lshl_add_u64 v[182:183], s[36:37], 2, v[182:183]
	s_lshl_b32 s16, s49, 2
	v_lshl_add_u64 v[182:183], v[182:183], 0, s[16:17]
	s_waitcnt lgkmcnt(0)
	v_add_f32_e32 v176, v176, v177
	global_store_dword v[182:183], v176, off
.LBB0_280:
	s_or_b64 exec, exec, s[38:39]
	s_waitcnt vmcnt(12)
	v_pk_add_f32 v[174:175], v[46:47], v[174:175]
	v_pk_add_f32 v[172:173], v[44:45], v[172:173]
	v_pk_add_f32 v[182:183], v[42:43], v[170:171]
	v_pk_add_f32 v[170:171], v[40:41], v[168:169]
	v_mul_f32_e32 v168, v173, v173
	v_mul_f32_e32 v169, v175, v175
	v_fmac_f32_e32 v168, v172, v172
	v_fmac_f32_e32 v169, v174, v174
	v_add_f32_e32 v168, v168, v169
	v_mul_f32_e32 v169, v171, v171
	v_mul_f32_e32 v186, v183, v183
	v_fmac_f32_e32 v169, v170, v170
	v_fmac_f32_e32 v186, v182, v182
	v_add_f32_e32 v169, v169, v186
	s_waitcnt vmcnt(10)
	v_pk_add_f32 v[166:167], v[38:39], v[166:167]
	v_pk_add_f32 v[164:165], v[36:37], v[164:165]
	v_add_f32_e32 v186, v168, v169
	v_cvt_pk_bf16_f32 v169, v174, v175
	v_pk_add_f32 v[174:175], v[32:33], v[160:161]
	v_mul_f32_e32 v160, v165, v165
	v_mul_f32_e32 v161, v167, v167
	v_cvt_pk_bf16_f32 v168, v172, v173
	v_pk_add_f32 v[172:173], v[34:35], v[162:163]
	v_fmac_f32_e32 v160, v164, v164
	v_fmac_f32_e32 v161, v166, v166
	v_add_f32_e32 v160, v160, v161
	v_mul_f32_e32 v161, v175, v175
	v_mul_f32_e32 v162, v173, v173
	v_fmac_f32_e32 v161, v174, v174
	v_fmac_f32_e32 v162, v172, v172
	v_add_f32_e32 v161, v161, v162
	v_add_f32_e32 v160, v160, v161
	v_add_f32_e32 v163, v186, v160
	v_cvt_pk_bf16_f32 v170, v170, v171
	v_cvt_pk_bf16_f32 v171, v182, v183
	ds_bpermute_b32 v182, v185, v163
	s_waitcnt lgkmcnt(1)
	v_lshlrev_b64 v[176:177], 11, v[180:181]
	v_lshl_add_u64 v[160:161], s[24:25], 0, v[176:177]
	v_lshl_add_u64 v[176:177], v[206:207], 1, v[160:161]
	v_cvt_pk_bf16_f32 v162, v164, v165
	s_waitcnt lgkmcnt(0)
	v_add_f32_e32 v160, v163, v182
	ds_bpermute_b32 v161, v184, v160
	v_cvt_pk_bf16_f32 v163, v166, v167
	v_cvt_pk_bf16_f32 v164, v174, v175
	v_cvt_pk_bf16_f32 v165, v172, v173
	global_store_dwordx4 v[176:177], v[168:171], off sc1
	global_store_dwordx4 v[176:177], v[162:165], off offset:256 sc1
	s_and_saveexec_b64 s[38:39], s[30:31]
	s_cbranch_execz .LBB0_282
	v_lshlrev_b64 v[162:163], 6, v[180:181]
	v_lshl_add_u64 v[162:163], s[26:27], 0, v[162:163]
	v_lshl_add_u64 v[162:163], s[36:37], 2, v[162:163]
	s_lshl_b32 s16, s49, 2
	v_lshl_add_u64 v[162:163], v[162:163], 0, s[16:17]
	s_waitcnt lgkmcnt(0)
	v_add_f32_e32 v160, v160, v161
	global_store_dword v[162:163], v160, off
.LBB0_282:
	s_or_b64 exec, exec, s[38:39]
	s_waitcnt vmcnt(10)
	v_pk_add_f32 v[158:159], v[30:31], v[158:159]
	v_pk_add_f32 v[156:157], v[28:29], v[156:157]
	v_pk_add_f32 v[162:163], v[26:27], v[154:155]
	v_pk_add_f32 v[154:155], v[24:25], v[152:153]
	v_mul_f32_e32 v152, v157, v157
	v_mul_f32_e32 v153, v159, v159
	v_fmac_f32_e32 v152, v156, v156
	v_fmac_f32_e32 v153, v158, v158
	v_add_f32_e32 v152, v152, v153
	v_mul_f32_e32 v153, v155, v155
	v_mul_f32_e32 v164, v163, v163
	v_fmac_f32_e32 v153, v154, v154
	v_fmac_f32_e32 v164, v162, v162
	v_add_f32_e32 v153, v153, v164
	s_waitcnt vmcnt(8)
	v_pk_add_f32 v[150:151], v[22:23], v[150:151]
	v_pk_add_f32 v[148:149], v[20:21], v[148:149]
	v_add_f32_e32 v164, v152, v153
	v_cvt_pk_bf16_f32 v153, v158, v159
	v_pk_add_f32 v[158:159], v[16:17], v[144:145]
	v_mul_f32_e32 v144, v149, v149
	v_mul_f32_e32 v145, v151, v151
	v_cvt_pk_bf16_f32 v152, v156, v157
	v_pk_add_f32 v[156:157], v[18:19], v[146:147]
	v_fmac_f32_e32 v144, v148, v148
	v_fmac_f32_e32 v145, v150, v150
	v_add_f32_e32 v144, v144, v145
	v_mul_f32_e32 v145, v159, v159
	v_mul_f32_e32 v146, v157, v157
	v_fmac_f32_e32 v145, v158, v158
	v_fmac_f32_e32 v146, v156, v156
	v_add_f32_e32 v145, v145, v146
	v_add_f32_e32 v144, v144, v145
	v_add_f32_e32 v147, v164, v144
	v_cvt_pk_bf16_f32 v154, v154, v155
	v_cvt_pk_bf16_f32 v155, v162, v163
	ds_bpermute_b32 v162, v185, v147
	s_waitcnt lgkmcnt(1)
	v_lshlrev_b64 v[160:161], 11, v[178:179]
	v_lshl_add_u64 v[144:145], s[24:25], 0, v[160:161]
	v_lshl_add_u64 v[160:161], v[206:207], 1, v[144:145]
	v_cvt_pk_bf16_f32 v146, v148, v149
	s_waitcnt lgkmcnt(0)
	v_add_f32_e32 v144, v147, v162
	ds_bpermute_b32 v145, v184, v144
	v_cvt_pk_bf16_f32 v147, v150, v151
	v_cvt_pk_bf16_f32 v148, v158, v159
	v_cvt_pk_bf16_f32 v149, v156, v157
	global_store_dwordx4 v[160:161], v[152:155], off sc1
	global_store_dwordx4 v[160:161], v[146:149], off offset:256 sc1
	s_and_saveexec_b64 s[38:39], s[30:31]
	s_cbranch_execz .LBB0_284
	v_lshlrev_b64 v[146:147], 6, v[178:179]
	v_lshl_add_u64 v[146:147], s[26:27], 0, v[146:147]
	v_lshl_add_u64 v[146:147], s[36:37], 2, v[146:147]
	s_lshl_b32 s16, s49, 2
	v_lshl_add_u64 v[146:147], v[146:147], 0, s[16:17]
	s_waitcnt lgkmcnt(0)
	v_add_f32_e32 v144, v144, v145
	global_store_dword v[146:147], v144, off
.LBB0_284:
	s_or_b64 exec, exec, s[38:39]
	s_waitcnt vmcnt(8)
	v_pk_add_f32 v[140:141], v[12:13], v[140:141]
	s_waitcnt vmcnt(6)
	v_pk_add_f32 v[132:133], v[4:5], v[132:133]
	v_pk_add_f32 v[148:149], v[8:9], v[136:137]
	v_cvt_pk_bf16_f32 v136, v140, v141
	v_pk_add_f32 v[150:151], v[2:3], v[130:131]
	v_mov_b32_e32 v130, v140
	v_mov_b32_e32 v140, v141
	v_mov_b32_e32 v141, v133
	v_pk_add_f32 v[142:143], v[14:15], v[142:143]
	v_pk_add_f32 v[134:135], v[6:7], v[134:135]
	v_mov_b32_e32 v131, v132
	v_pk_mul_f32 v[140:141], v[140:141], v[140:141]
	v_cvt_pk_bf16_f32 v137, v142, v143
	v_pk_fma_f32 v[130:131], v[130:131], v[130:131], v[140:141]
	v_mov_b32_e32 v140, v142
	v_mov_b32_e32 v142, v143
	v_mov_b32_e32 v143, v135
	v_pk_add_f32 v[128:129], v[0:1], v[128:129]
	v_mov_b32_e32 v141, v134
	v_pk_mul_f32 v[142:143], v[142:143], v[142:143]
	v_pk_add_f32 v[146:147], v[10:11], v[138:139]
	v_pk_fma_f32 v[140:141], v[140:141], v[140:141], v[142:143]
	v_mov_b32_e32 v142, v149
	v_mov_b32_e32 v143, v129
	v_pk_add_f32 v[130:131], v[130:131], v[140:141]
	v_mov_b32_e32 v140, v148
	v_mov_b32_e32 v141, v128
	v_pk_mul_f32 v[142:143], v[142:143], v[142:143]
	v_cvt_pk_bf16_f32 v139, v146, v147
	v_pk_fma_f32 v[140:141], v[140:141], v[140:141], v[142:143]
	v_mov_b32_e32 v142, v146
	v_mov_b32_e32 v146, v147
	v_mov_b32_e32 v147, v151
	v_mov_b32_e32 v143, v150
	v_pk_mul_f32 v[146:147], v[146:147], v[146:147]
	s_waitcnt lgkmcnt(0)
	v_lshlrev_b64 v[144:145], 11, v[212:213]
	v_pk_fma_f32 v[142:143], v[142:143], v[142:143], v[146:147]
	v_lshl_add_u64 v[144:145], s[24:25], 0, v[144:145]
	v_pk_add_f32 v[140:141], v[140:141], v[142:143]
	v_cvt_pk_bf16_f32 v138, v148, v149
	v_pk_add_f32 v[130:131], v[130:131], v[140:141]
	v_lshl_add_u64 v[144:145], v[206:207], 1, v[144:145]
	v_add_f32_e32 v140, v130, v131
	ds_bpermute_b32 v141, v185, v140
	v_cvt_pk_bf16_f32 v130, v132, v133
	v_cvt_pk_bf16_f32 v132, v128, v129
	v_cvt_pk_bf16_f32 v131, v134, v135
	v_cvt_pk_bf16_f32 v133, v150, v151
	s_waitcnt lgkmcnt(0)
	v_add_f32_e32 v128, v140, v141
	ds_bpermute_b32 v129, v184, v128
	s_mov_b64 s[38:39], s[30:31]
	global_store_dwordx4 v[144:145], v[136:139], off sc1
	global_store_dwordx4 v[144:145], v[130:133], off offset:256 sc1
	s_branch .LBB0_301
.LBB0_285:
	v_lshlrev_b64 v[238:239], 1, v[206:207]
	v_lshl_add_u64 v[132:133], s[24:25], 0, v[238:239]
	v_lshlrev_b64 v[240:241], 11, v[216:217]
	s_waitcnt lgkmcnt(0)
	v_lshl_add_u64 v[128:129], v[132:133], 0, v[240:241]
	global_load_dwordx4 v[188:191], v[128:129], off
	global_load_dwordx4 v[184:187], v[128:129], off offset:256
	v_lshlrev_b64 v[236:237], 11, v[214:215]
	v_lshl_add_u64 v[128:129], v[132:133], 0, v[236:237]
	v_lshlrev_b64 v[234:235], 11, v[210:211]
	v_add_u32_e32 v228, 0x80, v216
	global_load_dwordx4 v[180:183], v[128:129], off
	global_load_dwordx4 v[176:179], v[128:129], off offset:256
	v_lshl_add_u64 v[128:129], v[132:133], 0, v[234:235]
	v_lshlrev_b64 v[232:233], 11, v[208:209]
	v_ashrrev_i32_e32 v229, 31, v228
	v_add_u32_e32 v224, 0x90, v216
	global_load_dwordx4 v[172:175], v[128:129], off
	global_load_dwordx4 v[168:171], v[128:129], off offset:256
	v_lshl_add_u64 v[128:129], v[132:133], 0, v[232:233]
	v_lshlrev_b64 v[230:231], 11, v[228:229]
	v_ashrrev_i32_e32 v225, 31, v224
	v_add_u32_e32 v218, 0xa0, v216
	v_add_u32_e32 v212, 0xb0, v216
	global_load_dwordx4 v[164:167], v[128:129], off
	global_load_dwordx4 v[160:163], v[128:129], off offset:256
	v_lshl_add_u64 v[128:129], v[132:133], 0, v[230:231]
	v_lshlrev_b64 v[226:227], 11, v[224:225]
	v_ashrrev_i32_e32 v219, 31, v218
	v_ashrrev_i32_e32 v213, 31, v212
	global_load_dwordx4 v[156:159], v[128:129], off
	global_load_dwordx4 v[152:155], v[128:129], off offset:256
	v_lshl_add_u64 v[128:129], v[132:133], 0, v[226:227]
	v_lshlrev_b64 v[220:221], 11, v[218:219]
	v_lshlrev_b64 v[222:223], 11, v[212:213]
	global_load_dwordx4 v[148:151], v[128:129], off
	global_load_dwordx4 v[144:147], v[128:129], off offset:256
	v_lshl_add_u64 v[128:129], v[132:133], 0, v[220:221]
	v_lshl_add_u64 v[132:133], v[132:133], 0, v[222:223]
	global_load_dwordx4 v[140:143], v[128:129], off
	s_nop 0
	global_load_dwordx4 v[128:131], v[128:129], off offset:256
	s_nop 0
	global_load_dwordx4 v[136:139], v[132:133], off
	s_nop 0
	global_load_dwordx4 v[132:135], v[132:133], off offset:256
	v_and_b32_e32 v249, 64, v247
	v_xor_b32_e32 v248, 16, v247
	v_add_u32_e32 v249, 64, v249
	v_cmp_lt_i32_e32 vcc, v248, v249
	v_xor_b32_e32 v250, 32, v247
	s_lshl_b32 s36, s64, 2
	v_cndmask_b32_e32 v248, v247, v248, vcc
	v_cmp_lt_i32_e32 vcc, v250, v249
	v_lshlrev_b32_e32 v248, 2, v248
	s_ashr_i32 s37, s36, 31
	v_cndmask_b32_e32 v249, v247, v250, vcc
	v_lshlrev_b32_e32 v249, 2, v249
	s_waitcnt vmcnt(0)
	v_lshlrev_b32_e32 v250, 16, v188
	v_and_b32_e32 v251, 0xffff0000, v188
	v_lshlrev_b32_e32 v188, 16, v189
	v_and_b32_e32 v189, 0xffff0000, v189
	v_lshlrev_b32_e32 v252, 16, v190
	v_and_b32_e32 v253, 0xffff0000, v190
	v_lshlrev_b32_e32 v190, 16, v191
	v_and_b32_e32 v191, 0xffff0000, v191
	v_pk_add_f32 v[126:127], v[126:127], v[188:189]
	v_pk_add_f32 v[124:125], v[124:125], v[250:251]
	v_pk_add_f32 v[188:189], v[122:123], v[190:191]
	v_pk_add_f32 v[122:123], v[120:121], v[252:253]
	v_mul_f32_e32 v120, v125, v125
	v_mul_f32_e32 v121, v127, v127
	v_fmac_f32_e32 v120, v124, v124
	v_fmac_f32_e32 v121, v126, v126
	v_add_f32_e32 v120, v120, v121
	v_mul_f32_e32 v121, v123, v123
	v_mul_f32_e32 v190, v189, v189
	v_fmac_f32_e32 v121, v122, v122
	v_fmac_f32_e32 v190, v188, v188
	v_add_f32_e32 v121, v121, v190
	v_add_f32_e32 v190, v120, v121
	v_cvt_pk_bf16_f32 v120, v124, v125
	v_lshl_add_u64 v[124:125], s[24:25], 0, v[240:241]
	v_cvt_pk_bf16_f32 v121, v126, v127
	v_cvt_pk_bf16_f32 v122, v122, v123
	v_cvt_pk_bf16_f32 v123, v188, v189
	v_lshl_add_u64 v[124:125], v[124:125], 0, v[238:239]
	global_store_dwordx4 v[124:125], v[120:123], off sc1
	v_lshlrev_b32_e32 v126, 16, v186
	v_and_b32_e32 v127, 0xffff0000, v186
	v_lshlrev_b32_e32 v120, 16, v184
	v_and_b32_e32 v121, 0xffff0000, v184
	v_lshlrev_b32_e32 v122, 16, v185
	v_and_b32_e32 v123, 0xffff0000, v185
	v_lshlrev_b32_e32 v184, 16, v187
	v_and_b32_e32 v185, 0xffff0000, v187
	v_pk_add_f32 v[118:119], v[118:119], v[122:123]
	v_pk_add_f32 v[116:117], v[116:117], v[120:121]
	v_pk_add_f32 v[120:121], v[114:115], v[184:185]
	v_pk_add_f32 v[114:115], v[112:113], v[126:127]
	v_mul_f32_e32 v112, v117, v117
	v_mul_f32_e32 v113, v119, v119
	v_fmac_f32_e32 v112, v116, v116
	v_fmac_f32_e32 v113, v118, v118
	v_add_f32_e32 v112, v112, v113
	v_mul_f32_e32 v113, v115, v115
	v_mul_f32_e32 v122, v121, v121
	v_fmac_f32_e32 v113, v114, v114
	v_fmac_f32_e32 v122, v120, v120
	v_add_f32_e32 v113, v113, v122
	v_add_f32_e32 v112, v112, v113
	v_add_f32_e32 v122, v190, v112
	v_cvt_pk_bf16_f32 v112, v116, v117
	v_cvt_pk_bf16_f32 v113, v118, v119
	v_cvt_pk_bf16_f32 v114, v114, v115
	v_cvt_pk_bf16_f32 v115, v120, v121
	global_store_dwordx4 v[124:125], v[112:115], off offset:256 sc1
	ds_bpermute_b32 v112, v248, v122
	s_waitcnt lgkmcnt(0)
	v_add_f32_e32 v112, v122, v112
	ds_bpermute_b32 v113, v249, v112
	s_and_saveexec_b64 s[38:39], s[30:31]
	s_cbranch_execz .LBB0_287
	v_lshlrev_b64 v[114:115], 6, v[216:217]
	v_lshl_add_u64 v[114:115], s[26:27], 0, v[114:115]
	v_lshl_add_u64 v[114:115], s[36:37], 2, v[114:115]
	s_lshl_b32 s16, s49, 2
	v_lshl_add_u64 v[114:115], v[114:115], 0, s[16:17]
	s_waitcnt lgkmcnt(0)
	v_add_f32_e32 v112, v112, v113
	global_store_dword v[114:115], v112, off
.LBB0_287:
	s_or_b64 exec, exec, s[38:39]
	v_lshlrev_b32_e32 v112, 16, v180
	s_waitcnt lgkmcnt(0)
	v_and_b32_e32 v113, 0xffff0000, v180
	v_lshlrev_b32_e32 v114, 16, v181
	v_and_b32_e32 v115, 0xffff0000, v181
	v_lshlrev_b32_e32 v116, 16, v182
	v_and_b32_e32 v117, 0xffff0000, v182
	v_lshlrev_b32_e32 v118, 16, v183
	v_and_b32_e32 v119, 0xffff0000, v183
	v_pk_add_f32 v[110:111], v[110:111], v[114:115]
	v_pk_add_f32 v[108:109], v[108:109], v[112:113]
	v_pk_add_f32 v[112:113], v[106:107], v[118:119]
	v_pk_add_f32 v[106:107], v[104:105], v[116:117]
	v_mul_f32_e32 v104, v109, v109
	v_mul_f32_e32 v105, v111, v111
	v_fmac_f32_e32 v104, v108, v108
	v_fmac_f32_e32 v105, v110, v110
	v_add_f32_e32 v104, v104, v105
	v_mul_f32_e32 v105, v107, v107
	v_mul_f32_e32 v114, v113, v113
	v_fmac_f32_e32 v105, v106, v106
	v_fmac_f32_e32 v114, v112, v112
	v_add_f32_e32 v105, v105, v114
	v_add_f32_e32 v116, v104, v105
	v_cvt_pk_bf16_f32 v104, v108, v109
	v_cvt_pk_bf16_f32 v105, v110, v111
	v_lshlrev_b32_e32 v108, 16, v176
	v_and_b32_e32 v109, 0xffff0000, v176
	v_lshlrev_b32_e32 v110, 16, v177
	v_and_b32_e32 v111, 0xffff0000, v177
	v_cvt_pk_bf16_f32 v106, v106, v107
	v_cvt_pk_bf16_f32 v107, v112, v113
	v_lshlrev_b32_e32 v112, 16, v178
	v_and_b32_e32 v113, 0xffff0000, v178
	v_pk_add_f32 v[102:103], v[102:103], v[110:111]
	v_pk_add_f32 v[100:101], v[100:101], v[108:109]
	v_lshlrev_b32_e32 v114, 16, v179
	v_and_b32_e32 v115, 0xffff0000, v179
	v_pk_add_f32 v[110:111], v[96:97], v[112:113]
	v_mul_f32_e32 v96, v101, v101
	v_mul_f32_e32 v97, v103, v103
	v_pk_add_f32 v[108:109], v[98:99], v[114:115]
	v_fmac_f32_e32 v96, v100, v100
	v_fmac_f32_e32 v97, v102, v102
	v_add_f32_e32 v96, v96, v97
	v_mul_f32_e32 v97, v111, v111
	v_mul_f32_e32 v98, v109, v109
	v_fmac_f32_e32 v97, v110, v110
	v_fmac_f32_e32 v98, v108, v108
	v_add_f32_e32 v97, v97, v98
	v_add_f32_e32 v96, v96, v97
	v_add_f32_e32 v99, v116, v96
	ds_bpermute_b32 v114, v248, v99
	v_lshl_add_u64 v[96:97], s[24:25], 0, v[236:237]
	v_lshl_add_u64 v[112:113], v[206:207], 1, v[96:97]
	v_cvt_pk_bf16_f32 v98, v100, v101
	v_cvt_pk_bf16_f32 v100, v110, v111
	s_waitcnt lgkmcnt(0)
	v_add_f32_e32 v96, v99, v114
	ds_bpermute_b32 v97, v249, v96
	v_cvt_pk_bf16_f32 v99, v102, v103
	v_cvt_pk_bf16_f32 v101, v108, v109
	global_store_dwordx4 v[112:113], v[104:107], off sc1
	global_store_dwordx4 v[112:113], v[98:101], off offset:256 sc1
	s_and_saveexec_b64 s[38:39], s[30:31]
	s_cbranch_execz .LBB0_289
	v_lshlrev_b64 v[98:99], 6, v[214:215]
	v_lshl_add_u64 v[98:99], s[26:27], 0, v[98:99]
	v_lshl_add_u64 v[98:99], s[36:37], 2, v[98:99]
	s_lshl_b32 s16, s49, 2
	v_lshl_add_u64 v[98:99], v[98:99], 0, s[16:17]
	s_waitcnt lgkmcnt(0)
	v_add_f32_e32 v96, v96, v97
	global_store_dword v[98:99], v96, off
.LBB0_289:
	s_or_b64 exec, exec, s[38:39]
	v_lshlrev_b32_e32 v96, 16, v172
	s_waitcnt lgkmcnt(0)
	v_and_b32_e32 v97, 0xffff0000, v172
	v_lshlrev_b32_e32 v98, 16, v173
	v_and_b32_e32 v99, 0xffff0000, v173
	v_lshlrev_b32_e32 v100, 16, v174
	v_and_b32_e32 v101, 0xffff0000, v174
	v_lshlrev_b32_e32 v102, 16, v175
	v_and_b32_e32 v103, 0xffff0000, v175
	v_pk_add_f32 v[94:95], v[94:95], v[98:99]
	v_pk_add_f32 v[92:93], v[92:93], v[96:97]
	v_pk_add_f32 v[96:97], v[90:91], v[102:103]
	v_pk_add_f32 v[90:91], v[88:89], v[100:101]
	v_mul_f32_e32 v88, v93, v93
	v_mul_f32_e32 v89, v95, v95
	v_fmac_f32_e32 v88, v92, v92
	v_fmac_f32_e32 v89, v94, v94
	v_add_f32_e32 v88, v88, v89
	v_mul_f32_e32 v89, v91, v91
	v_mul_f32_e32 v98, v97, v97
	v_fmac_f32_e32 v89, v90, v90
	v_fmac_f32_e32 v98, v96, v96
	v_add_f32_e32 v89, v89, v98
	v_add_f32_e32 v100, v88, v89
	v_cvt_pk_bf16_f32 v88, v92, v93
	v_cvt_pk_bf16_f32 v89, v94, v95
	v_lshlrev_b32_e32 v92, 16, v168
	v_and_b32_e32 v93, 0xffff0000, v168
	v_lshlrev_b32_e32 v94, 16, v169
	v_and_b32_e32 v95, 0xffff0000, v169
	v_cvt_pk_bf16_f32 v90, v90, v91
	v_cvt_pk_bf16_f32 v91, v96, v97
	v_lshlrev_b32_e32 v96, 16, v170
	v_and_b32_e32 v97, 0xffff0000, v170
	v_pk_add_f32 v[86:87], v[86:87], v[94:95]
	v_pk_add_f32 v[84:85], v[84:85], v[92:93]
	v_lshlrev_b32_e32 v98, 16, v171
	v_and_b32_e32 v99, 0xffff0000, v171
	v_pk_add_f32 v[94:95], v[80:81], v[96:97]
	v_mul_f32_e32 v80, v85, v85
	v_mul_f32_e32 v81, v87, v87
	v_pk_add_f32 v[92:93], v[82:83], v[98:99]
	v_fmac_f32_e32 v80, v84, v84
	v_fmac_f32_e32 v81, v86, v86
	v_add_f32_e32 v80, v80, v81
	v_mul_f32_e32 v81, v95, v95
	v_mul_f32_e32 v82, v93, v93
	v_fmac_f32_e32 v81, v94, v94
	v_fmac_f32_e32 v82, v92, v92
	v_add_f32_e32 v81, v81, v82
	v_add_f32_e32 v80, v80, v81
	v_add_f32_e32 v83, v100, v80
	ds_bpermute_b32 v98, v248, v83
	v_lshl_add_u64 v[80:81], s[24:25], 0, v[234:235]
	v_lshl_add_u64 v[96:97], v[206:207], 1, v[80:81]
	v_cvt_pk_bf16_f32 v82, v84, v85
	v_cvt_pk_bf16_f32 v84, v94, v95
	s_waitcnt lgkmcnt(0)
	v_add_f32_e32 v80, v83, v98
	ds_bpermute_b32 v81, v249, v80
	v_cvt_pk_bf16_f32 v83, v86, v87
	v_cvt_pk_bf16_f32 v85, v92, v93
	global_store_dwordx4 v[96:97], v[88:91], off sc1
	global_store_dwordx4 v[96:97], v[82:85], off offset:256 sc1
	s_and_saveexec_b64 s[38:39], s[30:31]
	s_cbranch_execz .LBB0_291
	v_lshlrev_b64 v[82:83], 6, v[210:211]
	v_lshl_add_u64 v[82:83], s[26:27], 0, v[82:83]
	v_lshl_add_u64 v[82:83], s[36:37], 2, v[82:83]
	s_lshl_b32 s16, s49, 2
	v_lshl_add_u64 v[82:83], v[82:83], 0, s[16:17]
	s_waitcnt lgkmcnt(0)
	v_add_f32_e32 v80, v80, v81
	global_store_dword v[82:83], v80, off
.LBB0_291:
	s_or_b64 exec, exec, s[38:39]
	v_lshlrev_b32_e32 v80, 16, v164
	s_waitcnt lgkmcnt(0)
	v_and_b32_e32 v81, 0xffff0000, v164
	v_lshlrev_b32_e32 v82, 16, v165
	v_and_b32_e32 v83, 0xffff0000, v165
	v_lshlrev_b32_e32 v84, 16, v166
	v_and_b32_e32 v85, 0xffff0000, v166
	v_lshlrev_b32_e32 v86, 16, v167
	v_and_b32_e32 v87, 0xffff0000, v167
	v_pk_add_f32 v[78:79], v[78:79], v[82:83]
	v_pk_add_f32 v[76:77], v[76:77], v[80:81]
	v_pk_add_f32 v[80:81], v[74:75], v[86:87]
	v_pk_add_f32 v[74:75], v[72:73], v[84:85]
	v_mul_f32_e32 v72, v77, v77
	v_mul_f32_e32 v73, v79, v79
	v_fmac_f32_e32 v72, v76, v76
	v_fmac_f32_e32 v73, v78, v78
	v_add_f32_e32 v72, v72, v73
	v_mul_f32_e32 v73, v75, v75
	v_mul_f32_e32 v82, v81, v81
	v_fmac_f32_e32 v73, v74, v74
	v_fmac_f32_e32 v82, v80, v80
	v_add_f32_e32 v73, v73, v82
	v_add_f32_e32 v84, v72, v73
	v_cvt_pk_bf16_f32 v72, v76, v77
	v_cvt_pk_bf16_f32 v73, v78, v79
	v_lshlrev_b32_e32 v76, 16, v160
	v_and_b32_e32 v77, 0xffff0000, v160
	v_lshlrev_b32_e32 v78, 16, v161
	v_and_b32_e32 v79, 0xffff0000, v161
	v_cvt_pk_bf16_f32 v74, v74, v75
	v_cvt_pk_bf16_f32 v75, v80, v81
	v_lshlrev_b32_e32 v80, 16, v162
	v_and_b32_e32 v81, 0xffff0000, v162
	v_pk_add_f32 v[70:71], v[70:71], v[78:79]
	v_pk_add_f32 v[68:69], v[68:69], v[76:77]
	v_lshlrev_b32_e32 v82, 16, v163
	v_and_b32_e32 v83, 0xffff0000, v163
	v_pk_add_f32 v[78:79], v[64:65], v[80:81]
	v_mul_f32_e32 v64, v69, v69
	v_mul_f32_e32 v65, v71, v71
	v_pk_add_f32 v[76:77], v[66:67], v[82:83]
	v_fmac_f32_e32 v64, v68, v68
	v_fmac_f32_e32 v65, v70, v70
	v_add_f32_e32 v64, v64, v65
	v_mul_f32_e32 v65, v79, v79
	v_mul_f32_e32 v66, v77, v77
	v_fmac_f32_e32 v65, v78, v78
	v_fmac_f32_e32 v66, v76, v76
	v_add_f32_e32 v65, v65, v66
	v_add_f32_e32 v64, v64, v65
	v_add_f32_e32 v67, v84, v64
	ds_bpermute_b32 v82, v248, v67
	v_lshl_add_u64 v[64:65], s[24:25], 0, v[232:233]
	v_lshl_add_u64 v[80:81], v[206:207], 1, v[64:65]
	v_cvt_pk_bf16_f32 v66, v68, v69
	v_cvt_pk_bf16_f32 v68, v78, v79
	s_waitcnt lgkmcnt(0)
	v_add_f32_e32 v64, v67, v82
	ds_bpermute_b32 v65, v249, v64
	v_cvt_pk_bf16_f32 v67, v70, v71
	v_cvt_pk_bf16_f32 v69, v76, v77
	global_store_dwordx4 v[80:81], v[72:75], off sc1
	global_store_dwordx4 v[80:81], v[66:69], off offset:256 sc1
	s_and_saveexec_b64 s[38:39], s[30:31]
	s_cbranch_execz .LBB0_293
	v_lshlrev_b64 v[66:67], 6, v[208:209]
	v_lshl_add_u64 v[66:67], s[26:27], 0, v[66:67]
	v_lshl_add_u64 v[66:67], s[36:37], 2, v[66:67]
	s_lshl_b32 s16, s49, 2
	v_lshl_add_u64 v[66:67], v[66:67], 0, s[16:17]
	s_waitcnt lgkmcnt(0)
	v_add_f32_e32 v64, v64, v65
	global_store_dword v[66:67], v64, off
.LBB0_293:
	s_or_b64 exec, exec, s[38:39]
	v_lshlrev_b32_e32 v64, 16, v156
	s_waitcnt lgkmcnt(0)
	v_and_b32_e32 v65, 0xffff0000, v156
	v_lshlrev_b32_e32 v66, 16, v157
	v_and_b32_e32 v67, 0xffff0000, v157
	v_lshlrev_b32_e32 v68, 16, v158
	v_and_b32_e32 v69, 0xffff0000, v158
	v_lshlrev_b32_e32 v70, 16, v159
	v_and_b32_e32 v71, 0xffff0000, v159
	v_pk_add_f32 v[62:63], v[62:63], v[66:67]
	v_pk_add_f32 v[60:61], v[60:61], v[64:65]
	v_pk_add_f32 v[64:65], v[58:59], v[70:71]
	v_pk_add_f32 v[58:59], v[56:57], v[68:69]
	v_mul_f32_e32 v56, v61, v61
	v_mul_f32_e32 v57, v63, v63
	v_fmac_f32_e32 v56, v60, v60
	v_fmac_f32_e32 v57, v62, v62
	v_add_f32_e32 v56, v56, v57
	v_mul_f32_e32 v57, v59, v59
	v_mul_f32_e32 v66, v65, v65
	v_fmac_f32_e32 v57, v58, v58
	v_fmac_f32_e32 v66, v64, v64
	v_add_f32_e32 v57, v57, v66
	v_add_f32_e32 v68, v56, v57
	v_cvt_pk_bf16_f32 v56, v60, v61
	v_cvt_pk_bf16_f32 v57, v62, v63
	v_lshlrev_b32_e32 v60, 16, v152
	v_and_b32_e32 v61, 0xffff0000, v152
	v_lshlrev_b32_e32 v62, 16, v153
	v_and_b32_e32 v63, 0xffff0000, v153
	v_cvt_pk_bf16_f32 v58, v58, v59
	v_cvt_pk_bf16_f32 v59, v64, v65
	v_lshlrev_b32_e32 v64, 16, v154
	v_and_b32_e32 v65, 0xffff0000, v154
	v_pk_add_f32 v[54:55], v[54:55], v[62:63]
	v_pk_add_f32 v[52:53], v[52:53], v[60:61]
	v_lshlrev_b32_e32 v66, 16, v155
	v_and_b32_e32 v67, 0xffff0000, v155
	v_pk_add_f32 v[62:63], v[48:49], v[64:65]
	v_mul_f32_e32 v48, v53, v53
	v_mul_f32_e32 v49, v55, v55
	v_pk_add_f32 v[60:61], v[50:51], v[66:67]
	v_fmac_f32_e32 v48, v52, v52
	v_fmac_f32_e32 v49, v54, v54
	v_add_f32_e32 v48, v48, v49
	v_mul_f32_e32 v49, v63, v63
	v_mul_f32_e32 v50, v61, v61
	v_fmac_f32_e32 v49, v62, v62
	v_fmac_f32_e32 v50, v60, v60
	v_add_f32_e32 v49, v49, v50
	v_add_f32_e32 v48, v48, v49
	v_add_f32_e32 v51, v68, v48
	ds_bpermute_b32 v66, v248, v51
	v_lshl_add_u64 v[48:49], s[24:25], 0, v[230:231]
	v_lshl_add_u64 v[64:65], v[206:207], 1, v[48:49]
	v_cvt_pk_bf16_f32 v50, v52, v53
	v_cvt_pk_bf16_f32 v52, v62, v63
	s_waitcnt lgkmcnt(0)
	v_add_f32_e32 v48, v51, v66
	ds_bpermute_b32 v49, v249, v48
	v_cvt_pk_bf16_f32 v51, v54, v55
	v_cvt_pk_bf16_f32 v53, v60, v61
	global_store_dwordx4 v[64:65], v[56:59], off sc1
	global_store_dwordx4 v[64:65], v[50:53], off offset:256 sc1
	s_and_saveexec_b64 s[38:39], s[30:31]
	s_cbranch_execz .LBB0_295
	v_lshlrev_b64 v[50:51], 6, v[228:229]
	v_lshl_add_u64 v[50:51], s[26:27], 0, v[50:51]
	v_lshl_add_u64 v[50:51], s[36:37], 2, v[50:51]
	s_lshl_b32 s16, s49, 2
	v_lshl_add_u64 v[50:51], v[50:51], 0, s[16:17]
	s_waitcnt lgkmcnt(0)
	v_add_f32_e32 v48, v48, v49
	global_store_dword v[50:51], v48, off
.LBB0_295:
	s_or_b64 exec, exec, s[38:39]
	v_lshlrev_b32_e32 v48, 16, v148
	s_waitcnt lgkmcnt(0)
	v_and_b32_e32 v49, 0xffff0000, v148
	v_lshlrev_b32_e32 v50, 16, v149
	v_and_b32_e32 v51, 0xffff0000, v149
	v_lshlrev_b32_e32 v52, 16, v150
	v_and_b32_e32 v53, 0xffff0000, v150
	v_lshlrev_b32_e32 v54, 16, v151
	v_and_b32_e32 v55, 0xffff0000, v151
	v_pk_add_f32 v[46:47], v[46:47], v[50:51]
	v_pk_add_f32 v[44:45], v[44:45], v[48:49]
	v_pk_add_f32 v[48:49], v[42:43], v[54:55]
	v_pk_add_f32 v[42:43], v[40:41], v[52:53]
	v_mul_f32_e32 v40, v45, v45
	v_mul_f32_e32 v41, v47, v47
	v_fmac_f32_e32 v40, v44, v44
	v_fmac_f32_e32 v41, v46, v46
	v_add_f32_e32 v40, v40, v41
	v_mul_f32_e32 v41, v43, v43
	v_mul_f32_e32 v50, v49, v49
	v_fmac_f32_e32 v41, v42, v42
	v_fmac_f32_e32 v50, v48, v48
	v_add_f32_e32 v41, v41, v50
	v_add_f32_e32 v52, v40, v41
	v_cvt_pk_bf16_f32 v40, v44, v45
	v_cvt_pk_bf16_f32 v41, v46, v47
	v_lshlrev_b32_e32 v44, 16, v144
	v_and_b32_e32 v45, 0xffff0000, v144
	v_lshlrev_b32_e32 v46, 16, v145
	v_and_b32_e32 v47, 0xffff0000, v145
	v_cvt_pk_bf16_f32 v42, v42, v43
	v_cvt_pk_bf16_f32 v43, v48, v49
	v_lshlrev_b32_e32 v48, 16, v146
	v_and_b32_e32 v49, 0xffff0000, v146
	v_pk_add_f32 v[38:39], v[38:39], v[46:47]
	v_pk_add_f32 v[36:37], v[36:37], v[44:45]
	v_lshlrev_b32_e32 v50, 16, v147
	v_and_b32_e32 v51, 0xffff0000, v147
	v_pk_add_f32 v[46:47], v[32:33], v[48:49]
	v_mul_f32_e32 v32, v37, v37
	v_mul_f32_e32 v33, v39, v39
	v_pk_add_f32 v[44:45], v[34:35], v[50:51]
	v_fmac_f32_e32 v32, v36, v36
	v_fmac_f32_e32 v33, v38, v38
	v_add_f32_e32 v32, v32, v33
	v_mul_f32_e32 v33, v47, v47
	v_mul_f32_e32 v34, v45, v45
	v_fmac_f32_e32 v33, v46, v46
	v_fmac_f32_e32 v34, v44, v44
	v_add_f32_e32 v33, v33, v34
	v_add_f32_e32 v32, v32, v33
	v_add_f32_e32 v35, v52, v32
	ds_bpermute_b32 v50, v248, v35
	v_lshl_add_u64 v[32:33], s[24:25], 0, v[226:227]
	v_lshl_add_u64 v[48:49], v[206:207], 1, v[32:33]
	v_cvt_pk_bf16_f32 v34, v36, v37
	v_cvt_pk_bf16_f32 v36, v46, v47
	s_waitcnt lgkmcnt(0)
	v_add_f32_e32 v32, v35, v50
	ds_bpermute_b32 v33, v249, v32
	v_cvt_pk_bf16_f32 v35, v38, v39
	v_cvt_pk_bf16_f32 v37, v44, v45
	global_store_dwordx4 v[48:49], v[40:43], off sc1
	global_store_dwordx4 v[48:49], v[34:37], off offset:256 sc1
	s_and_saveexec_b64 s[38:39], s[30:31]
	s_cbranch_execz .LBB0_297
	v_lshlrev_b64 v[34:35], 6, v[224:225]
	v_lshl_add_u64 v[34:35], s[26:27], 0, v[34:35]
	v_lshl_add_u64 v[34:35], s[36:37], 2, v[34:35]
	s_lshl_b32 s16, s49, 2
	v_lshl_add_u64 v[34:35], v[34:35], 0, s[16:17]
	s_waitcnt lgkmcnt(0)
	v_add_f32_e32 v32, v32, v33
	global_store_dword v[34:35], v32, off
.LBB0_297:
	s_or_b64 exec, exec, s[38:39]
	v_lshlrev_b32_e32 v32, 16, v140
	s_waitcnt lgkmcnt(0)
	v_and_b32_e32 v33, 0xffff0000, v140
	v_lshlrev_b32_e32 v34, 16, v141
	v_and_b32_e32 v35, 0xffff0000, v141
	v_lshlrev_b32_e32 v36, 16, v142
	v_and_b32_e32 v37, 0xffff0000, v142
	v_lshlrev_b32_e32 v38, 16, v143
	v_and_b32_e32 v39, 0xffff0000, v143
	v_pk_add_f32 v[30:31], v[30:31], v[34:35]
	v_pk_add_f32 v[28:29], v[28:29], v[32:33]
	v_pk_add_f32 v[32:33], v[26:27], v[38:39]
	v_pk_add_f32 v[26:27], v[24:25], v[36:37]
	v_mul_f32_e32 v24, v29, v29
	v_mul_f32_e32 v25, v31, v31
	v_fmac_f32_e32 v24, v28, v28
	v_fmac_f32_e32 v25, v30, v30
	v_add_f32_e32 v24, v24, v25
	v_mul_f32_e32 v25, v27, v27
	v_mul_f32_e32 v34, v33, v33
	v_fmac_f32_e32 v25, v26, v26
	v_fmac_f32_e32 v34, v32, v32
	v_add_f32_e32 v25, v25, v34
	v_add_f32_e32 v36, v24, v25
	v_cvt_pk_bf16_f32 v24, v28, v29
	v_cvt_pk_bf16_f32 v25, v30, v31
	v_lshlrev_b32_e32 v28, 16, v128
	v_and_b32_e32 v29, 0xffff0000, v128
	v_lshlrev_b32_e32 v30, 16, v129
	v_and_b32_e32 v31, 0xffff0000, v129
	v_cvt_pk_bf16_f32 v26, v26, v27
	v_cvt_pk_bf16_f32 v27, v32, v33
	v_lshlrev_b32_e32 v32, 16, v130
	v_and_b32_e32 v33, 0xffff0000, v130
	v_pk_add_f32 v[22:23], v[22:23], v[30:31]
	v_pk_add_f32 v[20:21], v[20:21], v[28:29]
	v_lshlrev_b32_e32 v34, 16, v131
	v_and_b32_e32 v35, 0xffff0000, v131
	v_pk_add_f32 v[30:31], v[16:17], v[32:33]
	v_mul_f32_e32 v16, v21, v21
	v_mul_f32_e32 v17, v23, v23
	v_pk_add_f32 v[28:29], v[18:19], v[34:35]
	v_fmac_f32_e32 v16, v20, v20
	v_fmac_f32_e32 v17, v22, v22
	v_add_f32_e32 v16, v16, v17
	v_mul_f32_e32 v17, v31, v31
	v_mul_f32_e32 v18, v29, v29
	v_fmac_f32_e32 v17, v30, v30
	v_fmac_f32_e32 v18, v28, v28
	v_add_f32_e32 v17, v17, v18
	v_add_f32_e32 v16, v16, v17
	v_add_f32_e32 v19, v36, v16
	ds_bpermute_b32 v34, v248, v19
	v_lshl_add_u64 v[16:17], s[24:25], 0, v[220:221]
	v_lshl_add_u64 v[32:33], v[206:207], 1, v[16:17]
	v_cvt_pk_bf16_f32 v18, v20, v21
	v_cvt_pk_bf16_f32 v20, v30, v31
	s_waitcnt lgkmcnt(0)
	v_add_f32_e32 v16, v19, v34
	ds_bpermute_b32 v17, v249, v16
	v_cvt_pk_bf16_f32 v19, v22, v23
	v_cvt_pk_bf16_f32 v21, v28, v29
	global_store_dwordx4 v[32:33], v[24:27], off sc1
	global_store_dwordx4 v[32:33], v[18:21], off offset:256 sc1
	s_and_saveexec_b64 s[38:39], s[30:31]
	s_cbranch_execz .LBB0_299
	v_lshlrev_b64 v[18:19], 6, v[218:219]
	v_lshl_add_u64 v[18:19], s[26:27], 0, v[18:19]
	v_lshl_add_u64 v[18:19], s[36:37], 2, v[18:19]
	s_lshl_b32 s16, s49, 2
	v_lshl_add_u64 v[18:19], v[18:19], 0, s[16:17]
	s_waitcnt lgkmcnt(0)
	v_add_f32_e32 v16, v16, v17
	global_store_dword v[18:19], v16, off
.LBB0_299:
	s_or_b64 exec, exec, s[38:39]
	v_lshlrev_b32_e32 v16, 16, v136
	s_waitcnt lgkmcnt(0)
	v_and_b32_e32 v17, 0xffff0000, v136
	v_lshlrev_b32_e32 v22, 16, v139
	v_and_b32_e32 v23, 0xffff0000, v139
	v_pk_add_f32 v[12:13], v[12:13], v[16:17]
	v_pk_add_f32 v[16:17], v[10:11], v[22:23]
	v_lshlrev_b32_e32 v22, 16, v132
	v_and_b32_e32 v23, 0xffff0000, v132
	v_lshlrev_b32_e32 v18, 16, v137
	v_and_b32_e32 v19, 0xffff0000, v137
	v_lshlrev_b32_e32 v20, 16, v138
	v_and_b32_e32 v21, 0xffff0000, v138
	v_lshlrev_b32_e32 v26, 16, v134
	v_and_b32_e32 v27, 0xffff0000, v134
	v_lshlrev_b32_e32 v28, 16, v135
	v_and_b32_e32 v29, 0xffff0000, v135
	v_pk_add_f32 v[4:5], v[4:5], v[22:23]
	v_pk_add_f32 v[14:15], v[14:15], v[18:19]
	v_pk_add_f32 v[18:19], v[8:9], v[20:21]
	v_cvt_pk_bf16_f32 v8, v12, v13
	v_lshlrev_b32_e32 v24, 16, v133
	v_and_b32_e32 v25, 0xffff0000, v133
	v_pk_add_f32 v[22:23], v[2:3], v[28:29]
	v_pk_add_f32 v[2:3], v[0:1], v[26:27]
	v_mov_b32_e32 v0, v12
	v_mov_b32_e32 v12, v13
	v_mov_b32_e32 v13, v5
	v_pk_add_f32 v[6:7], v[6:7], v[24:25]
	v_mov_b32_e32 v1, v4
	v_pk_mul_f32 v[12:13], v[12:13], v[12:13]
	v_cvt_pk_bf16_f32 v9, v14, v15
	v_pk_fma_f32 v[0:1], v[0:1], v[0:1], v[12:13]
	v_mov_b32_e32 v12, v14
	v_mov_b32_e32 v14, v15
	v_mov_b32_e32 v15, v7
	v_mov_b32_e32 v13, v6
	v_pk_mul_f32 v[14:15], v[14:15], v[14:15]
	v_cvt_pk_bf16_f32 v11, v16, v17
	v_pk_fma_f32 v[12:13], v[12:13], v[12:13], v[14:15]
	v_mov_b32_e32 v14, v19
	v_mov_b32_e32 v15, v3
	v_pk_add_f32 v[0:1], v[0:1], v[12:13]
	v_mov_b32_e32 v12, v18
	v_mov_b32_e32 v13, v2
	v_pk_mul_f32 v[14:15], v[14:15], v[14:15]
	v_lshl_add_u64 v[20:21], s[24:25], 0, v[222:223]
	v_pk_fma_f32 v[12:13], v[12:13], v[12:13], v[14:15]
	v_mov_b32_e32 v14, v16
	v_mov_b32_e32 v16, v17
	v_mov_b32_e32 v17, v23
	v_mov_b32_e32 v15, v22
	v_pk_mul_f32 v[16:17], v[16:17], v[16:17]
	v_cvt_pk_bf16_f32 v10, v18, v19
	v_pk_fma_f32 v[14:15], v[14:15], v[14:15], v[16:17]
	v_cvt_pk_bf16_f32 v2, v2, v3
	v_pk_add_f32 v[12:13], v[12:13], v[14:15]
	v_cvt_pk_bf16_f32 v3, v22, v23
	v_pk_add_f32 v[0:1], v[0:1], v[12:13]
	v_lshl_add_u64 v[12:13], v[206:207], 1, v[20:21]
	v_add_f32_e32 v14, v0, v1
	ds_bpermute_b32 v15, v248, v14
	v_cvt_pk_bf16_f32 v0, v4, v5
	v_cvt_pk_bf16_f32 v1, v6, v7
	s_mov_b64 s[38:39], s[30:31]
	global_store_dwordx4 v[12:13], v[8:11], off sc1
	s_waitcnt lgkmcnt(0)
	v_add_f32_e32 v128, v14, v15
	ds_bpermute_b32 v129, v249, v128
	global_store_dwordx4 v[12:13], v[0:3], off offset:256 sc1
	s_and_saveexec_b64 s[40:41], s[38:39]
	s_cbranch_execz .LBB0_256
	s_branch .LBB0_302

.LBB0_375:
	ds_read2_b32 v[156:157], v161 offset1:16
	ds_read2_b32 v[154:155], v161 offset0:32 offset1:48
	ds_read2_b32 v[152:153], v161 offset0:64 offset1:80
	ds_read2_b32 v[148:149], v161 offset0:96 offset1:112
	v_add_u32_e32 v150, s37, v147
	s_cmp_gt_i32 s76, 21
	s_mov_b64 s[8:9], -1
	s_cbranch_scc0 .LBB0_379
	s_andn2_b64 vcc, exec, s[16:17]
	s_cbranch_vccnz .LBB0_378
	v_ashrrev_i32_e32 v151, 31, v150
	v_lshlrev_b64 v[170:171], 7, v[150:151]
	v_or_b32_e32 v172, 16, v150
	s_waitcnt lgkmcnt(0)
	v_pk_mul_f32 v[168:169], v[126:127], v[156:157] op_sel_hi:[1,0]
	v_pk_mul_f32 v[166:167], v[124:125], v[156:157] op_sel_hi:[1,0]
	v_lshl_add_u64 v[170:171], v[136:137], 0, v[170:171]
	v_ashrrev_i32_e32 v173, 31, v172
	global_store_dwordx4 v[170:171], v[166:169], off sc1
	v_mov_b32_e32 v174, v157
	v_lshlrev_b64 v[172:173], 7, v[172:173]
	v_pk_mul_f32 v[168:169], v[122:123], v[156:157] op_sel_hi:[1,0]
	v_pk_mul_f32 v[166:167], v[120:121], v[156:157] op_sel_hi:[1,0]
	global_store_dwordx4 v[170:171], v[166:169], off offset:16 sc1
	v_lshl_add_u64 v[172:173], v[136:137], 0, v[172:173]
	v_lshl_add_u64 v[178:179], v[170:171], 0, s[28:29]
	v_pk_mul_f32 v[168:169], v[118:119], v[174:175] op_sel_hi:[1,0]
	v_pk_mul_f32 v[166:167], v[116:117], v[174:175] op_sel_hi:[1,0]
	global_store_dwordx4 v[172:173], v[166:169], off sc1
	s_nop 1
	v_pk_mul_f32 v[168:169], v[110:111], v[174:175] op_sel_hi:[1,0]
	v_pk_mul_f32 v[166:167], v[108:109], v[174:175] op_sel_hi:[1,0]
	global_store_dwordx4 v[172:173], v[166:169], off offset:16 sc1
	v_or_b32_e32 v172, 32, v150
	v_ashrrev_i32_e32 v173, 31, v172
	v_lshlrev_b64 v[172:173], 7, v[172:173]
	v_pk_mul_f32 v[168:169], v[102:103], v[154:155] op_sel_hi:[1,0]
	v_pk_mul_f32 v[166:167], v[100:101], v[154:155] op_sel_hi:[1,0]
	v_lshl_add_u64 v[172:173], v[136:137], 0, v[172:173]
	global_store_dwordx4 v[172:173], v[166:169], off sc1
	v_mov_b32_e32 v174, v155
	s_nop 0
	v_pk_mul_f32 v[168:169], v[94:95], v[154:155] op_sel_hi:[1,0]
	v_pk_mul_f32 v[166:167], v[92:93], v[154:155] op_sel_hi:[1,0]
	global_store_dwordx4 v[172:173], v[166:169], off offset:16 sc1
	v_or_b32_e32 v172, 48, v150
	v_ashrrev_i32_e32 v173, 31, v172
	v_lshlrev_b64 v[172:173], 7, v[172:173]
	v_pk_mul_f32 v[168:169], v[86:87], v[174:175] op_sel_hi:[1,0]
	v_pk_mul_f32 v[166:167], v[84:85], v[174:175] op_sel_hi:[1,0]
	v_lshl_add_u64 v[172:173], v[136:137], 0, v[172:173]
	global_store_dwordx4 v[172:173], v[166:169], off sc1
	s_nop 1
	v_pk_mul_f32 v[168:169], v[78:79], v[174:175] op_sel_hi:[1,0]
	v_pk_mul_f32 v[166:167], v[76:77], v[174:175] op_sel_hi:[1,0]
	v_add_co_u32_e32 v174, vcc, s65, v170
	global_store_dwordx4 v[172:173], v[166:169], off offset:16 sc1
	s_nop 0
	v_addc_co_u32_e32 v175, vcc, 0, v171, vcc
	v_add_co_u32_e32 v176, vcc, s73, v170
	v_pk_mul_f32 v[168:169], v[62:63], v[152:153] op_sel_hi:[1,0]
	v_pk_mul_f32 v[166:167], v[60:61], v[152:153] op_sel_hi:[1,0]
	v_addc_co_u32_e32 v177, vcc, 0, v171, vcc
	v_lshl_add_u64 v[172:173], v[170:171], 0, s[26:27]
	global_store_dwordx4 v[176:177], v[166:169], off offset:-4096 sc1
	s_nop 1
	v_pk_mul_f32 v[168:169], v[58:59], v[152:153] op_sel_hi:[1,0]
	v_pk_mul_f32 v[166:167], v[56:57], v[152:153] op_sel_hi:[1,0]
	global_store_dwordx4 v[172:173], v[166:169], off offset:16 sc1
	v_mov_b32_e32 v172, v153
	s_nop 0
	v_pk_mul_f32 v[168:169], v[54:55], v[172:173] op_sel_hi:[1,0]
	v_pk_mul_f32 v[166:167], v[52:53], v[172:173] op_sel_hi:[1,0]
	global_store_dwordx4 v[174:175], v[166:169], off offset:2048 sc1
	s_nop 1
	v_pk_mul_f32 v[168:169], v[46:47], v[172:173] op_sel_hi:[1,0]
	v_pk_mul_f32 v[166:167], v[44:45], v[172:173] op_sel_hi:[1,0]
	global_store_dwordx4 v[178:179], v[166:169], off offset:16 sc1
	v_lshl_add_u64 v[172:173], v[170:171], 0, s[30:31]
	v_lshl_add_u64 v[170:171], v[170:171], 0, s[34:35]
	v_pk_mul_f32 v[168:169], v[38:39], v[148:149] op_sel_hi:[1,0]
	v_pk_mul_f32 v[166:167], v[36:37], v[148:149] op_sel_hi:[1,0]
	global_store_dwordx4 v[176:177], v[166:169], off sc1
	s_nop 1
	v_pk_mul_f32 v[168:169], v[30:31], v[148:149] op_sel_hi:[1,0]
	v_pk_mul_f32 v[166:167], v[28:29], v[148:149] op_sel_hi:[1,0]
	global_store_dwordx4 v[172:173], v[166:169], off offset:16 sc1
	v_mov_b32_e32 v172, v149
	s_nop 0
	v_pk_mul_f32 v[168:169], v[22:23], v[172:173] op_sel_hi:[1,0]
	v_pk_mul_f32 v[166:167], v[20:21], v[172:173] op_sel_hi:[1,0]
	global_store_dwordx4 v[176:177], v[166:169], off offset:2048 sc1
	s_nop 1
	v_pk_mul_f32 v[168:169], v[14:15], v[172:173] op_sel_hi:[1,0]
	v_pk_mul_f32 v[166:167], v[12:13], v[172:173] op_sel_hi:[1,0]
	global_store_dwordx4 v[170:171], v[166:169], off offset:16 sc1

.LBB0_379:
	s_andn2_b64 vcc, exec, s[8:9]
	s_cbranch_vccnz .LBB0_368
	v_lshl_or_b32 v166, s76, 8, v162
	s_waitcnt lgkmcnt(0)
	v_pk_mul_f32 v[126:127], v[126:127], v[156:157] op_sel_hi:[1,0]
	v_pk_mul_f32 v[124:125], v[124:125], v[156:157] op_sel_hi:[1,0]
	v_pk_mul_f32 v[120:121], v[120:121], v[156:157] op_sel_hi:[1,0]
	v_ashrrev_i32_e32 v167, 31, v166
	v_pk_mul_f32 v[122:123], v[122:123], v[156:157] op_sel_hi:[1,0]
	v_cvt_pk_bf16_f32 v124, v124, v125
	v_cvt_pk_bf16_f32 v125, v126, v127
	v_cvt_pk_bf16_f32 v126, v120, v121
	v_mov_b64_e32 v[120:121], s[10:11]
	v_cvt_pk_bf16_f32 v127, v122, v123
	v_mad_i64_i32 v[168:169], s[8:9], v150, s74, v[120:121]
	v_lshlrev_b64 v[122:123], 1, v[166:167]
	v_lshl_add_u64 v[166:167], v[168:169], 0, v[122:123]
	global_store_dwordx4 v[166:167], v[124:127], off sc1
	v_pk_mul_f32 v[114:115], v[114:115], v[156:157] op_sel_hi:[1,0]
	v_pk_mul_f32 v[112:113], v[112:113], v[156:157] op_sel_hi:[1,0]
	v_pk_mul_f32 v[124:125], v[106:107], v[156:157] op_sel_hi:[1,0]
	v_pk_mul_f32 v[106:107], v[104:105], v[156:157] op_sel_hi:[1,0]
	v_cvt_pk_bf16_f32 v104, v112, v113
	v_cvt_pk_bf16_f32 v105, v114, v115
	v_cvt_pk_bf16_f32 v106, v106, v107
	v_cvt_pk_bf16_f32 v107, v124, v125
	v_or_b32_e32 v113, 16, v150
	v_mov_b32_e32 v112, v157
	global_store_dwordx4 v[166:167], v[104:107], off offset:256 sc1
	v_pk_mul_f32 v[108:109], v[108:109], v[112:113] op_sel_hi:[1,0]
	v_pk_mul_f32 v[110:111], v[110:111], v[112:113] op_sel_hi:[1,0]
	v_pk_mul_f32 v[106:107], v[118:119], v[112:113] op_sel_hi:[1,0]
	v_pk_mul_f32 v[104:105], v[116:117], v[112:113] op_sel_hi:[1,0]
	v_pk_mul_f32 v[98:99], v[98:99], v[112:113] op_sel_hi:[1,0]
	v_cvt_pk_bf16_f32 v104, v104, v105
	v_cvt_pk_bf16_f32 v105, v106, v107
	v_cvt_pk_bf16_f32 v106, v108, v109
	v_mad_i64_i32 v[108:109], s[8:9], v113, s74, v[120:121]
	v_cvt_pk_bf16_f32 v107, v110, v111
	v_lshl_add_u64 v[108:109], v[108:109], 0, v[122:123]
	global_store_dwordx4 v[108:109], v[104:107], off sc1
	v_pk_mul_f32 v[96:97], v[96:97], v[112:113] op_sel_hi:[1,0]
	v_pk_mul_f32 v[92:93], v[92:93], v[154:155] op_sel_hi:[1,0]
	v_pk_mul_f32 v[104:105], v[90:91], v[112:113] op_sel_hi:[1,0]
	v_pk_mul_f32 v[90:91], v[88:89], v[112:113] op_sel_hi:[1,0]
	v_cvt_pk_bf16_f32 v88, v96, v97
	v_cvt_pk_bf16_f32 v89, v98, v99
	v_cvt_pk_bf16_f32 v90, v90, v91
	v_cvt_pk_bf16_f32 v91, v104, v105
	global_store_dwordx4 v[108:109], v[88:91], off offset:256 sc1
	v_or_b32_e32 v96, 32, v150
	v_pk_mul_f32 v[94:95], v[94:95], v[154:155] op_sel_hi:[1,0]
	v_pk_mul_f32 v[90:91], v[102:103], v[154:155] op_sel_hi:[1,0]
	v_pk_mul_f32 v[88:89], v[100:101], v[154:155] op_sel_hi:[1,0]
	v_pk_mul_f32 v[82:83], v[82:83], v[154:155] op_sel_hi:[1,0]
	v_cvt_pk_bf16_f32 v88, v88, v89
	v_cvt_pk_bf16_f32 v89, v90, v91
	v_cvt_pk_bf16_f32 v90, v92, v93
	v_mad_i64_i32 v[92:93], s[8:9], v96, s74, v[120:121]
	v_cvt_pk_bf16_f32 v91, v94, v95
	v_lshl_add_u64 v[92:93], v[92:93], 0, v[122:123]
	global_store_dwordx4 v[92:93], v[88:91], off sc1
	v_pk_mul_f32 v[80:81], v[80:81], v[154:155] op_sel_hi:[1,0]
	v_pk_mul_f32 v[60:61], v[60:61], v[152:153] op_sel_hi:[1,0]
	v_pk_mul_f32 v[88:89], v[74:75], v[154:155] op_sel_hi:[1,0]
	v_pk_mul_f32 v[74:75], v[72:73], v[154:155] op_sel_hi:[1,0]
	v_cvt_pk_bf16_f32 v72, v80, v81
	v_cvt_pk_bf16_f32 v73, v82, v83
	v_cvt_pk_bf16_f32 v74, v74, v75
	v_cvt_pk_bf16_f32 v75, v88, v89
	v_or_b32_e32 v81, 48, v150
	v_mov_b32_e32 v80, v155
	global_store_dwordx4 v[92:93], v[72:75], off offset:256 sc1
	v_pk_mul_f32 v[76:77], v[76:77], v[80:81] op_sel_hi:[1,0]
	v_pk_mul_f32 v[78:79], v[78:79], v[80:81] op_sel_hi:[1,0]
	v_pk_mul_f32 v[74:75], v[86:87], v[80:81] op_sel_hi:[1,0]
	v_pk_mul_f32 v[72:73], v[84:85], v[80:81] op_sel_hi:[1,0]
	v_pk_mul_f32 v[70:71], v[70:71], v[80:81] op_sel_hi:[1,0]
	v_cvt_pk_bf16_f32 v72, v72, v73
	v_cvt_pk_bf16_f32 v73, v74, v75
	v_cvt_pk_bf16_f32 v74, v76, v77
	v_mad_i64_i32 v[76:77], s[8:9], v81, s74, v[120:121]
	v_cvt_pk_bf16_f32 v75, v78, v79
	v_lshl_add_u64 v[76:77], v[76:77], 0, v[122:123]
	global_store_dwordx4 v[76:77], v[72:75], off sc1
	v_pk_mul_f32 v[68:69], v[68:69], v[80:81] op_sel_hi:[1,0]
	v_pk_mul_f32 v[62:63], v[62:63], v[152:153] op_sel_hi:[1,0]
	v_pk_mul_f32 v[72:73], v[66:67], v[80:81] op_sel_hi:[1,0]
	v_pk_mul_f32 v[66:67], v[64:65], v[80:81] op_sel_hi:[1,0]
	v_cvt_pk_bf16_f32 v64, v68, v69
	v_cvt_pk_bf16_f32 v65, v70, v71
	v_cvt_pk_bf16_f32 v66, v66, v67
	v_cvt_pk_bf16_f32 v67, v72, v73
	global_store_dwordx4 v[76:77], v[64:67], off offset:256 sc1
	v_pk_mul_f32 v[50:51], v[50:51], v[152:153] op_sel_hi:[1,0]
	v_pk_mul_f32 v[48:49], v[48:49], v[152:153] op_sel_hi:[1,0]
	v_add_u32_e32 v66, 0x80, v150
	v_pk_mul_f32 v[64:65], v[58:59], v[152:153] op_sel_hi:[1,0]
	v_pk_mul_f32 v[58:59], v[56:57], v[152:153] op_sel_hi:[1,0]
	v_cvt_pk_bf16_f32 v56, v60, v61
	v_mad_i64_i32 v[60:61], s[8:9], v66, s74, v[120:121]
	v_cvt_pk_bf16_f32 v57, v62, v63
	v_cvt_pk_bf16_f32 v58, v58, v59
	v_cvt_pk_bf16_f32 v59, v64, v65
	v_lshl_add_u64 v[60:61], v[60:61], 0, v[122:123]
	global_store_dwordx4 v[60:61], v[56:59], off sc1
	v_pk_mul_f32 v[28:29], v[28:29], v[148:149] op_sel_hi:[1,0]
	v_pk_mul_f32 v[30:31], v[30:31], v[148:149] op_sel_hi:[1,0]
	v_pk_mul_f32 v[56:57], v[42:43], v[152:153] op_sel_hi:[1,0]
	v_pk_mul_f32 v[42:43], v[40:41], v[152:153] op_sel_hi:[1,0]
	v_cvt_pk_bf16_f32 v40, v48, v49
	v_cvt_pk_bf16_f32 v41, v50, v51
	v_cvt_pk_bf16_f32 v42, v42, v43
	v_cvt_pk_bf16_f32 v43, v56, v57
	v_add_u32_e32 v49, 0x90, v150
	v_mov_b32_e32 v48, v153
	global_store_dwordx4 v[60:61], v[40:43], off offset:256 sc1
	v_pk_mul_f32 v[44:45], v[44:45], v[48:49] op_sel_hi:[1,0]
	v_pk_mul_f32 v[46:47], v[46:47], v[48:49] op_sel_hi:[1,0]
	v_pk_mul_f32 v[42:43], v[54:55], v[48:49] op_sel_hi:[1,0]
	v_pk_mul_f32 v[40:41], v[52:53], v[48:49] op_sel_hi:[1,0]
	v_pk_mul_f32 v[34:35], v[34:35], v[48:49] op_sel_hi:[1,0]
	v_cvt_pk_bf16_f32 v40, v40, v41
	v_cvt_pk_bf16_f32 v41, v42, v43
	v_cvt_pk_bf16_f32 v42, v44, v45
	v_mad_i64_i32 v[44:45], s[8:9], v49, s74, v[120:121]
	v_cvt_pk_bf16_f32 v43, v46, v47
	v_lshl_add_u64 v[44:45], v[44:45], 0, v[122:123]
	global_store_dwordx4 v[44:45], v[40:43], off sc1
	v_pk_mul_f32 v[32:33], v[32:33], v[48:49] op_sel_hi:[1,0]
	v_pk_mul_f32 v[18:19], v[18:19], v[148:149] op_sel_hi:[1,0]
	v_pk_mul_f32 v[40:41], v[26:27], v[48:49] op_sel_hi:[1,0]
	v_pk_mul_f32 v[26:27], v[24:25], v[48:49] op_sel_hi:[1,0]
	v_cvt_pk_bf16_f32 v24, v32, v33
	v_cvt_pk_bf16_f32 v25, v34, v35
	v_cvt_pk_bf16_f32 v26, v26, v27
	v_cvt_pk_bf16_f32 v27, v40, v41
	global_store_dwordx4 v[44:45], v[24:27], off offset:256 sc1
	v_add_u32_e32 v32, 0xa0, v150
	v_pk_mul_f32 v[16:17], v[16:17], v[148:149] op_sel_hi:[1,0]
	v_pk_mul_f32 v[26:27], v[38:39], v[148:149] op_sel_hi:[1,0]
	v_pk_mul_f32 v[24:25], v[36:37], v[148:149] op_sel_hi:[1,0]
	s_nop 0
	v_cvt_pk_bf16_f32 v24, v24, v25
	v_cvt_pk_bf16_f32 v25, v26, v27
	v_cvt_pk_bf16_f32 v26, v28, v29
	v_mad_i64_i32 v[28:29], s[8:9], v32, s74, v[120:121]
	v_cvt_pk_bf16_f32 v27, v30, v31
	v_lshl_add_u64 v[28:29], v[28:29], 0, v[122:123]
	global_store_dwordx4 v[28:29], v[24:27], off sc1
	s_nop 1
	v_pk_mul_f32 v[24:25], v[10:11], v[148:149] op_sel_hi:[1,0]
	v_pk_mul_f32 v[10:11], v[8:9], v[148:149] op_sel_hi:[1,0]
	v_cvt_pk_bf16_f32 v8, v16, v17
	v_cvt_pk_bf16_f32 v9, v18, v19
	v_cvt_pk_bf16_f32 v10, v10, v11
	v_cvt_pk_bf16_f32 v11, v24, v25
	v_add_u32_e32 v17, 0xb0, v150
	v_mov_b32_e32 v16, v149
	global_store_dwordx4 v[28:29], v[8:11], off offset:256 sc1
	v_pk_mul_f32 v[12:13], v[12:13], v[16:17] op_sel_hi:[1,0]
	v_pk_mul_f32 v[14:15], v[14:15], v[16:17] op_sel_hi:[1,0]
	v_pk_mul_f32 v[10:11], v[22:23], v[16:17] op_sel_hi:[1,0]
	v_pk_mul_f32 v[8:9], v[20:21], v[16:17] op_sel_hi:[1,0]
	v_pk_mul_f32 v[6:7], v[6:7], v[16:17] op_sel_hi:[1,0]
	v_cvt_pk_bf16_f32 v8, v8, v9
	v_cvt_pk_bf16_f32 v9, v10, v11
	v_cvt_pk_bf16_f32 v10, v12, v13
	v_mad_i64_i32 v[12:13], s[8:9], v17, s74, v[120:121]
	v_cvt_pk_bf16_f32 v11, v14, v15
	v_lshl_add_u64 v[12:13], v[12:13], 0, v[122:123]
	global_store_dwordx4 v[12:13], v[8:11], off sc1
	v_pk_mul_f32 v[4:5], v[4:5], v[16:17] op_sel_hi:[1,0]
	s_nop 0
	v_pk_mul_f32 v[8:9], v[2:3], v[16:17] op_sel_hi:[1,0]
	v_pk_mul_f32 v[2:3], v[0:1], v[16:17] op_sel_hi:[1,0]
	v_cvt_pk_bf16_f32 v0, v4, v5
	v_cvt_pk_bf16_f32 v1, v6, v7
	v_cvt_pk_bf16_f32 v2, v2, v3
	v_cvt_pk_bf16_f32 v3, v8, v9
	global_store_dwordx4 v[12:13], v[0:3], off offset:256 sc1
	s_branch .LBB0_368

.LBB0_445:
	v_lshl_add_u32 v46, s16, 6, v50
	v_cmp_gt_i32_e32 vcc, 3, v46
	s_add_i32 s17, s14, s15
	v_mad_u64_u32 v[66:67], s[30:31], v46, s26, v[44:45]
	v_cndmask_b32_e32 v61, -3, v53, vcc
	v_cmp_gt_i32_e32 vcc, 2, v46
	s_waitcnt vmcnt(1)
	ds_write_b128 v66, v[40:43] offset:16384
	v_add_u32_e32 v40, s17, v52
	v_cndmask_b32_e32 v67, -2, v54, vcc
	v_add_u32_e32 v42, v61, v46
	v_add_u32_e32 v43, v67, v46
	v_mad_i64_i32 v[40:41], s[30:31], v40, s27, v[48:49]
	v_mad_u64_u32 v[66:67], s[30:31], v42, s26, v[44:45]
	v_mad_u64_u32 v[70:71], s[30:31], v43, s26, v[44:45]
	global_load_dwordx4 v[40:43], v[40:41], off
	v_cmp_gt_i32_e32 vcc, 1, v46
	v_add_u32_e32 v69, 0xc0, v46
	s_waitcnt lgkmcnt(0)
	v_cndmask_b32_e32 v68, -1, v55, vcc
	v_cmp_gt_i32_e32 vcc, 0, v46
	v_add_u32_e32 v61, v68, v46
	v_add_u32_e32 v68, s17, v50
	v_cndmask_b32_e32 v46, v46, v69, vcc
	v_mad_u64_u32 v[74:75], s[30:31], v61, s26, v[44:45]
	v_mad_u64_u32 v[78:79], s[30:31], v46, s26, v[44:45]
	v_mad_i64_i32 v[82:83], s[30:31], v68, s27, v[48:49]
	s_barrier
	ds_read_b128 v[66:69], v66 offset:16384
	ds_read_b128 v[70:73], v70 offset:16384
	ds_read_b128 v[74:77], v74 offset:16384
	ds_read_b128 v[78:81], v78 offset:16384
	s_add_i32 s29, s16, 1
	s_waitcnt lgkmcnt(3)
	v_lshlrev_b32_e32 v84, 16, v66
	v_and_b32_e32 v85, 0xffff0000, v66
	v_lshlrev_b32_e32 v66, 16, v67
	v_and_b32_e32 v67, 0xffff0000, v67
	v_lshlrev_b32_e32 v92, 16, v68
	v_and_b32_e32 v93, 0xffff0000, v68
	v_lshlrev_b32_e32 v68, 16, v69
	v_and_b32_e32 v69, 0xffff0000, v69
	s_waitcnt lgkmcnt(2)
	v_lshlrev_b32_e32 v86, 16, v70
	v_and_b32_e32 v87, 0xffff0000, v70
	v_lshlrev_b32_e32 v70, 16, v71
	v_and_b32_e32 v71, 0xffff0000, v71
	v_lshlrev_b32_e32 v94, 16, v72
	v_and_b32_e32 v95, 0xffff0000, v72
	v_lshlrev_b32_e32 v72, 16, v73
	v_and_b32_e32 v73, 0xffff0000, v73
	v_pk_fma_f32 v[84:85], v[20:21], v[84:85], v[36:37]
	v_pk_fma_f32 v[66:67], v[22:23], v[66:67], v[38:39]
	v_pk_fma_f32 v[92:93], v[0:1], v[92:93], v[16:17]
	v_pk_fma_f32 v[68:69], v[2:3], v[68:69], v[18:19]
	s_waitcnt lgkmcnt(1)
	v_lshlrev_b32_e32 v88, 16, v74
	v_and_b32_e32 v89, 0xffff0000, v74
	v_lshlrev_b32_e32 v74, 16, v75
	v_and_b32_e32 v75, 0xffff0000, v75
	v_lshlrev_b32_e32 v96, 16, v76
	v_and_b32_e32 v97, 0xffff0000, v76
	v_lshlrev_b32_e32 v76, 16, v77
	v_and_b32_e32 v77, 0xffff0000, v77
	v_pk_fma_f32 v[84:85], v[28:29], v[86:87], v[84:85]
	v_pk_fma_f32 v[66:67], v[30:31], v[70:71], v[66:67]
	v_pk_fma_f32 v[70:71], v[8:9], v[94:95], v[92:93]
	v_pk_fma_f32 v[68:69], v[10:11], v[72:73], v[68:69]
	s_waitcnt lgkmcnt(0)
	v_lshlrev_b32_e32 v90, 16, v78
	v_and_b32_e32 v91, 0xffff0000, v78
	v_lshlrev_b32_e32 v78, 16, v79
	v_and_b32_e32 v79, 0xffff0000, v79
	v_lshlrev_b32_e32 v98, 16, v80
	v_and_b32_e32 v99, 0xffff0000, v80
	v_lshlrev_b32_e32 v80, 16, v81
	v_and_b32_e32 v81, 0xffff0000, v81
	v_pk_fma_f32 v[72:73], v[24:25], v[88:89], v[84:85]
	v_pk_fma_f32 v[66:67], v[26:27], v[74:75], v[66:67]
	v_pk_fma_f32 v[70:71], v[4:5], v[96:97], v[70:71]
	v_pk_fma_f32 v[68:69], v[6:7], v[76:77], v[68:69]
	v_pk_fma_f32 v[72:73], v[32:33], v[90:91], v[72:73]
	v_pk_fma_f32 v[66:67], v[34:35], v[78:79], v[66:67]
	v_pk_fma_f32 v[70:71], v[12:13], v[98:99], v[70:71]
	v_pk_fma_f32 v[68:69], v[14:15], v[80:81], v[68:69]
	v_mul_f32_e32 v46, 0xbfb8aa3b, v72
	v_mul_f32_e32 v61, 0xbfb8aa3b, v73
	v_mul_f32_e32 v74, 0xbfb8aa3b, v66
	v_mul_f32_e32 v75, 0xbfb8aa3b, v67
	v_mul_f32_e32 v76, 0xbfb8aa3b, v70
	v_mul_f32_e32 v77, 0xbfb8aa3b, v71
	v_mul_f32_e32 v78, 0xbfb8aa3b, v68
	v_mul_f32_e32 v79, 0xbfb8aa3b, v69
	v_exp_f32_e32 v46, v46
	v_exp_f32_e32 v61, v61
	v_exp_f32_e32 v74, v74
	v_exp_f32_e32 v75, v75
	v_exp_f32_e32 v76, v76
	v_exp_f32_e32 v77, v77
	v_exp_f32_e32 v78, v78
	v_exp_f32_e32 v79, v79
	v_add_f32_e32 v46, 1.0, v46
	v_add_f32_e32 v61, 1.0, v61
	v_add_f32_e32 v80, 1.0, v74
	v_add_f32_e32 v81, 1.0, v75
	v_add_f32_e32 v84, 1.0, v76
	v_add_f32_e32 v85, 1.0, v77
	v_add_f32_e32 v86, 1.0, v78
	v_add_f32_e32 v87, 1.0, v79
	v_rcp_f32_e32 v74, v46
	v_rcp_f32_e32 v75, v61
	v_rcp_f32_e32 v76, v80
	v_rcp_f32_e32 v77, v81
	v_rcp_f32_e32 v78, v84
	v_rcp_f32_e32 v79, v85
	v_rcp_f32_e32 v80, v86
	v_rcp_f32_e32 v81, v87
	s_cmp_lg_u32 s16, 2
	s_cselect_b32 s16, s29, 0
	s_add_i32 s15, s15, 64
	v_pk_mul_f32 v[72:73], v[72:73], v[74:75]
	v_pk_mul_f32 v[74:75], v[66:67], v[76:77]
	v_pk_mul_f32 v[70:71], v[70:71], v[78:79]
	v_pk_mul_f32 v[76:77], v[68:69], v[80:81]
	s_cmpk_lg_i32 s15, 0xfc0
	v_cvt_pk_bf16_f32 v66, v72, v73
	v_cvt_pk_bf16_f32 v67, v74, v75
	v_cvt_pk_bf16_f32 v68, v70, v71
	v_cvt_pk_bf16_f32 v69, v76, v77
	global_store_dwordx4 v[82:83], v[66:69], off sc1
	s_cbranch_scc1 .LBB0_445
	s_or_b32 s14, s14, 0xfc0
	s_waitcnt vmcnt(1)
	ds_write_b128 v57, v[40:43] offset:16384
	s_waitcnt lgkmcnt(0)
	s_barrier
	ds_read_b128 v[40:43], v58 offset:16384
	ds_read_b128 v[66:69], v59 offset:16384
	ds_read_b128 v[70:73], v60 offset:16384
	ds_read_b128 v[74:77], v57 offset:16384
	s_add_i32 s28, s28, s22
	s_waitcnt lgkmcnt(3)
	v_lshlrev_b32_e32 v78, 16, v40
	v_and_b32_e32 v79, 0xffff0000, v40
	v_pk_fma_f32 v[20:21], v[20:21], v[78:79], v[36:37]
	s_waitcnt lgkmcnt(2)
	v_lshlrev_b32_e32 v36, 16, v66
	v_and_b32_e32 v37, 0xffff0000, v66
	v_pk_fma_f32 v[20:21], v[28:29], v[36:37], v[20:21]
	s_waitcnt lgkmcnt(1)
	v_lshlrev_b32_e32 v28, 16, v70
	v_and_b32_e32 v29, 0xffff0000, v70
	v_pk_fma_f32 v[20:21], v[24:25], v[28:29], v[20:21]
	v_lshlrev_b32_e32 v28, 16, v41
	v_and_b32_e32 v29, 0xffff0000, v41
	v_pk_fma_f32 v[22:23], v[22:23], v[28:29], v[38:39]
	v_lshlrev_b32_e32 v28, 16, v67
	v_and_b32_e32 v29, 0xffff0000, v67
	v_pk_fma_f32 v[22:23], v[30:31], v[28:29], v[22:23]
	v_lshlrev_b32_e32 v28, 16, v71
	v_and_b32_e32 v29, 0xffff0000, v71
	v_pk_fma_f32 v[22:23], v[26:27], v[28:29], v[22:23]
	v_lshlrev_b32_e32 v28, 16, v42
	v_and_b32_e32 v29, 0xffff0000, v42
	v_pk_fma_f32 v[0:1], v[0:1], v[28:29], v[16:17]
	v_lshlrev_b32_e32 v16, 16, v68
	v_and_b32_e32 v17, 0xffff0000, v68
	v_pk_fma_f32 v[0:1], v[8:9], v[16:17], v[0:1]
	v_lshlrev_b32_e32 v8, 16, v72
	v_and_b32_e32 v9, 0xffff0000, v72
	v_pk_fma_f32 v[0:1], v[4:5], v[8:9], v[0:1]
	v_lshlrev_b32_e32 v8, 16, v43
	v_and_b32_e32 v9, 0xffff0000, v43
	v_pk_fma_f32 v[2:3], v[2:3], v[8:9], v[18:19]
	v_lshlrev_b32_e32 v8, 16, v69
	v_and_b32_e32 v9, 0xffff0000, v69
	s_waitcnt lgkmcnt(0)
	v_lshlrev_b32_e32 v4, 16, v76
	v_and_b32_e32 v5, 0xffff0000, v76
	v_pk_fma_f32 v[2:3], v[10:11], v[8:9], v[2:3]
	v_lshlrev_b32_e32 v8, 16, v73
	v_and_b32_e32 v9, 0xffff0000, v73
	v_lshlrev_b32_e32 v24, 16, v74
	v_and_b32_e32 v25, 0xffff0000, v74
	v_lshlrev_b32_e32 v26, 16, v75
	v_and_b32_e32 v27, 0xffff0000, v75
	v_pk_fma_f32 v[0:1], v[12:13], v[4:5], v[0:1]
	v_pk_fma_f32 v[2:3], v[6:7], v[8:9], v[2:3]
	v_lshlrev_b32_e32 v6, 16, v77
	v_and_b32_e32 v7, 0xffff0000, v77
	v_pk_fma_f32 v[20:21], v[32:33], v[24:25], v[20:21]
	v_pk_fma_f32 v[22:23], v[34:35], v[26:27], v[22:23]
	v_mul_f32_e32 v4, 0xbfb8aa3b, v0
	v_mul_f32_e32 v5, 0xbfb8aa3b, v1
	v_pk_fma_f32 v[2:3], v[14:15], v[6:7], v[2:3]
	v_mul_f32_e32 v24, 0xbfb8aa3b, v20
	v_mul_f32_e32 v25, 0xbfb8aa3b, v21
	v_mul_f32_e32 v26, 0xbfb8aa3b, v22
	v_mul_f32_e32 v27, 0xbfb8aa3b, v23
	v_exp_f32_e32 v4, v4
	v_exp_f32_e32 v5, v5
	v_mul_f32_e32 v6, 0xbfb8aa3b, v2
	v_mul_f32_e32 v7, 0xbfb8aa3b, v3
	v_exp_f32_e32 v24, v24
	v_exp_f32_e32 v25, v25
	v_exp_f32_e32 v26, v26
	v_exp_f32_e32 v27, v27
	v_exp_f32_e32 v6, v6
	v_exp_f32_e32 v7, v7
	v_add_f32_e32 v4, 1.0, v4
	v_add_f32_e32 v5, 1.0, v5
	v_add_f32_e32 v24, 1.0, v24
	v_add_f32_e32 v25, 1.0, v25
	v_add_f32_e32 v26, 1.0, v26
	v_add_f32_e32 v27, 1.0, v27
	v_rcp_f32_e32 v4, v4
	v_rcp_f32_e32 v5, v5
	v_add_f32_e32 v6, 1.0, v6
	v_add_f32_e32 v7, 1.0, v7
	v_rcp_f32_e32 v24, v24
	v_rcp_f32_e32 v25, v25
	v_rcp_f32_e32 v26, v26
	v_rcp_f32_e32 v27, v27
	v_rcp_f32_e32 v6, v6
	v_rcp_f32_e32 v7, v7
	v_pk_mul_f32 v[4:5], v[0:1], v[4:5]
	v_pk_mul_f32 v[8:9], v[20:21], v[24:25]
	v_pk_mul_f32 v[10:11], v[22:23], v[26:27]
	v_pk_mul_f32 v[6:7], v[2:3], v[6:7]
	v_cvt_pk_bf16_f32 v2, v4, v5
	v_add_u32_e32 v4, s14, v50
	v_cvt_pk_bf16_f32 v0, v8, v9
	v_cvt_pk_bf16_f32 v1, v10, v11
	v_cvt_pk_bf16_f32 v3, v6, v7
	v_mad_i64_i32 v[4:5], s[14:15], v4, s27, v[48:49]
	s_cmpk_gt_i32 s28, 0xbf
	global_store_dwordx4 v[4:5], v[0:3], off sc1
	s_barrier
	s_cbranch_scc0 .LBB0_442

.LBB0_461:
	s_or_b64 exec, exec, s[30:31]
	s_load_dwordx2 s[26:27], s[16:17], 0xf8
	s_waitcnt vmcnt(0)
	s_waitcnt vmcnt(0)
	ds_write_b128 v176, v[160:163]
	ds_write_b128 v176, v[164:167] offset:8192
	ds_write_b128 v176, v[168:171] offset:16384
	ds_write_b128 v176, v[172:175] offset:24576
	s_waitcnt lgkmcnt(0)
	s_barrier
	ds_read_u16 v98, v179
	ds_read_u16 v108, v179 offset:256
	ds_read_u16 v97, v179 offset:512
	ds_read_u16 v114, v179 offset:768
	ds_read_u16 v96, v179 offset:1024
	ds_read_u16 v116, v179 offset:1280
	ds_read_u16 v94, v179 offset:1536
	ds_read_u16 v118, v179 offset:1792
	ds_read_u16 v95, v179 offset:2048
	ds_read_u16 v119, v179 offset:2304
	ds_read_u16 v93, v179 offset:2560
	ds_read_u16 v132, v179 offset:2816
	ds_read_u16 v92, v179 offset:3072
	ds_read_u16 v131, v179 offset:3328
	ds_read_u16 v90, v179 offset:3584
	ds_read_u16 v103, v179 offset:3840
	ds_read_u16 v91, v179 offset:4096
	ds_read_u16 v115, v179 offset:4352
	ds_read_u16 v89, v179 offset:4608
	ds_read_u16 v130, v179 offset:4864
	ds_read_u16 v88, v179 offset:5120
	ds_read_u16 v128, v179 offset:5376
	ds_read_u16 v86, v179 offset:5632
	ds_read_u16 v129, v179 offset:5888
	ds_read_u16 v87, v179 offset:6144
	ds_read_u16 v121, v179 offset:6400
	ds_read_u16 v85, v179 offset:6656
	ds_read_u16 v122, v179 offset:6912
	ds_read_u16 v11, v179 offset:7168
	ds_read_u16 v123, v179 offset:7424
	ds_read_u16 v2, v179 offset:7680
	ds_read_u16 v125, v179 offset:7936
	s_waitcnt lgkmcnt(0)
	v_lshlrev_b32_e32 v124, 16, v116
	v_lshlrev_b32_e32 v116, 16, v132
	ds_read_b128 v[132:135], v81
	ds_read_b128 v[136:139], v81 offset:16
	ds_read_b128 v[140:143], v81 offset:32
	ds_read_b128 v[144:147], v81 offset:48
	v_lshlrev_b32_e32 v127, 16, v108
	v_lshlrev_b32_e32 v126, 16, v114
	s_waitcnt lgkmcnt(2)
	v_mul_f32_e32 v108, v107, v137
	v_mul_f32_e32 v9, v113, v133
	v_fmac_f32_e32 v9, v110, v132
	v_fmac_f32_e32 v9, v111, v134
	v_fmac_f32_e32 v108, v106, v136
	v_fmac_f32_e32 v9, v112, v135
	v_fmac_f32_e32 v108, v104, v138
	v_add_f32_e32 v9, v117, v9
	v_fmac_f32_e32 v108, v109, v139
	v_add_f32_e32 v9, v9, v108
	s_waitcnt lgkmcnt(1)
	v_mul_f32_e32 v108, v77, v141
	v_fmac_f32_e32 v108, v5, v140
	v_fmac_f32_e32 v108, v99, v142
	v_fmac_f32_e32 v108, v105, v143
	v_add_f32_e32 v9, v9, v108
	s_waitcnt lgkmcnt(0)
	v_mul_f32_e32 v108, v100, v145
	v_fmac_f32_e32 v108, v76, v144
	v_fmac_f32_e32 v108, v102, v146
	v_fmac_f32_e32 v108, v101, v147
	v_lshlrev_b32_e32 v114, 16, v131
	v_add_f32_e32 v131, v9, v108
	v_mul_f32_e64 v9, |v131|, s43
	v_exp_f32_e32 v9, v9
	v_lshlrev_b32_e32 v120, 16, v118
	v_lshlrev_b32_e32 v118, 16, v103
	v_lshlrev_b32_e32 v108, 16, v130
	v_add_f32_e32 v9, 1.0, v9
	v_cmp_gt_f32_e32 vcc, s44, v9
	v_min_f32_e32 v137, 0, v131
	v_ashrrev_i32_e32 v73, 31, v72
	v_cndmask_b32_e64 v103, 0, 32, vcc
	v_ldexp_f32 v9, v9, v103
	v_log_f32_e32 v136, v9
	v_lshlrev_b32_e32 v103, 16, v128
	v_lshlrev_b32_e32 v9, 16, v129
	ds_read_b128 v[128:131], v81 offset:64
	v_mul_f32_e32 v132, 0x3f317217, v136
	v_fma_f32 v138, v136, s45, -v132
	ds_read_b128 v[132:135], v81 offset:80
	v_fmac_f32_e32 v138, 0x3377d1cf, v136
	s_waitcnt lgkmcnt(1)
	v_mul_f32_e32 v129, v113, v129
	v_fmac_f32_e32 v129, v110, v128
	v_fmac_f32_e32 v129, v111, v130
	v_fmac_f32_e32 v129, v112, v131
	v_add_f32_e32 v139, v117, v129
	s_waitcnt lgkmcnt(0)
	v_mul_f32_e32 v133, v107, v133
	ds_read_b128 v[128:131], v81 offset:96
	v_fmac_f32_e32 v133, v106, v132
	v_fmac_f32_e32 v133, v104, v134
	v_fmac_f32_e32 v133, v109, v135
	v_add_f32_e32 v139, v139, v133
	ds_read_b128 v[132:135], v81 offset:112
	s_waitcnt lgkmcnt(1)
	v_mul_f32_e32 v129, v77, v129
	v_fmac_f32_e32 v129, v5, v128
	v_fmac_f32_e32 v129, v99, v130
	v_fmac_f32_e32 v129, v105, v131
	v_add_f32_e32 v128, v139, v129
	s_waitcnt lgkmcnt(0)
	v_mul_f32_e32 v129, v100, v133
	v_fmac_f32_e32 v129, v76, v132
	v_fmac_f32_e32 v129, v102, v134
	v_fmac_f32_e32 v129, v101, v135
	v_add_f32_e32 v129, v128, v129
	v_mul_f32_e64 v128, |v129|, s43
	v_exp_f32_e32 v128, v128
	v_fmac_f32_e32 v138, 0x3f317217, v136
	v_cmp_lt_f32_e64 s[16:17], |v136|, s46
	v_cndmask_b32_e32 v131, 0, v84, vcc
	v_add_f32_e32 v128, 1.0, v128
	v_cndmask_b32_e64 v130, v136, v138, s[16:17]
	v_cmp_gt_f32_e32 vcc, s44, v128
	v_sub_f32_e32 v130, v130, v131
	v_min_f32_e32 v129, 0, v129
	v_cndmask_b32_e64 v131, 0, 32, vcc
	v_ldexp_f32 v128, v128, v131
	v_log_f32_e32 v138, v128
	v_sub_f32_e32 v128, v137, v130
	ds_read_b128 v[130:133], v81 offset:128
	v_fma_f32 v128, v128, s47, 0
	v_mul_f32_e32 v134, 0x3f317217, v138
	v_fma_f32 v139, v138, s45, -v134
	ds_read_b128 v[134:137], v81 offset:144
	s_waitcnt lgkmcnt(1)
	v_mul_f32_e32 v131, v113, v131
	v_fmac_f32_e32 v131, v110, v130
	v_fmac_f32_e32 v131, v111, v132
	v_fmac_f32_e32 v131, v112, v133
	v_add_f32_e32 v140, v117, v131
	s_waitcnt lgkmcnt(0)
	v_mul_f32_e32 v135, v107, v135
	ds_read_b128 v[130:133], v81 offset:160
	v_fmac_f32_e32 v135, v106, v134
	v_fmac_f32_e32 v135, v104, v136
	v_fmac_f32_e32 v135, v109, v137
	v_add_f32_e32 v140, v140, v135
	ds_read_b128 v[134:137], v81 offset:176
	s_waitcnt lgkmcnt(1)
	v_mul_f32_e32 v131, v77, v131
	v_fmac_f32_e32 v131, v5, v130
	v_fmac_f32_e32 v131, v99, v132
	v_fmac_f32_e32 v131, v105, v133
	v_add_f32_e32 v130, v140, v131
	s_waitcnt lgkmcnt(0)
	v_mul_f32_e32 v131, v100, v135
	v_fmac_f32_e32 v131, v76, v134
	v_fmac_f32_e32 v131, v102, v136
	v_fmac_f32_e32 v131, v101, v137
	v_add_f32_e32 v130, v130, v131
	v_mul_f32_e64 v131, |v130|, s43
	v_exp_f32_e32 v131, v131
	v_fmac_f32_e32 v139, 0x3377d1cf, v138
	v_fmac_f32_e32 v139, 0x3f317217, v138
	v_cmp_lt_f32_e64 s[16:17], |v138|, s46
	v_add_f32_e32 v131, 1.0, v131
	v_cndmask_b32_e32 v133, 0, v84, vcc
	v_cndmask_b32_e64 v132, v138, v139, s[16:17]
	v_cmp_gt_f32_e32 vcc, s44, v131
	v_sub_f32_e32 v132, v132, v133
	v_sub_f32_e32 v129, v129, v132
	v_cndmask_b32_e64 v133, 0, 32, vcc
	v_ldexp_f32 v131, v131, v133
	v_log_f32_e32 v138, v131
	v_min_f32_e32 v139, 0, v130
	ds_read_b128 v[130:133], v81 offset:192
	v_fmamk_f32 v129, v129, 0x3d800000, v128
	v_mul_f32_e32 v134, 0x3f317217, v138
	v_fma_f32 v140, v138, s45, -v134
	ds_read_b128 v[134:137], v81 offset:208
	s_waitcnt lgkmcnt(1)
	v_mul_f32_e32 v131, v113, v131
	v_fmac_f32_e32 v131, v110, v130
	v_fmac_f32_e32 v131, v111, v132
	v_fmac_f32_e32 v131, v112, v133
	v_add_f32_e32 v141, v117, v131
	s_waitcnt lgkmcnt(0)
	v_mul_f32_e32 v135, v107, v135
	ds_read_b128 v[130:133], v81 offset:224
	v_fmac_f32_e32 v135, v106, v134
	v_fmac_f32_e32 v135, v104, v136
	v_fmac_f32_e32 v135, v109, v137
	v_add_f32_e32 v141, v141, v135
	ds_read_b128 v[134:137], v81 offset:240
	s_waitcnt lgkmcnt(1)
	v_mul_f32_e32 v131, v77, v131
	v_fmac_f32_e32 v131, v5, v130
	v_fmac_f32_e32 v131, v99, v132
	v_fmac_f32_e32 v131, v105, v133
	v_add_f32_e32 v130, v141, v131
	s_waitcnt lgkmcnt(0)
	v_mul_f32_e32 v131, v100, v135
	v_fmac_f32_e32 v131, v76, v134
	v_fmac_f32_e32 v131, v102, v136
	v_fmac_f32_e32 v131, v101, v137
	v_add_f32_e32 v131, v130, v131
	v_mul_f32_e64 v130, |v131|, s43
	v_exp_f32_e32 v130, v130
	v_fmac_f32_e32 v140, 0x3377d1cf, v138
	v_fmac_f32_e32 v140, 0x3f317217, v138
	v_cmp_lt_f32_e64 s[16:17], |v138|, s46
	v_add_f32_e32 v130, 1.0, v130
	v_cndmask_b32_e32 v133, 0, v84, vcc
	v_cndmask_b32_e64 v132, v138, v140, s[16:17]
	v_cmp_gt_f32_e32 vcc, s44, v130
	v_sub_f32_e32 v132, v132, v133
	v_min_f32_e32 v131, 0, v131
	v_cndmask_b32_e64 v133, 0, 32, vcc
	v_ldexp_f32 v130, v130, v133
	v_log_f32_e32 v140, v130
	v_sub_f32_e32 v130, v139, v132
	ds_read_b128 v[132:135], v81 offset:256
	v_fmamk_f32 v130, v130, 0x3d800000, v129
	v_mul_f32_e32 v136, 0x3f317217, v140
	v_fma_f32 v141, v140, s45, -v136
	ds_read_b128 v[136:139], v81 offset:272
	s_waitcnt lgkmcnt(1)
	v_mul_f32_e32 v133, v113, v133
	v_fmac_f32_e32 v133, v110, v132
	v_fmac_f32_e32 v133, v111, v134
	v_fmac_f32_e32 v133, v112, v135
	v_add_f32_e32 v142, v117, v133
	s_waitcnt lgkmcnt(0)
	v_mul_f32_e32 v137, v107, v137
	ds_read_b128 v[132:135], v81 offset:288
	v_fmac_f32_e32 v137, v106, v136
	v_fmac_f32_e32 v137, v104, v138
	v_fmac_f32_e32 v137, v109, v139
	v_add_f32_e32 v142, v142, v137
	ds_read_b128 v[136:139], v81 offset:304
	s_waitcnt lgkmcnt(1)
	v_mul_f32_e32 v133, v77, v133
	v_fmac_f32_e32 v133, v5, v132
	v_fmac_f32_e32 v133, v99, v134
	v_fmac_f32_e32 v133, v105, v135
	v_add_f32_e32 v132, v142, v133
	s_waitcnt lgkmcnt(0)
	v_mul_f32_e32 v133, v100, v137
	v_fmac_f32_e32 v133, v76, v136
	v_fmac_f32_e32 v133, v102, v138
	v_fmac_f32_e32 v133, v101, v139
	v_add_f32_e32 v132, v132, v133
	v_mul_f32_e64 v133, |v132|, s43
	v_exp_f32_e32 v133, v133
	v_fmac_f32_e32 v141, 0x3377d1cf, v140
	v_fmac_f32_e32 v141, 0x3f317217, v140
	v_cmp_lt_f32_e64 s[16:17], |v140|, s46
	v_add_f32_e32 v133, 1.0, v133
	v_cndmask_b32_e32 v135, 0, v84, vcc
	v_cndmask_b32_e64 v134, v140, v141, s[16:17]
	v_cmp_gt_f32_e32 vcc, s44, v133
	v_sub_f32_e32 v134, v134, v135
	v_sub_f32_e32 v131, v131, v134
	v_cndmask_b32_e64 v135, 0, 32, vcc
	v_ldexp_f32 v133, v133, v135
	v_log_f32_e32 v140, v133
	v_min_f32_e32 v141, 0, v132
	ds_read_b128 v[132:135], v81 offset:320
	v_fmamk_f32 v131, v131, 0x3d800000, v130
	v_mul_f32_e32 v136, 0x3f317217, v140
	v_fma_f32 v142, v140, s45, -v136
	ds_read_b128 v[136:139], v81 offset:336
	s_waitcnt lgkmcnt(1)
	v_mul_f32_e32 v133, v113, v133
	v_fmac_f32_e32 v133, v110, v132
	v_fmac_f32_e32 v133, v111, v134
	v_fmac_f32_e32 v133, v112, v135
	v_add_f32_e32 v143, v117, v133
	s_waitcnt lgkmcnt(0)
	v_mul_f32_e32 v137, v107, v137
	ds_read_b128 v[132:135], v81 offset:352
	v_fmac_f32_e32 v137, v106, v136
	v_fmac_f32_e32 v137, v104, v138
	v_fmac_f32_e32 v137, v109, v139
	v_add_f32_e32 v143, v143, v137
	ds_read_b128 v[136:139], v81 offset:368
	s_waitcnt lgkmcnt(1)
	v_mul_f32_e32 v133, v77, v133
	v_fmac_f32_e32 v133, v5, v132
	v_fmac_f32_e32 v133, v99, v134
	v_fmac_f32_e32 v133, v105, v135
	v_add_f32_e32 v132, v143, v133
	s_waitcnt lgkmcnt(0)
	v_mul_f32_e32 v133, v100, v137
	v_fmac_f32_e32 v133, v76, v136
	v_fmac_f32_e32 v133, v102, v138
	v_fmac_f32_e32 v133, v101, v139
	v_add_f32_e32 v133, v132, v133
	v_mul_f32_e64 v132, |v133|, s43
	v_exp_f32_e32 v132, v132
	v_fmac_f32_e32 v142, 0x3377d1cf, v140
	v_fmac_f32_e32 v142, 0x3f317217, v140
	v_cmp_lt_f32_e64 s[16:17], |v140|, s46
	v_add_f32_e32 v132, 1.0, v132
	v_cndmask_b32_e32 v135, 0, v84, vcc
	v_cndmask_b32_e64 v134, v140, v142, s[16:17]
	v_cmp_gt_f32_e32 vcc, s44, v132
	v_sub_f32_e32 v134, v134, v135
	v_min_f32_e32 v133, 0, v133
	v_cndmask_b32_e64 v135, 0, 32, vcc
	v_ldexp_f32 v132, v132, v135
	v_log_f32_e32 v142, v132
	v_sub_f32_e32 v132, v141, v134
	ds_read_b128 v[134:137], v81 offset:384
	v_fmamk_f32 v132, v132, 0x3d800000, v131
	v_mul_f32_e32 v138, 0x3f317217, v142
	v_fma_f32 v143, v142, s45, -v138
	ds_read_b128 v[138:141], v81 offset:400
	s_waitcnt lgkmcnt(1)
	v_mul_f32_e32 v135, v113, v135
	v_fmac_f32_e32 v135, v110, v134
	v_fmac_f32_e32 v135, v111, v136
	v_fmac_f32_e32 v135, v112, v137
	v_add_f32_e32 v144, v117, v135
	s_waitcnt lgkmcnt(0)
	v_mul_f32_e32 v139, v107, v139
	ds_read_b128 v[134:137], v81 offset:416
	v_fmac_f32_e32 v139, v106, v138
	v_fmac_f32_e32 v139, v104, v140
	v_fmac_f32_e32 v139, v109, v141
	v_add_f32_e32 v144, v144, v139
	ds_read_b128 v[138:141], v81 offset:432
	s_waitcnt lgkmcnt(1)
	v_mul_f32_e32 v135, v77, v135
	v_fmac_f32_e32 v135, v5, v134
	v_fmac_f32_e32 v135, v99, v136
	v_fmac_f32_e32 v135, v105, v137
	v_add_f32_e32 v134, v144, v135
	s_waitcnt lgkmcnt(0)
	v_mul_f32_e32 v135, v100, v139
	v_fmac_f32_e32 v135, v76, v138
	v_fmac_f32_e32 v135, v102, v140
	v_fmac_f32_e32 v135, v101, v141
	v_add_f32_e32 v134, v134, v135
	v_mul_f32_e64 v135, |v134|, s43
	v_exp_f32_e32 v135, v135
	v_fmac_f32_e32 v143, 0x3377d1cf, v142
	v_fmac_f32_e32 v143, 0x3f317217, v142
	v_cmp_lt_f32_e64 s[16:17], |v142|, s46
	v_add_f32_e32 v135, 1.0, v135
	v_cndmask_b32_e32 v137, 0, v84, vcc
	v_cndmask_b32_e64 v136, v142, v143, s[16:17]
	v_cmp_gt_f32_e32 vcc, s44, v135
	v_sub_f32_e32 v136, v136, v137
	v_sub_f32_e32 v133, v133, v136
	v_cndmask_b32_e64 v137, 0, 32, vcc
	v_ldexp_f32 v135, v135, v137
	v_log_f32_e32 v142, v135
	v_min_f32_e32 v143, 0, v134
	ds_read_b128 v[134:137], v81 offset:448
	v_fmamk_f32 v133, v133, 0x3d800000, v132
	v_mul_f32_e32 v138, 0x3f317217, v142
	v_fma_f32 v144, v142, s45, -v138
	ds_read_b128 v[138:141], v81 offset:464
	s_waitcnt lgkmcnt(1)
	v_mul_f32_e32 v135, v113, v135
	v_fmac_f32_e32 v135, v110, v134
	v_fmac_f32_e32 v135, v111, v136
	v_fmac_f32_e32 v135, v112, v137
	v_add_f32_e32 v145, v117, v135
	s_waitcnt lgkmcnt(0)
	v_mul_f32_e32 v139, v107, v139
	ds_read_b128 v[134:137], v81 offset:480
	v_fmac_f32_e32 v139, v106, v138
	v_fmac_f32_e32 v139, v104, v140
	v_fmac_f32_e32 v139, v109, v141
	v_add_f32_e32 v145, v145, v139
	ds_read_b128 v[138:141], v81 offset:496
	s_waitcnt lgkmcnt(1)
	v_mul_f32_e32 v135, v77, v135
	v_fmac_f32_e32 v135, v5, v134
	v_fmac_f32_e32 v135, v99, v136
	v_fmac_f32_e32 v135, v105, v137
	v_add_f32_e32 v134, v145, v135
	s_waitcnt lgkmcnt(0)
	v_mul_f32_e32 v135, v100, v139
	v_fmac_f32_e32 v135, v76, v138
	v_fmac_f32_e32 v135, v102, v140
	v_fmac_f32_e32 v135, v101, v141
	v_add_f32_e32 v135, v134, v135
	v_mul_f32_e64 v134, |v135|, s43
	v_exp_f32_e32 v134, v134
	v_fmac_f32_e32 v144, 0x3377d1cf, v142
	v_fmac_f32_e32 v144, 0x3f317217, v142
	v_cmp_lt_f32_e64 s[16:17], |v142|, s46
	v_add_f32_e32 v134, 1.0, v134
	v_cndmask_b32_e32 v137, 0, v84, vcc
	v_cndmask_b32_e64 v136, v142, v144, s[16:17]
	v_cmp_gt_f32_e32 vcc, s44, v134
	v_sub_f32_e32 v136, v136, v137
	v_min_f32_e32 v135, 0, v135
	v_cndmask_b32_e64 v137, 0, 32, vcc
	v_ldexp_f32 v134, v134, v137
	v_log_f32_e32 v144, v134
	v_sub_f32_e32 v134, v143, v136
	ds_read_b128 v[136:139], v81 offset:512
	v_fmamk_f32 v134, v134, 0x3d800000, v133
	v_mul_f32_e32 v140, 0x3f317217, v144
	v_fma_f32 v145, v144, s45, -v140
	ds_read_b128 v[140:143], v81 offset:528
	s_waitcnt lgkmcnt(1)
	v_mul_f32_e32 v137, v113, v137
	v_fmac_f32_e32 v137, v110, v136
	v_fmac_f32_e32 v137, v111, v138
	v_fmac_f32_e32 v137, v112, v139
	v_add_f32_e32 v146, v117, v137
	s_waitcnt lgkmcnt(0)
	v_mul_f32_e32 v141, v107, v141
	ds_read_b128 v[136:139], v81 offset:544
	v_fmac_f32_e32 v141, v106, v140
	v_fmac_f32_e32 v141, v104, v142
	v_fmac_f32_e32 v141, v109, v143
	v_add_f32_e32 v146, v146, v141
	ds_read_b128 v[140:143], v81 offset:560
	s_waitcnt lgkmcnt(1)
	v_mul_f32_e32 v137, v77, v137
	v_fmac_f32_e32 v137, v5, v136
	v_fmac_f32_e32 v137, v99, v138
	v_fmac_f32_e32 v137, v105, v139
	v_add_f32_e32 v136, v146, v137
	s_waitcnt lgkmcnt(0)
	v_mul_f32_e32 v137, v100, v141
	v_fmac_f32_e32 v137, v76, v140
	v_fmac_f32_e32 v137, v102, v142
	v_fmac_f32_e32 v137, v101, v143
	v_add_f32_e32 v136, v136, v137
	v_mul_f32_e64 v137, |v136|, s43
	v_exp_f32_e32 v137, v137
	v_fmac_f32_e32 v145, 0x3377d1cf, v144
	v_fmac_f32_e32 v145, 0x3f317217, v144
	v_cmp_lt_f32_e64 s[16:17], |v144|, s46
	v_add_f32_e32 v137, 1.0, v137
	v_cndmask_b32_e32 v139, 0, v84, vcc
	v_cndmask_b32_e64 v138, v144, v145, s[16:17]
	v_cmp_gt_f32_e32 vcc, s44, v137
	v_sub_f32_e32 v138, v138, v139
	v_sub_f32_e32 v135, v135, v138
	v_cndmask_b32_e64 v139, 0, 32, vcc
	v_ldexp_f32 v137, v137, v139
	v_log_f32_e32 v144, v137
	v_min_f32_e32 v145, 0, v136
	ds_read_b128 v[136:139], v81 offset:576
	v_fmamk_f32 v135, v135, 0x3d800000, v134
	v_mul_f32_e32 v140, 0x3f317217, v144
	v_fma_f32 v146, v144, s45, -v140
	ds_read_b128 v[140:143], v81 offset:592
	s_waitcnt lgkmcnt(1)
	v_mul_f32_e32 v137, v113, v137
	v_fmac_f32_e32 v137, v110, v136
	v_fmac_f32_e32 v137, v111, v138
	v_fmac_f32_e32 v137, v112, v139
	v_add_f32_e32 v147, v117, v137
	s_waitcnt lgkmcnt(0)
	v_mul_f32_e32 v141, v107, v141
	ds_read_b128 v[136:139], v81 offset:608
	v_fmac_f32_e32 v141, v106, v140
	v_fmac_f32_e32 v141, v104, v142
	v_fmac_f32_e32 v141, v109, v143
	v_add_f32_e32 v147, v147, v141
	ds_read_b128 v[140:143], v81 offset:624
	s_waitcnt lgkmcnt(1)
	v_mul_f32_e32 v137, v77, v137
	v_fmac_f32_e32 v137, v5, v136
	v_fmac_f32_e32 v137, v99, v138
	v_fmac_f32_e32 v137, v105, v139
	v_add_f32_e32 v136, v147, v137
	s_waitcnt lgkmcnt(0)
	v_mul_f32_e32 v137, v100, v141
	v_fmac_f32_e32 v137, v76, v140
	v_fmac_f32_e32 v137, v102, v142
	v_fmac_f32_e32 v137, v101, v143
	v_add_f32_e32 v137, v136, v137
	v_mul_f32_e64 v136, |v137|, s43
	v_exp_f32_e32 v136, v136
	v_fmac_f32_e32 v146, 0x3377d1cf, v144
	v_fmac_f32_e32 v146, 0x3f317217, v144
	v_cmp_lt_f32_e64 s[16:17], |v144|, s46
	v_add_f32_e32 v136, 1.0, v136
	v_cndmask_b32_e32 v139, 0, v84, vcc
	v_cndmask_b32_e64 v138, v144, v146, s[16:17]
	v_cmp_gt_f32_e32 vcc, s44, v136
	v_sub_f32_e32 v138, v138, v139
	v_min_f32_e32 v137, 0, v137
	v_cndmask_b32_e64 v139, 0, 32, vcc
	v_ldexp_f32 v136, v136, v139
	v_log_f32_e32 v146, v136
	v_sub_f32_e32 v136, v145, v138
	ds_read_b128 v[138:141], v81 offset:640
	v_fmamk_f32 v136, v136, 0x3d800000, v135
	v_mul_f32_e32 v142, 0x3f317217, v146
	v_fma_f32 v147, v146, s45, -v142
	ds_read_b128 v[142:145], v81 offset:656
	s_waitcnt lgkmcnt(1)
	v_mul_f32_e32 v139, v113, v139
	v_fmac_f32_e32 v139, v110, v138
	v_fmac_f32_e32 v139, v111, v140
	v_fmac_f32_e32 v139, v112, v141
	v_add_f32_e32 v148, v117, v139
	s_waitcnt lgkmcnt(0)
	v_mul_f32_e32 v143, v107, v143
	ds_read_b128 v[138:141], v81 offset:672
	v_fmac_f32_e32 v143, v106, v142
	v_fmac_f32_e32 v143, v104, v144
	v_fmac_f32_e32 v143, v109, v145
	v_add_f32_e32 v148, v148, v143
	ds_read_b128 v[142:145], v81 offset:688
	s_waitcnt lgkmcnt(1)
	v_mul_f32_e32 v139, v77, v139
	v_fmac_f32_e32 v139, v5, v138
	v_fmac_f32_e32 v139, v99, v140
	v_fmac_f32_e32 v139, v105, v141
	v_add_f32_e32 v138, v148, v139
	s_waitcnt lgkmcnt(0)
	v_mul_f32_e32 v139, v100, v143
	v_fmac_f32_e32 v139, v76, v142
	v_fmac_f32_e32 v139, v102, v144
	v_fmac_f32_e32 v139, v101, v145
	v_add_f32_e32 v138, v138, v139
	v_mul_f32_e64 v139, |v138|, s43
	v_exp_f32_e32 v139, v139
	v_fmac_f32_e32 v147, 0x3377d1cf, v146
	v_fmac_f32_e32 v147, 0x3f317217, v146
	v_cmp_lt_f32_e64 s[16:17], |v146|, s46
	v_add_f32_e32 v139, 1.0, v139
	v_cndmask_b32_e32 v141, 0, v84, vcc
	v_cndmask_b32_e64 v140, v146, v147, s[16:17]
	v_cmp_gt_f32_e32 vcc, s44, v139
	v_sub_f32_e32 v140, v140, v141
	v_sub_f32_e32 v137, v137, v140
	v_cndmask_b32_e64 v141, 0, 32, vcc
	v_ldexp_f32 v139, v139, v141
	v_log_f32_e32 v146, v139
	v_min_f32_e32 v147, 0, v138
	ds_read_b128 v[138:141], v81 offset:704
	v_fmamk_f32 v137, v137, 0x3d800000, v136
	v_mul_f32_e32 v142, 0x3f317217, v146
	v_fma_f32 v148, v146, s45, -v142
	ds_read_b128 v[142:145], v81 offset:720
	s_waitcnt lgkmcnt(1)
	v_mul_f32_e32 v139, v113, v139
	v_fmac_f32_e32 v139, v110, v138
	v_fmac_f32_e32 v139, v111, v140
	v_fmac_f32_e32 v139, v112, v141
	v_add_f32_e32 v149, v117, v139
	s_waitcnt lgkmcnt(0)
	v_mul_f32_e32 v143, v107, v143
	ds_read_b128 v[138:141], v81 offset:736
	v_fmac_f32_e32 v143, v106, v142
	v_fmac_f32_e32 v143, v104, v144
	v_fmac_f32_e32 v143, v109, v145
	v_add_f32_e32 v149, v149, v143
	ds_read_b128 v[142:145], v81 offset:752
	s_waitcnt lgkmcnt(1)
	v_mul_f32_e32 v139, v77, v139
	v_fmac_f32_e32 v139, v5, v138
	v_fmac_f32_e32 v139, v99, v140
	v_fmac_f32_e32 v139, v105, v141
	v_add_f32_e32 v138, v149, v139
	s_waitcnt lgkmcnt(0)
	v_mul_f32_e32 v139, v100, v143
	v_fmac_f32_e32 v139, v76, v142
	v_fmac_f32_e32 v139, v102, v144
	v_fmac_f32_e32 v139, v101, v145
	v_add_f32_e32 v139, v138, v139
	v_mul_f32_e64 v138, |v139|, s43
	v_exp_f32_e32 v138, v138
	v_fmac_f32_e32 v148, 0x3377d1cf, v146
	v_fmac_f32_e32 v148, 0x3f317217, v146
	v_cmp_lt_f32_e64 s[16:17], |v146|, s46
	v_add_f32_e32 v138, 1.0, v138
	v_cndmask_b32_e32 v141, 0, v84, vcc
	v_cndmask_b32_e64 v140, v146, v148, s[16:17]
	v_cmp_gt_f32_e32 vcc, s44, v138
	v_sub_f32_e32 v140, v140, v141
	v_min_f32_e32 v139, 0, v139
	v_cndmask_b32_e64 v141, 0, 32, vcc
	v_ldexp_f32 v138, v138, v141
	v_log_f32_e32 v148, v138
	v_sub_f32_e32 v138, v147, v140
	ds_read_b128 v[140:143], v81 offset:768
	v_fmamk_f32 v138, v138, 0x3d800000, v137
	v_mul_f32_e32 v144, 0x3f317217, v148
	v_fma_f32 v149, v148, s45, -v144
	ds_read_b128 v[144:147], v81 offset:784
	s_waitcnt lgkmcnt(1)
	v_mul_f32_e32 v141, v113, v141
	v_fmac_f32_e32 v141, v110, v140
	v_fmac_f32_e32 v141, v111, v142
	v_fmac_f32_e32 v141, v112, v143
	v_add_f32_e32 v150, v117, v141
	s_waitcnt lgkmcnt(0)
	v_mul_f32_e32 v145, v107, v145
	ds_read_b128 v[140:143], v81 offset:800
	v_fmac_f32_e32 v145, v106, v144
	v_fmac_f32_e32 v145, v104, v146
	v_fmac_f32_e32 v145, v109, v147
	v_add_f32_e32 v150, v150, v145
	ds_read_b128 v[144:147], v81 offset:816
	s_waitcnt lgkmcnt(1)
	v_mul_f32_e32 v141, v77, v141
	v_fmac_f32_e32 v141, v5, v140
	v_fmac_f32_e32 v141, v99, v142
	v_fmac_f32_e32 v141, v105, v143
	v_add_f32_e32 v140, v150, v141
	s_waitcnt lgkmcnt(0)
	v_mul_f32_e32 v141, v100, v145
	v_fmac_f32_e32 v141, v76, v144
	v_fmac_f32_e32 v141, v102, v146
	v_fmac_f32_e32 v141, v101, v147
	v_add_f32_e32 v140, v140, v141
	v_mul_f32_e64 v141, |v140|, s43
	v_exp_f32_e32 v141, v141
	v_fmac_f32_e32 v149, 0x3377d1cf, v148
	v_fmac_f32_e32 v149, 0x3f317217, v148
	v_cmp_lt_f32_e64 s[16:17], |v148|, s46
	v_add_f32_e32 v141, 1.0, v141
	v_cndmask_b32_e32 v143, 0, v84, vcc
	v_cndmask_b32_e64 v142, v148, v149, s[16:17]
	v_cmp_gt_f32_e32 vcc, s44, v141
	v_sub_f32_e32 v142, v142, v143
	v_sub_f32_e32 v139, v139, v142
	v_cndmask_b32_e64 v143, 0, 32, vcc
	v_ldexp_f32 v141, v141, v143
	v_log_f32_e32 v148, v141
	v_min_f32_e32 v149, 0, v140
	ds_read_b128 v[140:143], v81 offset:832
	v_fmamk_f32 v139, v139, 0x3d800000, v138
	v_mul_f32_e32 v144, 0x3f317217, v148
	v_fma_f32 v150, v148, s45, -v144
	ds_read_b128 v[144:147], v81 offset:848
	s_waitcnt lgkmcnt(1)
	v_mul_f32_e32 v141, v113, v141
	v_fmac_f32_e32 v141, v110, v140
	v_fmac_f32_e32 v141, v111, v142
	v_fmac_f32_e32 v141, v112, v143
	v_add_f32_e32 v151, v117, v141
	s_waitcnt lgkmcnt(0)
	v_mul_f32_e32 v145, v107, v145
	ds_read_b128 v[140:143], v81 offset:864
	v_fmac_f32_e32 v145, v106, v144
	v_fmac_f32_e32 v145, v104, v146
	v_fmac_f32_e32 v145, v109, v147
	v_add_f32_e32 v151, v151, v145
	ds_read_b128 v[144:147], v81 offset:880
	s_waitcnt lgkmcnt(1)
	v_mul_f32_e32 v141, v77, v141
	v_fmac_f32_e32 v141, v5, v140
	v_fmac_f32_e32 v141, v99, v142
	v_fmac_f32_e32 v141, v105, v143
	v_add_f32_e32 v140, v151, v141
	s_waitcnt lgkmcnt(0)
	v_mul_f32_e32 v141, v100, v145
	v_fmac_f32_e32 v141, v76, v144
	v_fmac_f32_e32 v141, v102, v146
	v_fmac_f32_e32 v141, v101, v147
	v_add_f32_e32 v140, v140, v141
	v_mul_f32_e64 v141, |v140|, s43
	v_exp_f32_e32 v141, v141
	v_fmac_f32_e32 v150, 0x3377d1cf, v148
	v_fmac_f32_e32 v150, 0x3f317217, v148
	v_cmp_lt_f32_e64 s[16:17], |v148|, s46
	v_add_f32_e32 v141, 1.0, v141
	v_cndmask_b32_e32 v143, 0, v84, vcc
	v_cndmask_b32_e64 v142, v148, v150, s[16:17]
	v_cmp_gt_f32_e32 vcc, s44, v141
	v_sub_f32_e32 v142, v142, v143
	v_min_f32_e32 v150, 0, v140
	v_cndmask_b32_e64 v143, 0, 32, vcc
	v_ldexp_f32 v141, v141, v143
	v_log_f32_e32 v148, v141
	v_sub_f32_e32 v141, v149, v142
	v_fmamk_f32 v149, v141, 0x3d800000, v139
	ds_read_b128 v[140:143], v81 offset:896
	v_mul_f32_e32 v144, 0x3f317217, v148
	v_fma_f32 v151, v148, s45, -v144
	ds_read_b128 v[144:147], v81 offset:912
	v_fmac_f32_e32 v151, 0x3377d1cf, v148
	s_waitcnt lgkmcnt(1)
	v_mul_f32_e32 v141, v113, v141
	v_fmac_f32_e32 v141, v110, v140
	v_fmac_f32_e32 v141, v111, v142
	v_fmac_f32_e32 v141, v112, v143
	v_add_f32_e32 v152, v117, v141
	s_waitcnt lgkmcnt(0)
	v_mul_f32_e32 v145, v107, v145
	ds_read_b128 v[140:143], v81 offset:928
	v_fmac_f32_e32 v145, v106, v144
	v_fmac_f32_e32 v145, v104, v146
	v_fmac_f32_e32 v145, v109, v147
	v_add_f32_e32 v152, v152, v145
	ds_read_b128 v[144:147], v81 offset:944
	s_waitcnt lgkmcnt(1)
	v_mul_f32_e32 v141, v77, v141
	v_fmac_f32_e32 v141, v5, v140
	v_fmac_f32_e32 v141, v99, v142
	v_fmac_f32_e32 v141, v105, v143
	v_add_f32_e32 v140, v152, v141
	s_waitcnt lgkmcnt(0)
	v_mul_f32_e32 v141, v100, v145
	v_fmac_f32_e32 v141, v76, v144
	v_fmac_f32_e32 v141, v102, v146
	v_fmac_f32_e32 v141, v101, v147
	v_add_f32_e32 v140, v140, v141
	v_mul_f32_e64 v141, |v140|, s43
	v_exp_f32_e32 v141, v141
	v_fmac_f32_e32 v151, 0x3f317217, v148
	v_cmp_lt_f32_e64 s[16:17], |v148|, s46
	v_cndmask_b32_e32 v143, 0, v84, vcc
	v_add_f32_e32 v141, 1.0, v141
	v_cndmask_b32_e64 v142, v148, v151, s[16:17]
	v_cmp_gt_f32_e32 vcc, s44, v141
	v_sub_f32_e32 v142, v142, v143
	v_min_f32_e32 v151, 0, v140
	v_cndmask_b32_e64 v143, 0, 32, vcc
	v_ldexp_f32 v141, v141, v143
	v_log_f32_e32 v148, v141
	v_sub_f32_e32 v141, v150, v142
	v_fmamk_f32 v150, v141, 0x3d800000, v149
	ds_read_b128 v[140:143], v81 offset:960
	v_mul_f32_e32 v144, 0x3f317217, v148
	v_fma_f32 v152, v148, s45, -v144
	ds_read_b128 v[144:147], v81 offset:976
	v_fmac_f32_e32 v152, 0x3377d1cf, v148
	s_waitcnt lgkmcnt(1)
	v_mul_f32_e32 v113, v113, v141
	v_fmac_f32_e32 v113, v110, v140
	v_fmac_f32_e32 v113, v111, v142
	v_fmac_f32_e32 v113, v112, v143
	v_add_f32_e32 v117, v117, v113
	ds_read_b128 v[110:113], v81 offset:992
	ds_read_b128 v[140:143], v81 offset:1008
	s_waitcnt lgkmcnt(2)
	v_mul_f32_e32 v107, v107, v145
	v_fmac_f32_e32 v107, v106, v144
	v_fmac_f32_e32 v107, v104, v146
	s_waitcnt lgkmcnt(1)
	v_mul_f32_e32 v77, v77, v111
	v_fmac_f32_e32 v77, v5, v110
	v_fmac_f32_e32 v107, v109, v147
	v_fmac_f32_e32 v77, v99, v112
	v_add_f32_e32 v104, v117, v107
	v_fmac_f32_e32 v77, v105, v113
	v_add_f32_e32 v5, v104, v77
	s_waitcnt lgkmcnt(0)
	v_mul_f32_e32 v77, v100, v141
	v_fmac_f32_e32 v77, v76, v140
	v_fmac_f32_e32 v77, v102, v142
	v_fmac_f32_e32 v77, v101, v143
	v_add_f32_e32 v5, v5, v77
	v_mul_f32_e64 v76, |v5|, s43
	v_exp_f32_e32 v76, v76
	v_fmac_f32_e32 v152, 0x3f317217, v148
	v_cmp_lt_f32_e64 s[16:17], |v148|, s46
	v_cndmask_b32_e32 v99, 0, v84, vcc
	v_add_f32_e32 v76, 1.0, v76
	v_cndmask_b32_e64 v77, v148, v152, s[16:17]
	v_cmp_gt_f32_e32 vcc, s44, v76
	v_sub_f32_e32 v77, v77, v99
	v_sub_f32_e32 v77, v151, v77
	v_cndmask_b32_e64 v99, 0, 32, vcc
	v_ldexp_f32 v76, v76, v99
	v_log_f32_e32 v76, v76
	v_fmamk_f32 v102, v77, 0x3d800000, v150
	v_min_f32_e32 v5, 0, v5
	v_lshlrev_b64 v[72:73], 10, v[72:73]
	v_mul_f32_e32 v77, 0x3f317217, v76
	v_fma_f32 v77, v76, s45, -v77
	v_fmac_f32_e32 v77, 0x3377d1cf, v76
	v_fmac_f32_e32 v77, 0x3f317217, v76
	v_cmp_lt_f32_e64 s[16:17], |v76|, s46
	v_ashrrev_i32_e32 v69, 31, v68
	v_lshlrev_b64 v[68:69], 10, v[68:69]
	v_cndmask_b32_e64 v76, v76, v77, s[16:17]
	v_cndmask_b32_e32 v77, 0, v84, vcc
	v_sub_f32_e32 v76, v76, v77
	v_sub_f32_e32 v5, v5, v76
	v_fmamk_f32 v104, v5, 0x3d800000, v102
	ds_write_b32 v82, v104 offset:4096
	s_waitcnt lgkmcnt(0)
	s_barrier
	ds_read2st64_b32 v[76:77], v83 offset0:16 offset1:18
	ds_read2st64_b32 v[100:101], v83 offset0:20 offset1:22
	s_add_u32 s16, s28, s24
	s_addc_u32 s17, s29, 0
	v_ashrrev_i32_e32 v65, 31, v64
	s_waitcnt lgkmcnt(1)
	v_add_f32_e32 v5, 0, v76
	v_cndmask_b32_e64 v76, v5, 0, s[8:9]
	v_add_f32_e32 v5, v5, v77
	v_add_f32_e32 v77, v77, v76
	v_cndmask_b32_e64 v76, v76, v77, s[10:11]
	s_waitcnt lgkmcnt(0)
	v_add_f32_e32 v77, v100, v76
	v_add_f32_e32 v5, v5, v100
	v_cndmask_b32_e64 v76, v76, v77, s[12:13]
	v_add_f32_e32 v5, v5, v101
	v_add_f32_e32 v77, v101, v76
	v_cndmask_b32_e64 v100, v76, v77, s[14:15]
	v_mul_f32_e32 v5, 0x3fb8aa3b, v5
	v_exp_f32_e32 v99, v5
	v_add_f32_e32 v5, v128, v100
	v_mul_f32_e32 v5, 0x3fb8aa3b, v5
	v_exp_f32_e32 v101, v5
	v_mov_b32_e32 v5, v3
	v_lshl_add_u64 v[76:77], s[16:17], 0, v[4:5]
	v_lshlrev_b32_e32 v5, 16, v98
	v_rcp_f32_e32 v98, v101
	v_mul_f32_e32 v5, v101, v5
	v_cvt_pk_bf16_f32 v5, v5, s0
	ds_write_b16 v178, v5
	v_mul_f32_e32 v5, v98, v127
	v_cvt_pk_bf16_f32 v5, v5, s0
	ds_write_b16 v178, v5 offset:256
	v_add_f32_e32 v74, v129, v100
	v_mul_f32_e32 v74, 0x3fb8aa3b, v74
	v_exp_f32_e32 v74, v74
	v_mul_f32_e32 v5, v99, v98
	v_mul_f32_e32 v5, v5, v127
	v_cvt_pk_bf16_f32 v5, v5, s0
	v_lshl_add_u64 v[72:73], v[76:77], 0, v[72:73]
	ds_write_b16 v178, v5 offset:512
	v_rcp_f32_e32 v72, v74
	v_lshlrev_b32_e32 v5, 16, v97
	v_mul_f32_e32 v5, v74, v5
	v_cvt_pk_bf16_f32 v5, v5, s0
	ds_write_b16 v178, v5 offset:768
	v_mul_f32_e32 v5, v72, v126
	v_cvt_pk_bf16_f32 v5, v5, s0
	ds_write_b16 v178, v5 offset:1024
	v_add_f32_e32 v70, v130, v100
	v_mul_f32_e32 v70, 0x3fb8aa3b, v70
	v_exp_f32_e32 v70, v70
	v_mul_f32_e32 v5, v99, v72
	v_mul_f32_e32 v5, v5, v126
	v_cvt_pk_bf16_f32 v5, v5, s0
	v_lshl_add_u64 v[68:69], v[76:77], 0, v[68:69]
	ds_write_b16 v178, v5 offset:1280
	v_rcp_f32_e32 v68, v70
	v_lshlrev_b32_e32 v5, 16, v96
	v_mul_f32_e32 v5, v70, v5
	v_cvt_pk_bf16_f32 v5, v5, s0
	ds_write_b16 v178, v5 offset:1536
	v_mul_f32_e32 v5, v68, v124
	v_cvt_pk_bf16_f32 v5, v5, s0
	ds_write_b16 v178, v5 offset:1792
	v_add_f32_e32 v66, v131, v100
	v_mul_f32_e32 v66, 0x3fb8aa3b, v66
	v_exp_f32_e32 v66, v66
	v_mul_f32_e32 v5, v99, v68
	v_mul_f32_e32 v5, v5, v124
	v_lshlrev_b64 v[64:65], 10, v[64:65]
	v_cvt_pk_bf16_f32 v5, v5, s0
	v_lshl_add_u64 v[64:65], v[76:77], 0, v[64:65]
	ds_write_b16 v178, v5 offset:2048
	v_rcp_f32_e32 v64, v66
	v_lshlrev_b32_e32 v5, 16, v94
	v_mul_f32_e32 v5, v66, v5
	v_cvt_pk_bf16_f32 v5, v5, s0
	ds_write_b16 v178, v5 offset:2304
	v_mul_f32_e32 v5, v64, v120
	v_cvt_pk_bf16_f32 v5, v5, s0
	ds_write_b16 v178, v5 offset:2560
	v_add_f32_e32 v62, v132, v100
	v_mul_f32_e32 v62, 0x3fb8aa3b, v62
	v_exp_f32_e32 v62, v62
	v_ashrrev_i32_e32 v61, 31, v60
	v_mul_f32_e32 v5, v99, v64
	v_mul_f32_e32 v5, v5, v120
	v_lshlrev_b64 v[60:61], 10, v[60:61]
	v_cvt_pk_bf16_f32 v5, v5, s0
	v_lshl_add_u64 v[60:61], v[76:77], 0, v[60:61]
	ds_write_b16 v178, v5 offset:2816
	v_rcp_f32_e32 v60, v62
	v_lshlrev_b32_e32 v5, 16, v95
	v_mul_f32_e32 v5, v62, v5
	v_lshlrev_b32_e32 v119, 16, v119
	v_cvt_pk_bf16_f32 v5, v5, s0
	ds_write_b16 v178, v5 offset:3072
	v_mul_f32_e32 v5, v60, v119
	v_cvt_pk_bf16_f32 v5, v5, s0
	ds_write_b16 v178, v5 offset:3328
	v_add_f32_e32 v58, v133, v100
	v_mul_f32_e32 v58, 0x3fb8aa3b, v58
	v_exp_f32_e32 v58, v58
	v_ashrrev_i32_e32 v57, 31, v56
	v_mul_f32_e32 v5, v99, v60
	v_mul_f32_e32 v5, v5, v119
	v_lshlrev_b64 v[56:57], 10, v[56:57]
	v_cvt_pk_bf16_f32 v5, v5, s0
	v_lshl_add_u64 v[56:57], v[76:77], 0, v[56:57]
	ds_write_b16 v178, v5 offset:3584
	v_rcp_f32_e32 v56, v58
	v_lshlrev_b32_e32 v5, 16, v93
	v_mul_f32_e32 v5, v58, v5
	v_cvt_pk_bf16_f32 v5, v5, s0
	ds_write_b16 v178, v5 offset:3840
	v_mul_f32_e32 v5, v56, v116
	v_cvt_pk_bf16_f32 v5, v5, s0
	ds_write_b16 v178, v5 offset:4096
	v_add_f32_e32 v54, v134, v100
	v_mul_f32_e32 v54, 0x3fb8aa3b, v54
	v_exp_f32_e32 v54, v54
	v_ashrrev_i32_e32 v53, 31, v52
	v_mul_f32_e32 v5, v99, v56
	v_mul_f32_e32 v5, v5, v116
	v_lshlrev_b64 v[52:53], 10, v[52:53]
	v_cvt_pk_bf16_f32 v5, v5, s0
	v_lshl_add_u64 v[52:53], v[76:77], 0, v[52:53]
	ds_write_b16 v178, v5 offset:4352
	v_rcp_f32_e32 v52, v54
	v_lshlrev_b32_e32 v5, 16, v92
	v_mul_f32_e32 v5, v54, v5
	v_cvt_pk_bf16_f32 v5, v5, s0
	ds_write_b16 v178, v5 offset:4608
	v_mul_f32_e32 v5, v52, v114
	v_cvt_pk_bf16_f32 v5, v5, s0
	ds_write_b16 v178, v5 offset:4864
	v_add_f32_e32 v50, v135, v100
	v_mul_f32_e32 v50, 0x3fb8aa3b, v50
	v_exp_f32_e32 v50, v50
	v_ashrrev_i32_e32 v49, 31, v48
	v_mul_f32_e32 v5, v99, v52
	v_mul_f32_e32 v5, v5, v114
	v_lshlrev_b64 v[48:49], 10, v[48:49]
	v_cvt_pk_bf16_f32 v5, v5, s0
	v_lshl_add_u64 v[48:49], v[76:77], 0, v[48:49]
	ds_write_b16 v178, v5 offset:5120
	v_rcp_f32_e32 v48, v50
	v_lshlrev_b32_e32 v5, 16, v90
	v_mul_f32_e32 v5, v50, v5
	v_cvt_pk_bf16_f32 v5, v5, s0
	ds_write_b16 v178, v5 offset:5376
	v_mul_f32_e32 v5, v48, v118
	v_cvt_pk_bf16_f32 v5, v5, s0
	ds_write_b16 v178, v5 offset:5632
	v_add_f32_e32 v46, v136, v100
	v_mul_f32_e32 v46, 0x3fb8aa3b, v46
	v_exp_f32_e32 v46, v46
	v_ashrrev_i32_e32 v45, 31, v44
	v_mul_f32_e32 v5, v99, v48
	v_mul_f32_e32 v5, v5, v118
	v_lshlrev_b64 v[44:45], 10, v[44:45]
	v_cvt_pk_bf16_f32 v5, v5, s0
	v_lshl_add_u64 v[44:45], v[76:77], 0, v[44:45]
	ds_write_b16 v178, v5 offset:5888
	v_rcp_f32_e32 v44, v46
	v_lshlrev_b32_e32 v5, 16, v91
	v_mul_f32_e32 v5, v46, v5
	v_lshlrev_b32_e32 v115, 16, v115
	v_cvt_pk_bf16_f32 v5, v5, s0
	ds_write_b16 v178, v5 offset:6144
	v_mul_f32_e32 v5, v44, v115
	v_cvt_pk_bf16_f32 v5, v5, s0
	ds_write_b16 v178, v5 offset:6400
	v_add_f32_e32 v42, v137, v100
	v_mul_f32_e32 v42, 0x3fb8aa3b, v42
	v_exp_f32_e32 v42, v42
	v_ashrrev_i32_e32 v41, 31, v40
	v_mul_f32_e32 v5, v99, v44
	v_mul_f32_e32 v5, v5, v115
	v_lshlrev_b64 v[40:41], 10, v[40:41]
	v_cvt_pk_bf16_f32 v5, v5, s0
	v_lshl_add_u64 v[40:41], v[76:77], 0, v[40:41]
	ds_write_b16 v178, v5 offset:6656
	v_rcp_f32_e32 v40, v42
	v_lshlrev_b32_e32 v5, 16, v89
	v_mul_f32_e32 v5, v42, v5
	v_cvt_pk_bf16_f32 v5, v5, s0
	ds_write_b16 v178, v5 offset:6912
	v_mul_f32_e32 v5, v40, v108
	v_cvt_pk_bf16_f32 v5, v5, s0
	ds_write_b16 v178, v5 offset:7168
	v_add_f32_e32 v38, v138, v100
	v_mul_f32_e32 v38, 0x3fb8aa3b, v38
	v_exp_f32_e32 v38, v38
	v_ashrrev_i32_e32 v37, 31, v36
	v_mul_f32_e32 v5, v99, v40
	v_mul_f32_e32 v5, v5, v108
	v_lshlrev_b64 v[36:37], 10, v[36:37]
	v_cvt_pk_bf16_f32 v5, v5, s0
	v_lshl_add_u64 v[36:37], v[76:77], 0, v[36:37]
	ds_write_b16 v178, v5 offset:7424
	v_rcp_f32_e32 v36, v38
	v_lshlrev_b32_e32 v5, 16, v88
	v_mul_f32_e32 v5, v38, v5
	v_cvt_pk_bf16_f32 v5, v5, s0
	ds_write_b16 v178, v5 offset:7680
	v_mul_f32_e32 v5, v36, v103
	v_cvt_pk_bf16_f32 v5, v5, s0
	ds_write_b16 v178, v5 offset:7936
	v_add_f32_e32 v34, v139, v100
	v_mul_f32_e32 v34, 0x3fb8aa3b, v34
	v_exp_f32_e32 v34, v34
	v_ashrrev_i32_e32 v33, 31, v32
	v_mul_f32_e32 v5, v99, v36
	v_mul_f32_e32 v5, v5, v103
	v_lshlrev_b64 v[32:33], 10, v[32:33]
	v_cvt_pk_bf16_f32 v5, v5, s0
	v_lshl_add_u64 v[32:33], v[76:77], 0, v[32:33]
	ds_write_b16 v178, v5 offset:8192
	v_rcp_f32_e32 v32, v34
	v_lshlrev_b32_e32 v5, 16, v86
	v_mul_f32_e32 v5, v34, v5
	v_cvt_pk_bf16_f32 v5, v5, s0
	ds_write_b16 v178, v5 offset:8448
	v_mul_f32_e32 v5, v32, v9
	v_cvt_pk_bf16_f32 v5, v5, s0
	ds_write_b16 v178, v5 offset:8704
	v_mul_f32_e32 v5, v99, v32
	v_mul_f32_e32 v5, v5, v9
	v_add_f32_e32 v9, v149, v100
	v_mul_f32_e32 v9, 0x3fb8aa3b, v9
	v_exp_f32_e32 v9, v9
	v_ashrrev_i32_e32 v29, 31, v28
	v_lshlrev_b64 v[28:29], 10, v[28:29]
	v_cvt_pk_bf16_f32 v5, v5, s0
	v_lshl_add_u64 v[28:29], v[76:77], 0, v[28:29]
	ds_write_b16 v178, v5 offset:8960
	v_rcp_f32_e32 v28, v9
	v_lshlrev_b32_e32 v5, 16, v87
	v_mul_f32_e32 v5, v9, v5
	v_lshlrev_b32_e32 v105, 16, v121
	v_cvt_pk_bf16_f32 v5, v5, s0
	v_add_f32_e32 v9, v150, v100
	ds_write_b16 v178, v5 offset:9216
	v_mul_f32_e32 v5, v28, v105
	v_mul_f32_e32 v9, 0x3fb8aa3b, v9
	v_cvt_pk_bf16_f32 v5, v5, s0
	v_exp_f32_e32 v9, v9
	v_ashrrev_i32_e32 v25, 31, v24
	ds_write_b16 v178, v5 offset:9472
	v_mul_f32_e32 v5, v99, v28
	v_mul_f32_e32 v5, v5, v105
	v_lshlrev_b64 v[24:25], 10, v[24:25]
	v_cvt_pk_bf16_f32 v5, v5, s0
	v_lshl_add_u64 v[24:25], v[76:77], 0, v[24:25]
	ds_write_b16 v178, v5 offset:9728
	v_rcp_f32_e32 v24, v9
	v_lshlrev_b32_e32 v5, 16, v85
	v_mul_f32_e32 v5, v9, v5
	v_lshlrev_b32_e32 v106, 16, v122
	v_cvt_pk_bf16_f32 v5, v5, s0
	v_add_f32_e32 v9, v102, v100
	ds_write_b16 v178, v5 offset:9984
	v_mul_f32_e32 v5, v24, v106
	v_mul_f32_e32 v9, 0x3fb8aa3b, v9
	v_cvt_pk_bf16_f32 v5, v5, s0
	v_exp_f32_e32 v9, v9
	v_ashrrev_i32_e32 v21, 31, v20
	ds_write_b16 v178, v5 offset:10240
	v_mul_f32_e32 v5, v99, v24
	v_mul_f32_e32 v5, v5, v106
	v_lshlrev_b64 v[20:21], 10, v[20:21]
	v_cvt_pk_bf16_f32 v5, v5, s0
	v_lshl_add_u64 v[20:21], v[76:77], 0, v[20:21]
	ds_write_b16 v178, v5 offset:10496
	v_lshlrev_b32_e32 v5, 16, v11
	v_rcp_f32_e32 v11, v9
	v_mul_f32_e32 v5, v9, v5
	v_lshlrev_b32_e32 v107, 16, v123
	v_cvt_pk_bf16_f32 v5, v5, s0
	v_add_f32_e32 v9, v100, v104
	ds_write_b16 v178, v5 offset:10752
	v_mul_f32_e32 v5, v11, v107
	v_mul_f32_e32 v9, 0x3fb8aa3b, v9
	v_cvt_pk_bf16_f32 v5, v5, s0
	v_exp_f32_e32 v9, v9
	v_ashrrev_i32_e32 v17, 31, v16
	ds_write_b16 v178, v5 offset:11008
	v_mul_f32_e32 v5, v99, v11
	v_mul_f32_e32 v5, v5, v107
	v_lshlrev_b64 v[16:17], 10, v[16:17]
	v_cvt_pk_bf16_f32 v5, v5, s0
	v_lshl_add_u64 v[16:17], v[76:77], 0, v[16:17]
	ds_write_b16 v178, v5 offset:11264
	v_rcp_f32_e32 v5, v9
	v_lshlrev_b32_e32 v2, 16, v2
	v_mul_f32_e32 v2, v9, v2
	v_lshlrev_b32_e32 v109, 16, v125
	v_cvt_pk_bf16_f32 v2, v2, s0
	ds_write_b16 v178, v2 offset:11520
	v_mul_f32_e32 v2, v5, v109
	v_cvt_pk_bf16_f32 v2, v2, s0
	v_ashrrev_i32_e32 v13, 31, v12
	ds_write_b16 v178, v2 offset:11776
	v_mul_f32_e32 v2, v99, v5
	v_mul_f32_e32 v2, v2, v109
	v_lshlrev_b64 v[12:13], 10, v[12:13]
	v_cvt_pk_bf16_f32 v2, v2, s0
	v_lshl_add_u64 v[12:13], v[76:77], 0, v[12:13]
	ds_write_b16 v178, v2 offset:12032
	s_waitcnt lgkmcnt(0)
	s_barrier
	v_mov_b64_e32 v[194:195], s[94:95]
	v_mov_b64_e32 v[196:197], s[96:97]
	s_mov_b32 s100, 0x5555556
	v_mov_b32_e32 v207, 0
	v_mov_b32_e32 v188, v192
	v_mul_hi_u32 v189, v188, s100
	v_mul_u32_u24_e32 v190, 48, v189
	v_sub_u32_e32 v190, v188, v190
	ds_read_b128 v[184:187], v177
	v_and_b32_e32 v202, 15, v190
	v_lshlrev_b32_e32 v202, 4, v202
	v_bfe_u32 v203, v190, 4, 1
	v_lshl_add_u32 v202, v203, 10, v202
	v_mad_u32_u24 v204, v189, s99, v202
	v_lshlrev_b32_e32 v205, 10, v189
	v_lshl_add_u32 v205, v190, 4, v205
	v_add_u32_e32 v205, 0xfffffe00, v205
	v_cmp_gt_u32_e32 vcc, 32, v190
	s_nop 1
	v_cndmask_b32_e32 v206, v205, v204, vcc
	v_cndmask_b32_e32 v200, v196, v194, vcc
	v_cndmask_b32_e32 v201, v197, v195, vcc
	v_lshl_add_u64 v[200:201], v[206:207], 0, v[200:201]
	s_waitcnt lgkmcnt(0)
	global_store_dwordx4 v[200:201], v[184:187], off sc1
	v_add_u32_e32 v188, 0x200, v192
	v_mul_hi_u32 v189, v188, s100
	v_mul_u32_u24_e32 v190, 48, v189
	v_sub_u32_e32 v190, v188, v190
	ds_read_b128 v[208:211], v177 offset:8192
	v_and_b32_e32 v202, 15, v190
	v_lshlrev_b32_e32 v202, 4, v202
	v_bfe_u32 v203, v190, 4, 1
	v_lshl_add_u32 v202, v203, 10, v202
	v_mad_u32_u24 v204, v189, s99, v202
	v_lshlrev_b32_e32 v205, 10, v189
	v_lshl_add_u32 v205, v190, 4, v205
	v_add_u32_e32 v205, 0xfffffe00, v205
	v_cmp_gt_u32_e32 vcc, 32, v190
	s_nop 1
	v_cndmask_b32_e32 v206, v205, v204, vcc
	v_cndmask_b32_e32 v200, v196, v194, vcc
	v_cndmask_b32_e32 v201, v197, v195, vcc
	v_lshl_add_u64 v[200:201], v[206:207], 0, v[200:201]
	s_waitcnt lgkmcnt(0)
	global_store_dwordx4 v[200:201], v[208:211], off sc1
	v_add_u32_e32 v188, 0x400, v192
	v_mul_hi_u32 v189, v188, s100
	v_mul_u32_u24_e32 v190, 48, v189
	v_sub_u32_e32 v190, v188, v190
	ds_read_b128 v[184:187], v177 offset:16384
	v_and_b32_e32 v202, 15, v190
	v_lshlrev_b32_e32 v202, 4, v202
	v_bfe_u32 v203, v190, 4, 1
	v_lshl_add_u32 v202, v203, 10, v202
	v_mad_u32_u24 v204, v189, s99, v202
	v_lshlrev_b32_e32 v205, 10, v189
	v_lshl_add_u32 v205, v190, 4, v205
	v_add_u32_e32 v205, 0xfffffe00, v205
	v_cmp_gt_u32_e32 vcc, 32, v190
	s_nop 1
	v_cndmask_b32_e32 v206, v205, v204, vcc
	v_cndmask_b32_e32 v200, v196, v194, vcc
	v_cndmask_b32_e32 v201, v197, v195, vcc
	v_lshl_add_u64 v[200:201], v[206:207], 0, v[200:201]
	s_waitcnt lgkmcnt(0)
	global_store_dwordx4 v[200:201], v[184:187], off sc1
	v_add_u32_e32 v188, 0x600, v192
	v_mul_hi_u32 v189, v188, s100
	v_mul_u32_u24_e32 v190, 48, v189
	v_sub_u32_e32 v190, v188, v190
	ds_read_b128 v[208:211], v177 offset:24576
	v_and_b32_e32 v202, 15, v190
	v_lshlrev_b32_e32 v202, 4, v202
	v_bfe_u32 v203, v190, 4, 1
	v_lshl_add_u32 v202, v203, 10, v202
	v_mad_u32_u24 v204, v189, s99, v202
	v_lshlrev_b32_e32 v205, 10, v189
	v_lshl_add_u32 v205, v190, 4, v205
	v_add_u32_e32 v205, 0xfffffe00, v205
	v_cmp_gt_u32_e32 vcc, 32, v190
	s_nop 1
	v_cndmask_b32_e32 v206, v205, v204, vcc
	v_cndmask_b32_e32 v200, v196, v194, vcc
	v_cndmask_b32_e32 v201, v197, v195, vcc
	v_lshl_add_u64 v[200:201], v[206:207], 0, v[200:201]
	s_waitcnt lgkmcnt(0)
	global_store_dwordx4 v[200:201], v[208:211], off sc1
	v_add_u32_e32 v188, 0x800, v192
	v_mul_hi_u32 v189, v188, s100
	v_mul_u32_u24_e32 v190, 48, v189
	v_sub_u32_e32 v190, v188, v190
	ds_read_b128 v[184:187], v177 offset:32768
	v_and_b32_e32 v202, 15, v190
	v_lshlrev_b32_e32 v202, 4, v202
	v_bfe_u32 v203, v190, 4, 1
	v_lshl_add_u32 v202, v203, 10, v202
	v_mad_u32_u24 v204, v189, s99, v202
	v_lshlrev_b32_e32 v205, 10, v189
	v_lshl_add_u32 v205, v190, 4, v205
	v_add_u32_e32 v205, 0xfffffe00, v205
	v_cmp_gt_u32_e32 vcc, 32, v190
	s_nop 1
	v_cndmask_b32_e32 v206, v205, v204, vcc
	v_cndmask_b32_e32 v200, v196, v194, vcc
	v_cndmask_b32_e32 v201, v197, v195, vcc
	v_lshl_add_u64 v[200:201], v[206:207], 0, v[200:201]
	s_waitcnt lgkmcnt(0)
	global_store_dwordx4 v[200:201], v[184:187], off sc1
	v_add_u32_e32 v188, 0xa00, v192
	v_mul_hi_u32 v189, v188, s100
	v_mul_u32_u24_e32 v190, 48, v189
	v_sub_u32_e32 v190, v188, v190
	ds_read_b128 v[208:211], v177 offset:40960
	v_and_b32_e32 v202, 15, v190
	v_lshlrev_b32_e32 v202, 4, v202
	v_bfe_u32 v203, v190, 4, 1
	v_lshl_add_u32 v202, v203, 10, v202
	v_mad_u32_u24 v204, v189, s99, v202
	v_lshlrev_b32_e32 v205, 10, v189
	v_lshl_add_u32 v205, v190, 4, v205
	v_add_u32_e32 v205, 0xfffffe00, v205
	v_cmp_gt_u32_e32 vcc, 32, v190
	s_nop 1
	v_cndmask_b32_e32 v206, v205, v204, vcc
	v_cndmask_b32_e32 v200, v196, v194, vcc
	v_cndmask_b32_e32 v201, v197, v195, vcc
	v_lshl_add_u64 v[200:201], v[206:207], 0, v[200:201]
	s_waitcnt lgkmcnt(0)
	global_store_dwordx4 v[200:201], v[208:211], off sc1
	s_and_saveexec_b64 s[16:17], s[8:9]
	s_cbranch_execz .LBB0_458
	s_lshl_b32 s24, s51, 6
	s_or_b32 s28, s24, s50
	s_ashr_i32 s29, s28, 31
	s_lshl_b64 s[28:29], s[28:29], 11
	s_add_u32 s24, s26, s28
	s_addc_u32 s27, s27, s29
	s_lshl_b32 s26, s49, 2
	s_add_u32 s26, s24, s26
	s_addc_u32 s27, s27, 0
	v_mov_b32_e32 v11, v3
	v_lshl_add_u64 v[12:13], s[26:27], 0, v[10:11]
	v_add_co_u32_e32 v12, vcc, 0x2000000, v12
	s_nop 1
	v_addc_co_u32_e32 v13, vcc, 0, v13, vcc
	global_store_dword v[12:13], v99, off
	s_branch .LBB0_458

.LBB0_470:
	s_nop 0
	v_lshl_add_u32 v54, s11, 6, v47
	v_mad_u64_u32 v[52:53], s[6:7], v54, s9, v[46:47]
	v_cmp_gt_i32_e64 s[6:7], 3, v54
	s_add_i32 s12, s3, s8
	v_add_u32_e32 v57, 0xc0, v54
	v_cndmask_b32_e64 v53, -3, v49, s[6:7]
	v_cmp_gt_i32_e64 s[6:7], 2, v54
	s_waitcnt vmcnt(1)
	ds_write_b128 v52, v[40:43] offset:16384
	v_add_u32_e32 v40, s12, v48
	v_cndmask_b32_e64 v55, -2, v50, s[6:7]
	v_cmp_gt_i32_e64 s[6:7], 1, v54
	v_add_u32_e32 v42, v53, v54
	v_add_u32_e32 v43, v55, v54
	v_cndmask_b32_e64 v56, -1, v51, s[6:7]
	v_cmp_gt_i32_e64 s[6:7], 0, v54
	v_add_u32_e32 v55, v56, v54
	v_add_u32_e32 v58, s12, v47
	v_cndmask_b32_e64 v54, v54, v57, s[6:7]
	v_mad_i64_i32 v[40:41], s[6:7], v40, s10, v[44:45]
	v_mad_u64_u32 v[52:53], s[6:7], v42, s9, v[46:47]
	v_mad_u64_u32 v[56:57], s[6:7], v43, s9, v[46:47]
	global_load_dwordx4 v[40:43], v[40:41], off
	v_mad_u64_u32 v[60:61], s[6:7], v55, s9, v[46:47]
	v_mad_u64_u32 v[64:65], s[6:7], v54, s9, v[46:47]
	v_mad_i64_i32 v[68:69], s[6:7], v58, s10, v[44:45]
	s_waitcnt lgkmcnt(0)
	s_barrier
	ds_read_b128 v[52:55], v52 offset:16384
	ds_read_b128 v[56:59], v56 offset:16384
	ds_read_b128 v[60:63], v60 offset:16384
	ds_read_b128 v[64:67], v64 offset:16384
	s_add_i32 s13, s11, 1
	s_waitcnt lgkmcnt(3)
	v_lshlrev_b32_e32 v70, 16, v52
	v_and_b32_e32 v71, 0xffff0000, v52
	v_lshlrev_b32_e32 v52, 16, v53
	v_and_b32_e32 v53, 0xffff0000, v53
	v_lshlrev_b32_e32 v80, 16, v54
	v_and_b32_e32 v81, 0xffff0000, v54
	v_lshlrev_b32_e32 v54, 16, v55
	v_and_b32_e32 v55, 0xffff0000, v55
	s_waitcnt lgkmcnt(2)
	v_lshlrev_b32_e32 v72, 16, v56
	v_and_b32_e32 v73, 0xffff0000, v56
	v_lshlrev_b32_e32 v56, 16, v57
	v_and_b32_e32 v57, 0xffff0000, v57
	v_lshlrev_b32_e32 v82, 16, v58
	v_and_b32_e32 v83, 0xffff0000, v58
	v_lshlrev_b32_e32 v58, 16, v59
	v_and_b32_e32 v59, 0xffff0000, v59
	v_pk_fma_f32 v[70:71], v[20:21], v[70:71], v[36:37]
	v_pk_fma_f32 v[52:53], v[22:23], v[52:53], v[38:39]
	v_pk_fma_f32 v[80:81], v[0:1], v[80:81], v[16:17]
	v_pk_fma_f32 v[54:55], v[2:3], v[54:55], v[18:19]
	s_waitcnt lgkmcnt(1)
	v_lshlrev_b32_e32 v74, 16, v60
	v_and_b32_e32 v75, 0xffff0000, v60
	v_lshlrev_b32_e32 v60, 16, v61
	v_and_b32_e32 v61, 0xffff0000, v61
	v_lshlrev_b32_e32 v84, 16, v62
	v_and_b32_e32 v85, 0xffff0000, v62
	v_lshlrev_b32_e32 v62, 16, v63
	v_and_b32_e32 v63, 0xffff0000, v63
	v_pk_fma_f32 v[70:71], v[28:29], v[72:73], v[70:71]
	v_pk_fma_f32 v[52:53], v[30:31], v[56:57], v[52:53]
	v_pk_fma_f32 v[56:57], v[8:9], v[82:83], v[80:81]
	v_pk_fma_f32 v[54:55], v[10:11], v[58:59], v[54:55]
	s_waitcnt lgkmcnt(0)
	v_lshlrev_b32_e32 v76, 16, v64
	v_and_b32_e32 v77, 0xffff0000, v64
	v_lshlrev_b32_e32 v64, 16, v65
	v_and_b32_e32 v65, 0xffff0000, v65
	v_lshlrev_b32_e32 v86, 16, v66
	v_and_b32_e32 v87, 0xffff0000, v66
	v_lshlrev_b32_e32 v66, 16, v67
	v_and_b32_e32 v67, 0xffff0000, v67
	v_pk_fma_f32 v[58:59], v[24:25], v[74:75], v[70:71]
	v_pk_fma_f32 v[52:53], v[26:27], v[60:61], v[52:53]
	v_pk_fma_f32 v[56:57], v[4:5], v[84:85], v[56:57]
	v_pk_fma_f32 v[54:55], v[6:7], v[62:63], v[54:55]
	v_pk_fma_f32 v[58:59], v[32:33], v[76:77], v[58:59]
	v_pk_fma_f32 v[52:53], v[34:35], v[64:65], v[52:53]
	v_pk_fma_f32 v[56:57], v[12:13], v[86:87], v[56:57]
	v_pk_fma_f32 v[54:55], v[14:15], v[66:67], v[54:55]
	v_mul_f32_e32 v60, 0xbfb8aa3b, v58
	v_mul_f32_e32 v61, 0xbfb8aa3b, v59
	v_mul_f32_e32 v62, 0xbfb8aa3b, v52
	v_mul_f32_e32 v63, 0xbfb8aa3b, v53
	v_mul_f32_e32 v64, 0xbfb8aa3b, v56
	v_mul_f32_e32 v65, 0xbfb8aa3b, v57
	v_mul_f32_e32 v66, 0xbfb8aa3b, v54
	v_mul_f32_e32 v67, 0xbfb8aa3b, v55
	v_exp_f32_e32 v60, v60
	v_exp_f32_e32 v61, v61
	v_exp_f32_e32 v62, v62
	v_exp_f32_e32 v63, v63
	v_exp_f32_e32 v64, v64
	v_exp_f32_e32 v65, v65
	v_exp_f32_e32 v66, v66
	v_exp_f32_e32 v67, v67
	v_add_f32_e32 v60, 1.0, v60
	v_add_f32_e32 v61, 1.0, v61
	v_add_f32_e32 v62, 1.0, v62
	v_add_f32_e32 v63, 1.0, v63
	v_add_f32_e32 v64, 1.0, v64
	v_add_f32_e32 v65, 1.0, v65
	v_add_f32_e32 v66, 1.0, v66
	v_add_f32_e32 v67, 1.0, v67
	v_rcp_f32_e32 v60, v60
	v_rcp_f32_e32 v61, v61
	v_rcp_f32_e32 v62, v62
	v_rcp_f32_e32 v63, v63
	v_rcp_f32_e32 v64, v64
	v_rcp_f32_e32 v65, v65
	v_rcp_f32_e32 v66, v66
	v_rcp_f32_e32 v67, v67
	s_cmp_lg_u32 s11, 2
	s_cselect_b32 s11, s13, 0
	s_add_i32 s8, s8, 64
	v_pk_mul_f32 v[58:59], v[58:59], v[60:61]
	v_pk_mul_f32 v[60:61], v[52:53], v[62:63]
	v_pk_mul_f32 v[56:57], v[56:57], v[64:65]
	v_pk_mul_f32 v[62:63], v[54:55], v[66:67]
	s_cmpk_lg_i32 s8, 0xfc0
	v_cvt_pk_bf16_f32 v52, v58, v59
	v_cvt_pk_bf16_f32 v53, v60, v61
	v_cvt_pk_bf16_f32 v54, v56, v57
	v_cvt_pk_bf16_f32 v55, v62, v63
	global_store_dwordx4 v[68:69], v[52:55], off sc1
	s_cbranch_scc1 .LBB0_470
	s_or_b32 s6, s3, 0xfc0
	s_movk_i32 s3, 0x90
	v_mad_u32_u24 v56, v47, s3, v46
	s_waitcnt vmcnt(1)
	ds_write_b128 v56, v[40:43] offset:16384
	v_mov_b32_e32 v40, 0xbd
	v_cndmask_b32_e32 v40, -3, v40, vcc
	v_add_u32_e32 v40, v40, v47
	v_mad_i32_i24 v40, v40, s3, v46
	v_mov_b32_e32 v48, 0xbe
	v_cmp_gt_u32_e32 vcc, 16, v192
	s_waitcnt lgkmcnt(0)
	s_barrier
	ds_read_b128 v[40:43], v40 offset:16384
	v_cndmask_b32_e32 v48, -2, v48, vcc
	v_mov_b32_e32 v49, 0xbf
	v_cmp_gt_u32_e32 vcc, 8, v192
	v_add_u32_e32 v48, v48, v47
	v_mad_i32_i24 v48, v48, s3, v46
	v_cndmask_b32_e32 v49, -1, v49, vcc
	v_add_u32_e32 v49, v49, v47
	v_mad_i32_i24 v46, v49, s3, v46
	ds_read_b128 v[48:51], v48 offset:16384
	ds_read_b128 v[52:55], v46 offset:16384
	ds_read_b128 v[56:59], v56 offset:16384
	s_waitcnt lgkmcnt(3)
	v_lshlrev_b32_e32 v60, 16, v40
	v_and_b32_e32 v61, 0xffff0000, v40
	v_pk_fma_f32 v[20:21], v[20:21], v[60:61], v[36:37]
	s_waitcnt lgkmcnt(2)
	v_lshlrev_b32_e32 v36, 16, v48
	v_and_b32_e32 v37, 0xffff0000, v48
	v_pk_fma_f32 v[20:21], v[28:29], v[36:37], v[20:21]
	s_waitcnt lgkmcnt(1)
	v_lshlrev_b32_e32 v28, 16, v52
	v_and_b32_e32 v29, 0xffff0000, v52
	v_pk_fma_f32 v[20:21], v[24:25], v[28:29], v[20:21]
	v_lshlrev_b32_e32 v28, 16, v41
	v_and_b32_e32 v29, 0xffff0000, v41
	v_pk_fma_f32 v[22:23], v[22:23], v[28:29], v[38:39]
	v_lshlrev_b32_e32 v28, 16, v49
	v_and_b32_e32 v29, 0xffff0000, v49
	v_pk_fma_f32 v[22:23], v[30:31], v[28:29], v[22:23]
	v_lshlrev_b32_e32 v28, 16, v53
	v_and_b32_e32 v29, 0xffff0000, v53
	v_pk_fma_f32 v[22:23], v[26:27], v[28:29], v[22:23]
	v_lshlrev_b32_e32 v28, 16, v42
	v_and_b32_e32 v29, 0xffff0000, v42
	v_pk_fma_f32 v[0:1], v[0:1], v[28:29], v[16:17]
	v_lshlrev_b32_e32 v16, 16, v50
	v_and_b32_e32 v17, 0xffff0000, v50
	v_pk_fma_f32 v[0:1], v[8:9], v[16:17], v[0:1]
	v_lshlrev_b32_e32 v8, 16, v54
	v_and_b32_e32 v9, 0xffff0000, v54
	v_pk_fma_f32 v[0:1], v[4:5], v[8:9], v[0:1]
	v_lshlrev_b32_e32 v8, 16, v43
	v_and_b32_e32 v9, 0xffff0000, v43
	v_pk_fma_f32 v[2:3], v[2:3], v[8:9], v[18:19]
	v_lshlrev_b32_e32 v8, 16, v51
	v_and_b32_e32 v9, 0xffff0000, v51
	s_waitcnt lgkmcnt(0)
	v_lshlrev_b32_e32 v4, 16, v58
	v_and_b32_e32 v5, 0xffff0000, v58
	v_pk_fma_f32 v[2:3], v[10:11], v[8:9], v[2:3]
	v_lshlrev_b32_e32 v8, 16, v55
	v_and_b32_e32 v9, 0xffff0000, v55
	v_lshlrev_b32_e32 v24, 16, v56
	v_and_b32_e32 v25, 0xffff0000, v56
	v_lshlrev_b32_e32 v26, 16, v57
	v_and_b32_e32 v27, 0xffff0000, v57
	v_pk_fma_f32 v[0:1], v[12:13], v[4:5], v[0:1]
	v_pk_fma_f32 v[2:3], v[6:7], v[8:9], v[2:3]
	v_lshlrev_b32_e32 v6, 16, v59
	v_and_b32_e32 v7, 0xffff0000, v59
	v_pk_fma_f32 v[20:21], v[32:33], v[24:25], v[20:21]
	v_pk_fma_f32 v[22:23], v[34:35], v[26:27], v[22:23]
	v_mul_f32_e32 v4, 0xbfb8aa3b, v0
	v_mul_f32_e32 v5, 0xbfb8aa3b, v1
	v_pk_fma_f32 v[2:3], v[14:15], v[6:7], v[2:3]
	v_mul_f32_e32 v24, 0xbfb8aa3b, v20
	v_mul_f32_e32 v25, 0xbfb8aa3b, v21
	v_mul_f32_e32 v26, 0xbfb8aa3b, v22
	v_mul_f32_e32 v27, 0xbfb8aa3b, v23
	v_exp_f32_e32 v4, v4
	v_exp_f32_e32 v5, v5
	v_mul_f32_e32 v6, 0xbfb8aa3b, v2
	v_mul_f32_e32 v7, 0xbfb8aa3b, v3
	v_exp_f32_e32 v24, v24
	v_exp_f32_e32 v25, v25
	v_exp_f32_e32 v26, v26
	v_exp_f32_e32 v27, v27
	v_exp_f32_e32 v6, v6
	v_exp_f32_e32 v7, v7
	v_add_f32_e32 v4, 1.0, v4
	v_add_f32_e32 v5, 1.0, v5
	v_add_f32_e32 v24, 1.0, v24
	v_add_f32_e32 v25, 1.0, v25
	v_add_f32_e32 v26, 1.0, v26
	v_add_f32_e32 v27, 1.0, v27
	v_rcp_f32_e32 v4, v4
	v_rcp_f32_e32 v5, v5
	v_add_f32_e32 v6, 1.0, v6
	v_add_f32_e32 v7, 1.0, v7
	v_rcp_f32_e32 v24, v24
	v_rcp_f32_e32 v25, v25
	v_rcp_f32_e32 v26, v26
	v_rcp_f32_e32 v27, v27
	v_rcp_f32_e32 v6, v6
	v_rcp_f32_e32 v7, v7
	v_pk_mul_f32 v[4:5], v[0:1], v[4:5]
	v_pk_mul_f32 v[8:9], v[20:21], v[24:25]
	v_pk_mul_f32 v[10:11], v[22:23], v[26:27]
	v_pk_mul_f32 v[6:7], v[2:3], v[6:7]
	v_cvt_pk_bf16_f32 v2, v4, v5
	v_add_u32_e32 v4, s6, v47
	s_movk_i32 s34, 0x2c00
	v_cvt_pk_bf16_f32 v0, v8, v9
	v_cvt_pk_bf16_f32 v1, v10, v11
	v_cvt_pk_bf16_f32 v3, v6, v7
	v_mad_i64_i32 v[4:5], s[6:7], v4, s34, v[44:45]
	global_store_dwordx4 v[4:5], v[0:3], off sc1
	v_lshlrev_b32_e32 v4, 2, v192
	s_mul_i32 s35, s2, 5
	v_and_b32_e32 v2, 12, v4
	v_and_b32_e32 v0, 0x7f, v192
	s_movk_i32 s6, 0x100
	v_lshlrev_b32_e32 v5, 6, v78
	v_lshlrev_b32_e32 v6, 2, v2
	s_movk_i32 s8, 0x80
	s_movk_i32 s10, 0xff
	s_movk_i32 s12, 0x17f
	s_movk_i32 s14, 0x1ff
	s_mul_i32 s16, s2, 0x280
	s_mov_b32 s3, 0xbfb8aa3b
	v_lshlrev_b32_e32 v1, 4, v79
	v_mov_b32_e32 v3, 0
	v_cmp_gt_u32_e64 s[6:7], s6, v192
	s_mov_b32 s25, 0
	v_add3_u32 v74, 0, v5, v6
	v_lshl_add_u32 v75, v79, 10, 0
	v_add_u32_e32 v76, 0, v4
	v_lshl_add_u32 v77, v0, 2, 0
	v_cmp_gt_u32_e64 s[8:9], s8, v192
	v_cmp_lt_u32_e64 s[10:11], s10, v192
	v_cmp_lt_u32_e64 s[12:13], s12, v192
	v_cmp_lt_u32_e64 s[14:15], s14, v192
	s_addk_i32 s35, 0x440
	s_add_i32 s36, s16, 0x22000
	s_movk_i32 s37, 0x1000
	s_movk_i32 s38, 0x2000
	s_movk_i32 s39, 0x3000
	s_movk_i32 s40, 0x4000
	s_movk_i32 s41, 0x5000
	s_movk_i32 s42, 0x6000
	s_movk_i32 s43, 0x7000
	v_lshlrev_b32_e32 v4, 2, v2
	s_mov_b32 s44, 0x800000
	s_mov_b32 s45, 0x3f317217
	s_mov_b32 s46, 0x7f800000
	s_mov_b32 s47, 0x3d800000
	v_lshlrev_b32_e32 v2, 1, v0
	v_lshlrev_b32_e32 v6, 2, v192
	v_mov_b32_e32 v79, 0x41b17218
	s_mov_b32 s48, 0
	s_barrier
	s_branch .LBB0_473

.LBB0_475:
	s_or_b64 exec, exec, s[30:31]
	s_load_dwordx2 s[26:27], s[16:17], 0xf8
	s_waitcnt vmcnt(0)
	ds_write_b128 v176, v[160:163]
	ds_write_b128 v176, v[164:167] offset:8192
	ds_write_b128 v176, v[168:171] offset:16384
	ds_write_b128 v176, v[172:175] offset:24576
	s_waitcnt lgkmcnt(0)
	s_barrier
	ds_read_u16 v94, v179
	ds_read_u16 v106, v179 offset:256
	ds_read_u16 v93, v179 offset:512
	ds_read_u16 v111, v179 offset:768
	ds_read_u16 v92, v179 offset:1024
	ds_read_u16 v114, v179 offset:1280
	ds_read_u16 v90, v179 offset:1536
	ds_read_u16 v115, v179 offset:1792
	ds_read_u16 v91, v179 offset:2048
	ds_read_u16 v116, v179 offset:2304
	ds_read_u16 v89, v179 offset:2560
	ds_read_u16 v129, v179 offset:2816
	ds_read_u16 v88, v179 offset:3072
	ds_read_u16 v128, v179 offset:3328
	ds_read_u16 v86, v179 offset:3584
	ds_read_u16 v102, v179 offset:3840
	ds_read_u16 v87, v179 offset:4096
	ds_read_u16 v112, v179 offset:4352
	ds_read_u16 v85, v179 offset:4608
	ds_read_u16 v127, v179 offset:4864
	ds_read_u16 v84, v179 offset:5120
	ds_read_u16 v125, v179 offset:5376
	ds_read_u16 v82, v179 offset:5632
	ds_read_u16 v126, v179 offset:5888
	ds_read_u16 v83, v179 offset:6144
	ds_read_u16 v118, v179 offset:6400
	ds_read_u16 v81, v179 offset:6656
	ds_read_u16 v119, v179 offset:6912
	ds_read_u16 v80, v179 offset:7168
	ds_read_u16 v120, v179 offset:7424
	ds_read_u16 v7, v179 offset:7680
	ds_read_u16 v121, v179 offset:7936
	s_waitcnt lgkmcnt(0)
	ds_read_b128 v[130:133], v75
	ds_read_b128 v[134:137], v75 offset:16
	ds_read_b128 v[138:141], v75 offset:32
	ds_read_b128 v[142:145], v75 offset:48
	s_waitcnt vmcnt(30)
	v_lshlrev_b32_e32 v124, 16, v106
	s_waitcnt vmcnt(28)
	v_lshlrev_b32_e32 v123, 16, v111
	s_waitcnt lgkmcnt(2)
	v_mul_f32_e32 v106, v104, v135
	v_mul_f32_e32 v5, v110, v131
	v_fmac_f32_e32 v5, v107, v130
	v_fmac_f32_e32 v5, v108, v132
	v_fmac_f32_e32 v106, v103, v134
	v_fmac_f32_e32 v5, v109, v133
	v_fmac_f32_e32 v106, v100, v136
	v_add_f32_e32 v5, v113, v5
	v_fmac_f32_e32 v106, v105, v137
	v_add_f32_e32 v5, v5, v106
	s_waitcnt lgkmcnt(1)
	v_mul_f32_e32 v106, v95, v139
	v_fmac_f32_e32 v106, v72, v138
	v_fmac_f32_e32 v106, v96, v140
	v_fmac_f32_e32 v106, v101, v141
	v_add_f32_e32 v5, v5, v106
	s_waitcnt lgkmcnt(0)
	v_mul_f32_e32 v106, v97, v143
	v_fmac_f32_e32 v106, v73, v142
	v_fmac_f32_e32 v106, v99, v144
	v_fmac_f32_e32 v106, v98, v145
	s_waitcnt vmcnt(18)
	v_lshlrev_b32_e32 v111, 16, v128
	v_add_f32_e32 v128, v5, v106
	v_mul_f32_e64 v5, |v128|, s3
	v_exp_f32_e32 v5, v5
	v_lshlrev_b32_e32 v117, 16, v115
	s_waitcnt vmcnt(16)
	v_lshlrev_b32_e32 v115, 16, v102
	v_lshlrev_b32_e32 v122, 16, v114
	v_add_f32_e32 v5, 1.0, v5
	v_cmp_gt_f32_e32 vcc, s44, v5
	v_lshlrev_b32_e32 v114, 16, v129
	s_waitcnt vmcnt(12)
	v_lshlrev_b32_e32 v106, 16, v127
	v_cndmask_b32_e64 v102, 0, 32, vcc
	v_ldexp_f32 v5, v5, v102
	v_log_f32_e32 v134, v5
	s_waitcnt vmcnt(10)
	v_lshlrev_b32_e32 v102, 16, v125
	s_waitcnt vmcnt(8)
	v_lshlrev_b32_e32 v5, 16, v126
	v_min_f32_e32 v125, 0, v128
	ds_read_b128 v[126:129], v75 offset:64
	v_mul_f32_e32 v130, 0x3f317217, v134
	v_fma_f32 v135, v134, s45, -v130
	ds_read_b128 v[130:133], v75 offset:80
	v_fmac_f32_e32 v135, 0x3377d1cf, v134
	s_waitcnt lgkmcnt(1)
	v_mul_f32_e32 v127, v110, v127
	v_fmac_f32_e32 v127, v107, v126
	v_fmac_f32_e32 v127, v108, v128
	v_fmac_f32_e32 v127, v109, v129
	v_add_f32_e32 v136, v113, v127
	s_waitcnt lgkmcnt(0)
	v_mul_f32_e32 v131, v104, v131
	ds_read_b128 v[126:129], v75 offset:96
	v_fmac_f32_e32 v131, v103, v130
	v_fmac_f32_e32 v131, v100, v132
	v_fmac_f32_e32 v131, v105, v133
	v_add_f32_e32 v136, v136, v131
	ds_read_b128 v[130:133], v75 offset:112
	s_waitcnt lgkmcnt(1)
	v_mul_f32_e32 v127, v95, v127
	v_fmac_f32_e32 v127, v72, v126
	v_fmac_f32_e32 v127, v96, v128
	v_fmac_f32_e32 v127, v101, v129
	v_add_f32_e32 v126, v136, v127
	s_waitcnt lgkmcnt(0)
	v_mul_f32_e32 v127, v97, v131
	v_fmac_f32_e32 v127, v73, v130
	v_fmac_f32_e32 v127, v99, v132
	v_fmac_f32_e32 v127, v98, v133
	v_add_f32_e32 v126, v126, v127
	v_mul_f32_e64 v127, |v126|, s3
	v_exp_f32_e32 v127, v127
	v_fmac_f32_e32 v135, 0x3f317217, v134
	v_cmp_lt_f32_e64 s[16:17], |v134|, s46
	v_cndmask_b32_e32 v129, 0, v79, vcc
	v_add_f32_e32 v127, 1.0, v127
	v_cndmask_b32_e64 v128, v134, v135, s[16:17]
	v_cmp_gt_f32_e32 vcc, s44, v127
	v_sub_f32_e32 v128, v128, v129
	v_sub_f32_e32 v125, v125, v128
	v_cndmask_b32_e64 v129, 0, 32, vcc
	v_ldexp_f32 v127, v127, v129
	v_log_f32_e32 v134, v127
	v_min_f32_e32 v135, 0, v126
	ds_read_b128 v[126:129], v75 offset:128
	v_fma_f32 v125, v125, s47, 0
	v_mul_f32_e32 v130, 0x3f317217, v134
	v_fma_f32 v136, v134, s45, -v130
	ds_read_b128 v[130:133], v75 offset:144
	s_waitcnt lgkmcnt(1)
	v_mul_f32_e32 v127, v110, v127
	v_fmac_f32_e32 v127, v107, v126
	v_fmac_f32_e32 v127, v108, v128
	v_fmac_f32_e32 v127, v109, v129
	v_add_f32_e32 v137, v113, v127
	s_waitcnt lgkmcnt(0)
	v_mul_f32_e32 v131, v104, v131
	ds_read_b128 v[126:129], v75 offset:160
	v_fmac_f32_e32 v131, v103, v130
	v_fmac_f32_e32 v131, v100, v132
	v_fmac_f32_e32 v131, v105, v133
	v_add_f32_e32 v137, v137, v131
	ds_read_b128 v[130:133], v75 offset:176
	s_waitcnt lgkmcnt(1)
	v_mul_f32_e32 v127, v95, v127
	v_fmac_f32_e32 v127, v72, v126
	v_fmac_f32_e32 v127, v96, v128
	v_fmac_f32_e32 v127, v101, v129
	v_add_f32_e32 v126, v137, v127
	s_waitcnt lgkmcnt(0)
	v_mul_f32_e32 v127, v97, v131
	v_fmac_f32_e32 v127, v73, v130
	v_fmac_f32_e32 v127, v99, v132
	v_fmac_f32_e32 v127, v98, v133
	v_add_f32_e32 v127, v126, v127
	v_mul_f32_e64 v126, |v127|, s3
	v_exp_f32_e32 v126, v126
	v_fmac_f32_e32 v136, 0x3377d1cf, v134
	v_fmac_f32_e32 v136, 0x3f317217, v134
	v_cmp_lt_f32_e64 s[16:17], |v134|, s46
	v_add_f32_e32 v126, 1.0, v126
	v_cndmask_b32_e32 v129, 0, v79, vcc
	v_cndmask_b32_e64 v128, v134, v136, s[16:17]
	v_cmp_gt_f32_e32 vcc, s44, v126
	v_sub_f32_e32 v128, v128, v129
	v_min_f32_e32 v127, 0, v127
	v_cndmask_b32_e64 v129, 0, 32, vcc
	v_ldexp_f32 v126, v126, v129
	v_log_f32_e32 v136, v126
	v_sub_f32_e32 v126, v135, v128
	ds_read_b128 v[128:131], v75 offset:192
	v_fmamk_f32 v126, v126, 0x3d800000, v125
	v_mul_f32_e32 v132, 0x3f317217, v136
	v_fma_f32 v137, v136, s45, -v132
	ds_read_b128 v[132:135], v75 offset:208
	s_waitcnt lgkmcnt(1)
	v_mul_f32_e32 v129, v110, v129
	v_fmac_f32_e32 v129, v107, v128
	v_fmac_f32_e32 v129, v108, v130
	v_fmac_f32_e32 v129, v109, v131
	v_add_f32_e32 v138, v113, v129
	s_waitcnt lgkmcnt(0)
	v_mul_f32_e32 v133, v104, v133
	ds_read_b128 v[128:131], v75 offset:224
	v_fmac_f32_e32 v133, v103, v132
	v_fmac_f32_e32 v133, v100, v134
	v_fmac_f32_e32 v133, v105, v135
	v_add_f32_e32 v138, v138, v133
	ds_read_b128 v[132:135], v75 offset:240
	s_waitcnt lgkmcnt(1)
	v_mul_f32_e32 v129, v95, v129
	v_fmac_f32_e32 v129, v72, v128
	v_fmac_f32_e32 v129, v96, v130
	v_fmac_f32_e32 v129, v101, v131
	v_add_f32_e32 v128, v138, v129
	s_waitcnt lgkmcnt(0)
	v_mul_f32_e32 v129, v97, v133
	v_fmac_f32_e32 v129, v73, v132
	v_fmac_f32_e32 v129, v99, v134
	v_fmac_f32_e32 v129, v98, v135
	v_add_f32_e32 v128, v128, v129
	v_mul_f32_e64 v129, |v128|, s3
	v_exp_f32_e32 v129, v129
	v_fmac_f32_e32 v137, 0x3377d1cf, v136
	v_fmac_f32_e32 v137, 0x3f317217, v136
	v_cmp_lt_f32_e64 s[16:17], |v136|, s46
	v_add_f32_e32 v129, 1.0, v129
	v_cndmask_b32_e32 v131, 0, v79, vcc
	v_cndmask_b32_e64 v130, v136, v137, s[16:17]
	v_cmp_gt_f32_e32 vcc, s44, v129
	v_sub_f32_e32 v130, v130, v131
	v_sub_f32_e32 v127, v127, v130
	v_cndmask_b32_e64 v131, 0, 32, vcc
	v_ldexp_f32 v129, v129, v131
	v_log_f32_e32 v136, v129
	v_min_f32_e32 v137, 0, v128
	ds_read_b128 v[128:131], v75 offset:256
	v_fmamk_f32 v127, v127, 0x3d800000, v126
	v_mul_f32_e32 v132, 0x3f317217, v136
	v_fma_f32 v138, v136, s45, -v132
	ds_read_b128 v[132:135], v75 offset:272
	s_waitcnt lgkmcnt(1)
	v_mul_f32_e32 v129, v110, v129
	v_fmac_f32_e32 v129, v107, v128
	v_fmac_f32_e32 v129, v108, v130
	v_fmac_f32_e32 v129, v109, v131
	v_add_f32_e32 v139, v113, v129
	s_waitcnt lgkmcnt(0)
	v_mul_f32_e32 v133, v104, v133
	ds_read_b128 v[128:131], v75 offset:288
	v_fmac_f32_e32 v133, v103, v132
	v_fmac_f32_e32 v133, v100, v134
	v_fmac_f32_e32 v133, v105, v135
	v_add_f32_e32 v139, v139, v133
	ds_read_b128 v[132:135], v75 offset:304
	s_waitcnt lgkmcnt(1)
	v_mul_f32_e32 v129, v95, v129
	v_fmac_f32_e32 v129, v72, v128
	v_fmac_f32_e32 v129, v96, v130
	v_fmac_f32_e32 v129, v101, v131
	v_add_f32_e32 v128, v139, v129
	s_waitcnt lgkmcnt(0)
	v_mul_f32_e32 v129, v97, v133
	v_fmac_f32_e32 v129, v73, v132
	v_fmac_f32_e32 v129, v99, v134
	v_fmac_f32_e32 v129, v98, v135
	v_add_f32_e32 v129, v128, v129
	v_mul_f32_e64 v128, |v129|, s3
	v_exp_f32_e32 v128, v128
	v_fmac_f32_e32 v138, 0x3377d1cf, v136
	v_fmac_f32_e32 v138, 0x3f317217, v136
	v_cmp_lt_f32_e64 s[16:17], |v136|, s46
	v_add_f32_e32 v128, 1.0, v128
	v_cndmask_b32_e32 v131, 0, v79, vcc
	v_cndmask_b32_e64 v130, v136, v138, s[16:17]
	v_cmp_gt_f32_e32 vcc, s44, v128
	v_sub_f32_e32 v130, v130, v131
	v_min_f32_e32 v129, 0, v129
	v_cndmask_b32_e64 v131, 0, 32, vcc
	v_ldexp_f32 v128, v128, v131
	v_log_f32_e32 v138, v128
	v_sub_f32_e32 v128, v137, v130
	ds_read_b128 v[130:133], v75 offset:320
	v_fmamk_f32 v128, v128, 0x3d800000, v127
	v_mul_f32_e32 v134, 0x3f317217, v138
	v_fma_f32 v139, v138, s45, -v134
	ds_read_b128 v[134:137], v75 offset:336
	s_waitcnt lgkmcnt(1)
	v_mul_f32_e32 v131, v110, v131
	v_fmac_f32_e32 v131, v107, v130
	v_fmac_f32_e32 v131, v108, v132
	v_fmac_f32_e32 v131, v109, v133
	v_add_f32_e32 v140, v113, v131
	s_waitcnt lgkmcnt(0)
	v_mul_f32_e32 v135, v104, v135
	ds_read_b128 v[130:133], v75 offset:352
	v_fmac_f32_e32 v135, v103, v134
	v_fmac_f32_e32 v135, v100, v136
	v_fmac_f32_e32 v135, v105, v137
	v_add_f32_e32 v140, v140, v135
	ds_read_b128 v[134:137], v75 offset:368
	s_waitcnt lgkmcnt(1)
	v_mul_f32_e32 v131, v95, v131
	v_fmac_f32_e32 v131, v72, v130
	v_fmac_f32_e32 v131, v96, v132
	v_fmac_f32_e32 v131, v101, v133
	v_add_f32_e32 v130, v140, v131
	s_waitcnt lgkmcnt(0)
	v_mul_f32_e32 v131, v97, v135
	v_fmac_f32_e32 v131, v73, v134
	v_fmac_f32_e32 v131, v99, v136
	v_fmac_f32_e32 v131, v98, v137
	v_add_f32_e32 v130, v130, v131
	v_mul_f32_e64 v131, |v130|, s3
	v_exp_f32_e32 v131, v131
	v_fmac_f32_e32 v139, 0x3377d1cf, v138
	v_fmac_f32_e32 v139, 0x3f317217, v138
	v_cmp_lt_f32_e64 s[16:17], |v138|, s46
	v_add_f32_e32 v131, 1.0, v131
	v_cndmask_b32_e32 v133, 0, v79, vcc
	v_cndmask_b32_e64 v132, v138, v139, s[16:17]
	v_cmp_gt_f32_e32 vcc, s44, v131
	v_sub_f32_e32 v132, v132, v133
	v_sub_f32_e32 v129, v129, v132
	v_cndmask_b32_e64 v133, 0, 32, vcc
	v_ldexp_f32 v131, v131, v133
	v_log_f32_e32 v138, v131
	v_min_f32_e32 v139, 0, v130
	ds_read_b128 v[130:133], v75 offset:384
	v_fmamk_f32 v129, v129, 0x3d800000, v128
	v_mul_f32_e32 v134, 0x3f317217, v138
	v_fma_f32 v140, v138, s45, -v134
	ds_read_b128 v[134:137], v75 offset:400
	s_waitcnt lgkmcnt(1)
	v_mul_f32_e32 v131, v110, v131
	v_fmac_f32_e32 v131, v107, v130
	v_fmac_f32_e32 v131, v108, v132
	v_fmac_f32_e32 v131, v109, v133
	v_add_f32_e32 v141, v113, v131
	s_waitcnt lgkmcnt(0)
	v_mul_f32_e32 v135, v104, v135
	ds_read_b128 v[130:133], v75 offset:416
	v_fmac_f32_e32 v135, v103, v134
	v_fmac_f32_e32 v135, v100, v136
	v_fmac_f32_e32 v135, v105, v137
	v_add_f32_e32 v141, v141, v135
	ds_read_b128 v[134:137], v75 offset:432
	s_waitcnt lgkmcnt(1)
	v_mul_f32_e32 v131, v95, v131
	v_fmac_f32_e32 v131, v72, v130
	v_fmac_f32_e32 v131, v96, v132
	v_fmac_f32_e32 v131, v101, v133
	v_add_f32_e32 v130, v141, v131
	s_waitcnt lgkmcnt(0)
	v_mul_f32_e32 v131, v97, v135
	v_fmac_f32_e32 v131, v73, v134
	v_fmac_f32_e32 v131, v99, v136
	v_fmac_f32_e32 v131, v98, v137
	v_add_f32_e32 v131, v130, v131
	v_mul_f32_e64 v130, |v131|, s3
	v_exp_f32_e32 v130, v130
	v_fmac_f32_e32 v140, 0x3377d1cf, v138
	v_fmac_f32_e32 v140, 0x3f317217, v138
	v_cmp_lt_f32_e64 s[16:17], |v138|, s46
	v_add_f32_e32 v130, 1.0, v130
	v_cndmask_b32_e32 v133, 0, v79, vcc
	v_cndmask_b32_e64 v132, v138, v140, s[16:17]
	v_cmp_gt_f32_e32 vcc, s44, v130
	v_sub_f32_e32 v132, v132, v133
	v_min_f32_e32 v131, 0, v131
	v_cndmask_b32_e64 v133, 0, 32, vcc
	v_ldexp_f32 v130, v130, v133
	v_log_f32_e32 v140, v130
	v_sub_f32_e32 v130, v139, v132
	ds_read_b128 v[132:135], v75 offset:448
	v_fmamk_f32 v130, v130, 0x3d800000, v129
	v_mul_f32_e32 v136, 0x3f317217, v140
	v_fma_f32 v141, v140, s45, -v136
	ds_read_b128 v[136:139], v75 offset:464
	s_waitcnt lgkmcnt(1)
	v_mul_f32_e32 v133, v110, v133
	v_fmac_f32_e32 v133, v107, v132
	v_fmac_f32_e32 v133, v108, v134
	v_fmac_f32_e32 v133, v109, v135
	v_add_f32_e32 v142, v113, v133
	s_waitcnt lgkmcnt(0)
	v_mul_f32_e32 v137, v104, v137
	ds_read_b128 v[132:135], v75 offset:480
	v_fmac_f32_e32 v137, v103, v136
	v_fmac_f32_e32 v137, v100, v138
	v_fmac_f32_e32 v137, v105, v139
	v_add_f32_e32 v142, v142, v137
	ds_read_b128 v[136:139], v75 offset:496
	s_waitcnt lgkmcnt(1)
	v_mul_f32_e32 v133, v95, v133
	v_fmac_f32_e32 v133, v72, v132
	v_fmac_f32_e32 v133, v96, v134
	v_fmac_f32_e32 v133, v101, v135
	v_add_f32_e32 v132, v142, v133
	s_waitcnt lgkmcnt(0)
	v_mul_f32_e32 v133, v97, v137
	v_fmac_f32_e32 v133, v73, v136
	v_fmac_f32_e32 v133, v99, v138
	v_fmac_f32_e32 v133, v98, v139
	v_add_f32_e32 v132, v132, v133
	v_mul_f32_e64 v133, |v132|, s3
	v_exp_f32_e32 v133, v133
	v_fmac_f32_e32 v141, 0x3377d1cf, v140
	v_fmac_f32_e32 v141, 0x3f317217, v140
	v_cmp_lt_f32_e64 s[16:17], |v140|, s46
	v_add_f32_e32 v133, 1.0, v133
	v_cndmask_b32_e32 v135, 0, v79, vcc
	v_cndmask_b32_e64 v134, v140, v141, s[16:17]
	v_cmp_gt_f32_e32 vcc, s44, v133
	v_sub_f32_e32 v134, v134, v135
	v_sub_f32_e32 v131, v131, v134
	v_cndmask_b32_e64 v135, 0, 32, vcc
	v_ldexp_f32 v133, v133, v135
	v_log_f32_e32 v140, v133
	v_min_f32_e32 v141, 0, v132
	ds_read_b128 v[132:135], v75 offset:512
	v_fmamk_f32 v131, v131, 0x3d800000, v130
	v_mul_f32_e32 v136, 0x3f317217, v140
	v_fma_f32 v142, v140, s45, -v136
	ds_read_b128 v[136:139], v75 offset:528
	s_waitcnt lgkmcnt(1)
	v_mul_f32_e32 v133, v110, v133
	v_fmac_f32_e32 v133, v107, v132
	v_fmac_f32_e32 v133, v108, v134
	v_fmac_f32_e32 v133, v109, v135
	v_add_f32_e32 v143, v113, v133
	s_waitcnt lgkmcnt(0)
	v_mul_f32_e32 v137, v104, v137
	ds_read_b128 v[132:135], v75 offset:544
	v_fmac_f32_e32 v137, v103, v136
	v_fmac_f32_e32 v137, v100, v138
	v_fmac_f32_e32 v137, v105, v139
	v_add_f32_e32 v143, v143, v137
	ds_read_b128 v[136:139], v75 offset:560
	s_waitcnt lgkmcnt(1)
	v_mul_f32_e32 v133, v95, v133
	v_fmac_f32_e32 v133, v72, v132
	v_fmac_f32_e32 v133, v96, v134
	v_fmac_f32_e32 v133, v101, v135
	v_add_f32_e32 v132, v143, v133
	s_waitcnt lgkmcnt(0)
	v_mul_f32_e32 v133, v97, v137
	v_fmac_f32_e32 v133, v73, v136
	v_fmac_f32_e32 v133, v99, v138
	v_fmac_f32_e32 v133, v98, v139
	v_add_f32_e32 v133, v132, v133
	v_mul_f32_e64 v132, |v133|, s3
	v_exp_f32_e32 v132, v132
	v_fmac_f32_e32 v142, 0x3377d1cf, v140
	v_fmac_f32_e32 v142, 0x3f317217, v140
	v_cmp_lt_f32_e64 s[16:17], |v140|, s46
	v_add_f32_e32 v132, 1.0, v132
	v_cndmask_b32_e32 v135, 0, v79, vcc
	v_cndmask_b32_e64 v134, v140, v142, s[16:17]
	v_cmp_gt_f32_e32 vcc, s44, v132
	v_sub_f32_e32 v134, v134, v135
	v_min_f32_e32 v133, 0, v133
	v_cndmask_b32_e64 v135, 0, 32, vcc
	v_ldexp_f32 v132, v132, v135
	v_log_f32_e32 v142, v132
	v_sub_f32_e32 v132, v141, v134
	ds_read_b128 v[134:137], v75 offset:576
	v_fmamk_f32 v132, v132, 0x3d800000, v131
	v_mul_f32_e32 v138, 0x3f317217, v142
	v_fma_f32 v143, v142, s45, -v138
	ds_read_b128 v[138:141], v75 offset:592
	s_waitcnt lgkmcnt(1)
	v_mul_f32_e32 v135, v110, v135
	v_fmac_f32_e32 v135, v107, v134
	v_fmac_f32_e32 v135, v108, v136
	v_fmac_f32_e32 v135, v109, v137
	v_add_f32_e32 v144, v113, v135
	s_waitcnt lgkmcnt(0)
	v_mul_f32_e32 v139, v104, v139
	ds_read_b128 v[134:137], v75 offset:608
	v_fmac_f32_e32 v139, v103, v138
	v_fmac_f32_e32 v139, v100, v140
	v_fmac_f32_e32 v139, v105, v141
	v_add_f32_e32 v144, v144, v139
	ds_read_b128 v[138:141], v75 offset:624
	s_waitcnt lgkmcnt(1)
	v_mul_f32_e32 v135, v95, v135
	v_fmac_f32_e32 v135, v72, v134
	v_fmac_f32_e32 v135, v96, v136
	v_fmac_f32_e32 v135, v101, v137
	v_add_f32_e32 v134, v144, v135
	s_waitcnt lgkmcnt(0)
	v_mul_f32_e32 v135, v97, v139
	v_fmac_f32_e32 v135, v73, v138
	v_fmac_f32_e32 v135, v99, v140
	v_fmac_f32_e32 v135, v98, v141
	v_add_f32_e32 v134, v134, v135
	v_mul_f32_e64 v135, |v134|, s3
	v_exp_f32_e32 v135, v135
	v_fmac_f32_e32 v143, 0x3377d1cf, v142
	v_fmac_f32_e32 v143, 0x3f317217, v142
	v_cmp_lt_f32_e64 s[16:17], |v142|, s46
	v_add_f32_e32 v135, 1.0, v135
	v_cndmask_b32_e32 v137, 0, v79, vcc
	v_cndmask_b32_e64 v136, v142, v143, s[16:17]
	v_cmp_gt_f32_e32 vcc, s44, v135
	v_sub_f32_e32 v136, v136, v137
	v_sub_f32_e32 v133, v133, v136
	v_cndmask_b32_e64 v137, 0, 32, vcc
	v_ldexp_f32 v135, v135, v137
	v_log_f32_e32 v142, v135
	v_min_f32_e32 v143, 0, v134
	ds_read_b128 v[134:137], v75 offset:640
	v_fmamk_f32 v133, v133, 0x3d800000, v132
	v_mul_f32_e32 v138, 0x3f317217, v142
	v_fma_f32 v144, v142, s45, -v138
	ds_read_b128 v[138:141], v75 offset:656
	s_waitcnt lgkmcnt(1)
	v_mul_f32_e32 v135, v110, v135
	v_fmac_f32_e32 v135, v107, v134
	v_fmac_f32_e32 v135, v108, v136
	v_fmac_f32_e32 v135, v109, v137
	v_add_f32_e32 v145, v113, v135
	s_waitcnt lgkmcnt(0)
	v_mul_f32_e32 v139, v104, v139
	ds_read_b128 v[134:137], v75 offset:672
	v_fmac_f32_e32 v139, v103, v138
	v_fmac_f32_e32 v139, v100, v140
	v_fmac_f32_e32 v139, v105, v141
	v_add_f32_e32 v145, v145, v139
	ds_read_b128 v[138:141], v75 offset:688
	s_waitcnt lgkmcnt(1)
	v_mul_f32_e32 v135, v95, v135
	v_fmac_f32_e32 v135, v72, v134
	v_fmac_f32_e32 v135, v96, v136
	v_fmac_f32_e32 v135, v101, v137
	v_add_f32_e32 v134, v145, v135
	s_waitcnt lgkmcnt(0)
	v_mul_f32_e32 v135, v97, v139
	v_fmac_f32_e32 v135, v73, v138
	v_fmac_f32_e32 v135, v99, v140
	v_fmac_f32_e32 v135, v98, v141
	v_add_f32_e32 v135, v134, v135
	v_mul_f32_e64 v134, |v135|, s3
	v_exp_f32_e32 v134, v134
	v_fmac_f32_e32 v144, 0x3377d1cf, v142
	v_fmac_f32_e32 v144, 0x3f317217, v142
	v_cmp_lt_f32_e64 s[16:17], |v142|, s46
	v_add_f32_e32 v134, 1.0, v134
	v_cndmask_b32_e32 v137, 0, v79, vcc
	v_cndmask_b32_e64 v136, v142, v144, s[16:17]
	v_cmp_gt_f32_e32 vcc, s44, v134
	v_sub_f32_e32 v136, v136, v137
	v_min_f32_e32 v135, 0, v135
	v_cndmask_b32_e64 v137, 0, 32, vcc
	v_ldexp_f32 v134, v134, v137
	v_log_f32_e32 v144, v134
	v_sub_f32_e32 v134, v143, v136
	ds_read_b128 v[136:139], v75 offset:704
	v_fmamk_f32 v134, v134, 0x3d800000, v133
	v_mul_f32_e32 v140, 0x3f317217, v144
	v_fma_f32 v145, v144, s45, -v140
	ds_read_b128 v[140:143], v75 offset:720
	s_waitcnt lgkmcnt(1)
	v_mul_f32_e32 v137, v110, v137
	v_fmac_f32_e32 v137, v107, v136
	v_fmac_f32_e32 v137, v108, v138
	v_fmac_f32_e32 v137, v109, v139
	v_add_f32_e32 v146, v113, v137
	s_waitcnt lgkmcnt(0)
	v_mul_f32_e32 v141, v104, v141
	ds_read_b128 v[136:139], v75 offset:736
	v_fmac_f32_e32 v141, v103, v140
	v_fmac_f32_e32 v141, v100, v142
	v_fmac_f32_e32 v141, v105, v143
	v_add_f32_e32 v146, v146, v141
	ds_read_b128 v[140:143], v75 offset:752
	s_waitcnt lgkmcnt(1)
	v_mul_f32_e32 v137, v95, v137
	v_fmac_f32_e32 v137, v72, v136
	v_fmac_f32_e32 v137, v96, v138
	v_fmac_f32_e32 v137, v101, v139
	v_add_f32_e32 v136, v146, v137
	s_waitcnt lgkmcnt(0)
	v_mul_f32_e32 v137, v97, v141
	v_fmac_f32_e32 v137, v73, v140
	v_fmac_f32_e32 v137, v99, v142
	v_fmac_f32_e32 v137, v98, v143
	v_add_f32_e32 v136, v136, v137
	v_mul_f32_e64 v137, |v136|, s3
	v_exp_f32_e32 v137, v137
	v_fmac_f32_e32 v145, 0x3377d1cf, v144
	v_fmac_f32_e32 v145, 0x3f317217, v144
	v_cmp_lt_f32_e64 s[16:17], |v144|, s46
	v_add_f32_e32 v137, 1.0, v137
	v_cndmask_b32_e32 v139, 0, v79, vcc
	v_cndmask_b32_e64 v138, v144, v145, s[16:17]
	v_cmp_gt_f32_e32 vcc, s44, v137
	v_sub_f32_e32 v138, v138, v139
	v_sub_f32_e32 v135, v135, v138
	v_cndmask_b32_e64 v139, 0, 32, vcc
	v_ldexp_f32 v137, v137, v139
	v_log_f32_e32 v144, v137
	v_min_f32_e32 v145, 0, v136
	ds_read_b128 v[136:139], v75 offset:768
	v_fmamk_f32 v135, v135, 0x3d800000, v134
	v_mul_f32_e32 v140, 0x3f317217, v144
	v_fma_f32 v146, v144, s45, -v140
	ds_read_b128 v[140:143], v75 offset:784
	s_waitcnt lgkmcnt(1)
	v_mul_f32_e32 v137, v110, v137
	v_fmac_f32_e32 v137, v107, v136
	v_fmac_f32_e32 v137, v108, v138
	v_fmac_f32_e32 v137, v109, v139
	v_add_f32_e32 v147, v113, v137
	s_waitcnt lgkmcnt(0)
	v_mul_f32_e32 v141, v104, v141
	ds_read_b128 v[136:139], v75 offset:800
	v_fmac_f32_e32 v141, v103, v140
	v_fmac_f32_e32 v141, v100, v142
	v_fmac_f32_e32 v141, v105, v143
	v_add_f32_e32 v147, v147, v141
	ds_read_b128 v[140:143], v75 offset:816
	s_waitcnt lgkmcnt(1)
	v_mul_f32_e32 v137, v95, v137
	v_fmac_f32_e32 v137, v72, v136
	v_fmac_f32_e32 v137, v96, v138
	v_fmac_f32_e32 v137, v101, v139
	v_add_f32_e32 v136, v147, v137
	s_waitcnt lgkmcnt(0)
	v_mul_f32_e32 v137, v97, v141
	v_fmac_f32_e32 v137, v73, v140
	v_fmac_f32_e32 v137, v99, v142
	v_fmac_f32_e32 v137, v98, v143
	v_add_f32_e32 v136, v136, v137
	v_mul_f32_e64 v137, |v136|, s3
	v_exp_f32_e32 v137, v137
	v_fmac_f32_e32 v146, 0x3377d1cf, v144
	v_fmac_f32_e32 v146, 0x3f317217, v144
	v_cmp_lt_f32_e64 s[16:17], |v144|, s46
	v_add_f32_e32 v137, 1.0, v137
	v_cndmask_b32_e32 v139, 0, v79, vcc
	v_cndmask_b32_e64 v138, v144, v146, s[16:17]
	v_cmp_gt_f32_e32 vcc, s44, v137
	v_sub_f32_e32 v138, v138, v139
	v_min_f32_e32 v146, 0, v136
	v_cndmask_b32_e64 v139, 0, 32, vcc
	v_ldexp_f32 v137, v137, v139
	v_log_f32_e32 v144, v137
	v_sub_f32_e32 v137, v145, v138
	v_fmamk_f32 v145, v137, 0x3d800000, v135
	ds_read_b128 v[136:139], v75 offset:832
	v_mul_f32_e32 v140, 0x3f317217, v144
	v_fma_f32 v147, v144, s45, -v140
	ds_read_b128 v[140:143], v75 offset:848
	v_fmac_f32_e32 v147, 0x3377d1cf, v144
	s_waitcnt lgkmcnt(1)
	v_mul_f32_e32 v137, v110, v137
	v_fmac_f32_e32 v137, v107, v136
	v_fmac_f32_e32 v137, v108, v138
	v_fmac_f32_e32 v137, v109, v139
	v_add_f32_e32 v148, v113, v137
	s_waitcnt lgkmcnt(0)
	v_mul_f32_e32 v141, v104, v141
	ds_read_b128 v[136:139], v75 offset:864
	v_fmac_f32_e32 v141, v103, v140
	v_fmac_f32_e32 v141, v100, v142
	v_fmac_f32_e32 v141, v105, v143
	v_add_f32_e32 v148, v148, v141
	ds_read_b128 v[140:143], v75 offset:880
	s_waitcnt lgkmcnt(1)
	v_mul_f32_e32 v137, v95, v137
	v_fmac_f32_e32 v137, v72, v136
	v_fmac_f32_e32 v137, v96, v138
	v_fmac_f32_e32 v137, v101, v139
	v_add_f32_e32 v136, v148, v137
	s_waitcnt lgkmcnt(0)
	v_mul_f32_e32 v137, v97, v141
	v_fmac_f32_e32 v137, v73, v140
	v_fmac_f32_e32 v137, v99, v142
	v_fmac_f32_e32 v137, v98, v143
	v_add_f32_e32 v136, v136, v137
	v_mul_f32_e64 v137, |v136|, s3
	v_exp_f32_e32 v137, v137
	v_fmac_f32_e32 v147, 0x3f317217, v144
	v_cmp_lt_f32_e64 s[16:17], |v144|, s46
	v_cndmask_b32_e32 v139, 0, v79, vcc
	v_add_f32_e32 v137, 1.0, v137
	v_cndmask_b32_e64 v138, v144, v147, s[16:17]
	v_cmp_gt_f32_e32 vcc, s44, v137
	v_sub_f32_e32 v138, v138, v139
	v_min_f32_e32 v147, 0, v136
	v_cndmask_b32_e64 v139, 0, 32, vcc
	v_ldexp_f32 v137, v137, v139
	v_log_f32_e32 v144, v137
	v_sub_f32_e32 v137, v146, v138
	v_fmamk_f32 v146, v137, 0x3d800000, v145
	ds_read_b128 v[136:139], v75 offset:896
	v_mul_f32_e32 v140, 0x3f317217, v144
	v_fma_f32 v148, v144, s45, -v140
	ds_read_b128 v[140:143], v75 offset:912
	v_fmac_f32_e32 v148, 0x3377d1cf, v144
	s_waitcnt lgkmcnt(1)
	v_mul_f32_e32 v137, v110, v137
	v_fmac_f32_e32 v137, v107, v136
	v_fmac_f32_e32 v137, v108, v138
	v_fmac_f32_e32 v137, v109, v139
	v_add_f32_e32 v149, v113, v137
	s_waitcnt lgkmcnt(0)
	v_mul_f32_e32 v141, v104, v141
	ds_read_b128 v[136:139], v75 offset:928
	v_fmac_f32_e32 v141, v103, v140
	v_fmac_f32_e32 v141, v100, v142
	v_fmac_f32_e32 v141, v105, v143
	v_add_f32_e32 v149, v149, v141
	ds_read_b128 v[140:143], v75 offset:944
	s_waitcnt lgkmcnt(1)
	v_mul_f32_e32 v137, v95, v137
	v_fmac_f32_e32 v137, v72, v136
	v_fmac_f32_e32 v137, v96, v138
	v_fmac_f32_e32 v137, v101, v139
	v_add_f32_e32 v136, v149, v137
	s_waitcnt lgkmcnt(0)
	v_mul_f32_e32 v137, v97, v141
	v_fmac_f32_e32 v137, v73, v140
	v_fmac_f32_e32 v137, v99, v142
	v_fmac_f32_e32 v137, v98, v143
	v_add_f32_e32 v136, v136, v137
	v_mul_f32_e64 v137, |v136|, s3
	v_exp_f32_e32 v137, v137
	v_fmac_f32_e32 v148, 0x3f317217, v144
	v_cmp_lt_f32_e64 s[16:17], |v144|, s46
	v_cndmask_b32_e32 v139, 0, v79, vcc
	v_add_f32_e32 v137, 1.0, v137
	v_cndmask_b32_e64 v138, v144, v148, s[16:17]
	v_cmp_gt_f32_e32 vcc, s44, v137
	v_sub_f32_e32 v138, v138, v139
	v_min_f32_e32 v148, 0, v136
	v_cndmask_b32_e64 v139, 0, 32, vcc
	v_ldexp_f32 v137, v137, v139
	v_log_f32_e32 v144, v137
	v_sub_f32_e32 v137, v147, v138
	v_fmamk_f32 v147, v137, 0x3d800000, v146
	ds_read_b128 v[136:139], v75 offset:960
	v_mul_f32_e32 v140, 0x3f317217, v144
	v_fma_f32 v149, v144, s45, -v140
	ds_read_b128 v[140:143], v75 offset:976
	v_fmac_f32_e32 v149, 0x3377d1cf, v144
	s_waitcnt lgkmcnt(1)
	v_mul_f32_e32 v110, v110, v137
	v_fmac_f32_e32 v110, v107, v136
	v_fmac_f32_e32 v110, v108, v138
	v_fmac_f32_e32 v110, v109, v139
	ds_read_b128 v[136:139], v75 offset:992
	s_waitcnt lgkmcnt(1)
	v_mul_f32_e32 v104, v104, v141
	v_fmac_f32_e32 v104, v103, v140
	v_fmac_f32_e32 v104, v100, v142
	v_fmac_f32_e32 v104, v105, v143
	ds_read_b128 v[140:143], v75 offset:1008
	s_waitcnt lgkmcnt(1)
	v_mul_f32_e32 v95, v95, v137
	v_fmac_f32_e32 v95, v72, v136
	v_add_f32_e32 v107, v113, v110
	v_fmac_f32_e32 v95, v96, v138
	v_add_f32_e32 v100, v107, v104
	v_fmac_f32_e32 v95, v101, v139
	v_add_f32_e32 v72, v100, v95
	s_waitcnt lgkmcnt(0)
	v_mul_f32_e32 v95, v97, v141
	v_fmac_f32_e32 v95, v73, v140
	v_fmac_f32_e32 v95, v99, v142
	v_fmac_f32_e32 v95, v98, v143
	v_add_f32_e32 v72, v72, v95
	v_mul_f32_e64 v73, |v72|, s3
	v_exp_f32_e32 v73, v73
	v_fmac_f32_e32 v149, 0x3f317217, v144
	v_cmp_lt_f32_e64 s[16:17], |v144|, s46
	v_cndmask_b32_e32 v96, 0, v79, vcc
	v_add_f32_e32 v73, 1.0, v73
	v_cndmask_b32_e64 v95, v144, v149, s[16:17]
	v_cmp_gt_f32_e32 vcc, s44, v73
	v_sub_f32_e32 v95, v95, v96
	v_sub_f32_e32 v95, v148, v95
	v_cndmask_b32_e64 v96, 0, 32, vcc
	v_ldexp_f32 v73, v73, v96
	v_log_f32_e32 v73, v73
	v_fmamk_f32 v98, v95, 0x3d800000, v147
	v_min_f32_e32 v72, 0, v72
	v_lshlrev_b32_e32 v94, 16, v94
	v_mul_f32_e32 v95, 0x3f317217, v73
	v_fma_f32 v95, v73, s45, -v95
	v_fmac_f32_e32 v95, 0x3377d1cf, v73
	v_fmac_f32_e32 v95, 0x3f317217, v73
	v_cmp_lt_f32_e64 s[16:17], |v73|, s46
	v_ashrrev_i32_e32 v69, 31, v68
	v_lshlrev_b64 v[68:69], 10, v[68:69]
	v_cndmask_b32_e64 v73, v73, v95, s[16:17]
	v_cndmask_b32_e32 v95, 0, v79, vcc
	v_sub_f32_e32 v73, v73, v95
	v_sub_f32_e32 v72, v72, v73
	v_fmamk_f32 v99, v72, 0x3d800000, v98
	ds_write_b32 v76, v99 offset:4096
	s_waitcnt lgkmcnt(0)
	s_barrier
	ds_read2st64_b32 v[72:73], v77 offset0:16 offset1:18
	ds_read2st64_b32 v[96:97], v77 offset0:20 offset1:22
	s_add_u32 s16, s28, s24
	s_addc_u32 s17, s29, 0
	v_ashrrev_i32_e32 v65, 31, v64
	s_waitcnt lgkmcnt(1)
	v_add_f32_e32 v72, 0, v72
	v_cndmask_b32_e64 v95, v72, 0, s[8:9]
	v_add_f32_e32 v72, v72, v73
	v_add_f32_e32 v73, v73, v95
	v_cndmask_b32_e64 v73, v95, v73, s[10:11]
	s_waitcnt lgkmcnt(0)
	v_add_f32_e32 v95, v96, v73
	v_add_f32_e32 v72, v72, v96
	v_cndmask_b32_e64 v73, v73, v95, s[12:13]
	v_add_f32_e32 v72, v72, v97
	v_add_f32_e32 v95, v97, v73
	v_cndmask_b32_e64 v96, v73, v95, s[14:15]
	v_mul_f32_e32 v72, 0x3fb8aa3b, v72
	v_exp_f32_e32 v95, v72
	v_add_f32_e32 v72, v125, v96
	v_mul_f32_e32 v72, 0x3fb8aa3b, v72
	v_exp_f32_e32 v97, v72
	v_lshl_add_u64 v[72:73], s[16:17], 0, v[2:3]
	v_lshl_add_u64 v[68:69], v[72:73], 0, v[68:69]
	v_lshlrev_b64 v[64:65], 10, v[64:65]
	v_rcp_f32_e32 v105, v97
	v_mul_f32_e32 v94, v97, v94
	v_cvt_pk_bf16_f32 v94, v94, s0
	ds_write_b16 v178, v94
	v_mul_f32_e32 v94, v105, v124
	v_cvt_pk_bf16_f32 v94, v94, s0
	ds_write_b16 v178, v94 offset:256
	v_add_f32_e32 v71, v126, v96
	v_mul_f32_e32 v71, 0x3fb8aa3b, v71
	v_exp_f32_e32 v71, v71
	v_mul_f32_e32 v70, v95, v105
	v_mul_f32_e32 v70, v70, v124
	v_cvt_pk_bf16_f32 v70, v70, s0
	ds_write_b16 v178, v70 offset:512
	v_rcp_f32_e32 v69, v71
	v_lshlrev_b32_e32 v68, 16, v93
	v_mul_f32_e32 v68, v71, v68
	v_cvt_pk_bf16_f32 v68, v68, s0
	ds_write_b16 v178, v68 offset:768
	v_mul_f32_e32 v68, v69, v123
	v_cvt_pk_bf16_f32 v68, v68, s0
	ds_write_b16 v178, v68 offset:1024
	v_add_f32_e32 v67, v127, v96
	v_mul_f32_e32 v67, 0x3fb8aa3b, v67
	v_exp_f32_e32 v67, v67
	v_mul_f32_e32 v66, v95, v69
	v_mul_f32_e32 v66, v66, v123
	v_cvt_pk_bf16_f32 v66, v66, s0
	v_lshl_add_u64 v[64:65], v[72:73], 0, v[64:65]
	ds_write_b16 v178, v66 offset:1280
	v_rcp_f32_e32 v65, v67
	v_lshlrev_b32_e32 v64, 16, v92
	v_mul_f32_e32 v64, v67, v64
	v_cvt_pk_bf16_f32 v64, v64, s0
	ds_write_b16 v178, v64 offset:1536
	v_mul_f32_e32 v64, v65, v122
	v_cvt_pk_bf16_f32 v64, v64, s0
	ds_write_b16 v178, v64 offset:1792
	v_add_f32_e32 v63, v128, v96
	v_mul_f32_e32 v63, 0x3fb8aa3b, v63
	v_exp_f32_e32 v63, v63
	v_ashrrev_i32_e32 v61, 31, v60
	v_mul_f32_e32 v62, v95, v65
	v_mul_f32_e32 v62, v62, v122
	v_lshlrev_b64 v[60:61], 10, v[60:61]
	v_cvt_pk_bf16_f32 v62, v62, s0
	v_lshl_add_u64 v[60:61], v[72:73], 0, v[60:61]
	ds_write_b16 v178, v62 offset:2048
	v_rcp_f32_e32 v61, v63
	v_lshlrev_b32_e32 v60, 16, v90
	v_mul_f32_e32 v60, v63, v60
	v_cvt_pk_bf16_f32 v60, v60, s0
	ds_write_b16 v178, v60 offset:2304
	v_mul_f32_e32 v60, v61, v117
	v_cvt_pk_bf16_f32 v60, v60, s0
	ds_write_b16 v178, v60 offset:2560
	v_add_f32_e32 v59, v129, v96
	v_mul_f32_e32 v59, 0x3fb8aa3b, v59
	v_exp_f32_e32 v59, v59
	v_ashrrev_i32_e32 v57, 31, v56
	v_mul_f32_e32 v58, v95, v61
	v_mul_f32_e32 v58, v58, v117
	v_lshlrev_b64 v[56:57], 10, v[56:57]
	v_cvt_pk_bf16_f32 v58, v58, s0
	v_lshl_add_u64 v[56:57], v[72:73], 0, v[56:57]
	ds_write_b16 v178, v58 offset:2816
	v_rcp_f32_e32 v57, v59
	v_lshlrev_b32_e32 v56, 16, v91
	v_mul_f32_e32 v56, v59, v56
	v_lshlrev_b32_e32 v116, 16, v116
	v_cvt_pk_bf16_f32 v56, v56, s0
	ds_write_b16 v178, v56 offset:3072
	v_mul_f32_e32 v56, v57, v116
	v_cvt_pk_bf16_f32 v56, v56, s0
	ds_write_b16 v178, v56 offset:3328
	v_add_f32_e32 v55, v130, v96
	v_mul_f32_e32 v55, 0x3fb8aa3b, v55
	v_exp_f32_e32 v55, v55
	v_ashrrev_i32_e32 v53, 31, v52
	v_mul_f32_e32 v54, v95, v57
	v_mul_f32_e32 v54, v54, v116
	v_lshlrev_b64 v[52:53], 10, v[52:53]
	v_cvt_pk_bf16_f32 v54, v54, s0
	v_lshl_add_u64 v[52:53], v[72:73], 0, v[52:53]
	ds_write_b16 v178, v54 offset:3584
	v_rcp_f32_e32 v53, v55
	v_lshlrev_b32_e32 v52, 16, v89
	v_mul_f32_e32 v52, v55, v52
	v_cvt_pk_bf16_f32 v52, v52, s0
	ds_write_b16 v178, v52 offset:3840
	v_mul_f32_e32 v52, v53, v114
	v_cvt_pk_bf16_f32 v52, v52, s0
	ds_write_b16 v178, v52 offset:4096
	v_add_f32_e32 v51, v131, v96
	v_mul_f32_e32 v51, 0x3fb8aa3b, v51
	v_exp_f32_e32 v51, v51
	v_ashrrev_i32_e32 v49, 31, v48
	v_mul_f32_e32 v50, v95, v53
	v_mul_f32_e32 v50, v50, v114
	v_lshlrev_b64 v[48:49], 10, v[48:49]
	v_cvt_pk_bf16_f32 v50, v50, s0
	v_lshl_add_u64 v[48:49], v[72:73], 0, v[48:49]
	ds_write_b16 v178, v50 offset:4352
	v_rcp_f32_e32 v49, v51
	v_lshlrev_b32_e32 v48, 16, v88
	v_mul_f32_e32 v48, v51, v48
	v_cvt_pk_bf16_f32 v48, v48, s0
	ds_write_b16 v178, v48 offset:4608
	v_mul_f32_e32 v48, v49, v111
	v_cvt_pk_bf16_f32 v48, v48, s0
	ds_write_b16 v178, v48 offset:4864
	v_add_f32_e32 v47, v132, v96
	v_mul_f32_e32 v47, 0x3fb8aa3b, v47
	v_exp_f32_e32 v47, v47
	v_ashrrev_i32_e32 v45, 31, v44
	v_mul_f32_e32 v46, v95, v49
	v_mul_f32_e32 v46, v46, v111
	v_lshlrev_b64 v[44:45], 10, v[44:45]
	v_cvt_pk_bf16_f32 v46, v46, s0
	v_lshl_add_u64 v[44:45], v[72:73], 0, v[44:45]
	ds_write_b16 v178, v46 offset:5120
	v_rcp_f32_e32 v45, v47
	v_lshlrev_b32_e32 v44, 16, v86
	v_mul_f32_e32 v44, v47, v44
	v_cvt_pk_bf16_f32 v44, v44, s0
	ds_write_b16 v178, v44 offset:5376
	v_mul_f32_e32 v44, v45, v115
	v_cvt_pk_bf16_f32 v44, v44, s0
	ds_write_b16 v178, v44 offset:5632
	v_add_f32_e32 v43, v133, v96
	v_mul_f32_e32 v43, 0x3fb8aa3b, v43
	v_exp_f32_e32 v43, v43
	v_ashrrev_i32_e32 v41, 31, v40
	v_mul_f32_e32 v42, v95, v45
	v_mul_f32_e32 v42, v42, v115
	v_lshlrev_b64 v[40:41], 10, v[40:41]
	v_cvt_pk_bf16_f32 v42, v42, s0
	v_lshl_add_u64 v[40:41], v[72:73], 0, v[40:41]
	ds_write_b16 v178, v42 offset:5888
	v_rcp_f32_e32 v41, v43
	v_lshlrev_b32_e32 v40, 16, v87
	v_mul_f32_e32 v40, v43, v40
	v_lshlrev_b32_e32 v112, 16, v112
	v_cvt_pk_bf16_f32 v40, v40, s0
	ds_write_b16 v178, v40 offset:6144
	v_mul_f32_e32 v40, v41, v112
	v_cvt_pk_bf16_f32 v40, v40, s0
	ds_write_b16 v178, v40 offset:6400
	v_add_f32_e32 v39, v134, v96
	v_mul_f32_e32 v39, 0x3fb8aa3b, v39
	v_exp_f32_e32 v39, v39
	v_ashrrev_i32_e32 v37, 31, v36
	v_mul_f32_e32 v38, v95, v41
	v_mul_f32_e32 v38, v38, v112
	v_lshlrev_b64 v[36:37], 10, v[36:37]
	v_cvt_pk_bf16_f32 v38, v38, s0
	v_lshl_add_u64 v[36:37], v[72:73], 0, v[36:37]
	ds_write_b16 v178, v38 offset:6656
	v_rcp_f32_e32 v37, v39
	v_lshlrev_b32_e32 v36, 16, v85
	v_mul_f32_e32 v36, v39, v36
	v_cvt_pk_bf16_f32 v36, v36, s0
	ds_write_b16 v178, v36 offset:6912
	v_mul_f32_e32 v36, v37, v106
	v_cvt_pk_bf16_f32 v36, v36, s0
	ds_write_b16 v178, v36 offset:7168
	v_add_f32_e32 v35, v135, v96
	v_mul_f32_e32 v35, 0x3fb8aa3b, v35
	v_exp_f32_e32 v35, v35
	v_ashrrev_i32_e32 v33, 31, v32
	v_mul_f32_e32 v34, v95, v37
	v_mul_f32_e32 v34, v34, v106
	v_lshlrev_b64 v[32:33], 10, v[32:33]
	v_cvt_pk_bf16_f32 v34, v34, s0
	v_lshl_add_u64 v[32:33], v[72:73], 0, v[32:33]
	ds_write_b16 v178, v34 offset:7424
	v_rcp_f32_e32 v33, v35
	v_lshlrev_b32_e32 v32, 16, v84
	v_mul_f32_e32 v32, v35, v32
	v_cvt_pk_bf16_f32 v32, v32, s0
	ds_write_b16 v178, v32 offset:7680
	v_mul_f32_e32 v32, v33, v102
	v_cvt_pk_bf16_f32 v32, v32, s0
	ds_write_b16 v178, v32 offset:7936
	v_add_f32_e32 v31, v145, v96
	v_mul_f32_e32 v31, 0x3fb8aa3b, v31
	v_exp_f32_e32 v31, v31
	v_ashrrev_i32_e32 v29, 31, v28
	v_mul_f32_e32 v30, v95, v33
	v_mul_f32_e32 v30, v30, v102
	v_lshlrev_b64 v[28:29], 10, v[28:29]
	v_cvt_pk_bf16_f32 v30, v30, s0
	v_lshl_add_u64 v[28:29], v[72:73], 0, v[28:29]
	ds_write_b16 v178, v30 offset:8192
	v_rcp_f32_e32 v29, v31
	v_lshlrev_b32_e32 v28, 16, v82
	v_mul_f32_e32 v28, v31, v28
	v_cvt_pk_bf16_f32 v28, v28, s0
	ds_write_b16 v178, v28 offset:8448
	v_mul_f32_e32 v28, v29, v5
	v_cvt_pk_bf16_f32 v28, v28, s0
	ds_write_b16 v178, v28 offset:8704
	v_mul_f32_e32 v26, v95, v29
	v_mul_f32_e32 v5, v26, v5
	v_add_f32_e32 v26, v146, v96
	v_mul_f32_e32 v26, 0x3fb8aa3b, v26
	v_exp_f32_e32 v26, v26
	v_ashrrev_i32_e32 v25, 31, v24
	v_lshlrev_b64 v[24:25], 10, v[24:25]
	v_cvt_pk_bf16_f32 v5, v5, s0
	v_lshl_add_u64 v[24:25], v[72:73], 0, v[24:25]
	ds_write_b16 v178, v5 offset:8960
	v_rcp_f32_e32 v24, v26
	s_waitcnt vmcnt(43)
	v_lshlrev_b32_e32 v5, 16, v83
	v_mul_f32_e32 v5, v26, v5
	s_waitcnt vmcnt(42)
	v_lshlrev_b32_e32 v100, 16, v118
	v_cvt_pk_bf16_f32 v5, v5, s0
	ds_write_b16 v178, v5 offset:9216
	v_mul_f32_e32 v5, v24, v100
	v_cvt_pk_bf16_f32 v5, v5, s0
	ds_write_b16 v178, v5 offset:9472
	v_add_f32_e32 v22, v147, v96
	v_mul_f32_e32 v22, 0x3fb8aa3b, v22
	v_exp_f32_e32 v22, v22
	v_ashrrev_i32_e32 v21, 31, v20
	v_mul_f32_e32 v5, v95, v24
	v_mul_f32_e32 v5, v5, v100
	v_lshlrev_b64 v[20:21], 10, v[20:21]
	v_cvt_pk_bf16_f32 v5, v5, s0
	v_lshl_add_u64 v[20:21], v[72:73], 0, v[20:21]
	ds_write_b16 v178, v5 offset:9728
	v_rcp_f32_e32 v20, v22
	s_waitcnt vmcnt(44)
	v_lshlrev_b32_e32 v5, 16, v81
	v_mul_f32_e32 v5, v22, v5
	s_waitcnt vmcnt(43)
	v_lshlrev_b32_e32 v101, 16, v119
	v_cvt_pk_bf16_f32 v5, v5, s0
	ds_write_b16 v178, v5 offset:9984
	v_mul_f32_e32 v5, v20, v101
	v_cvt_pk_bf16_f32 v5, v5, s0
	ds_write_b16 v178, v5 offset:10240
	v_add_f32_e32 v18, v98, v96
	v_mul_f32_e32 v18, 0x3fb8aa3b, v18
	v_exp_f32_e32 v18, v18
	v_ashrrev_i32_e32 v17, 31, v16
	v_mul_f32_e32 v5, v95, v20
	v_mul_f32_e32 v5, v5, v101
	v_lshlrev_b64 v[16:17], 10, v[16:17]
	v_cvt_pk_bf16_f32 v5, v5, s0
	v_lshl_add_u64 v[16:17], v[72:73], 0, v[16:17]
	ds_write_b16 v178, v5 offset:10496
	v_rcp_f32_e32 v16, v18
	s_waitcnt vmcnt(45)
	v_lshlrev_b32_e32 v5, 16, v80
	v_mul_f32_e32 v5, v18, v5
	s_waitcnt vmcnt(44)
	v_lshlrev_b32_e32 v103, 16, v120
	v_cvt_pk_bf16_f32 v5, v5, s0
	ds_write_b16 v178, v5 offset:10752
	v_mul_f32_e32 v5, v16, v103
	v_cvt_pk_bf16_f32 v5, v5, s0
	ds_write_b16 v178, v5 offset:11008
	v_add_f32_e32 v14, v96, v99
	v_mul_f32_e32 v14, 0x3fb8aa3b, v14
	v_exp_f32_e32 v14, v14
	v_ashrrev_i32_e32 v13, 31, v12
	v_mul_f32_e32 v5, v95, v16
	v_mul_f32_e32 v5, v5, v103
	v_lshlrev_b64 v[12:13], 10, v[12:13]
	v_cvt_pk_bf16_f32 v5, v5, s0
	v_lshl_add_u64 v[12:13], v[72:73], 0, v[12:13]
	ds_write_b16 v178, v5 offset:11264
	s_waitcnt vmcnt(46)
	v_lshlrev_b32_e32 v5, 16, v7
	v_rcp_f32_e32 v7, v14
	v_mul_f32_e32 v5, v14, v5
	s_waitcnt vmcnt(45)
	v_lshlrev_b32_e32 v104, 16, v121
	v_cvt_pk_bf16_f32 v5, v5, s0
	ds_write_b16 v178, v5 offset:11520
	v_mul_f32_e32 v5, v7, v104
	v_cvt_pk_bf16_f32 v5, v5, s0
	v_ashrrev_i32_e32 v9, 31, v8
	ds_write_b16 v178, v5 offset:11776
	v_mul_f32_e32 v5, v95, v7
	v_mul_f32_e32 v5, v5, v104
	v_lshlrev_b64 v[8:9], 10, v[8:9]
	v_cvt_pk_bf16_f32 v5, v5, s0
	v_lshl_add_u64 v[8:9], v[72:73], 0, v[8:9]
	ds_write_b16 v178, v5 offset:12032
	s_waitcnt lgkmcnt(0)
	s_barrier
	v_mov_b64_e32 v[194:195], s[94:95]
	v_mov_b64_e32 v[196:197], s[96:97]
	s_mov_b32 s100, 0x5555556
	v_mov_b32_e32 v207, 0
	v_mov_b32_e32 v188, v192
	v_mul_hi_u32 v189, v188, s100
	v_mul_u32_u24_e32 v190, 48, v189
	v_sub_u32_e32 v190, v188, v190
	ds_read_b128 v[184:187], v177
	v_and_b32_e32 v202, 15, v190
	v_lshlrev_b32_e32 v202, 4, v202
	v_bfe_u32 v203, v190, 4, 1
	v_lshl_add_u32 v202, v203, 10, v202
	v_mad_u32_u24 v204, v189, s99, v202
	v_lshlrev_b32_e32 v205, 10, v189
	v_lshl_add_u32 v205, v190, 4, v205
	v_add_u32_e32 v205, 0xfffffe00, v205
	v_cmp_gt_u32_e32 vcc, 32, v190
	s_nop 1
	v_cndmask_b32_e32 v206, v205, v204, vcc
	v_cndmask_b32_e32 v200, v196, v194, vcc
	v_cndmask_b32_e32 v201, v197, v195, vcc
	v_lshl_add_u64 v[200:201], v[206:207], 0, v[200:201]
	s_waitcnt lgkmcnt(0)
	global_store_dwordx4 v[200:201], v[184:187], off sc1
	v_add_u32_e32 v188, 0x200, v192
	v_mul_hi_u32 v189, v188, s100
	v_mul_u32_u24_e32 v190, 48, v189
	v_sub_u32_e32 v190, v188, v190
	ds_read_b128 v[208:211], v177 offset:8192
	v_and_b32_e32 v202, 15, v190
	v_lshlrev_b32_e32 v202, 4, v202
	v_bfe_u32 v203, v190, 4, 1
	v_lshl_add_u32 v202, v203, 10, v202
	v_mad_u32_u24 v204, v189, s99, v202
	v_lshlrev_b32_e32 v205, 10, v189
	v_lshl_add_u32 v205, v190, 4, v205
	v_add_u32_e32 v205, 0xfffffe00, v205
	v_cmp_gt_u32_e32 vcc, 32, v190
	s_nop 1
	v_cndmask_b32_e32 v206, v205, v204, vcc
	v_cndmask_b32_e32 v200, v196, v194, vcc
	v_cndmask_b32_e32 v201, v197, v195, vcc
	v_lshl_add_u64 v[200:201], v[206:207], 0, v[200:201]
	s_waitcnt lgkmcnt(0)
	global_store_dwordx4 v[200:201], v[208:211], off sc1
	v_add_u32_e32 v188, 0x400, v192
	v_mul_hi_u32 v189, v188, s100
	v_mul_u32_u24_e32 v190, 48, v189
	v_sub_u32_e32 v190, v188, v190
	ds_read_b128 v[184:187], v177 offset:16384
	v_and_b32_e32 v202, 15, v190
	v_lshlrev_b32_e32 v202, 4, v202
	v_bfe_u32 v203, v190, 4, 1
	v_lshl_add_u32 v202, v203, 10, v202
	v_mad_u32_u24 v204, v189, s99, v202
	v_lshlrev_b32_e32 v205, 10, v189
	v_lshl_add_u32 v205, v190, 4, v205
	v_add_u32_e32 v205, 0xfffffe00, v205
	v_cmp_gt_u32_e32 vcc, 32, v190
	s_nop 1
	v_cndmask_b32_e32 v206, v205, v204, vcc
	v_cndmask_b32_e32 v200, v196, v194, vcc
	v_cndmask_b32_e32 v201, v197, v195, vcc
	v_lshl_add_u64 v[200:201], v[206:207], 0, v[200:201]
	s_waitcnt lgkmcnt(0)
	global_store_dwordx4 v[200:201], v[184:187], off sc1
	v_add_u32_e32 v188, 0x600, v192
	v_mul_hi_u32 v189, v188, s100
	v_mul_u32_u24_e32 v190, 48, v189
	v_sub_u32_e32 v190, v188, v190
	ds_read_b128 v[208:211], v177 offset:24576
	v_and_b32_e32 v202, 15, v190
	v_lshlrev_b32_e32 v202, 4, v202
	v_bfe_u32 v203, v190, 4, 1
	v_lshl_add_u32 v202, v203, 10, v202
	v_mad_u32_u24 v204, v189, s99, v202
	v_lshlrev_b32_e32 v205, 10, v189
	v_lshl_add_u32 v205, v190, 4, v205
	v_add_u32_e32 v205, 0xfffffe00, v205
	v_cmp_gt_u32_e32 vcc, 32, v190
	s_nop 1
	v_cndmask_b32_e32 v206, v205, v204, vcc
	v_cndmask_b32_e32 v200, v196, v194, vcc
	v_cndmask_b32_e32 v201, v197, v195, vcc
	v_lshl_add_u64 v[200:201], v[206:207], 0, v[200:201]
	s_waitcnt lgkmcnt(0)
	global_store_dwordx4 v[200:201], v[208:211], off sc1
	v_add_u32_e32 v188, 0x800, v192
	v_mul_hi_u32 v189, v188, s100
	v_mul_u32_u24_e32 v190, 48, v189
	v_sub_u32_e32 v190, v188, v190
	ds_read_b128 v[184:187], v177 offset:32768
	v_and_b32_e32 v202, 15, v190
	v_lshlrev_b32_e32 v202, 4, v202
	v_bfe_u32 v203, v190, 4, 1
	v_lshl_add_u32 v202, v203, 10, v202
	v_mad_u32_u24 v204, v189, s99, v202
	v_lshlrev_b32_e32 v205, 10, v189
	v_lshl_add_u32 v205, v190, 4, v205
	v_add_u32_e32 v205, 0xfffffe00, v205
	v_cmp_gt_u32_e32 vcc, 32, v190
	s_nop 1
	v_cndmask_b32_e32 v206, v205, v204, vcc
	v_cndmask_b32_e32 v200, v196, v194, vcc
	v_cndmask_b32_e32 v201, v197, v195, vcc
	v_lshl_add_u64 v[200:201], v[206:207], 0, v[200:201]
	s_waitcnt lgkmcnt(0)
	global_store_dwordx4 v[200:201], v[184:187], off sc1
	v_add_u32_e32 v188, 0xa00, v192
	v_mul_hi_u32 v189, v188, s100
	v_mul_u32_u24_e32 v190, 48, v189
	v_sub_u32_e32 v190, v188, v190
	ds_read_b128 v[208:211], v177 offset:40960
	v_and_b32_e32 v202, 15, v190
	v_lshlrev_b32_e32 v202, 4, v202
	v_bfe_u32 v203, v190, 4, 1
	v_lshl_add_u32 v202, v203, 10, v202
	v_mad_u32_u24 v204, v189, s99, v202
	v_lshlrev_b32_e32 v205, 10, v189
	v_lshl_add_u32 v205, v190, 4, v205
	v_add_u32_e32 v205, 0xfffffe00, v205
	v_cmp_gt_u32_e32 vcc, 32, v190
	s_nop 1
	v_cndmask_b32_e32 v206, v205, v204, vcc
	v_cndmask_b32_e32 v200, v196, v194, vcc
	v_cndmask_b32_e32 v201, v197, v195, vcc
	v_lshl_add_u64 v[200:201], v[206:207], 0, v[200:201]
	s_waitcnt lgkmcnt(0)
	global_store_dwordx4 v[200:201], v[208:211], off sc1
	s_and_saveexec_b64 s[16:17], s[8:9]
	s_cbranch_execz .LBB0_472
	s_lshl_b32 s24, s51, 6
	s_or_b32 s28, s24, s50
	s_ashr_i32 s29, s28, 31
	s_lshl_b64 s[28:29], s[28:29], 11
	s_add_u32 s24, s26, s28
	s_addc_u32 s27, s27, s29
	s_lshl_b32 s26, s49, 2
	s_add_u32 s26, s24, s26
	s_addc_u32 s27, s27, 0
	v_mov_b32_e32 v7, v3
	v_lshl_add_u64 v[8:9], s[26:27], 0, v[6:7]
	v_add_co_u32_e32 v8, vcc, 0x2000000, v8
	s_nop 1
	v_addc_co_u32_e32 v9, vcc, 0, v9, vcc
	global_store_dword v[8:9], v95, off
	s_branch .LBB0_472

.LBB0_745:
	v_mad_i64_i32 v[26:27], s[26:27], v30, s13, v[10:11]
	v_lshl_add_u64 v[24:25], v[26:27], 0, s[10:11]
	v_lshl_add_u64 v[32:33], v[26:27], 0, s[14:15]
	v_lshl_add_u64 v[40:41], v[24:25], 0, v[4:5]
	v_lshl_add_u64 v[42:43], v[24:25], 0, v[12:13]
	v_lshl_add_u64 v[44:45], v[24:25], 0, v[16:17]
	v_lshl_add_u64 v[28:29], v[24:25], 0, v[18:19]
	v_lshl_add_u64 v[26:27], v[32:33], 0, v[20:21]
	v_lshl_add_u64 v[24:25], v[32:33], 0, v[22:23]
	v_add_u32_e32 v30, s3, v30
	v_min_i32_e32 v178, s24, v30
	s_waitcnt vmcnt(6)
	v_mov_b64_e32 v[34:35], v[140:141]
	v_mov_b64_e32 v[36:37], v[142:143]
	v_mov_b64_e32 v[38:39], v[144:145]
	v_mov_b64_e32 v[46:47], v[146:147]
	v_mov_b64_e32 v[32:33], v[148:149]
	v_mov_b64_e32 v[48:49], v[150:151]
	v_mov_b64_e32 v[50:51], v[152:153]
	v_mov_b64_e32 v[52:53], v[154:155]
	v_mov_b64_e32 v[164:165], v[156:157]
	v_mov_b64_e32 v[166:167], v[158:159]
	v_mov_b64_e32 v[168:169], v[160:161]
	v_mov_b64_e32 v[170:171], v[162:163]
	v_mov_b64_e32 v[0:1], v[100:101]
	v_mov_b64_e32 v[2:3], v[102:103]
	v_mad_i64_i32 v[172:173], s[26:27], v178, s13, v[10:11]
	v_lshl_add_u64 v[174:175], v[172:173], 0, v[4:5]
	global_load_dwordx2 v[140:141], v[174:175], off offset:2048
	global_load_dwordx2 v[142:143], v[174:175], off offset:2560
	global_load_dwordx2 v[144:145], v[174:175], off offset:3072
	global_load_dwordx2 v[146:147], v[174:175], off offset:3584
	v_lshl_add_u64 v[176:177], v[172:173], 0, s[10:11]
	v_lshl_add_u64 v[174:175], v[176:177], 0, v[4:5]
	global_load_dwordx2 v[148:149], v[174:175], off
	v_lshl_add_u64 v[174:175], v[176:177], 0, v[12:13]
	global_load_dwordx2 v[150:151], v[174:175], off
	v_lshl_add_u64 v[174:175], v[176:177], 0, v[16:17]
	global_load_dwordx2 v[152:153], v[174:175], off
	v_lshl_add_u64 v[174:175], v[176:177], 0, v[18:19]
	global_load_dwordx2 v[154:155], v[174:175], off
	v_lshl_add_u64 v[176:177], v[172:173], 0, s[14:15]
	v_lshl_add_u64 v[174:175], v[176:177], 0, v[20:21]
	global_load_dwordx4 v[156:159], v[174:175], off
	v_lshl_add_u64 v[174:175], v[176:177], 0, v[22:23]
	global_load_dwordx4 v[160:163], v[174:175], off
	v_lshlrev_b32_e32 v54, 16, v35
	v_and_b32_e32 v55, 0xffff0000, v35
	v_lshlrev_b32_e32 v56, 16, v34
	v_and_b32_e32 v57, 0xffff0000, v34
	v_lshlrev_b32_e32 v34, 16, v37
	v_and_b32_e32 v35, 0xffff0000, v37
	v_lshlrev_b32_e32 v58, 16, v36
	v_and_b32_e32 v59, 0xffff0000, v36
	v_lshlrev_b32_e32 v36, 16, v39
	v_and_b32_e32 v37, 0xffff0000, v39
	v_lshlrev_b32_e32 v60, 16, v38
	v_and_b32_e32 v61, 0xffff0000, v38
	v_lshlrev_b32_e32 v62, 16, v47
	v_and_b32_e32 v63, 0xffff0000, v47
	v_lshlrev_b32_e32 v64, 16, v46
	v_and_b32_e32 v65, 0xffff0000, v46
	v_lshlrev_b32_e32 v38, 16, v33
	v_and_b32_e32 v39, 0xffff0000, v33
	v_pk_mul_f32 v[46:47], v[54:55], v[54:55]
	v_lshlrev_b32_e32 v66, 16, v32
	v_and_b32_e32 v67, 0xffff0000, v32
	v_pk_mul_f32 v[32:33], v[56:57], v[56:57]
	v_lshlrev_b32_e32 v68, 16, v49
	v_and_b32_e32 v69, 0xffff0000, v49
	v_pk_mul_f32 v[70:71], v[34:35], v[34:35]
	v_lshlrev_b32_e32 v72, 16, v48
	v_and_b32_e32 v73, 0xffff0000, v48
	v_pk_mul_f32 v[48:49], v[58:59], v[58:59]
	v_pk_mul_f32 v[80:81], v[62:63], v[62:63]
	v_pk_mul_f32 v[82:83], v[64:65], v[64:65]
	v_mul_f32_e32 v31, 0xbfb8aa3b, v66
	v_mul_f32_e32 v84, 0xbfb8aa3b, v67
	v_add_f32_e32 v46, v46, v47
	v_add_f32_e32 v32, v32, v33
	v_add_f32_e32 v70, v70, v71
	v_add_f32_e32 v48, v48, v49
	v_mul_f32_e32 v33, 0xbfb8aa3b, v38
	v_mul_f32_e32 v47, 0xbfb8aa3b, v39
	v_add_f32_e32 v80, v80, v81
	v_add_f32_e32 v81, v82, v83
	v_exp_f32_e32 v31, v31
	v_exp_f32_e32 v82, v84
	v_add_f32_e32 v32, v32, v46
	v_add_f32_e32 v48, v48, v70
	v_mul_f32_e32 v85, 0xbfb8aa3b, v72
	v_exp_f32_e32 v33, v33
	v_exp_f32_e32 v46, v47
	v_add_f32_dpp v32, v32, v32 quad_perm:[1,0,3,2] row_mask:0xf bank_mask:0xf bound_ctrl:1
	v_add_f32_dpp v48, v48, v48 quad_perm:[1,0,3,2] row_mask:0xf bank_mask:0xf bound_ctrl:1
	v_lshlrev_b32_e32 v74, 16, v51
	v_and_b32_e32 v75, 0xffff0000, v51
	v_pk_mul_f32 v[76:77], v[36:37], v[36:37]
	v_lshlrev_b32_e32 v78, 16, v50
	v_and_b32_e32 v79, 0xffff0000, v50
	v_pk_mul_f32 v[50:51], v[60:61], v[60:61]
	v_mul_f32_e32 v86, 0xbfb8aa3b, v73
	v_exp_f32_e32 v47, v85
	v_add_f32_dpp v32, v32, v32 quad_perm:[2,3,0,1] row_mask:0xf bank_mask:0xf bound_ctrl:1
	v_add_f32_dpp v48, v48, v48 quad_perm:[2,3,0,1] row_mask:0xf bank_mask:0xf bound_ctrl:1
	v_mul_f32_e32 v49, 0xbfb8aa3b, v68
	v_mul_f32_e32 v71, 0xbfb8aa3b, v69
	v_mul_f32_e32 v87, 0xbfb8aa3b, v78
	v_add_f32_e32 v76, v76, v77
	v_add_f32_e32 v50, v50, v51
	v_mul_f32_e32 v77, 0xbfb8aa3b, v75
	v_exp_f32_e32 v83, v86
	v_add_f32_dpp v32, v32, v32 row_half_mirror row_mask:0xf bank_mask:0xf bound_ctrl:1
	v_add_f32_dpp v48, v48, v48 row_half_mirror row_mask:0xf bank_mask:0xf bound_ctrl:1
	v_exp_f32_e32 v49, v49
	v_exp_f32_e32 v70, v71
	v_exp_f32_e32 v71, v87
	v_add_f32_e32 v50, v50, v76
	v_exp_f32_e32 v76, v77
	v_add_f32_e32 v77, v81, v80
	v_add_f32_e32 v31, 1.0, v31
	v_add_f32_e32 v80, 1.0, v82
	v_add_f32_dpp v81, v32, v32 row_mirror row_mask:0xf bank_mask:0xf bound_ctrl:1
	v_add_f32_dpp v87, v48, v48 row_mirror row_mask:0xf bank_mask:0xf bound_ctrl:1
	v_add_f32_e32 v82, 1.0, v33
	v_add_f32_e32 v85, 1.0, v46
	v_rcp_f32_e32 v32, v31
	v_rcp_f32_e32 v33, v80
	v_mov_b32_e32 v31, v81
	v_mov_b32_e32 v80, v87
	v_add_f32_e32 v86, 1.0, v47
	v_rcp_f32_e32 v46, v82
	v_rcp_f32_e32 v47, v85
	v_permlane16_swap_b32_e32 v81, v31
	v_permlane16_swap_b32_e32 v87, v80
	v_mul_f32_e32 v88, 0xbfb8aa3b, v79
	v_add_f32_e32 v83, 1.0, v83
	v_add_f32_e32 v81, v81, v31
	v_add_f32_e32 v80, v87, v80
	v_exp_f32_e32 v84, v88
	v_add_f32_e32 v88, 1.0, v49
	v_rcp_f32_e32 v49, v83
	v_mov_b32_e32 v83, v81
	v_mov_b32_e32 v82, v80
	s_nop 0
	v_permlane32_swap_b32_e32 v81, v83
	v_permlane32_swap_b32_e32 v80, v82
	v_pk_mul_f32 v[38:39], v[46:47], v[38:39]
	v_pk_add_f32 v[46:47], v[80:81], v[82:83]
	v_pk_mul_f32 v[32:33], v[32:33], v[66:67]
	v_pk_fma_f32 v[46:47], v[46:47], s[12:13], v[14:15] op_sel_hi:[1,0,0]
	v_mul_f32_e32 v51, 0xbfb8aa3b, v74
	v_mul_f32_e32 v31, 0x4b800000, v47
	v_cmp_gt_f32_e32 vcc, s17, v47
	v_exp_f32_e32 v51, v51
	v_add_f32_dpp v50, v50, v50 quad_perm:[1,0,3,2] row_mask:0xf bank_mask:0xf bound_ctrl:1
	v_cndmask_b32_e32 v31, v47, v31, vcc
	v_rsq_f32_e32 v31, v31
	v_add_f32_dpp v50, v50, v50 quad_perm:[2,3,0,1] row_mask:0xf bank_mask:0xf bound_ctrl:1
	v_add_f32_e32 v70, 1.0, v70
	v_rcp_f32_e32 v48, v86
	v_mul_f32_e32 v47, 0x45800000, v31
	v_cndmask_b32_e32 v66, v31, v47, vcc
	v_pk_mul_f32 v[56:57], v[66:67], v[56:57] op_sel_hi:[0,1]
	v_pk_mul_f32 v[54:55], v[66:67], v[54:55] op_sel_hi:[0,1]
	v_pk_mul_f32 v[0:1], v[0:1], v[56:57]
	v_pk_mul_f32 v[2:3], v[2:3], v[54:55]
	v_pk_mul_f32 v[0:1], v[32:33], v[0:1]
	v_pk_mul_f32 v[2:3], v[38:39], v[2:3]
	v_cvt_pk_bf16_f32 v0, v0, v1
	v_cvt_pk_bf16_f32 v1, v2, v3
	global_store_dwordx2 v[40:41], v[0:1], off
	v_mul_f32_e32 v31, 0x4b800000, v46
	v_cmp_gt_f32_e32 vcc, s17, v46
	v_add_f32_dpp v50, v50, v50 row_half_mirror row_mask:0xf bank_mask:0xf bound_ctrl:1
	v_add_f32_e32 v90, 1.0, v51
	v_cndmask_b32_e32 v31, v46, v31, vcc
	v_rsq_f32_e32 v31, v31
	v_add_f32_dpp v89, v50, v50 row_mirror row_mask:0xf bank_mask:0xf bound_ctrl:1
	v_rcp_f32_e32 v50, v88
	v_rcp_f32_e32 v51, v70
	v_mul_f32_e32 v46, 0x45800000, v31
	v_cndmask_b32_e32 v46, v31, v46, vcc
	v_pk_mul_f32 v[38:39], v[48:49], v[72:73]
	v_pk_mul_f32 v[48:49], v[46:47], v[58:59] op_sel_hi:[0,1]
	v_pk_mul_f32 v[34:35], v[46:47], v[34:35] op_sel_hi:[0,1]
	v_pk_mul_f32 v[40:41], v[50:51], v[68:69]
	v_add_f32_dpp v77, v77, v77 quad_perm:[1,0,3,2] row_mask:0xf bank_mask:0xf bound_ctrl:1
	v_add_f32_e32 v71, 1.0, v71
	v_add_f32_e32 v84, 1.0, v84
	v_add_f32_dpp v77, v77, v77 quad_perm:[2,3,0,1] row_mask:0xf bank_mask:0xf bound_ctrl:1
	v_rcp_f32_e32 v70, v71
	v_rcp_f32_e32 v71, v84
	v_add_f32_dpp v77, v77, v77 row_half_mirror row_mask:0xf bank_mask:0xf bound_ctrl:1
	v_mov_b32_e32 v84, v89
	s_nop 1
	v_permlane16_swap_b32_e32 v89, v84
	v_add_f32_dpp v92, v77, v77 row_mirror row_mask:0xf bank_mask:0xf bound_ctrl:1
	v_mov_b32_e32 v85, v92
	s_nop 1
	v_permlane16_swap_b32_e32 v92, v85
	v_add_f32_e32 v33, v89, v84
	v_add_f32_e32 v32, v92, v85
	v_add_f32_e32 v91, 1.0, v76
	v_rcp_f32_e32 v76, v90
	v_rcp_f32_e32 v77, v91
	v_pk_mul_f32 v[0:1], v[104:105], v[48:49]
	v_pk_mul_f32 v[2:3], v[106:107], v[34:35]
	v_pk_mul_f32 v[0:1], v[38:39], v[0:1]
	v_pk_mul_f32 v[2:3], v[40:41], v[2:3]
	v_cvt_pk_bf16_f32 v0, v0, v1
	v_cvt_pk_bf16_f32 v1, v2, v3
	global_store_dwordx2 v[42:43], v[0:1], off
	v_mov_b32_e32 v35, v33
	v_mov_b32_e32 v34, v32
	s_nop 0
	v_permlane32_swap_b32_e32 v33, v35
	v_permlane32_swap_b32_e32 v32, v34
	v_pk_add_f32 v[32:33], v[32:33], v[34:35]
	v_pk_mul_f32 v[38:39], v[70:71], v[78:79]
	v_pk_fma_f32 v[42:43], v[32:33], s[12:13], v[14:15] op_sel_hi:[1,0,0]
	v_pk_mul_f32 v[40:41], v[76:77], v[74:75]
	v_mul_f32_e32 v31, 0x4b800000, v43
	v_cmp_gt_f32_e32 vcc, s17, v43
	s_nop 1
	v_cndmask_b32_e32 v31, v43, v31, vcc
	v_rsq_f32_e32 v31, v31
	s_nop 0
	v_mul_f32_e32 v32, 0x45800000, v31
	v_cndmask_b32_e32 v32, v31, v32, vcc
	v_pk_mul_f32 v[34:35], v[32:33], v[60:61] op_sel_hi:[0,1]
	v_pk_mul_f32 v[32:33], v[32:33], v[36:37] op_sel_hi:[0,1]
	v_cmp_gt_f32_e32 vcc, s17, v42
	v_pk_mul_f32 v[0:1], v[108:109], v[34:35]
	v_pk_mul_f32 v[2:3], v[110:111], v[32:33]
	v_pk_mul_f32 v[0:1], v[38:39], v[0:1]
	v_pk_mul_f32 v[2:3], v[40:41], v[2:3]
	v_cvt_pk_bf16_f32 v0, v0, v1
	v_cvt_pk_bf16_f32 v1, v2, v3
	global_store_dwordx2 v[44:45], v[0:1], off
	v_mov_b64_e32 v[32:33], v[164:165]
	v_mov_b64_e32 v[34:35], v[166:167]
	v_mov_b64_e32 v[36:37], v[168:169]
	v_mov_b64_e32 v[38:39], v[170:171]
	v_lshlrev_b32_e32 v44, 16, v52
	v_and_b32_e32 v45, 0xffff0000, v52
	v_mul_f32_e32 v31, 0xbfb8aa3b, v44
	v_lshlrev_b32_e32 v40, 16, v53
	v_and_b32_e32 v41, 0xffff0000, v53
	v_exp_f32_e32 v31, v31
	v_lshlrev_b32_e32 v52, 16, v32
	v_and_b32_e32 v53, 0xffff0000, v32
	v_mul_f32_e32 v32, 0xbfb8aa3b, v45
	v_lshlrev_b32_e32 v48, 16, v34
	v_and_b32_e32 v49, 0xffff0000, v34
	v_lshlrev_b32_e32 v50, 16, v33
	v_and_b32_e32 v51, 0xffff0000, v33
	v_mul_f32_e32 v33, 0xbfb8aa3b, v40
	v_mul_f32_e32 v34, 0xbfb8aa3b, v41
	v_exp_f32_e32 v32, v32
	v_exp_f32_e32 v33, v33
	v_exp_f32_e32 v34, v34
	v_add_f32_e32 v31, 1.0, v31
	v_lshlrev_b32_e32 v46, 16, v35
	v_and_b32_e32 v47, 0xffff0000, v35
	v_add_f32_e32 v35, 1.0, v32
	v_rcp_f32_e32 v32, v31
	v_mul_f32_e32 v31, 0x4b800000, v42
	v_add_f32_e32 v43, 1.0, v33
	v_add_f32_e32 v54, 1.0, v34
	v_cndmask_b32_e32 v31, v42, v31, vcc
	v_rcp_f32_e32 v33, v35
	v_rcp_f32_e32 v34, v43
	v_rcp_f32_e32 v35, v54
	v_rsq_f32_e32 v31, v31
	v_pk_mul_f32 v[32:33], v[32:33], v[44:45]
	v_lshlrev_b32_e32 v44, 16, v36
	v_pk_mul_f32 v[34:35], v[34:35], v[40:41]
	v_mul_f32_e32 v40, 0x45800000, v31
	v_cndmask_b32_e32 v40, v31, v40, vcc
	v_pk_mul_f32 v[42:43], v[40:41], v[64:65] op_sel_hi:[0,1]
	v_pk_mul_f32 v[40:41], v[40:41], v[62:63] op_sel_hi:[0,1]
	v_pk_mul_f32 v[0:1], v[112:113], v[42:43]
	v_pk_mul_f32 v[2:3], v[114:115], v[40:41]
	v_pk_mul_f32 v[0:1], v[32:33], v[0:1]
	v_pk_mul_f32 v[2:3], v[34:35], v[2:3]
	v_cvt_pk_bf16_f32 v0, v0, v1
	v_cvt_pk_bf16_f32 v1, v2, v3
	global_store_dwordx2 v[28:29], v[0:1], off
	v_and_b32_e32 v45, 0xffff0000, v36
	v_lshlrev_b32_e32 v40, 16, v39
	v_and_b32_e32 v41, 0xffff0000, v39
	v_lshlrev_b32_e32 v42, 16, v38
	v_and_b32_e32 v43, 0xffff0000, v38
	v_lshlrev_b32_e32 v38, 16, v37
	v_and_b32_e32 v39, 0xffff0000, v37
	v_pk_mul_f32 v[56:57], v[52:53], v[52:53]
	v_pk_mul_f32 v[64:65], v[44:45], v[44:45]
	v_pk_mul_f32 v[54:55], v[50:51], v[50:51]
	v_pk_mul_f32 v[62:63], v[38:39], v[38:39]
	v_add_f32_e32 v31, v56, v57
	v_add_f32_e32 v56, v64, v65
	v_add_f32_e32 v31, v54, v31
	v_add_f32_e32 v54, v62, v56
	v_pk_mul_f32 v[36:37], v[48:49], v[48:49]
	v_pk_mul_f32 v[60:61], v[42:43], v[42:43]
	v_add_f32_e32 v31, v55, v31
	v_add_f32_e32 v54, v63, v54
	v_add_f32_e32 v31, v36, v31
	v_add_f32_e32 v36, v60, v54
	v_pk_mul_f32 v[28:29], v[46:47], v[46:47]
	v_pk_mul_f32 v[58:59], v[40:41], v[40:41]
	v_add_f32_e32 v31, v37, v31
	v_add_f32_e32 v36, v61, v36
	v_add_f32_e32 v28, v28, v31
	v_add_f32_e32 v31, v58, v36
	v_add_f32_e32 v28, v29, v28
	v_add_f32_e32 v29, v59, v31
	s_nop 0
	v_add_f32_dpp v28, v28, v28 quad_perm:[1,0,3,2] row_mask:0xf bank_mask:0xf bound_ctrl:1
	v_add_f32_dpp v29, v29, v29 quad_perm:[1,0,3,2] row_mask:0xf bank_mask:0xf bound_ctrl:1
	s_nop 0
	v_add_f32_dpp v28, v28, v28 quad_perm:[2,3,0,1] row_mask:0xf bank_mask:0xf bound_ctrl:1
	v_add_f32_dpp v29, v29, v29 quad_perm:[2,3,0,1] row_mask:0xf bank_mask:0xf bound_ctrl:1
	s_nop 0
	v_add_f32_dpp v28, v28, v28 row_half_mirror row_mask:0xf bank_mask:0xf bound_ctrl:1
	v_add_f32_dpp v29, v29, v29 row_half_mirror row_mask:0xf bank_mask:0xf bound_ctrl:1
	s_nop 0
	v_add_f32_dpp v28, v28, v28 row_mirror row_mask:0xf bank_mask:0xf bound_ctrl:1
	v_add_f32_dpp v31, v29, v29 row_mirror row_mask:0xf bank_mask:0xf bound_ctrl:1
	v_mov_b32_e32 v29, v28
	v_mov_b32_e32 v36, v31
	s_nop 0
	v_permlane16_swap_b32_e32 v28, v29
	v_permlane16_swap_b32_e32 v31, v36
	v_add_f32_e32 v29, v28, v29
	v_add_f32_e32 v28, v31, v36
	v_mov_b32_e32 v37, v29
	v_mov_b32_e32 v36, v28
	s_nop 0
	v_permlane32_swap_b32_e32 v29, v37
	v_permlane32_swap_b32_e32 v28, v36
	v_pk_add_f32 v[28:29], v[28:29], v[36:37]
	s_nop 0
	v_pk_fma_f32 v[36:37], v[28:29], s[16:17], v[14:15] op_sel_hi:[1,0,0]
	s_nop 0
	v_mul_f32_e32 v28, 0x4b800000, v37
	v_cmp_gt_f32_e32 vcc, s17, v37
	v_mul_f32_e32 v31, 0x4b800000, v36
	s_nop 0
	v_cndmask_b32_e32 v28, v37, v28, vcc
	v_rsq_f32_e32 v28, v28
	s_nop 0
	v_mul_f32_e32 v29, 0x45800000, v28
	v_cndmask_b32_e32 v28, v28, v29, vcc
	v_pk_mul_f32 v[52:53], v[28:29], v[52:53] op_sel_hi:[0,1]
	v_pk_mul_f32 v[50:51], v[28:29], v[50:51] op_sel_hi:[0,1]
	v_pk_mul_f32 v[48:49], v[28:29], v[48:49] op_sel_hi:[0,1]
	v_pk_mul_f32 v[28:29], v[28:29], v[46:47] op_sel_hi:[0,1]
	v_cmp_lt_i32_e32 vcc, s24, v30
	s_or_b64 s[8:9], vcc, s[8:9]
	v_cmp_gt_f32_e32 vcc, s17, v36
	v_pk_mul_f32 v[0:1], v[116:117], v[52:53]
	v_pk_mul_f32 v[2:3], v[118:119], v[50:51]
	v_pk_mul_f32 v[32:33], v[120:121], v[48:49]
	v_pk_mul_f32 v[28:29], v[122:123], v[28:29]
	v_cvt_pk_bf16_f32 v0, v0, v1
	v_cvt_pk_bf16_f32 v1, v2, v3
	v_cvt_pk_bf16_f32 v2, v32, v33
	v_cvt_pk_bf16_f32 v3, v28, v29
	global_store_dwordx4 v[26:27], v[0:3], off sc1
	v_cndmask_b32_e32 v31, v36, v31, vcc
	v_rsq_f32_e32 v31, v31
	s_nop 0
	v_mul_f32_e32 v32, 0x45800000, v31
	v_cndmask_b32_e32 v32, v31, v32, vcc
	v_pk_mul_f32 v[34:35], v[32:33], v[44:45] op_sel_hi:[0,1]
	v_pk_mul_f32 v[36:37], v[32:33], v[38:39] op_sel_hi:[0,1]
	v_pk_mul_f32 v[38:39], v[32:33], v[42:43] op_sel_hi:[0,1]
	v_pk_mul_f32 v[32:33], v[32:33], v[40:41] op_sel_hi:[0,1]
	v_pk_mul_f32 v[0:1], v[124:125], v[34:35]
	v_pk_mul_f32 v[2:3], v[126:127], v[36:37]
	v_pk_mul_f32 v[26:27], v[128:129], v[38:39]
	v_pk_mul_f32 v[28:29], v[130:131], v[32:33]
	v_cvt_pk_bf16_f32 v0, v0, v1
	v_cvt_pk_bf16_f32 v1, v2, v3
	v_cvt_pk_bf16_f32 v2, v26, v27
	v_cvt_pk_bf16_f32 v3, v28, v29
	global_store_dwordx4 v[24:25], v[0:3], off sc1
	s_andn2_b64 exec, exec, s[8:9]
	s_cbranch_execnz .LBB0_745

.LBB0_818:
	ds_read_b128 v[120:123], v244
	ds_read_b128 v[124:127], v244 offset:1024
	ds_read_b128 v[132:135], v244 offset:2048
	ds_read_b128 v[140:143], v244 offset:3072
	s_add_u32 s34, s10, 0xffea0080
	s_addc_u32 s35, s11, -1
	s_cmp_eq_u32 s65, 28
	s_cselect_b32 s37, s29, s35
	s_cselect_b32 s36, s28, s34
	s_cselect_b32 s35, s27, s64
	s_cselect_b32 s34, s58, s59
	v_lshl_add_u64 v[176:177], s[10:11], 0, v[202:203]
	s_add_i32 m0, s43, 0xc000
	ds_read_b128 v[144:147], v245
	ds_read_b128 v[148:151], v245 offset:1024
	ds_read_b128 v[152:155], v245 offset:2048
	ds_read_b128 v[156:159], v245 offset:3072
	ds_read_b128 v[160:163], v245 offset:4096
	ds_read_b128 v[164:167], v245 offset:5120
	ds_read_b128 v[168:171], v245 offset:6144
	ds_read_b128 v[172:175], v245 offset:7168
	global_load_lds_dwordx4 v[176:177], off
	v_lshl_add_u64 v[176:177], s[10:11], 0, v[204:205]
	s_add_i32 m0, s43, 0xe000
	s_nop 0
	global_load_lds_dwordx4 v[176:177], off
	s_waitcnt lgkmcnt(8)
	s_barrier
	s_waitcnt lgkmcnt(0)
	s_setprio 1
	s_waitcnt lgkmcnt(0)
	v_mfma_f32_16x16x32_bf16 v[136:139], v[120:123], v[144:147], v[136:139]
	v_mfma_f32_16x16x32_bf16 v[128:131], v[132:135], v[144:147], v[128:131]
	v_mfma_f32_16x16x32_bf16 v[108:111], v[120:123], v[152:155], v[108:111]
	v_mfma_f32_16x16x32_bf16 v[104:107], v[132:135], v[152:155], v[104:107]
	v_mfma_f32_16x16x32_bf16 v[92:95], v[120:123], v[160:163], v[92:95]
	v_mfma_f32_16x16x32_bf16 v[88:91], v[132:135], v[160:163], v[88:91]
	v_mfma_f32_16x16x32_bf16 v[76:79], v[120:123], v[168:171], v[76:79]
	v_mfma_f32_16x16x32_bf16 v[72:75], v[132:135], v[168:171], v[72:75]
	v_mfma_f32_16x16x32_bf16 v[136:139], v[124:127], v[148:151], v[136:139]
	v_mfma_f32_16x16x32_bf16 v[128:131], v[140:143], v[148:151], v[128:131]
	v_mfma_f32_16x16x32_bf16 v[108:111], v[124:127], v[156:159], v[108:111]
	v_mfma_f32_16x16x32_bf16 v[104:107], v[140:143], v[156:159], v[104:107]
	v_mfma_f32_16x16x32_bf16 v[92:95], v[124:127], v[164:167], v[92:95]
	v_mfma_f32_16x16x32_bf16 v[88:91], v[140:143], v[164:167], v[88:91]
	v_mfma_f32_16x16x32_bf16 v[76:79], v[124:127], v[172:175], v[76:79]
	v_mfma_f32_16x16x32_bf16 v[72:75], v[140:143], v[172:175], v[72:75]
	s_setprio 0
	s_barrier
	s_add_i32 s66, s53, s42
	v_lshl_add_u64 v[206:207], s[34:35], 0, v[196:197]
	s_mov_b32 m0, s66
	ds_read_b128 v[176:179], v246
	ds_read_b128 v[180:183], v246 offset:1024
	ds_read_b128 v[184:187], v246 offset:2048
	ds_read_b128 v[188:191], v246 offset:3072
	global_load_lds_dwordx4 v[206:207], off
	v_lshl_add_u64 v[208:209], s[34:35], 0, v[200:201]
	s_add_i32 m0, s66, 0x2000
	s_nop 0
	global_load_lds_dwordx4 v[208:209], off
	s_barrier
	s_waitcnt lgkmcnt(0)
	s_setprio 1
	s_waitcnt lgkmcnt(0)
	v_mfma_f32_16x16x32_bf16 v[116:119], v[176:179], v[144:147], v[116:119]
	v_mfma_f32_16x16x32_bf16 v[112:115], v[184:187], v[144:147], v[112:115]
	v_mfma_f32_16x16x32_bf16 v[100:103], v[176:179], v[152:155], v[100:103]
	v_mfma_f32_16x16x32_bf16 v[96:99], v[184:187], v[152:155], v[96:99]
	v_mfma_f32_16x16x32_bf16 v[84:87], v[176:179], v[160:163], v[84:87]
	v_mfma_f32_16x16x32_bf16 v[80:83], v[184:187], v[160:163], v[80:83]
	v_mfma_f32_16x16x32_bf16 v[68:71], v[176:179], v[168:171], v[68:71]
	v_mfma_f32_16x16x32_bf16 v[64:67], v[184:187], v[168:171], v[64:67]
	v_mfma_f32_16x16x32_bf16 v[116:119], v[180:183], v[148:151], v[116:119]
	v_mfma_f32_16x16x32_bf16 v[112:115], v[188:191], v[148:151], v[112:115]
	v_mfma_f32_16x16x32_bf16 v[100:103], v[180:183], v[156:159], v[100:103]
	v_mfma_f32_16x16x32_bf16 v[96:99], v[188:191], v[156:159], v[96:99]
	v_mfma_f32_16x16x32_bf16 v[84:87], v[180:183], v[164:167], v[84:87]
	v_mfma_f32_16x16x32_bf16 v[80:83], v[188:191], v[164:167], v[80:83]
	v_mfma_f32_16x16x32_bf16 v[68:71], v[180:183], v[172:175], v[68:71]
	v_mfma_f32_16x16x32_bf16 v[64:67], v[188:191], v[172:175], v[64:67]
	s_setprio 0
	s_mov_b32 m0, s43
	v_lshl_add_u64 v[210:211], s[36:37], 0, v[194:195]
	s_barrier
	ds_read_b128 v[144:147], v245 offset:16384
	ds_read_b128 v[148:151], v245 offset:17408
	ds_read_b128 v[152:155], v245 offset:18432
	ds_read_b128 v[156:159], v245 offset:19456
	ds_read_b128 v[160:163], v245 offset:20480
	ds_read_b128 v[164:167], v245 offset:21504
	ds_read_b128 v[168:171], v245 offset:22528
	ds_read_b128 v[172:175], v245 offset:23552
	global_load_lds_dwordx4 v[210:211], off
	v_lshl_add_u64 v[212:213], s[36:37], 0, v[198:199]
	s_mov_b32 m0, s44
	s_nop 0
	global_load_lds_dwordx4 v[212:213], off
	s_barrier
	s_waitcnt lgkmcnt(0)
	s_setprio 1
	s_waitcnt lgkmcnt(0)
	v_mfma_f32_16x16x32_bf16 v[60:63], v[120:123], v[144:147], v[60:63]
	v_mfma_f32_16x16x32_bf16 v[56:59], v[132:135], v[144:147], v[56:59]
	v_mfma_f32_16x16x32_bf16 v[44:47], v[120:123], v[152:155], v[44:47]
	v_mfma_f32_16x16x32_bf16 v[40:43], v[132:135], v[152:155], v[40:43]
	v_mfma_f32_16x16x32_bf16 v[28:31], v[120:123], v[160:163], v[28:31]
	v_mfma_f32_16x16x32_bf16 v[24:27], v[132:135], v[160:163], v[24:27]
	v_mfma_f32_16x16x32_bf16 v[12:15], v[120:123], v[168:171], v[12:15]
	v_mfma_f32_16x16x32_bf16 v[8:11], v[132:135], v[168:171], v[8:11]
	v_mfma_f32_16x16x32_bf16 v[60:63], v[124:127], v[148:151], v[60:63]
	v_mfma_f32_16x16x32_bf16 v[56:59], v[140:143], v[148:151], v[56:59]
	v_mfma_f32_16x16x32_bf16 v[44:47], v[124:127], v[156:159], v[44:47]
	v_mfma_f32_16x16x32_bf16 v[40:43], v[140:143], v[156:159], v[40:43]
	v_mfma_f32_16x16x32_bf16 v[28:31], v[124:127], v[164:167], v[28:31]
	v_mfma_f32_16x16x32_bf16 v[24:27], v[140:143], v[164:167], v[24:27]
	v_mfma_f32_16x16x32_bf16 v[12:15], v[124:127], v[172:175], v[12:15]
	v_mfma_f32_16x16x32_bf16 v[8:11], v[140:143], v[172:175], v[8:11]
	s_setprio 0
	s_barrier
	s_add_u32 s66, s34, 0x80000
	s_addc_u32 s67, s35, 0
	s_add_i32 s68, s54, s42
	v_lshl_add_u64 v[120:121], s[66:67], 0, v[196:197]
	s_mov_b32 m0, s68
	s_nop 0
	global_load_lds_dwordx4 v[120:121], off
	v_lshl_add_u64 v[120:121], s[66:67], 0, v[200:201]
	s_add_i32 m0, s68, 0x2000
	s_nop 0
	global_load_lds_dwordx4 v[120:121], off
	s_waitcnt vmcnt(6)
	s_barrier
	s_setprio 1
	v_mfma_f32_16x16x32_bf16 v[52:55], v[176:179], v[144:147], v[52:55]
	v_mfma_f32_16x16x32_bf16 v[48:51], v[184:187], v[144:147], v[48:51]
	v_mfma_f32_16x16x32_bf16 v[36:39], v[176:179], v[152:155], v[36:39]
	v_mfma_f32_16x16x32_bf16 v[32:35], v[184:187], v[152:155], v[32:35]
	v_mfma_f32_16x16x32_bf16 v[20:23], v[176:179], v[160:163], v[20:23]
	v_mfma_f32_16x16x32_bf16 v[16:19], v[184:187], v[160:163], v[16:19]
	v_mfma_f32_16x16x32_bf16 v[4:7], v[176:179], v[168:171], v[4:7]
	v_mfma_f32_16x16x32_bf16 v[0:3], v[184:187], v[168:171], v[0:3]
	v_mfma_f32_16x16x32_bf16 v[52:55], v[180:183], v[148:151], v[52:55]
	v_mfma_f32_16x16x32_bf16 v[48:51], v[188:191], v[148:151], v[48:51]
	v_mfma_f32_16x16x32_bf16 v[36:39], v[180:183], v[156:159], v[36:39]
	v_mfma_f32_16x16x32_bf16 v[32:35], v[188:191], v[156:159], v[32:35]
	v_mfma_f32_16x16x32_bf16 v[20:23], v[180:183], v[164:167], v[20:23]
	v_mfma_f32_16x16x32_bf16 v[16:19], v[188:191], v[164:167], v[16:19]
	v_mfma_f32_16x16x32_bf16 v[4:7], v[180:183], v[172:175], v[4:7]
	v_mfma_f32_16x16x32_bf16 v[0:3], v[188:191], v[172:175], v[0:3]
	s_setprio 0
	s_add_i32 s66, 0, 0x18000
	v_add_u32_e32 v140, s66, v242
	s_barrier
	ds_read_b128 v[120:123], v140
	ds_read_b128 v[124:127], v140 offset:1024
	ds_read_b128 v[132:135], v140 offset:2048
	ds_read_b128 v[140:143], v140 offset:3072
	s_add_u32 s36, s36, 0x160000
	s_addc_u32 s37, s37, 0
	s_mov_b32 m0, s45
	v_lshl_add_u64 v[176:177], s[36:37], 0, v[194:195]
	ds_read_b128 v[144:147], v245 offset:32768
	ds_read_b128 v[148:151], v245 offset:33792
	ds_read_b128 v[152:155], v245 offset:34816
	ds_read_b128 v[156:159], v245 offset:35840
	ds_read_b128 v[160:163], v245 offset:36864
	ds_read_b128 v[164:167], v245 offset:37888
	ds_read_b128 v[168:171], v245 offset:38912
	ds_read_b128 v[172:175], v245 offset:39936
	global_load_lds_dwordx4 v[176:177], off
	v_lshl_add_u64 v[176:177], s[36:37], 0, v[198:199]
	s_mov_b32 m0, s46
	s_nop 0
	global_load_lds_dwordx4 v[176:177], off
	s_waitcnt lgkmcnt(8)
	s_barrier
	s_waitcnt lgkmcnt(0)
	s_setprio 1
	s_waitcnt lgkmcnt(0)
	v_mfma_f32_16x16x32_bf16 v[136:139], v[120:123], v[144:147], v[136:139]
	v_mfma_f32_16x16x32_bf16 v[128:131], v[132:135], v[144:147], v[128:131]
	v_mfma_f32_16x16x32_bf16 v[108:111], v[120:123], v[152:155], v[108:111]
	v_mfma_f32_16x16x32_bf16 v[104:107], v[132:135], v[152:155], v[104:107]
	v_mfma_f32_16x16x32_bf16 v[92:95], v[120:123], v[160:163], v[92:95]
	v_mfma_f32_16x16x32_bf16 v[88:91], v[132:135], v[160:163], v[88:91]
	v_mfma_f32_16x16x32_bf16 v[76:79], v[120:123], v[168:171], v[76:79]
	v_mfma_f32_16x16x32_bf16 v[72:75], v[132:135], v[168:171], v[72:75]
	v_mfma_f32_16x16x32_bf16 v[136:139], v[124:127], v[148:151], v[136:139]
	v_mfma_f32_16x16x32_bf16 v[128:131], v[140:143], v[148:151], v[128:131]
	v_mfma_f32_16x16x32_bf16 v[108:111], v[124:127], v[156:159], v[108:111]
	v_mfma_f32_16x16x32_bf16 v[104:107], v[140:143], v[156:159], v[104:107]
	v_mfma_f32_16x16x32_bf16 v[92:95], v[124:127], v[164:167], v[92:95]
	v_mfma_f32_16x16x32_bf16 v[88:91], v[140:143], v[164:167], v[88:91]
	v_mfma_f32_16x16x32_bf16 v[76:79], v[124:127], v[172:175], v[76:79]
	v_mfma_f32_16x16x32_bf16 v[72:75], v[140:143], v[172:175], v[72:75]
	s_setprio 0
	s_barrier
	s_add_i32 s36, 0, 0x1c000
	s_add_i32 s37, s66, s42
	v_add_u32_e32 v188, s36, v242
	v_lshl_add_u64 v[206:207], v[206:207], 0, s[24:25]
	s_mov_b32 m0, s37
	ds_read_b128 v[176:179], v188
	ds_read_b128 v[180:183], v188 offset:1024
	ds_read_b128 v[184:187], v188 offset:2048
	ds_read_b128 v[188:191], v188 offset:3072
	global_load_lds_dwordx4 v[206:207], off
	v_lshl_add_u64 v[206:207], v[208:209], 0, s[24:25]
	s_add_i32 m0, s37, 0x2000
	s_nop 0
	global_load_lds_dwordx4 v[206:207], off
	s_barrier
	s_waitcnt lgkmcnt(0)
	s_setprio 1
	s_waitcnt lgkmcnt(0)
	v_mfma_f32_16x16x32_bf16 v[116:119], v[176:179], v[144:147], v[116:119]
	v_mfma_f32_16x16x32_bf16 v[112:115], v[184:187], v[144:147], v[112:115]
	v_mfma_f32_16x16x32_bf16 v[100:103], v[176:179], v[152:155], v[100:103]
	v_mfma_f32_16x16x32_bf16 v[96:99], v[184:187], v[152:155], v[96:99]
	v_mfma_f32_16x16x32_bf16 v[84:87], v[176:179], v[160:163], v[84:87]
	v_mfma_f32_16x16x32_bf16 v[80:83], v[184:187], v[160:163], v[80:83]
	v_mfma_f32_16x16x32_bf16 v[68:71], v[176:179], v[168:171], v[68:71]
	v_mfma_f32_16x16x32_bf16 v[64:67], v[184:187], v[168:171], v[64:67]
	v_mfma_f32_16x16x32_bf16 v[116:119], v[180:183], v[148:151], v[116:119]
	v_mfma_f32_16x16x32_bf16 v[112:115], v[188:191], v[148:151], v[112:115]
	v_mfma_f32_16x16x32_bf16 v[100:103], v[180:183], v[156:159], v[100:103]
	v_mfma_f32_16x16x32_bf16 v[96:99], v[188:191], v[156:159], v[96:99]
	v_mfma_f32_16x16x32_bf16 v[84:87], v[180:183], v[164:167], v[84:87]
	v_mfma_f32_16x16x32_bf16 v[80:83], v[188:191], v[164:167], v[80:83]
	v_mfma_f32_16x16x32_bf16 v[68:71], v[180:183], v[172:175], v[68:71]
	v_mfma_f32_16x16x32_bf16 v[64:67], v[188:191], v[172:175], v[64:67]
	s_setprio 0
	s_mov_b32 m0, s48
	v_lshl_add_u64 v[206:207], v[210:211], 0, s[24:25]
	s_barrier
	ds_read_b128 v[144:147], v245 offset:49152
	ds_read_b128 v[148:151], v245 offset:50176
	ds_read_b128 v[152:155], v245 offset:51200
	ds_read_b128 v[156:159], v245 offset:52224
	ds_read_b128 v[160:163], v245 offset:53248
	ds_read_b128 v[164:167], v245 offset:54272
	ds_read_b128 v[168:171], v245 offset:55296
	ds_read_b128 v[172:175], v245 offset:56320
	global_load_lds_dwordx4 v[206:207], off
	v_lshl_add_u64 v[206:207], v[212:213], 0, s[24:25]
	s_mov_b32 m0, s49
	s_nop 0
	global_load_lds_dwordx4 v[206:207], off
	s_barrier
	s_waitcnt lgkmcnt(0)
	s_setprio 1
	s_waitcnt lgkmcnt(0)
	v_mfma_f32_16x16x32_bf16 v[60:63], v[120:123], v[144:147], v[60:63]
	v_mfma_f32_16x16x32_bf16 v[56:59], v[132:135], v[144:147], v[56:59]
	v_mfma_f32_16x16x32_bf16 v[44:47], v[120:123], v[152:155], v[44:47]
	v_mfma_f32_16x16x32_bf16 v[40:43], v[132:135], v[152:155], v[40:43]
	v_mfma_f32_16x16x32_bf16 v[28:31], v[120:123], v[160:163], v[28:31]
	v_mfma_f32_16x16x32_bf16 v[24:27], v[132:135], v[160:163], v[24:27]
	v_mfma_f32_16x16x32_bf16 v[12:15], v[120:123], v[168:171], v[12:15]
	v_mfma_f32_16x16x32_bf16 v[8:11], v[132:135], v[168:171], v[8:11]
	v_mfma_f32_16x16x32_bf16 v[60:63], v[124:127], v[148:151], v[60:63]
	v_mfma_f32_16x16x32_bf16 v[56:59], v[140:143], v[148:151], v[56:59]
	v_mfma_f32_16x16x32_bf16 v[44:47], v[124:127], v[156:159], v[44:47]
	v_mfma_f32_16x16x32_bf16 v[40:43], v[140:143], v[156:159], v[40:43]
	v_mfma_f32_16x16x32_bf16 v[28:31], v[124:127], v[164:167], v[28:31]
	v_mfma_f32_16x16x32_bf16 v[24:27], v[140:143], v[164:167], v[24:27]
	v_mfma_f32_16x16x32_bf16 v[12:15], v[124:127], v[172:175], v[12:15]
	v_mfma_f32_16x16x32_bf16 v[8:11], v[140:143], v[172:175], v[8:11]
	s_setprio 0
	s_barrier
	s_add_u32 s34, s34, 0x80080
	s_addc_u32 s35, s35, 0
	s_add_i32 s36, s36, s42
	v_lshl_add_u64 v[120:121], s[34:35], 0, v[196:197]
	s_mov_b32 m0, s36
	s_nop 0
	global_load_lds_dwordx4 v[120:121], off
	v_lshl_add_u64 v[120:121], s[34:35], 0, v[200:201]
	s_add_i32 m0, s36, 0x2000
	s_nop 0
	global_load_lds_dwordx4 v[120:121], off
	s_waitcnt vmcnt(6)
	s_barrier
	s_setprio 1
	v_mfma_f32_16x16x32_bf16 v[52:55], v[176:179], v[144:147], v[52:55]
	v_mfma_f32_16x16x32_bf16 v[48:51], v[184:187], v[144:147], v[48:51]
	v_mfma_f32_16x16x32_bf16 v[36:39], v[176:179], v[152:155], v[36:39]
	v_mfma_f32_16x16x32_bf16 v[32:35], v[184:187], v[152:155], v[32:35]
	v_mfma_f32_16x16x32_bf16 v[20:23], v[176:179], v[160:163], v[20:23]
	v_mfma_f32_16x16x32_bf16 v[16:19], v[184:187], v[160:163], v[16:19]
	v_mfma_f32_16x16x32_bf16 v[4:7], v[176:179], v[168:171], v[4:7]
	v_mfma_f32_16x16x32_bf16 v[0:3], v[184:187], v[168:171], v[0:3]
	v_mfma_f32_16x16x32_bf16 v[52:55], v[180:183], v[148:151], v[52:55]
	v_mfma_f32_16x16x32_bf16 v[48:51], v[188:191], v[148:151], v[48:51]
	v_mfma_f32_16x16x32_bf16 v[36:39], v[180:183], v[156:159], v[36:39]
	v_mfma_f32_16x16x32_bf16 v[32:35], v[188:191], v[156:159], v[32:35]
	v_mfma_f32_16x16x32_bf16 v[20:23], v[180:183], v[164:167], v[20:23]
	v_mfma_f32_16x16x32_bf16 v[16:19], v[188:191], v[164:167], v[16:19]
	v_mfma_f32_16x16x32_bf16 v[4:7], v[180:183], v[172:175], v[4:7]
	v_mfma_f32_16x16x32_bf16 v[0:3], v[188:191], v[172:175], v[0:3]
	s_setprio 0
	s_add_i32 s65, s65, 2
	s_add_u32 s10, s10, 0x100
	s_addc_u32 s11, s11, 0
	s_add_u32 s59, s59, 0x100
	s_addc_u32 s64, s64, 0
	s_cmp_gt_u32 s65, 29
	s_barrier
	s_cbranch_scc0 .LBB0_818
	v_lshl_or_b32 v206, s12, 8, v243
	v_lshl_add_u32 v236, s57, 8, v193
	v_ashrrev_i32_e32 v207, 31, v206
	v_lshlrev_b64 v[238:239], 1, v[206:207]
	v_ashrrev_i32_e32 v237, 31, v236
	v_lshl_add_u64 v[124:125], s[14:15], 0, v[238:239]
	v_lshlrev_b64 v[240:241], 11, v[236:237]
	v_lshl_add_u64 v[120:121], v[124:125], 0, v[240:241]
	global_load_dwordx4 v[188:191], v[120:121], off
	global_load_dwordx4 v[184:187], v[120:121], off offset:256
	v_or_b32_e32 v232, 16, v236
	v_ashrrev_i32_e32 v233, 31, v232
	v_or_b32_e32 v228, 32, v236
	v_lshlrev_b64 v[234:235], 11, v[232:233]
	v_ashrrev_i32_e32 v229, 31, v228
	v_or_b32_e32 v224, 48, v236
	v_lshl_add_u64 v[120:121], v[124:125], 0, v[234:235]
	v_lshlrev_b64 v[230:231], 11, v[228:229]
	v_ashrrev_i32_e32 v225, 31, v224
	v_add_u32_e32 v220, 0x80, v236
	global_load_dwordx4 v[180:183], v[120:121], off
	global_load_dwordx4 v[176:179], v[120:121], off offset:256
	v_lshl_add_u64 v[120:121], v[124:125], 0, v[230:231]
	v_lshlrev_b64 v[226:227], 11, v[224:225]
	v_ashrrev_i32_e32 v221, 31, v220
	v_add_u32_e32 v216, 0x90, v236
	global_load_dwordx4 v[172:175], v[120:121], off
	global_load_dwordx4 v[168:171], v[120:121], off offset:256
	v_lshl_add_u64 v[120:121], v[124:125], 0, v[226:227]
	v_lshlrev_b64 v[222:223], 11, v[220:221]
	v_ashrrev_i32_e32 v217, 31, v216
	v_add_u32_e32 v212, 0xa0, v236
	v_add_u32_e32 v208, 0xb0, v236
	global_load_dwordx4 v[164:167], v[120:121], off
	global_load_dwordx4 v[160:163], v[120:121], off offset:256
	v_lshl_add_u64 v[120:121], v[124:125], 0, v[222:223]
	v_lshlrev_b64 v[218:219], 11, v[216:217]
	v_ashrrev_i32_e32 v213, 31, v212
	v_ashrrev_i32_e32 v209, 31, v208
	global_load_dwordx4 v[156:159], v[120:121], off
	global_load_dwordx4 v[152:155], v[120:121], off offset:256
	v_lshl_add_u64 v[120:121], v[124:125], 0, v[218:219]
	v_lshlrev_b64 v[214:215], 11, v[212:213]
	v_lshlrev_b64 v[210:211], 11, v[208:209]
	global_load_dwordx4 v[148:151], v[120:121], off
	global_load_dwordx4 v[144:147], v[120:121], off offset:256
	v_lshl_add_u64 v[120:121], v[124:125], 0, v[214:215]
	v_lshl_add_u64 v[124:125], v[124:125], 0, v[210:211]
	global_load_dwordx4 v[132:135], v[120:121], off
	s_nop 0
	global_load_dwordx4 v[120:123], v[120:121], off offset:256
	s_nop 0
	global_load_dwordx4 v[140:143], v[124:125], off
	s_nop 0
	global_load_dwordx4 v[124:127], v[124:125], off offset:256
	v_and_b32_e32 v249, 64, v247
	v_xor_b32_e32 v248, 16, v247
	v_add_u32_e32 v249, 64, v249
	v_cmp_lt_i32_e32 vcc, v248, v249
	v_xor_b32_e32 v250, 32, v247
	s_lshl_b32 s10, s12, 2
	v_cndmask_b32_e32 v248, v247, v248, vcc
	v_cmp_lt_i32_e32 vcc, v250, v249
	v_lshlrev_b32_e32 v248, 2, v248
	s_ashr_i32 s11, s10, 31
	v_cndmask_b32_e32 v249, v247, v250, vcc
	v_lshlrev_b32_e32 v249, 2, v249
	s_waitcnt vmcnt(0)
	v_lshlrev_b32_e32 v250, 16, v188
	v_and_b32_e32 v251, 0xffff0000, v188
	v_lshlrev_b32_e32 v188, 16, v189
	v_and_b32_e32 v189, 0xffff0000, v189
	v_lshlrev_b32_e32 v252, 16, v190
	v_and_b32_e32 v253, 0xffff0000, v190
	v_lshlrev_b32_e32 v190, 16, v191
	v_and_b32_e32 v191, 0xffff0000, v191
	v_pk_add_f32 v[138:139], v[138:139], v[188:189]
	v_pk_add_f32 v[136:137], v[136:137], v[250:251]
	v_pk_add_f32 v[188:189], v[130:131], v[190:191]
	v_pk_add_f32 v[130:131], v[128:129], v[252:253]
	v_mul_f32_e32 v128, v137, v137
	v_mul_f32_e32 v129, v139, v139
	v_fmac_f32_e32 v128, v136, v136
	v_fmac_f32_e32 v129, v138, v138
	v_add_f32_e32 v128, v128, v129
	v_mul_f32_e32 v129, v131, v131
	v_mul_f32_e32 v190, v189, v189
	v_fmac_f32_e32 v129, v130, v130
	v_fmac_f32_e32 v190, v188, v188
	v_add_f32_e32 v129, v129, v190
	v_add_f32_e32 v190, v128, v129
	v_cvt_pk_bf16_f32 v128, v136, v137
	v_lshl_add_u64 v[136:137], s[14:15], 0, v[240:241]
	v_cvt_pk_bf16_f32 v129, v138, v139
	v_cvt_pk_bf16_f32 v130, v130, v131
	v_cvt_pk_bf16_f32 v131, v188, v189
	v_lshl_add_u64 v[136:137], v[136:137], 0, v[238:239]
	global_store_dwordx4 v[136:137], v[128:131], off sc1
	v_lshlrev_b32_e32 v138, 16, v186
	v_and_b32_e32 v139, 0xffff0000, v186
	v_lshlrev_b32_e32 v128, 16, v184
	v_and_b32_e32 v129, 0xffff0000, v184
	v_lshlrev_b32_e32 v130, 16, v185
	v_and_b32_e32 v131, 0xffff0000, v185
	v_lshlrev_b32_e32 v184, 16, v187
	v_and_b32_e32 v185, 0xffff0000, v187
	v_pk_add_f32 v[118:119], v[118:119], v[130:131]
	v_pk_add_f32 v[116:117], v[116:117], v[128:129]
	v_pk_add_f32 v[128:129], v[114:115], v[184:185]
	v_pk_add_f32 v[114:115], v[112:113], v[138:139]
	v_mul_f32_e32 v112, v117, v117
	v_mul_f32_e32 v113, v119, v119
	v_fmac_f32_e32 v112, v116, v116
	v_fmac_f32_e32 v113, v118, v118
	v_add_f32_e32 v112, v112, v113
	v_mul_f32_e32 v113, v115, v115
	v_mul_f32_e32 v130, v129, v129
	v_fmac_f32_e32 v113, v114, v114
	v_fmac_f32_e32 v130, v128, v128
	v_add_f32_e32 v113, v113, v130
	v_add_f32_e32 v112, v112, v113
	v_add_f32_e32 v130, v190, v112
	v_cvt_pk_bf16_f32 v112, v116, v117
	v_cvt_pk_bf16_f32 v113, v118, v119
	v_cvt_pk_bf16_f32 v114, v114, v115
	v_cvt_pk_bf16_f32 v115, v128, v129
	global_store_dwordx4 v[136:137], v[112:115], off offset:256 sc1
	ds_bpermute_b32 v112, v248, v130
	s_waitcnt lgkmcnt(0)
	v_add_f32_e32 v112, v130, v112
	ds_bpermute_b32 v113, v249, v112
	s_and_saveexec_b64 s[34:35], s[6:7]
	s_cbranch_execz .LBB0_821
	v_lshlrev_b64 v[114:115], 6, v[236:237]
	v_lshl_add_u64 v[114:115], s[16:17], 0, v[114:115]
	v_lshl_add_u64 v[114:115], s[10:11], 2, v[114:115]
	s_lshl_b32 s12, s47, 2
	v_lshl_add_u64 v[114:115], v[114:115], 0, s[12:13]
	s_waitcnt lgkmcnt(0)
	v_add_f32_e32 v112, v112, v113
	global_store_dword v[114:115], v112, off
.LBB0_821:
	s_or_b64 exec, exec, s[34:35]
	v_lshlrev_b32_e32 v112, 16, v180
	s_waitcnt lgkmcnt(0)
	v_and_b32_e32 v113, 0xffff0000, v180
	v_lshlrev_b32_e32 v114, 16, v181
	v_and_b32_e32 v115, 0xffff0000, v181
	v_lshlrev_b32_e32 v116, 16, v182
	v_and_b32_e32 v117, 0xffff0000, v182
	v_lshlrev_b32_e32 v118, 16, v183
	v_and_b32_e32 v119, 0xffff0000, v183
	v_pk_add_f32 v[110:111], v[110:111], v[114:115]
	v_pk_add_f32 v[108:109], v[108:109], v[112:113]
	v_pk_add_f32 v[112:113], v[106:107], v[118:119]
	v_pk_add_f32 v[106:107], v[104:105], v[116:117]
	v_mul_f32_e32 v104, v109, v109
	v_mul_f32_e32 v105, v111, v111
	v_fmac_f32_e32 v104, v108, v108
	v_fmac_f32_e32 v105, v110, v110
	v_add_f32_e32 v104, v104, v105
	v_mul_f32_e32 v105, v107, v107
	v_mul_f32_e32 v114, v113, v113
	v_fmac_f32_e32 v105, v106, v106
	v_fmac_f32_e32 v114, v112, v112
	v_add_f32_e32 v105, v105, v114
	v_add_f32_e32 v116, v104, v105
	v_cvt_pk_bf16_f32 v104, v108, v109
	v_cvt_pk_bf16_f32 v105, v110, v111
	v_lshlrev_b32_e32 v108, 16, v176
	v_and_b32_e32 v109, 0xffff0000, v176
	v_lshlrev_b32_e32 v110, 16, v177
	v_and_b32_e32 v111, 0xffff0000, v177
	v_cvt_pk_bf16_f32 v106, v106, v107
	v_cvt_pk_bf16_f32 v107, v112, v113
	v_lshlrev_b32_e32 v112, 16, v178
	v_and_b32_e32 v113, 0xffff0000, v178
	v_pk_add_f32 v[102:103], v[102:103], v[110:111]
	v_pk_add_f32 v[100:101], v[100:101], v[108:109]
	v_lshlrev_b32_e32 v114, 16, v179
	v_and_b32_e32 v115, 0xffff0000, v179
	v_pk_add_f32 v[110:111], v[96:97], v[112:113]
	v_mul_f32_e32 v96, v101, v101
	v_mul_f32_e32 v97, v103, v103
	v_pk_add_f32 v[108:109], v[98:99], v[114:115]
	v_fmac_f32_e32 v96, v100, v100
	v_fmac_f32_e32 v97, v102, v102
	v_add_f32_e32 v96, v96, v97
	v_mul_f32_e32 v97, v111, v111
	v_mul_f32_e32 v98, v109, v109
	v_fmac_f32_e32 v97, v110, v110
	v_fmac_f32_e32 v98, v108, v108
	v_add_f32_e32 v97, v97, v98
	v_add_f32_e32 v96, v96, v97
	v_add_f32_e32 v99, v116, v96
	ds_bpermute_b32 v114, v248, v99
	v_lshl_add_u64 v[96:97], s[14:15], 0, v[234:235]
	v_lshl_add_u64 v[112:113], v[206:207], 1, v[96:97]
	v_cvt_pk_bf16_f32 v98, v100, v101
	v_cvt_pk_bf16_f32 v100, v110, v111
	s_waitcnt lgkmcnt(0)
	v_add_f32_e32 v96, v99, v114
	ds_bpermute_b32 v97, v249, v96
	v_cvt_pk_bf16_f32 v99, v102, v103
	v_cvt_pk_bf16_f32 v101, v108, v109
	global_store_dwordx4 v[112:113], v[104:107], off sc1
	global_store_dwordx4 v[112:113], v[98:101], off offset:256 sc1
	s_and_saveexec_b64 s[34:35], s[6:7]
	s_cbranch_execz .LBB0_823
	v_lshlrev_b64 v[98:99], 6, v[232:233]
	v_lshl_add_u64 v[98:99], s[16:17], 0, v[98:99]
	v_lshl_add_u64 v[98:99], s[10:11], 2, v[98:99]
	s_lshl_b32 s12, s47, 2
	v_lshl_add_u64 v[98:99], v[98:99], 0, s[12:13]
	s_waitcnt lgkmcnt(0)
	v_add_f32_e32 v96, v96, v97
	global_store_dword v[98:99], v96, off
.LBB0_823:
	s_or_b64 exec, exec, s[34:35]
	v_lshlrev_b32_e32 v96, 16, v172
	s_waitcnt lgkmcnt(0)
	v_and_b32_e32 v97, 0xffff0000, v172
	v_lshlrev_b32_e32 v98, 16, v173
	v_and_b32_e32 v99, 0xffff0000, v173
	v_lshlrev_b32_e32 v100, 16, v174
	v_and_b32_e32 v101, 0xffff0000, v174
	v_lshlrev_b32_e32 v102, 16, v175
	v_and_b32_e32 v103, 0xffff0000, v175
	v_pk_add_f32 v[94:95], v[94:95], v[98:99]
	v_pk_add_f32 v[92:93], v[92:93], v[96:97]
	v_pk_add_f32 v[96:97], v[90:91], v[102:103]
	v_pk_add_f32 v[90:91], v[88:89], v[100:101]
	v_mul_f32_e32 v88, v93, v93
	v_mul_f32_e32 v89, v95, v95
	v_fmac_f32_e32 v88, v92, v92
	v_fmac_f32_e32 v89, v94, v94
	v_add_f32_e32 v88, v88, v89
	v_mul_f32_e32 v89, v91, v91
	v_mul_f32_e32 v98, v97, v97
	v_fmac_f32_e32 v89, v90, v90
	v_fmac_f32_e32 v98, v96, v96
	v_add_f32_e32 v89, v89, v98
	v_add_f32_e32 v100, v88, v89
	v_cvt_pk_bf16_f32 v88, v92, v93
	v_cvt_pk_bf16_f32 v89, v94, v95
	v_lshlrev_b32_e32 v92, 16, v168
	v_and_b32_e32 v93, 0xffff0000, v168
	v_lshlrev_b32_e32 v94, 16, v169
	v_and_b32_e32 v95, 0xffff0000, v169
	v_cvt_pk_bf16_f32 v90, v90, v91
	v_cvt_pk_bf16_f32 v91, v96, v97
	v_lshlrev_b32_e32 v96, 16, v170
	v_and_b32_e32 v97, 0xffff0000, v170
	v_pk_add_f32 v[86:87], v[86:87], v[94:95]
	v_pk_add_f32 v[84:85], v[84:85], v[92:93]
	v_lshlrev_b32_e32 v98, 16, v171
	v_and_b32_e32 v99, 0xffff0000, v171
	v_pk_add_f32 v[94:95], v[80:81], v[96:97]
	v_mul_f32_e32 v80, v85, v85
	v_mul_f32_e32 v81, v87, v87
	v_pk_add_f32 v[92:93], v[82:83], v[98:99]
	v_fmac_f32_e32 v80, v84, v84
	v_fmac_f32_e32 v81, v86, v86
	v_add_f32_e32 v80, v80, v81
	v_mul_f32_e32 v81, v95, v95
	v_mul_f32_e32 v82, v93, v93
	v_fmac_f32_e32 v81, v94, v94
	v_fmac_f32_e32 v82, v92, v92
	v_add_f32_e32 v81, v81, v82
	v_add_f32_e32 v80, v80, v81
	v_add_f32_e32 v83, v100, v80
	ds_bpermute_b32 v98, v248, v83
	v_lshl_add_u64 v[80:81], s[14:15], 0, v[230:231]
	v_lshl_add_u64 v[96:97], v[206:207], 1, v[80:81]
	v_cvt_pk_bf16_f32 v82, v84, v85
	v_cvt_pk_bf16_f32 v84, v94, v95
	s_waitcnt lgkmcnt(0)
	v_add_f32_e32 v80, v83, v98
	ds_bpermute_b32 v81, v249, v80
	v_cvt_pk_bf16_f32 v83, v86, v87
	v_cvt_pk_bf16_f32 v85, v92, v93
	global_store_dwordx4 v[96:97], v[88:91], off sc1
	global_store_dwordx4 v[96:97], v[82:85], off offset:256 sc1
	s_and_saveexec_b64 s[34:35], s[6:7]
	s_cbranch_execz .LBB0_825
	v_lshlrev_b64 v[82:83], 6, v[228:229]
	v_lshl_add_u64 v[82:83], s[16:17], 0, v[82:83]
	v_lshl_add_u64 v[82:83], s[10:11], 2, v[82:83]
	s_lshl_b32 s12, s47, 2
	v_lshl_add_u64 v[82:83], v[82:83], 0, s[12:13]
	s_waitcnt lgkmcnt(0)
	v_add_f32_e32 v80, v80, v81
	global_store_dword v[82:83], v80, off
.LBB0_825:
	s_or_b64 exec, exec, s[34:35]
	v_lshlrev_b32_e32 v80, 16, v164
	s_waitcnt lgkmcnt(0)
	v_and_b32_e32 v81, 0xffff0000, v164
	v_lshlrev_b32_e32 v82, 16, v165
	v_and_b32_e32 v83, 0xffff0000, v165
	v_lshlrev_b32_e32 v84, 16, v166
	v_and_b32_e32 v85, 0xffff0000, v166
	v_lshlrev_b32_e32 v86, 16, v167
	v_and_b32_e32 v87, 0xffff0000, v167
	v_pk_add_f32 v[78:79], v[78:79], v[82:83]
	v_pk_add_f32 v[76:77], v[76:77], v[80:81]
	v_pk_add_f32 v[80:81], v[74:75], v[86:87]
	v_pk_add_f32 v[74:75], v[72:73], v[84:85]
	v_mul_f32_e32 v72, v77, v77
	v_mul_f32_e32 v73, v79, v79
	v_fmac_f32_e32 v72, v76, v76
	v_fmac_f32_e32 v73, v78, v78
	v_add_f32_e32 v72, v72, v73
	v_mul_f32_e32 v73, v75, v75
	v_mul_f32_e32 v82, v81, v81
	v_fmac_f32_e32 v73, v74, v74
	v_fmac_f32_e32 v82, v80, v80
	v_add_f32_e32 v73, v73, v82
	v_add_f32_e32 v84, v72, v73
	v_cvt_pk_bf16_f32 v72, v76, v77
	v_cvt_pk_bf16_f32 v73, v78, v79
	v_lshlrev_b32_e32 v76, 16, v160
	v_and_b32_e32 v77, 0xffff0000, v160
	v_lshlrev_b32_e32 v78, 16, v161
	v_and_b32_e32 v79, 0xffff0000, v161
	v_cvt_pk_bf16_f32 v74, v74, v75
	v_cvt_pk_bf16_f32 v75, v80, v81
	v_lshlrev_b32_e32 v80, 16, v162
	v_and_b32_e32 v81, 0xffff0000, v162
	v_pk_add_f32 v[70:71], v[70:71], v[78:79]
	v_pk_add_f32 v[68:69], v[68:69], v[76:77]
	v_lshlrev_b32_e32 v82, 16, v163
	v_and_b32_e32 v83, 0xffff0000, v163
	v_pk_add_f32 v[78:79], v[64:65], v[80:81]
	v_mul_f32_e32 v64, v69, v69
	v_mul_f32_e32 v65, v71, v71
	v_pk_add_f32 v[76:77], v[66:67], v[82:83]
	v_fmac_f32_e32 v64, v68, v68
	v_fmac_f32_e32 v65, v70, v70
	v_add_f32_e32 v64, v64, v65
	v_mul_f32_e32 v65, v79, v79
	v_mul_f32_e32 v66, v77, v77
	v_fmac_f32_e32 v65, v78, v78
	v_fmac_f32_e32 v66, v76, v76
	v_add_f32_e32 v65, v65, v66
	v_add_f32_e32 v64, v64, v65
	v_add_f32_e32 v67, v84, v64
	ds_bpermute_b32 v82, v248, v67
	v_lshl_add_u64 v[64:65], s[14:15], 0, v[226:227]
	v_lshl_add_u64 v[80:81], v[206:207], 1, v[64:65]
	v_cvt_pk_bf16_f32 v66, v68, v69
	v_cvt_pk_bf16_f32 v68, v78, v79
	s_waitcnt lgkmcnt(0)
	v_add_f32_e32 v64, v67, v82
	ds_bpermute_b32 v65, v249, v64
	v_cvt_pk_bf16_f32 v67, v70, v71
	v_cvt_pk_bf16_f32 v69, v76, v77
	global_store_dwordx4 v[80:81], v[72:75], off sc1
	global_store_dwordx4 v[80:81], v[66:69], off offset:256 sc1
	s_and_saveexec_b64 s[34:35], s[6:7]
	s_cbranch_execz .LBB0_827
	v_lshlrev_b64 v[66:67], 6, v[224:225]
	v_lshl_add_u64 v[66:67], s[16:17], 0, v[66:67]
	v_lshl_add_u64 v[66:67], s[10:11], 2, v[66:67]
	s_lshl_b32 s12, s47, 2
	v_lshl_add_u64 v[66:67], v[66:67], 0, s[12:13]
	s_waitcnt lgkmcnt(0)
	v_add_f32_e32 v64, v64, v65
	global_store_dword v[66:67], v64, off
.LBB0_827:
	s_or_b64 exec, exec, s[34:35]
	v_lshlrev_b32_e32 v64, 16, v156
	s_waitcnt lgkmcnt(0)
	v_and_b32_e32 v65, 0xffff0000, v156
	v_lshlrev_b32_e32 v66, 16, v157
	v_and_b32_e32 v67, 0xffff0000, v157
	v_lshlrev_b32_e32 v68, 16, v158
	v_and_b32_e32 v69, 0xffff0000, v158
	v_lshlrev_b32_e32 v70, 16, v159
	v_and_b32_e32 v71, 0xffff0000, v159
	v_pk_add_f32 v[62:63], v[62:63], v[66:67]
	v_pk_add_f32 v[60:61], v[60:61], v[64:65]
	v_pk_add_f32 v[64:65], v[58:59], v[70:71]
	v_pk_add_f32 v[58:59], v[56:57], v[68:69]
	v_mul_f32_e32 v56, v61, v61
	v_mul_f32_e32 v57, v63, v63
	v_fmac_f32_e32 v56, v60, v60
	v_fmac_f32_e32 v57, v62, v62
	v_add_f32_e32 v56, v56, v57
	v_mul_f32_e32 v57, v59, v59
	v_mul_f32_e32 v66, v65, v65
	v_fmac_f32_e32 v57, v58, v58
	v_fmac_f32_e32 v66, v64, v64
	v_add_f32_e32 v57, v57, v66
	v_add_f32_e32 v68, v56, v57
	v_cvt_pk_bf16_f32 v56, v60, v61
	v_cvt_pk_bf16_f32 v57, v62, v63
	v_lshlrev_b32_e32 v60, 16, v152
	v_and_b32_e32 v61, 0xffff0000, v152
	v_lshlrev_b32_e32 v62, 16, v153
	v_and_b32_e32 v63, 0xffff0000, v153
	v_cvt_pk_bf16_f32 v58, v58, v59
	v_cvt_pk_bf16_f32 v59, v64, v65
	v_lshlrev_b32_e32 v64, 16, v154
	v_and_b32_e32 v65, 0xffff0000, v154
	v_pk_add_f32 v[54:55], v[54:55], v[62:63]
	v_pk_add_f32 v[52:53], v[52:53], v[60:61]
	v_lshlrev_b32_e32 v66, 16, v155
	v_and_b32_e32 v67, 0xffff0000, v155
	v_pk_add_f32 v[62:63], v[48:49], v[64:65]
	v_mul_f32_e32 v48, v53, v53
	v_mul_f32_e32 v49, v55, v55
	v_pk_add_f32 v[60:61], v[50:51], v[66:67]
	v_fmac_f32_e32 v48, v52, v52
	v_fmac_f32_e32 v49, v54, v54
	v_add_f32_e32 v48, v48, v49
	v_mul_f32_e32 v49, v63, v63
	v_mul_f32_e32 v50, v61, v61
	v_fmac_f32_e32 v49, v62, v62
	v_fmac_f32_e32 v50, v60, v60
	v_add_f32_e32 v49, v49, v50
	v_add_f32_e32 v48, v48, v49
	v_add_f32_e32 v51, v68, v48
	ds_bpermute_b32 v66, v248, v51
	v_lshl_add_u64 v[48:49], s[14:15], 0, v[222:223]
	v_lshl_add_u64 v[64:65], v[206:207], 1, v[48:49]
	v_cvt_pk_bf16_f32 v50, v52, v53
	v_cvt_pk_bf16_f32 v52, v62, v63
	s_waitcnt lgkmcnt(0)
	v_add_f32_e32 v48, v51, v66
	ds_bpermute_b32 v49, v249, v48
	v_cvt_pk_bf16_f32 v51, v54, v55
	v_cvt_pk_bf16_f32 v53, v60, v61
	global_store_dwordx4 v[64:65], v[56:59], off sc1
	global_store_dwordx4 v[64:65], v[50:53], off offset:256 sc1
	s_and_saveexec_b64 s[34:35], s[6:7]
	s_cbranch_execz .LBB0_829
	v_lshlrev_b64 v[50:51], 6, v[220:221]
	v_lshl_add_u64 v[50:51], s[16:17], 0, v[50:51]
	v_lshl_add_u64 v[50:51], s[10:11], 2, v[50:51]
	s_lshl_b32 s12, s47, 2
	v_lshl_add_u64 v[50:51], v[50:51], 0, s[12:13]
	s_waitcnt lgkmcnt(0)
	v_add_f32_e32 v48, v48, v49
	global_store_dword v[50:51], v48, off
.LBB0_829:
	s_or_b64 exec, exec, s[34:35]
	v_lshlrev_b32_e32 v48, 16, v148
	s_waitcnt lgkmcnt(0)
	v_and_b32_e32 v49, 0xffff0000, v148
	v_lshlrev_b32_e32 v50, 16, v149
	v_and_b32_e32 v51, 0xffff0000, v149
	v_lshlrev_b32_e32 v52, 16, v150
	v_and_b32_e32 v53, 0xffff0000, v150
	v_lshlrev_b32_e32 v54, 16, v151
	v_and_b32_e32 v55, 0xffff0000, v151
	v_pk_add_f32 v[46:47], v[46:47], v[50:51]
	v_pk_add_f32 v[44:45], v[44:45], v[48:49]
	v_pk_add_f32 v[48:49], v[42:43], v[54:55]
	v_pk_add_f32 v[42:43], v[40:41], v[52:53]
	v_mul_f32_e32 v40, v45, v45
	v_mul_f32_e32 v41, v47, v47
	v_fmac_f32_e32 v40, v44, v44
	v_fmac_f32_e32 v41, v46, v46
	v_add_f32_e32 v40, v40, v41
	v_mul_f32_e32 v41, v43, v43
	v_mul_f32_e32 v50, v49, v49
	v_fmac_f32_e32 v41, v42, v42
	v_fmac_f32_e32 v50, v48, v48
	v_add_f32_e32 v41, v41, v50
	v_add_f32_e32 v52, v40, v41
	v_cvt_pk_bf16_f32 v40, v44, v45
	v_cvt_pk_bf16_f32 v41, v46, v47
	v_lshlrev_b32_e32 v44, 16, v144
	v_and_b32_e32 v45, 0xffff0000, v144
	v_lshlrev_b32_e32 v46, 16, v145
	v_and_b32_e32 v47, 0xffff0000, v145
	v_cvt_pk_bf16_f32 v42, v42, v43
	v_cvt_pk_bf16_f32 v43, v48, v49
	v_lshlrev_b32_e32 v48, 16, v146
	v_and_b32_e32 v49, 0xffff0000, v146
	v_pk_add_f32 v[38:39], v[38:39], v[46:47]
	v_pk_add_f32 v[36:37], v[36:37], v[44:45]
	v_lshlrev_b32_e32 v50, 16, v147
	v_and_b32_e32 v51, 0xffff0000, v147
	v_pk_add_f32 v[46:47], v[32:33], v[48:49]
	v_mul_f32_e32 v32, v37, v37
	v_mul_f32_e32 v33, v39, v39
	v_pk_add_f32 v[44:45], v[34:35], v[50:51]
	v_fmac_f32_e32 v32, v36, v36
	v_fmac_f32_e32 v33, v38, v38
	v_add_f32_e32 v32, v32, v33
	v_mul_f32_e32 v33, v47, v47
	v_mul_f32_e32 v34, v45, v45
	v_fmac_f32_e32 v33, v46, v46
	v_fmac_f32_e32 v34, v44, v44
	v_add_f32_e32 v33, v33, v34
	v_add_f32_e32 v32, v32, v33
	v_add_f32_e32 v35, v52, v32
	ds_bpermute_b32 v50, v248, v35
	v_lshl_add_u64 v[32:33], s[14:15], 0, v[218:219]
	v_lshl_add_u64 v[48:49], v[206:207], 1, v[32:33]
	v_cvt_pk_bf16_f32 v34, v36, v37
	v_cvt_pk_bf16_f32 v36, v46, v47
	s_waitcnt lgkmcnt(0)
	v_add_f32_e32 v32, v35, v50
	ds_bpermute_b32 v33, v249, v32
	v_cvt_pk_bf16_f32 v35, v38, v39
	v_cvt_pk_bf16_f32 v37, v44, v45
	global_store_dwordx4 v[48:49], v[40:43], off sc1
	global_store_dwordx4 v[48:49], v[34:37], off offset:256 sc1
	s_and_saveexec_b64 s[34:35], s[6:7]
	s_cbranch_execz .LBB0_831
	v_lshlrev_b64 v[34:35], 6, v[216:217]
	v_lshl_add_u64 v[34:35], s[16:17], 0, v[34:35]
	v_lshl_add_u64 v[34:35], s[10:11], 2, v[34:35]
	s_lshl_b32 s12, s47, 2
	v_lshl_add_u64 v[34:35], v[34:35], 0, s[12:13]
	s_waitcnt lgkmcnt(0)
	v_add_f32_e32 v32, v32, v33
	global_store_dword v[34:35], v32, off
.LBB0_831:
	s_or_b64 exec, exec, s[34:35]
	v_lshlrev_b32_e32 v32, 16, v132
	s_waitcnt lgkmcnt(0)
	v_and_b32_e32 v33, 0xffff0000, v132
	v_lshlrev_b32_e32 v34, 16, v133
	v_and_b32_e32 v35, 0xffff0000, v133
	v_lshlrev_b32_e32 v36, 16, v134
	v_and_b32_e32 v37, 0xffff0000, v134
	v_lshlrev_b32_e32 v38, 16, v135
	v_and_b32_e32 v39, 0xffff0000, v135
	v_pk_add_f32 v[30:31], v[30:31], v[34:35]
	v_pk_add_f32 v[28:29], v[28:29], v[32:33]
	v_pk_add_f32 v[32:33], v[26:27], v[38:39]
	v_pk_add_f32 v[26:27], v[24:25], v[36:37]
	v_mul_f32_e32 v24, v29, v29
	v_mul_f32_e32 v25, v31, v31
	v_fmac_f32_e32 v24, v28, v28
	v_fmac_f32_e32 v25, v30, v30
	v_add_f32_e32 v24, v24, v25
	v_mul_f32_e32 v25, v27, v27
	v_mul_f32_e32 v34, v33, v33
	v_fmac_f32_e32 v25, v26, v26
	v_fmac_f32_e32 v34, v32, v32
	v_add_f32_e32 v25, v25, v34
	v_add_f32_e32 v36, v24, v25
	v_cvt_pk_bf16_f32 v24, v28, v29
	v_cvt_pk_bf16_f32 v25, v30, v31
	v_lshlrev_b32_e32 v28, 16, v120
	v_and_b32_e32 v29, 0xffff0000, v120
	v_lshlrev_b32_e32 v30, 16, v121
	v_and_b32_e32 v31, 0xffff0000, v121
	v_cvt_pk_bf16_f32 v26, v26, v27
	v_cvt_pk_bf16_f32 v27, v32, v33
	v_lshlrev_b32_e32 v32, 16, v122
	v_and_b32_e32 v33, 0xffff0000, v122
	v_pk_add_f32 v[22:23], v[22:23], v[30:31]
	v_pk_add_f32 v[20:21], v[20:21], v[28:29]
	v_lshlrev_b32_e32 v34, 16, v123
	v_and_b32_e32 v35, 0xffff0000, v123
	v_pk_add_f32 v[30:31], v[16:17], v[32:33]
	v_mul_f32_e32 v16, v21, v21
	v_mul_f32_e32 v17, v23, v23
	v_pk_add_f32 v[28:29], v[18:19], v[34:35]
	v_fmac_f32_e32 v16, v20, v20
	v_fmac_f32_e32 v17, v22, v22
	v_add_f32_e32 v16, v16, v17
	v_mul_f32_e32 v17, v31, v31
	v_mul_f32_e32 v18, v29, v29
	v_fmac_f32_e32 v17, v30, v30
	v_fmac_f32_e32 v18, v28, v28
	v_add_f32_e32 v17, v17, v18
	v_add_f32_e32 v16, v16, v17
	v_add_f32_e32 v19, v36, v16
	ds_bpermute_b32 v34, v248, v19
	v_lshl_add_u64 v[16:17], s[14:15], 0, v[214:215]
	v_lshl_add_u64 v[32:33], v[206:207], 1, v[16:17]
	v_cvt_pk_bf16_f32 v18, v20, v21
	v_cvt_pk_bf16_f32 v20, v30, v31
	s_waitcnt lgkmcnt(0)
	v_add_f32_e32 v16, v19, v34
	ds_bpermute_b32 v17, v249, v16
	v_cvt_pk_bf16_f32 v19, v22, v23
	v_cvt_pk_bf16_f32 v21, v28, v29
	global_store_dwordx4 v[32:33], v[24:27], off sc1
	global_store_dwordx4 v[32:33], v[18:21], off offset:256 sc1
	s_and_saveexec_b64 s[34:35], s[6:7]
	s_cbranch_execz .LBB0_833
	v_lshlrev_b64 v[18:19], 6, v[212:213]
	v_lshl_add_u64 v[18:19], s[16:17], 0, v[18:19]
	v_lshl_add_u64 v[18:19], s[10:11], 2, v[18:19]
	s_lshl_b32 s12, s47, 2
	v_lshl_add_u64 v[18:19], v[18:19], 0, s[12:13]
	s_waitcnt lgkmcnt(0)
	v_add_f32_e32 v16, v16, v17
	global_store_dword v[18:19], v16, off
.LBB0_833:
	s_or_b64 exec, exec, s[34:35]
	v_lshlrev_b32_e32 v16, 16, v140
	s_waitcnt lgkmcnt(0)
	v_and_b32_e32 v17, 0xffff0000, v140
	v_lshlrev_b32_e32 v18, 16, v141
	v_and_b32_e32 v19, 0xffff0000, v141
	v_lshlrev_b32_e32 v20, 16, v142
	v_and_b32_e32 v21, 0xffff0000, v142
	v_lshlrev_b32_e32 v22, 16, v143
	v_and_b32_e32 v23, 0xffff0000, v143
	v_pk_add_f32 v[14:15], v[14:15], v[18:19]
	v_pk_add_f32 v[12:13], v[12:13], v[16:17]
	v_pk_add_f32 v[16:17], v[10:11], v[22:23]
	v_pk_add_f32 v[10:11], v[8:9], v[20:21]
	v_mul_f32_e32 v8, v13, v13
	v_mul_f32_e32 v9, v15, v15
	v_fmac_f32_e32 v8, v12, v12
	v_fmac_f32_e32 v9, v14, v14
	v_add_f32_e32 v8, v8, v9
	v_mul_f32_e32 v9, v11, v11
	v_mul_f32_e32 v18, v17, v17
	v_fmac_f32_e32 v9, v10, v10
	v_fmac_f32_e32 v18, v16, v16
	v_add_f32_e32 v9, v9, v18
	v_add_f32_e32 v20, v8, v9
	v_cvt_pk_bf16_f32 v8, v12, v13
	v_cvt_pk_bf16_f32 v9, v14, v15
	v_lshlrev_b32_e32 v12, 16, v124
	v_and_b32_e32 v13, 0xffff0000, v124
	v_lshlrev_b32_e32 v14, 16, v125
	v_and_b32_e32 v15, 0xffff0000, v125
	v_cvt_pk_bf16_f32 v10, v10, v11
	v_cvt_pk_bf16_f32 v11, v16, v17
	v_lshlrev_b32_e32 v16, 16, v126
	v_and_b32_e32 v17, 0xffff0000, v126
	v_pk_add_f32 v[6:7], v[6:7], v[14:15]
	v_pk_add_f32 v[4:5], v[4:5], v[12:13]
	v_lshlrev_b32_e32 v18, 16, v127
	v_and_b32_e32 v19, 0xffff0000, v127
	v_pk_add_f32 v[14:15], v[0:1], v[16:17]
	v_mul_f32_e32 v0, v5, v5
	v_mul_f32_e32 v1, v7, v7
	v_pk_add_f32 v[12:13], v[2:3], v[18:19]
	v_fmac_f32_e32 v0, v4, v4
	v_fmac_f32_e32 v1, v6, v6
	v_add_f32_e32 v0, v0, v1
	v_mul_f32_e32 v1, v15, v15
	v_mul_f32_e32 v2, v13, v13
	v_fmac_f32_e32 v1, v14, v14
	v_fmac_f32_e32 v2, v12, v12
	v_add_f32_e32 v1, v1, v2
	v_add_f32_e32 v0, v0, v1
	v_add_f32_e32 v3, v20, v0
	ds_bpermute_b32 v18, v248, v3
	v_lshl_add_u64 v[0:1], s[14:15], 0, v[210:211]
	v_lshl_add_u64 v[16:17], v[206:207], 1, v[0:1]
	v_cvt_pk_bf16_f32 v2, v4, v5
	v_cvt_pk_bf16_f32 v4, v14, v15
	s_waitcnt lgkmcnt(0)
	v_add_f32_e32 v0, v3, v18
	ds_bpermute_b32 v1, v249, v0
	v_cvt_pk_bf16_f32 v3, v6, v7
	v_cvt_pk_bf16_f32 v5, v12, v13
	global_store_dwordx4 v[16:17], v[8:11], off sc1
	global_store_dwordx4 v[16:17], v[2:5], off offset:256 sc1
	s_and_saveexec_b64 s[34:35], s[6:7]
	s_cbranch_execz .LBB0_808
	s_waitcnt lgkmcnt(0)
	v_add_f32_e32 v2, v0, v1
	v_lshlrev_b64 v[0:1], 6, v[208:209]
	v_lshl_add_u64 v[0:1], s[16:17], 0, v[0:1]
	v_lshl_add_u64 v[0:1], s[10:11], 2, v[0:1]
	s_lshl_b32 s12, s47, 2
	v_lshl_add_u64 v[0:1], v[0:1], 0, s[12:13]
	global_store_dword v[0:1], v2, off
	s_branch .LBB0_808

.LBB0_984:
	ds_read_b128 v[120:123], v244
	ds_read_b128 v[124:127], v244 offset:1024
	ds_read_b128 v[132:135], v244 offset:2048
	ds_read_b128 v[140:143], v244 offset:3072
	s_add_u32 s34, s30, 0xfff50080
	s_addc_u32 s35, s31, -1
	s_cmp_eq_u32 s59, 40
	s_cselect_b32 s37, s11, s35
	s_cselect_b32 s36, s10, s34
	s_cselect_b32 s35, s13, s58
	s_cselect_b32 s34, s12, s57
	v_lshl_add_u64 v[176:177], s[30:31], 0, v[202:203]
	s_add_i32 m0, s41, 0xc000
	ds_read_b128 v[144:147], v245
	ds_read_b128 v[148:151], v245 offset:1024
	ds_read_b128 v[152:155], v245 offset:2048
	ds_read_b128 v[156:159], v245 offset:3072
	ds_read_b128 v[160:163], v245 offset:4096
	ds_read_b128 v[164:167], v245 offset:5120
	ds_read_b128 v[168:171], v245 offset:6144
	ds_read_b128 v[172:175], v245 offset:7168
	global_load_lds_dwordx4 v[176:177], off
	v_lshl_add_u64 v[176:177], s[30:31], 0, v[204:205]
	s_add_i32 m0, s41, 0xe000
	s_nop 0
	global_load_lds_dwordx4 v[176:177], off
	s_waitcnt lgkmcnt(8)
	s_barrier
	s_waitcnt lgkmcnt(0)
	s_setprio 1
	s_waitcnt lgkmcnt(0)
	v_mfma_f32_16x16x32_bf16 v[136:139], v[120:123], v[144:147], v[136:139]
	v_mfma_f32_16x16x32_bf16 v[128:131], v[132:135], v[144:147], v[128:131]
	v_mfma_f32_16x16x32_bf16 v[108:111], v[120:123], v[152:155], v[108:111]
	v_mfma_f32_16x16x32_bf16 v[104:107], v[132:135], v[152:155], v[104:107]
	v_mfma_f32_16x16x32_bf16 v[92:95], v[120:123], v[160:163], v[92:95]
	v_mfma_f32_16x16x32_bf16 v[88:91], v[132:135], v[160:163], v[88:91]
	v_mfma_f32_16x16x32_bf16 v[76:79], v[120:123], v[168:171], v[76:79]
	v_mfma_f32_16x16x32_bf16 v[72:75], v[132:135], v[168:171], v[72:75]
	v_mfma_f32_16x16x32_bf16 v[136:139], v[124:127], v[148:151], v[136:139]
	v_mfma_f32_16x16x32_bf16 v[128:131], v[140:143], v[148:151], v[128:131]
	v_mfma_f32_16x16x32_bf16 v[108:111], v[124:127], v[156:159], v[108:111]
	v_mfma_f32_16x16x32_bf16 v[104:107], v[140:143], v[156:159], v[104:107]
	v_mfma_f32_16x16x32_bf16 v[92:95], v[124:127], v[164:167], v[92:95]
	v_mfma_f32_16x16x32_bf16 v[88:91], v[140:143], v[164:167], v[88:91]
	v_mfma_f32_16x16x32_bf16 v[76:79], v[124:127], v[172:175], v[76:79]
	v_mfma_f32_16x16x32_bf16 v[72:75], v[140:143], v[172:175], v[72:75]
	s_setprio 0
	s_barrier
	s_add_i32 s64, s51, s40
	v_lshl_add_u64 v[206:207], s[34:35], 0, v[196:197]
	s_mov_b32 m0, s64
	ds_read_b128 v[176:179], v246
	ds_read_b128 v[180:183], v246 offset:1024
	ds_read_b128 v[184:187], v246 offset:2048
	ds_read_b128 v[188:191], v246 offset:3072
	global_load_lds_dwordx4 v[206:207], off
	v_lshl_add_u64 v[208:209], s[34:35], 0, v[200:201]
	s_add_i32 m0, s64, 0x2000
	s_nop 0
	global_load_lds_dwordx4 v[208:209], off
	s_barrier
	s_waitcnt lgkmcnt(0)
	s_setprio 1
	s_waitcnt lgkmcnt(0)
	v_mfma_f32_16x16x32_bf16 v[116:119], v[176:179], v[144:147], v[116:119]
	v_mfma_f32_16x16x32_bf16 v[112:115], v[184:187], v[144:147], v[112:115]
	v_mfma_f32_16x16x32_bf16 v[100:103], v[176:179], v[152:155], v[100:103]
	v_mfma_f32_16x16x32_bf16 v[96:99], v[184:187], v[152:155], v[96:99]
	v_mfma_f32_16x16x32_bf16 v[84:87], v[176:179], v[160:163], v[84:87]
	v_mfma_f32_16x16x32_bf16 v[80:83], v[184:187], v[160:163], v[80:83]
	v_mfma_f32_16x16x32_bf16 v[68:71], v[176:179], v[168:171], v[68:71]
	v_mfma_f32_16x16x32_bf16 v[64:67], v[184:187], v[168:171], v[64:67]
	v_mfma_f32_16x16x32_bf16 v[116:119], v[180:183], v[148:151], v[116:119]
	v_mfma_f32_16x16x32_bf16 v[112:115], v[188:191], v[148:151], v[112:115]
	v_mfma_f32_16x16x32_bf16 v[100:103], v[180:183], v[156:159], v[100:103]
	v_mfma_f32_16x16x32_bf16 v[96:99], v[188:191], v[156:159], v[96:99]
	v_mfma_f32_16x16x32_bf16 v[84:87], v[180:183], v[164:167], v[84:87]
	v_mfma_f32_16x16x32_bf16 v[80:83], v[188:191], v[164:167], v[80:83]
	v_mfma_f32_16x16x32_bf16 v[68:71], v[180:183], v[172:175], v[68:71]
	v_mfma_f32_16x16x32_bf16 v[64:67], v[188:191], v[172:175], v[64:67]
	s_setprio 0
	s_mov_b32 m0, s41
	v_lshl_add_u64 v[210:211], s[36:37], 0, v[194:195]
	s_barrier
	ds_read_b128 v[144:147], v245 offset:16384
	ds_read_b128 v[148:151], v245 offset:17408
	ds_read_b128 v[152:155], v245 offset:18432
	ds_read_b128 v[156:159], v245 offset:19456
	ds_read_b128 v[160:163], v245 offset:20480
	ds_read_b128 v[164:167], v245 offset:21504
	ds_read_b128 v[168:171], v245 offset:22528
	ds_read_b128 v[172:175], v245 offset:23552
	global_load_lds_dwordx4 v[210:211], off
	v_lshl_add_u64 v[212:213], s[36:37], 0, v[198:199]
	s_mov_b32 m0, s42
	s_nop 0
	global_load_lds_dwordx4 v[212:213], off
	s_barrier
	s_waitcnt lgkmcnt(0)
	s_setprio 1
	s_waitcnt lgkmcnt(0)
	v_mfma_f32_16x16x32_bf16 v[60:63], v[120:123], v[144:147], v[60:63]
	v_mfma_f32_16x16x32_bf16 v[56:59], v[132:135], v[144:147], v[56:59]
	v_mfma_f32_16x16x32_bf16 v[44:47], v[120:123], v[152:155], v[44:47]
	v_mfma_f32_16x16x32_bf16 v[40:43], v[132:135], v[152:155], v[40:43]
	v_mfma_f32_16x16x32_bf16 v[28:31], v[120:123], v[160:163], v[28:31]
	v_mfma_f32_16x16x32_bf16 v[24:27], v[132:135], v[160:163], v[24:27]
	v_mfma_f32_16x16x32_bf16 v[12:15], v[120:123], v[168:171], v[12:15]
	v_mfma_f32_16x16x32_bf16 v[8:11], v[132:135], v[168:171], v[8:11]
	v_mfma_f32_16x16x32_bf16 v[60:63], v[124:127], v[148:151], v[60:63]
	v_mfma_f32_16x16x32_bf16 v[56:59], v[140:143], v[148:151], v[56:59]
	v_mfma_f32_16x16x32_bf16 v[44:47], v[124:127], v[156:159], v[44:47]
	v_mfma_f32_16x16x32_bf16 v[40:43], v[140:143], v[156:159], v[40:43]
	v_mfma_f32_16x16x32_bf16 v[28:31], v[124:127], v[164:167], v[28:31]
	v_mfma_f32_16x16x32_bf16 v[24:27], v[140:143], v[164:167], v[24:27]
	v_mfma_f32_16x16x32_bf16 v[12:15], v[124:127], v[172:175], v[12:15]
	v_mfma_f32_16x16x32_bf16 v[8:11], v[140:143], v[172:175], v[8:11]
	s_setprio 0
	s_barrier
	s_add_u32 s64, s34, 0xb0000
	s_addc_u32 s65, s35, 0
	s_add_i32 s66, s52, s40
	v_lshl_add_u64 v[120:121], s[64:65], 0, v[196:197]
	s_mov_b32 m0, s66
	s_nop 0
	global_load_lds_dwordx4 v[120:121], off
	v_lshl_add_u64 v[120:121], s[64:65], 0, v[200:201]
	s_add_i32 m0, s66, 0x2000
	s_nop 0
	global_load_lds_dwordx4 v[120:121], off
	s_waitcnt vmcnt(6)
	s_barrier
	s_setprio 1
	v_mfma_f32_16x16x32_bf16 v[52:55], v[176:179], v[144:147], v[52:55]
	v_mfma_f32_16x16x32_bf16 v[48:51], v[184:187], v[144:147], v[48:51]
	v_mfma_f32_16x16x32_bf16 v[36:39], v[176:179], v[152:155], v[36:39]
	v_mfma_f32_16x16x32_bf16 v[32:35], v[184:187], v[152:155], v[32:35]
	v_mfma_f32_16x16x32_bf16 v[20:23], v[176:179], v[160:163], v[20:23]
	v_mfma_f32_16x16x32_bf16 v[16:19], v[184:187], v[160:163], v[16:19]
	v_mfma_f32_16x16x32_bf16 v[4:7], v[176:179], v[168:171], v[4:7]
	v_mfma_f32_16x16x32_bf16 v[0:3], v[184:187], v[168:171], v[0:3]
	v_mfma_f32_16x16x32_bf16 v[52:55], v[180:183], v[148:151], v[52:55]
	v_mfma_f32_16x16x32_bf16 v[48:51], v[188:191], v[148:151], v[48:51]
	v_mfma_f32_16x16x32_bf16 v[36:39], v[180:183], v[156:159], v[36:39]
	v_mfma_f32_16x16x32_bf16 v[32:35], v[188:191], v[156:159], v[32:35]
	v_mfma_f32_16x16x32_bf16 v[20:23], v[180:183], v[164:167], v[20:23]
	v_mfma_f32_16x16x32_bf16 v[16:19], v[188:191], v[164:167], v[16:19]
	v_mfma_f32_16x16x32_bf16 v[4:7], v[180:183], v[172:175], v[4:7]
	v_mfma_f32_16x16x32_bf16 v[0:3], v[188:191], v[172:175], v[0:3]
	s_setprio 0
	s_add_i32 s64, 0, 0x18000
	v_add_u32_e32 v140, s64, v242
	s_barrier
	ds_read_b128 v[120:123], v140
	ds_read_b128 v[124:127], v140 offset:1024
	ds_read_b128 v[132:135], v140 offset:2048
	ds_read_b128 v[140:143], v140 offset:3072
	s_add_u32 s36, s36, 0xb0000
	s_addc_u32 s37, s37, 0
	s_mov_b32 m0, s43
	v_lshl_add_u64 v[176:177], s[36:37], 0, v[194:195]
	ds_read_b128 v[144:147], v245 offset:32768
	ds_read_b128 v[148:151], v245 offset:33792
	ds_read_b128 v[152:155], v245 offset:34816
	ds_read_b128 v[156:159], v245 offset:35840
	ds_read_b128 v[160:163], v245 offset:36864
	ds_read_b128 v[164:167], v245 offset:37888
	ds_read_b128 v[168:171], v245 offset:38912
	ds_read_b128 v[172:175], v245 offset:39936
	global_load_lds_dwordx4 v[176:177], off
	v_lshl_add_u64 v[176:177], s[36:37], 0, v[198:199]
	s_mov_b32 m0, s44
	s_nop 0
	global_load_lds_dwordx4 v[176:177], off
	s_waitcnt lgkmcnt(8)
	s_barrier
	s_waitcnt lgkmcnt(0)
	s_setprio 1
	s_waitcnt lgkmcnt(0)
	v_mfma_f32_16x16x32_bf16 v[136:139], v[120:123], v[144:147], v[136:139]
	v_mfma_f32_16x16x32_bf16 v[128:131], v[132:135], v[144:147], v[128:131]
	v_mfma_f32_16x16x32_bf16 v[108:111], v[120:123], v[152:155], v[108:111]
	v_mfma_f32_16x16x32_bf16 v[104:107], v[132:135], v[152:155], v[104:107]
	v_mfma_f32_16x16x32_bf16 v[92:95], v[120:123], v[160:163], v[92:95]
	v_mfma_f32_16x16x32_bf16 v[88:91], v[132:135], v[160:163], v[88:91]
	v_mfma_f32_16x16x32_bf16 v[76:79], v[120:123], v[168:171], v[76:79]
	v_mfma_f32_16x16x32_bf16 v[72:75], v[132:135], v[168:171], v[72:75]
	v_mfma_f32_16x16x32_bf16 v[136:139], v[124:127], v[148:151], v[136:139]
	v_mfma_f32_16x16x32_bf16 v[128:131], v[140:143], v[148:151], v[128:131]
	v_mfma_f32_16x16x32_bf16 v[108:111], v[124:127], v[156:159], v[108:111]
	v_mfma_f32_16x16x32_bf16 v[104:107], v[140:143], v[156:159], v[104:107]
	v_mfma_f32_16x16x32_bf16 v[92:95], v[124:127], v[164:167], v[92:95]
	v_mfma_f32_16x16x32_bf16 v[88:91], v[140:143], v[164:167], v[88:91]
	v_mfma_f32_16x16x32_bf16 v[76:79], v[124:127], v[172:175], v[76:79]
	v_mfma_f32_16x16x32_bf16 v[72:75], v[140:143], v[172:175], v[72:75]
	s_setprio 0
	s_barrier
	s_add_i32 s36, 0, 0x1c000
	s_add_i32 s37, s64, s40
	v_add_u32_e32 v188, s36, v242
	v_lshl_add_u64 v[206:207], v[206:207], 0, s[28:29]
	s_mov_b32 m0, s37
	ds_read_b128 v[176:179], v188
	ds_read_b128 v[180:183], v188 offset:1024
	ds_read_b128 v[184:187], v188 offset:2048
	ds_read_b128 v[188:191], v188 offset:3072
	global_load_lds_dwordx4 v[206:207], off
	v_lshl_add_u64 v[206:207], v[208:209], 0, s[28:29]
	s_add_i32 m0, s37, 0x2000
	s_nop 0
	global_load_lds_dwordx4 v[206:207], off
	s_barrier
	s_waitcnt lgkmcnt(0)
	s_setprio 1
	s_waitcnt lgkmcnt(0)
	v_mfma_f32_16x16x32_bf16 v[116:119], v[176:179], v[144:147], v[116:119]
	v_mfma_f32_16x16x32_bf16 v[112:115], v[184:187], v[144:147], v[112:115]
	v_mfma_f32_16x16x32_bf16 v[100:103], v[176:179], v[152:155], v[100:103]
	v_mfma_f32_16x16x32_bf16 v[96:99], v[184:187], v[152:155], v[96:99]
	v_mfma_f32_16x16x32_bf16 v[84:87], v[176:179], v[160:163], v[84:87]
	v_mfma_f32_16x16x32_bf16 v[80:83], v[184:187], v[160:163], v[80:83]
	v_mfma_f32_16x16x32_bf16 v[68:71], v[176:179], v[168:171], v[68:71]
	v_mfma_f32_16x16x32_bf16 v[64:67], v[184:187], v[168:171], v[64:67]
	v_mfma_f32_16x16x32_bf16 v[116:119], v[180:183], v[148:151], v[116:119]
	v_mfma_f32_16x16x32_bf16 v[112:115], v[188:191], v[148:151], v[112:115]
	v_mfma_f32_16x16x32_bf16 v[100:103], v[180:183], v[156:159], v[100:103]
	v_mfma_f32_16x16x32_bf16 v[96:99], v[188:191], v[156:159], v[96:99]
	v_mfma_f32_16x16x32_bf16 v[84:87], v[180:183], v[164:167], v[84:87]
	v_mfma_f32_16x16x32_bf16 v[80:83], v[188:191], v[164:167], v[80:83]
	v_mfma_f32_16x16x32_bf16 v[68:71], v[180:183], v[172:175], v[68:71]
	v_mfma_f32_16x16x32_bf16 v[64:67], v[188:191], v[172:175], v[64:67]
	s_setprio 0
	s_mov_b32 m0, s46
	v_lshl_add_u64 v[206:207], v[210:211], 0, s[28:29]
	s_barrier
	ds_read_b128 v[144:147], v245 offset:49152
	ds_read_b128 v[148:151], v245 offset:50176
	ds_read_b128 v[152:155], v245 offset:51200
	ds_read_b128 v[156:159], v245 offset:52224
	ds_read_b128 v[160:163], v245 offset:53248
	ds_read_b128 v[164:167], v245 offset:54272
	ds_read_b128 v[168:171], v245 offset:55296
	ds_read_b128 v[172:175], v245 offset:56320
	global_load_lds_dwordx4 v[206:207], off
	v_lshl_add_u64 v[206:207], v[212:213], 0, s[28:29]
	s_mov_b32 m0, s47
	s_nop 0
	global_load_lds_dwordx4 v[206:207], off
	s_barrier
	s_waitcnt lgkmcnt(0)
	s_setprio 1
	s_waitcnt lgkmcnt(0)
	v_mfma_f32_16x16x32_bf16 v[60:63], v[120:123], v[144:147], v[60:63]
	v_mfma_f32_16x16x32_bf16 v[56:59], v[132:135], v[144:147], v[56:59]
	v_mfma_f32_16x16x32_bf16 v[44:47], v[120:123], v[152:155], v[44:47]
	v_mfma_f32_16x16x32_bf16 v[40:43], v[132:135], v[152:155], v[40:43]
	v_mfma_f32_16x16x32_bf16 v[28:31], v[120:123], v[160:163], v[28:31]
	v_mfma_f32_16x16x32_bf16 v[24:27], v[132:135], v[160:163], v[24:27]
	v_mfma_f32_16x16x32_bf16 v[12:15], v[120:123], v[168:171], v[12:15]
	v_mfma_f32_16x16x32_bf16 v[8:11], v[132:135], v[168:171], v[8:11]
	v_mfma_f32_16x16x32_bf16 v[60:63], v[124:127], v[148:151], v[60:63]
	v_mfma_f32_16x16x32_bf16 v[56:59], v[140:143], v[148:151], v[56:59]
	v_mfma_f32_16x16x32_bf16 v[44:47], v[124:127], v[156:159], v[44:47]
	v_mfma_f32_16x16x32_bf16 v[40:43], v[140:143], v[156:159], v[40:43]
	v_mfma_f32_16x16x32_bf16 v[28:31], v[124:127], v[164:167], v[28:31]
	v_mfma_f32_16x16x32_bf16 v[24:27], v[140:143], v[164:167], v[24:27]
	v_mfma_f32_16x16x32_bf16 v[12:15], v[124:127], v[172:175], v[12:15]
	v_mfma_f32_16x16x32_bf16 v[8:11], v[140:143], v[172:175], v[8:11]
	s_setprio 0
	s_barrier
	s_add_u32 s34, s34, 0xb0080
	s_addc_u32 s35, s35, 0
	s_add_i32 s36, s36, s40
	v_lshl_add_u64 v[120:121], s[34:35], 0, v[196:197]
	s_mov_b32 m0, s36
	s_nop 0
	global_load_lds_dwordx4 v[120:121], off
	v_lshl_add_u64 v[120:121], s[34:35], 0, v[200:201]
	s_add_i32 m0, s36, 0x2000
	s_nop 0
	global_load_lds_dwordx4 v[120:121], off
	s_waitcnt vmcnt(6)
	s_barrier
	s_setprio 1
	v_mfma_f32_16x16x32_bf16 v[52:55], v[176:179], v[144:147], v[52:55]
	v_mfma_f32_16x16x32_bf16 v[48:51], v[184:187], v[144:147], v[48:51]
	v_mfma_f32_16x16x32_bf16 v[36:39], v[176:179], v[152:155], v[36:39]
	v_mfma_f32_16x16x32_bf16 v[32:35], v[184:187], v[152:155], v[32:35]
	v_mfma_f32_16x16x32_bf16 v[20:23], v[176:179], v[160:163], v[20:23]
	v_mfma_f32_16x16x32_bf16 v[16:19], v[184:187], v[160:163], v[16:19]
	v_mfma_f32_16x16x32_bf16 v[4:7], v[176:179], v[168:171], v[4:7]
	v_mfma_f32_16x16x32_bf16 v[0:3], v[184:187], v[168:171], v[0:3]
	v_mfma_f32_16x16x32_bf16 v[52:55], v[180:183], v[148:151], v[52:55]
	v_mfma_f32_16x16x32_bf16 v[48:51], v[188:191], v[148:151], v[48:51]
	v_mfma_f32_16x16x32_bf16 v[36:39], v[180:183], v[156:159], v[36:39]
	v_mfma_f32_16x16x32_bf16 v[32:35], v[188:191], v[156:159], v[32:35]
	v_mfma_f32_16x16x32_bf16 v[20:23], v[180:183], v[164:167], v[20:23]
	v_mfma_f32_16x16x32_bf16 v[16:19], v[188:191], v[164:167], v[16:19]
	v_mfma_f32_16x16x32_bf16 v[4:7], v[180:183], v[172:175], v[4:7]
	v_mfma_f32_16x16x32_bf16 v[0:3], v[188:191], v[172:175], v[0:3]
	s_setprio 0
	s_add_i32 s59, s59, 2
	s_add_u32 s30, s30, 0x100
	s_addc_u32 s31, s31, 0
	s_add_u32 s57, s57, 0x100
	s_addc_u32 s58, s58, 0
	s_cmp_gt_u32 s59, 41
	s_barrier
	s_cbranch_scc0 .LBB0_984
	v_lshl_or_b32 v206, s16, 8, v243
	v_lshl_add_u32 v236, s56, 8, v193
	v_ashrrev_i32_e32 v207, 31, v206
	v_lshlrev_b64 v[238:239], 1, v[206:207]
	v_ashrrev_i32_e32 v237, 31, v236
	v_lshl_add_u64 v[124:125], s[24:25], 0, v[238:239]
	v_lshlrev_b64 v[240:241], 11, v[236:237]
	v_lshl_add_u64 v[120:121], v[124:125], 0, v[240:241]
	global_load_dwordx4 v[188:191], v[120:121], off
	global_load_dwordx4 v[184:187], v[120:121], off offset:256
	v_or_b32_e32 v232, 16, v236
	v_ashrrev_i32_e32 v233, 31, v232
	v_or_b32_e32 v228, 32, v236
	v_lshlrev_b64 v[234:235], 11, v[232:233]
	v_ashrrev_i32_e32 v229, 31, v228
	v_or_b32_e32 v224, 48, v236
	v_lshl_add_u64 v[120:121], v[124:125], 0, v[234:235]
	v_lshlrev_b64 v[230:231], 11, v[228:229]
	v_ashrrev_i32_e32 v225, 31, v224
	v_add_u32_e32 v220, 0x80, v236
	global_load_dwordx4 v[180:183], v[120:121], off
	global_load_dwordx4 v[176:179], v[120:121], off offset:256
	v_lshl_add_u64 v[120:121], v[124:125], 0, v[230:231]
	v_lshlrev_b64 v[226:227], 11, v[224:225]
	v_ashrrev_i32_e32 v221, 31, v220
	v_add_u32_e32 v216, 0x90, v236
	global_load_dwordx4 v[172:175], v[120:121], off
	global_load_dwordx4 v[168:171], v[120:121], off offset:256
	v_lshl_add_u64 v[120:121], v[124:125], 0, v[226:227]
	v_lshlrev_b64 v[222:223], 11, v[220:221]
	v_ashrrev_i32_e32 v217, 31, v216
	v_add_u32_e32 v212, 0xa0, v236
	v_add_u32_e32 v208, 0xb0, v236
	global_load_dwordx4 v[164:167], v[120:121], off
	global_load_dwordx4 v[160:163], v[120:121], off offset:256
	v_lshl_add_u64 v[120:121], v[124:125], 0, v[222:223]
	v_lshlrev_b64 v[218:219], 11, v[216:217]
	v_ashrrev_i32_e32 v213, 31, v212
	v_ashrrev_i32_e32 v209, 31, v208
	global_load_dwordx4 v[156:159], v[120:121], off
	global_load_dwordx4 v[152:155], v[120:121], off offset:256
	v_lshl_add_u64 v[120:121], v[124:125], 0, v[218:219]
	v_lshlrev_b64 v[214:215], 11, v[212:213]
	v_lshlrev_b64 v[210:211], 11, v[208:209]
	global_load_dwordx4 v[148:151], v[120:121], off
	global_load_dwordx4 v[144:147], v[120:121], off offset:256
	v_lshl_add_u64 v[120:121], v[124:125], 0, v[214:215]
	v_lshl_add_u64 v[124:125], v[124:125], 0, v[210:211]
	global_load_dwordx4 v[132:135], v[120:121], off
	s_nop 0
	global_load_dwordx4 v[120:123], v[120:121], off offset:256
	s_nop 0
	global_load_dwordx4 v[140:143], v[124:125], off
	s_nop 0
	global_load_dwordx4 v[124:127], v[124:125], off offset:256
	v_and_b32_e32 v249, 64, v247
	v_xor_b32_e32 v248, 16, v247
	v_add_u32_e32 v249, 64, v249
	v_cmp_lt_i32_e32 vcc, v248, v249
	v_xor_b32_e32 v250, 32, v247
	s_lshl_b32 s30, s16, 2
	v_cndmask_b32_e32 v248, v247, v248, vcc
	v_cmp_lt_i32_e32 vcc, v250, v249
	v_lshlrev_b32_e32 v248, 2, v248
	s_ashr_i32 s31, s30, 31
	v_cndmask_b32_e32 v249, v247, v250, vcc
	v_lshlrev_b32_e32 v249, 2, v249
	s_waitcnt vmcnt(0)
	v_lshlrev_b32_e32 v250, 16, v188
	v_and_b32_e32 v251, 0xffff0000, v188
	v_lshlrev_b32_e32 v188, 16, v189
	v_and_b32_e32 v189, 0xffff0000, v189
	v_lshlrev_b32_e32 v252, 16, v190
	v_and_b32_e32 v253, 0xffff0000, v190
	v_lshlrev_b32_e32 v190, 16, v191
	v_and_b32_e32 v191, 0xffff0000, v191
	v_pk_add_f32 v[138:139], v[138:139], v[188:189]
	v_pk_add_f32 v[136:137], v[136:137], v[250:251]
	v_pk_add_f32 v[188:189], v[130:131], v[190:191]
	v_pk_add_f32 v[130:131], v[128:129], v[252:253]
	v_mul_f32_e32 v128, v137, v137
	v_mul_f32_e32 v129, v139, v139
	v_fmac_f32_e32 v128, v136, v136
	v_fmac_f32_e32 v129, v138, v138
	v_add_f32_e32 v128, v128, v129
	v_mul_f32_e32 v129, v131, v131
	v_mul_f32_e32 v190, v189, v189
	v_fmac_f32_e32 v129, v130, v130
	v_fmac_f32_e32 v190, v188, v188
	v_add_f32_e32 v129, v129, v190
	v_add_f32_e32 v190, v128, v129
	v_cvt_pk_bf16_f32 v128, v136, v137
	v_lshl_add_u64 v[136:137], s[24:25], 0, v[240:241]
	v_cvt_pk_bf16_f32 v129, v138, v139
	v_cvt_pk_bf16_f32 v130, v130, v131
	v_cvt_pk_bf16_f32 v131, v188, v189
	v_lshl_add_u64 v[136:137], v[136:137], 0, v[238:239]
	global_store_dwordx4 v[136:137], v[128:131], off sc1
	v_lshlrev_b32_e32 v138, 16, v186
	v_and_b32_e32 v139, 0xffff0000, v186
	v_lshlrev_b32_e32 v128, 16, v184
	v_and_b32_e32 v129, 0xffff0000, v184
	v_lshlrev_b32_e32 v130, 16, v185
	v_and_b32_e32 v131, 0xffff0000, v185
	v_lshlrev_b32_e32 v184, 16, v187
	v_and_b32_e32 v185, 0xffff0000, v187
	v_pk_add_f32 v[118:119], v[118:119], v[130:131]
	v_pk_add_f32 v[116:117], v[116:117], v[128:129]
	v_pk_add_f32 v[128:129], v[114:115], v[184:185]
	v_pk_add_f32 v[114:115], v[112:113], v[138:139]
	v_mul_f32_e32 v112, v117, v117
	v_mul_f32_e32 v113, v119, v119
	v_fmac_f32_e32 v112, v116, v116
	v_fmac_f32_e32 v113, v118, v118
	v_add_f32_e32 v112, v112, v113
	v_mul_f32_e32 v113, v115, v115
	v_mul_f32_e32 v130, v129, v129
	v_fmac_f32_e32 v113, v114, v114
	v_fmac_f32_e32 v130, v128, v128
	v_add_f32_e32 v113, v113, v130
	v_add_f32_e32 v112, v112, v113
	v_add_f32_e32 v130, v190, v112
	v_cvt_pk_bf16_f32 v112, v116, v117
	v_cvt_pk_bf16_f32 v113, v118, v119
	v_cvt_pk_bf16_f32 v114, v114, v115
	v_cvt_pk_bf16_f32 v115, v128, v129
	global_store_dwordx4 v[136:137], v[112:115], off offset:256 sc1
	ds_bpermute_b32 v112, v248, v130
	s_waitcnt lgkmcnt(0)
	v_add_f32_e32 v112, v130, v112
	ds_bpermute_b32 v113, v249, v112
	s_and_saveexec_b64 s[34:35], s[6:7]
	s_cbranch_execz .LBB0_987
	v_lshlrev_b64 v[114:115], 6, v[236:237]
	v_lshl_add_u64 v[114:115], s[26:27], 0, v[114:115]
	v_lshl_add_u64 v[114:115], s[30:31], 2, v[114:115]
	s_lshl_b32 s16, s45, 2
	v_lshl_add_u64 v[114:115], v[114:115], 0, s[16:17]
	s_waitcnt lgkmcnt(0)
	v_add_f32_e32 v112, v112, v113
	global_store_dword v[114:115], v112, off
.LBB0_987:
	s_or_b64 exec, exec, s[34:35]
	v_lshlrev_b32_e32 v112, 16, v180
	s_waitcnt lgkmcnt(0)
	v_and_b32_e32 v113, 0xffff0000, v180
	v_lshlrev_b32_e32 v114, 16, v181
	v_and_b32_e32 v115, 0xffff0000, v181
	v_lshlrev_b32_e32 v116, 16, v182
	v_and_b32_e32 v117, 0xffff0000, v182
	v_lshlrev_b32_e32 v118, 16, v183
	v_and_b32_e32 v119, 0xffff0000, v183
	v_pk_add_f32 v[110:111], v[110:111], v[114:115]
	v_pk_add_f32 v[108:109], v[108:109], v[112:113]
	v_pk_add_f32 v[112:113], v[106:107], v[118:119]
	v_pk_add_f32 v[106:107], v[104:105], v[116:117]
	v_mul_f32_e32 v104, v109, v109
	v_mul_f32_e32 v105, v111, v111
	v_fmac_f32_e32 v104, v108, v108
	v_fmac_f32_e32 v105, v110, v110
	v_add_f32_e32 v104, v104, v105
	v_mul_f32_e32 v105, v107, v107
	v_mul_f32_e32 v114, v113, v113
	v_fmac_f32_e32 v105, v106, v106
	v_fmac_f32_e32 v114, v112, v112
	v_add_f32_e32 v105, v105, v114
	v_add_f32_e32 v116, v104, v105
	v_cvt_pk_bf16_f32 v104, v108, v109
	v_cvt_pk_bf16_f32 v105, v110, v111
	v_lshlrev_b32_e32 v108, 16, v176
	v_and_b32_e32 v109, 0xffff0000, v176
	v_lshlrev_b32_e32 v110, 16, v177
	v_and_b32_e32 v111, 0xffff0000, v177
	v_cvt_pk_bf16_f32 v106, v106, v107
	v_cvt_pk_bf16_f32 v107, v112, v113
	v_lshlrev_b32_e32 v112, 16, v178
	v_and_b32_e32 v113, 0xffff0000, v178
	v_pk_add_f32 v[102:103], v[102:103], v[110:111]
	v_pk_add_f32 v[100:101], v[100:101], v[108:109]
	v_lshlrev_b32_e32 v114, 16, v179
	v_and_b32_e32 v115, 0xffff0000, v179
	v_pk_add_f32 v[110:111], v[96:97], v[112:113]
	v_mul_f32_e32 v96, v101, v101
	v_mul_f32_e32 v97, v103, v103
	v_pk_add_f32 v[108:109], v[98:99], v[114:115]
	v_fmac_f32_e32 v96, v100, v100
	v_fmac_f32_e32 v97, v102, v102
	v_add_f32_e32 v96, v96, v97
	v_mul_f32_e32 v97, v111, v111
	v_mul_f32_e32 v98, v109, v109
	v_fmac_f32_e32 v97, v110, v110
	v_fmac_f32_e32 v98, v108, v108
	v_add_f32_e32 v97, v97, v98
	v_add_f32_e32 v96, v96, v97
	v_add_f32_e32 v99, v116, v96
	ds_bpermute_b32 v114, v248, v99
	v_lshl_add_u64 v[96:97], s[24:25], 0, v[234:235]
	v_lshl_add_u64 v[112:113], v[206:207], 1, v[96:97]
	v_cvt_pk_bf16_f32 v98, v100, v101
	v_cvt_pk_bf16_f32 v100, v110, v111
	s_waitcnt lgkmcnt(0)
	v_add_f32_e32 v96, v99, v114
	ds_bpermute_b32 v97, v249, v96
	v_cvt_pk_bf16_f32 v99, v102, v103
	v_cvt_pk_bf16_f32 v101, v108, v109
	global_store_dwordx4 v[112:113], v[104:107], off sc1
	global_store_dwordx4 v[112:113], v[98:101], off offset:256 sc1
	s_and_saveexec_b64 s[34:35], s[6:7]
	s_cbranch_execz .LBB0_989
	v_lshlrev_b64 v[98:99], 6, v[232:233]
	v_lshl_add_u64 v[98:99], s[26:27], 0, v[98:99]
	v_lshl_add_u64 v[98:99], s[30:31], 2, v[98:99]
	s_lshl_b32 s16, s45, 2
	v_lshl_add_u64 v[98:99], v[98:99], 0, s[16:17]
	s_waitcnt lgkmcnt(0)
	v_add_f32_e32 v96, v96, v97
	global_store_dword v[98:99], v96, off
.LBB0_989:
	s_or_b64 exec, exec, s[34:35]
	v_lshlrev_b32_e32 v96, 16, v172
	s_waitcnt lgkmcnt(0)
	v_and_b32_e32 v97, 0xffff0000, v172
	v_lshlrev_b32_e32 v98, 16, v173
	v_and_b32_e32 v99, 0xffff0000, v173
	v_lshlrev_b32_e32 v100, 16, v174
	v_and_b32_e32 v101, 0xffff0000, v174
	v_lshlrev_b32_e32 v102, 16, v175
	v_and_b32_e32 v103, 0xffff0000, v175
	v_pk_add_f32 v[94:95], v[94:95], v[98:99]
	v_pk_add_f32 v[92:93], v[92:93], v[96:97]
	v_pk_add_f32 v[96:97], v[90:91], v[102:103]
	v_pk_add_f32 v[90:91], v[88:89], v[100:101]
	v_mul_f32_e32 v88, v93, v93
	v_mul_f32_e32 v89, v95, v95
	v_fmac_f32_e32 v88, v92, v92
	v_fmac_f32_e32 v89, v94, v94
	v_add_f32_e32 v88, v88, v89
	v_mul_f32_e32 v89, v91, v91
	v_mul_f32_e32 v98, v97, v97
	v_fmac_f32_e32 v89, v90, v90
	v_fmac_f32_e32 v98, v96, v96
	v_add_f32_e32 v89, v89, v98
	v_add_f32_e32 v100, v88, v89
	v_cvt_pk_bf16_f32 v88, v92, v93
	v_cvt_pk_bf16_f32 v89, v94, v95
	v_lshlrev_b32_e32 v92, 16, v168
	v_and_b32_e32 v93, 0xffff0000, v168
	v_lshlrev_b32_e32 v94, 16, v169
	v_and_b32_e32 v95, 0xffff0000, v169
	v_cvt_pk_bf16_f32 v90, v90, v91
	v_cvt_pk_bf16_f32 v91, v96, v97
	v_lshlrev_b32_e32 v96, 16, v170
	v_and_b32_e32 v97, 0xffff0000, v170
	v_pk_add_f32 v[86:87], v[86:87], v[94:95]
	v_pk_add_f32 v[84:85], v[84:85], v[92:93]
	v_lshlrev_b32_e32 v98, 16, v171
	v_and_b32_e32 v99, 0xffff0000, v171
	v_pk_add_f32 v[94:95], v[80:81], v[96:97]
	v_mul_f32_e32 v80, v85, v85
	v_mul_f32_e32 v81, v87, v87
	v_pk_add_f32 v[92:93], v[82:83], v[98:99]
	v_fmac_f32_e32 v80, v84, v84
	v_fmac_f32_e32 v81, v86, v86
	v_add_f32_e32 v80, v80, v81
	v_mul_f32_e32 v81, v95, v95
	v_mul_f32_e32 v82, v93, v93
	v_fmac_f32_e32 v81, v94, v94
	v_fmac_f32_e32 v82, v92, v92
	v_add_f32_e32 v81, v81, v82
	v_add_f32_e32 v80, v80, v81
	v_add_f32_e32 v83, v100, v80
	ds_bpermute_b32 v98, v248, v83
	v_lshl_add_u64 v[80:81], s[24:25], 0, v[230:231]
	v_lshl_add_u64 v[96:97], v[206:207], 1, v[80:81]
	v_cvt_pk_bf16_f32 v82, v84, v85
	v_cvt_pk_bf16_f32 v84, v94, v95
	s_waitcnt lgkmcnt(0)
	v_add_f32_e32 v80, v83, v98
	ds_bpermute_b32 v81, v249, v80
	v_cvt_pk_bf16_f32 v83, v86, v87
	v_cvt_pk_bf16_f32 v85, v92, v93
	global_store_dwordx4 v[96:97], v[88:91], off sc1
	global_store_dwordx4 v[96:97], v[82:85], off offset:256 sc1
	s_and_saveexec_b64 s[34:35], s[6:7]
	s_cbranch_execz .LBB0_991
	v_lshlrev_b64 v[82:83], 6, v[228:229]
	v_lshl_add_u64 v[82:83], s[26:27], 0, v[82:83]
	v_lshl_add_u64 v[82:83], s[30:31], 2, v[82:83]
	s_lshl_b32 s16, s45, 2
	v_lshl_add_u64 v[82:83], v[82:83], 0, s[16:17]
	s_waitcnt lgkmcnt(0)
	v_add_f32_e32 v80, v80, v81
	global_store_dword v[82:83], v80, off
.LBB0_991:
	s_or_b64 exec, exec, s[34:35]
	v_lshlrev_b32_e32 v80, 16, v164
	s_waitcnt lgkmcnt(0)
	v_and_b32_e32 v81, 0xffff0000, v164
	v_lshlrev_b32_e32 v82, 16, v165
	v_and_b32_e32 v83, 0xffff0000, v165
	v_lshlrev_b32_e32 v84, 16, v166
	v_and_b32_e32 v85, 0xffff0000, v166
	v_lshlrev_b32_e32 v86, 16, v167
	v_and_b32_e32 v87, 0xffff0000, v167
	v_pk_add_f32 v[78:79], v[78:79], v[82:83]
	v_pk_add_f32 v[76:77], v[76:77], v[80:81]
	v_pk_add_f32 v[80:81], v[74:75], v[86:87]
	v_pk_add_f32 v[74:75], v[72:73], v[84:85]
	v_mul_f32_e32 v72, v77, v77
	v_mul_f32_e32 v73, v79, v79
	v_fmac_f32_e32 v72, v76, v76
	v_fmac_f32_e32 v73, v78, v78
	v_add_f32_e32 v72, v72, v73
	v_mul_f32_e32 v73, v75, v75
	v_mul_f32_e32 v82, v81, v81
	v_fmac_f32_e32 v73, v74, v74
	v_fmac_f32_e32 v82, v80, v80
	v_add_f32_e32 v73, v73, v82
	v_add_f32_e32 v84, v72, v73
	v_cvt_pk_bf16_f32 v72, v76, v77
	v_cvt_pk_bf16_f32 v73, v78, v79
	v_lshlrev_b32_e32 v76, 16, v160
	v_and_b32_e32 v77, 0xffff0000, v160
	v_lshlrev_b32_e32 v78, 16, v161
	v_and_b32_e32 v79, 0xffff0000, v161
	v_cvt_pk_bf16_f32 v74, v74, v75
	v_cvt_pk_bf16_f32 v75, v80, v81
	v_lshlrev_b32_e32 v80, 16, v162
	v_and_b32_e32 v81, 0xffff0000, v162
	v_pk_add_f32 v[70:71], v[70:71], v[78:79]
	v_pk_add_f32 v[68:69], v[68:69], v[76:77]
	v_lshlrev_b32_e32 v82, 16, v163
	v_and_b32_e32 v83, 0xffff0000, v163
	v_pk_add_f32 v[78:79], v[64:65], v[80:81]
	v_mul_f32_e32 v64, v69, v69
	v_mul_f32_e32 v65, v71, v71
	v_pk_add_f32 v[76:77], v[66:67], v[82:83]
	v_fmac_f32_e32 v64, v68, v68
	v_fmac_f32_e32 v65, v70, v70
	v_add_f32_e32 v64, v64, v65
	v_mul_f32_e32 v65, v79, v79
	v_mul_f32_e32 v66, v77, v77
	v_fmac_f32_e32 v65, v78, v78
	v_fmac_f32_e32 v66, v76, v76
	v_add_f32_e32 v65, v65, v66
	v_add_f32_e32 v64, v64, v65
	v_add_f32_e32 v67, v84, v64
	ds_bpermute_b32 v82, v248, v67
	v_lshl_add_u64 v[64:65], s[24:25], 0, v[226:227]
	v_lshl_add_u64 v[80:81], v[206:207], 1, v[64:65]
	v_cvt_pk_bf16_f32 v66, v68, v69
	v_cvt_pk_bf16_f32 v68, v78, v79
	s_waitcnt lgkmcnt(0)
	v_add_f32_e32 v64, v67, v82
	ds_bpermute_b32 v65, v249, v64
	v_cvt_pk_bf16_f32 v67, v70, v71
	v_cvt_pk_bf16_f32 v69, v76, v77
	global_store_dwordx4 v[80:81], v[72:75], off sc1
	global_store_dwordx4 v[80:81], v[66:69], off offset:256 sc1
	s_and_saveexec_b64 s[34:35], s[6:7]
	s_cbranch_execz .LBB0_993
	v_lshlrev_b64 v[66:67], 6, v[224:225]
	v_lshl_add_u64 v[66:67], s[26:27], 0, v[66:67]
	v_lshl_add_u64 v[66:67], s[30:31], 2, v[66:67]
	s_lshl_b32 s16, s45, 2
	v_lshl_add_u64 v[66:67], v[66:67], 0, s[16:17]
	s_waitcnt lgkmcnt(0)
	v_add_f32_e32 v64, v64, v65
	global_store_dword v[66:67], v64, off
.LBB0_993:
	s_or_b64 exec, exec, s[34:35]
	v_lshlrev_b32_e32 v64, 16, v156
	s_waitcnt lgkmcnt(0)
	v_and_b32_e32 v65, 0xffff0000, v156
	v_lshlrev_b32_e32 v66, 16, v157
	v_and_b32_e32 v67, 0xffff0000, v157
	v_lshlrev_b32_e32 v68, 16, v158
	v_and_b32_e32 v69, 0xffff0000, v158
	v_lshlrev_b32_e32 v70, 16, v159
	v_and_b32_e32 v71, 0xffff0000, v159
	v_pk_add_f32 v[62:63], v[62:63], v[66:67]
	v_pk_add_f32 v[60:61], v[60:61], v[64:65]
	v_pk_add_f32 v[64:65], v[58:59], v[70:71]
	v_pk_add_f32 v[58:59], v[56:57], v[68:69]
	v_mul_f32_e32 v56, v61, v61
	v_mul_f32_e32 v57, v63, v63
	v_fmac_f32_e32 v56, v60, v60
	v_fmac_f32_e32 v57, v62, v62
	v_add_f32_e32 v56, v56, v57
	v_mul_f32_e32 v57, v59, v59
	v_mul_f32_e32 v66, v65, v65
	v_fmac_f32_e32 v57, v58, v58
	v_fmac_f32_e32 v66, v64, v64
	v_add_f32_e32 v57, v57, v66
	v_add_f32_e32 v68, v56, v57
	v_cvt_pk_bf16_f32 v56, v60, v61
	v_cvt_pk_bf16_f32 v57, v62, v63
	v_lshlrev_b32_e32 v60, 16, v152
	v_and_b32_e32 v61, 0xffff0000, v152
	v_lshlrev_b32_e32 v62, 16, v153
	v_and_b32_e32 v63, 0xffff0000, v153
	v_cvt_pk_bf16_f32 v58, v58, v59
	v_cvt_pk_bf16_f32 v59, v64, v65
	v_lshlrev_b32_e32 v64, 16, v154
	v_and_b32_e32 v65, 0xffff0000, v154
	v_pk_add_f32 v[54:55], v[54:55], v[62:63]
	v_pk_add_f32 v[52:53], v[52:53], v[60:61]
	v_lshlrev_b32_e32 v66, 16, v155
	v_and_b32_e32 v67, 0xffff0000, v155
	v_pk_add_f32 v[62:63], v[48:49], v[64:65]
	v_mul_f32_e32 v48, v53, v53
	v_mul_f32_e32 v49, v55, v55
	v_pk_add_f32 v[60:61], v[50:51], v[66:67]
	v_fmac_f32_e32 v48, v52, v52
	v_fmac_f32_e32 v49, v54, v54
	v_add_f32_e32 v48, v48, v49
	v_mul_f32_e32 v49, v63, v63
	v_mul_f32_e32 v50, v61, v61
	v_fmac_f32_e32 v49, v62, v62
	v_fmac_f32_e32 v50, v60, v60
	v_add_f32_e32 v49, v49, v50
	v_add_f32_e32 v48, v48, v49
	v_add_f32_e32 v51, v68, v48
	ds_bpermute_b32 v66, v248, v51
	v_lshl_add_u64 v[48:49], s[24:25], 0, v[222:223]
	v_lshl_add_u64 v[64:65], v[206:207], 1, v[48:49]
	v_cvt_pk_bf16_f32 v50, v52, v53
	v_cvt_pk_bf16_f32 v52, v62, v63
	s_waitcnt lgkmcnt(0)
	v_add_f32_e32 v48, v51, v66
	ds_bpermute_b32 v49, v249, v48
	v_cvt_pk_bf16_f32 v51, v54, v55
	v_cvt_pk_bf16_f32 v53, v60, v61
	global_store_dwordx4 v[64:65], v[56:59], off sc1
	global_store_dwordx4 v[64:65], v[50:53], off offset:256 sc1
	s_and_saveexec_b64 s[34:35], s[6:7]
	s_cbranch_execz .LBB0_995
	v_lshlrev_b64 v[50:51], 6, v[220:221]
	v_lshl_add_u64 v[50:51], s[26:27], 0, v[50:51]
	v_lshl_add_u64 v[50:51], s[30:31], 2, v[50:51]
	s_lshl_b32 s16, s45, 2
	v_lshl_add_u64 v[50:51], v[50:51], 0, s[16:17]
	s_waitcnt lgkmcnt(0)
	v_add_f32_e32 v48, v48, v49
	global_store_dword v[50:51], v48, off
.LBB0_995:
	s_or_b64 exec, exec, s[34:35]
	v_lshlrev_b32_e32 v48, 16, v148
	s_waitcnt lgkmcnt(0)
	v_and_b32_e32 v49, 0xffff0000, v148
	v_lshlrev_b32_e32 v50, 16, v149
	v_and_b32_e32 v51, 0xffff0000, v149
	v_lshlrev_b32_e32 v52, 16, v150
	v_and_b32_e32 v53, 0xffff0000, v150
	v_lshlrev_b32_e32 v54, 16, v151
	v_and_b32_e32 v55, 0xffff0000, v151
	v_pk_add_f32 v[46:47], v[46:47], v[50:51]
	v_pk_add_f32 v[44:45], v[44:45], v[48:49]
	v_pk_add_f32 v[48:49], v[42:43], v[54:55]
	v_pk_add_f32 v[42:43], v[40:41], v[52:53]
	v_mul_f32_e32 v40, v45, v45
	v_mul_f32_e32 v41, v47, v47
	v_fmac_f32_e32 v40, v44, v44
	v_fmac_f32_e32 v41, v46, v46
	v_add_f32_e32 v40, v40, v41
	v_mul_f32_e32 v41, v43, v43
	v_mul_f32_e32 v50, v49, v49
	v_fmac_f32_e32 v41, v42, v42
	v_fmac_f32_e32 v50, v48, v48
	v_add_f32_e32 v41, v41, v50
	v_add_f32_e32 v52, v40, v41
	v_cvt_pk_bf16_f32 v40, v44, v45
	v_cvt_pk_bf16_f32 v41, v46, v47
	v_lshlrev_b32_e32 v44, 16, v144
	v_and_b32_e32 v45, 0xffff0000, v144
	v_lshlrev_b32_e32 v46, 16, v145
	v_and_b32_e32 v47, 0xffff0000, v145
	v_cvt_pk_bf16_f32 v42, v42, v43
	v_cvt_pk_bf16_f32 v43, v48, v49
	v_lshlrev_b32_e32 v48, 16, v146
	v_and_b32_e32 v49, 0xffff0000, v146
	v_pk_add_f32 v[38:39], v[38:39], v[46:47]
	v_pk_add_f32 v[36:37], v[36:37], v[44:45]
	v_lshlrev_b32_e32 v50, 16, v147
	v_and_b32_e32 v51, 0xffff0000, v147
	v_pk_add_f32 v[46:47], v[32:33], v[48:49]
	v_mul_f32_e32 v32, v37, v37
	v_mul_f32_e32 v33, v39, v39
	v_pk_add_f32 v[44:45], v[34:35], v[50:51]
	v_fmac_f32_e32 v32, v36, v36
	v_fmac_f32_e32 v33, v38, v38
	v_add_f32_e32 v32, v32, v33
	v_mul_f32_e32 v33, v47, v47
	v_mul_f32_e32 v34, v45, v45
	v_fmac_f32_e32 v33, v46, v46
	v_fmac_f32_e32 v34, v44, v44
	v_add_f32_e32 v33, v33, v34
	v_add_f32_e32 v32, v32, v33
	v_add_f32_e32 v35, v52, v32
	ds_bpermute_b32 v50, v248, v35
	v_lshl_add_u64 v[32:33], s[24:25], 0, v[218:219]
	v_lshl_add_u64 v[48:49], v[206:207], 1, v[32:33]
	v_cvt_pk_bf16_f32 v34, v36, v37
	v_cvt_pk_bf16_f32 v36, v46, v47
	s_waitcnt lgkmcnt(0)
	v_add_f32_e32 v32, v35, v50
	ds_bpermute_b32 v33, v249, v32
	v_cvt_pk_bf16_f32 v35, v38, v39
	v_cvt_pk_bf16_f32 v37, v44, v45
	global_store_dwordx4 v[48:49], v[40:43], off sc1
	global_store_dwordx4 v[48:49], v[34:37], off offset:256 sc1
	s_and_saveexec_b64 s[34:35], s[6:7]
	s_cbranch_execz .LBB0_997
	v_lshlrev_b64 v[34:35], 6, v[216:217]
	v_lshl_add_u64 v[34:35], s[26:27], 0, v[34:35]
	v_lshl_add_u64 v[34:35], s[30:31], 2, v[34:35]
	s_lshl_b32 s16, s45, 2
	v_lshl_add_u64 v[34:35], v[34:35], 0, s[16:17]
	s_waitcnt lgkmcnt(0)
	v_add_f32_e32 v32, v32, v33
	global_store_dword v[34:35], v32, off
.LBB0_997:
	s_or_b64 exec, exec, s[34:35]
	v_lshlrev_b32_e32 v32, 16, v132
	s_waitcnt lgkmcnt(0)
	v_and_b32_e32 v33, 0xffff0000, v132
	v_lshlrev_b32_e32 v34, 16, v133
	v_and_b32_e32 v35, 0xffff0000, v133
	v_lshlrev_b32_e32 v36, 16, v134
	v_and_b32_e32 v37, 0xffff0000, v134
	v_lshlrev_b32_e32 v38, 16, v135
	v_and_b32_e32 v39, 0xffff0000, v135
	v_pk_add_f32 v[30:31], v[30:31], v[34:35]
	v_pk_add_f32 v[28:29], v[28:29], v[32:33]
	v_pk_add_f32 v[32:33], v[26:27], v[38:39]
	v_pk_add_f32 v[26:27], v[24:25], v[36:37]
	v_mul_f32_e32 v24, v29, v29
	v_mul_f32_e32 v25, v31, v31
	v_fmac_f32_e32 v24, v28, v28
	v_fmac_f32_e32 v25, v30, v30
	v_add_f32_e32 v24, v24, v25
	v_mul_f32_e32 v25, v27, v27
	v_mul_f32_e32 v34, v33, v33
	v_fmac_f32_e32 v25, v26, v26
	v_fmac_f32_e32 v34, v32, v32
	v_add_f32_e32 v25, v25, v34
	v_add_f32_e32 v36, v24, v25
	v_cvt_pk_bf16_f32 v24, v28, v29
	v_cvt_pk_bf16_f32 v25, v30, v31
	v_lshlrev_b32_e32 v28, 16, v120
	v_and_b32_e32 v29, 0xffff0000, v120
	v_lshlrev_b32_e32 v30, 16, v121
	v_and_b32_e32 v31, 0xffff0000, v121
	v_cvt_pk_bf16_f32 v26, v26, v27
	v_cvt_pk_bf16_f32 v27, v32, v33
	v_lshlrev_b32_e32 v32, 16, v122
	v_and_b32_e32 v33, 0xffff0000, v122
	v_pk_add_f32 v[22:23], v[22:23], v[30:31]
	v_pk_add_f32 v[20:21], v[20:21], v[28:29]
	v_lshlrev_b32_e32 v34, 16, v123
	v_and_b32_e32 v35, 0xffff0000, v123
	v_pk_add_f32 v[30:31], v[16:17], v[32:33]
	v_mul_f32_e32 v16, v21, v21
	v_mul_f32_e32 v17, v23, v23
	v_pk_add_f32 v[28:29], v[18:19], v[34:35]
	v_fmac_f32_e32 v16, v20, v20
	v_fmac_f32_e32 v17, v22, v22
	v_add_f32_e32 v16, v16, v17
	v_mul_f32_e32 v17, v31, v31
	v_mul_f32_e32 v18, v29, v29
	v_fmac_f32_e32 v17, v30, v30
	v_fmac_f32_e32 v18, v28, v28
	v_add_f32_e32 v17, v17, v18
	v_add_f32_e32 v16, v16, v17
	v_add_f32_e32 v19, v36, v16
	ds_bpermute_b32 v34, v248, v19
	v_lshl_add_u64 v[16:17], s[24:25], 0, v[214:215]
	v_lshl_add_u64 v[32:33], v[206:207], 1, v[16:17]
	v_cvt_pk_bf16_f32 v18, v20, v21
	v_cvt_pk_bf16_f32 v20, v30, v31
	s_waitcnt lgkmcnt(0)
	v_add_f32_e32 v16, v19, v34
	ds_bpermute_b32 v17, v249, v16
	v_cvt_pk_bf16_f32 v19, v22, v23
	v_cvt_pk_bf16_f32 v21, v28, v29
	global_store_dwordx4 v[32:33], v[24:27], off sc1
	global_store_dwordx4 v[32:33], v[18:21], off offset:256 sc1
	s_and_saveexec_b64 s[34:35], s[6:7]
	s_cbranch_execz .LBB0_999
	v_lshlrev_b64 v[18:19], 6, v[212:213]
	v_lshl_add_u64 v[18:19], s[26:27], 0, v[18:19]
	v_lshl_add_u64 v[18:19], s[30:31], 2, v[18:19]
	s_lshl_b32 s16, s45, 2
	v_lshl_add_u64 v[18:19], v[18:19], 0, s[16:17]
	s_waitcnt lgkmcnt(0)
	v_add_f32_e32 v16, v16, v17
	global_store_dword v[18:19], v16, off
.LBB0_999:
	s_or_b64 exec, exec, s[34:35]
	v_lshlrev_b32_e32 v16, 16, v140
	s_waitcnt lgkmcnt(0)
	v_and_b32_e32 v17, 0xffff0000, v140
	v_lshlrev_b32_e32 v18, 16, v141
	v_and_b32_e32 v19, 0xffff0000, v141
	v_lshlrev_b32_e32 v20, 16, v142
	v_and_b32_e32 v21, 0xffff0000, v142
	v_lshlrev_b32_e32 v22, 16, v143
	v_and_b32_e32 v23, 0xffff0000, v143
	v_pk_add_f32 v[14:15], v[14:15], v[18:19]
	v_pk_add_f32 v[12:13], v[12:13], v[16:17]
	v_pk_add_f32 v[16:17], v[10:11], v[22:23]
	v_pk_add_f32 v[10:11], v[8:9], v[20:21]
	v_mul_f32_e32 v8, v13, v13
	v_mul_f32_e32 v9, v15, v15
	v_fmac_f32_e32 v8, v12, v12
	v_fmac_f32_e32 v9, v14, v14
	v_add_f32_e32 v8, v8, v9
	v_mul_f32_e32 v9, v11, v11
	v_mul_f32_e32 v18, v17, v17
	v_fmac_f32_e32 v9, v10, v10
	v_fmac_f32_e32 v18, v16, v16
	v_add_f32_e32 v9, v9, v18
	v_add_f32_e32 v20, v8, v9
	v_cvt_pk_bf16_f32 v8, v12, v13
	v_cvt_pk_bf16_f32 v9, v14, v15
	v_lshlrev_b32_e32 v12, 16, v124
	v_and_b32_e32 v13, 0xffff0000, v124
	v_lshlrev_b32_e32 v14, 16, v125
	v_and_b32_e32 v15, 0xffff0000, v125
	v_cvt_pk_bf16_f32 v10, v10, v11
	v_cvt_pk_bf16_f32 v11, v16, v17
	v_lshlrev_b32_e32 v16, 16, v126
	v_and_b32_e32 v17, 0xffff0000, v126
	v_pk_add_f32 v[6:7], v[6:7], v[14:15]
	v_pk_add_f32 v[4:5], v[4:5], v[12:13]
	v_lshlrev_b32_e32 v18, 16, v127
	v_and_b32_e32 v19, 0xffff0000, v127
	v_pk_add_f32 v[14:15], v[0:1], v[16:17]
	v_mul_f32_e32 v0, v5, v5
	v_mul_f32_e32 v1, v7, v7
	v_pk_add_f32 v[12:13], v[2:3], v[18:19]
	v_fmac_f32_e32 v0, v4, v4
	v_fmac_f32_e32 v1, v6, v6
	v_add_f32_e32 v0, v0, v1
	v_mul_f32_e32 v1, v15, v15
	v_mul_f32_e32 v2, v13, v13
	v_fmac_f32_e32 v1, v14, v14
	v_fmac_f32_e32 v2, v12, v12
	v_add_f32_e32 v1, v1, v2
	v_add_f32_e32 v0, v0, v1
	v_add_f32_e32 v3, v20, v0
	ds_bpermute_b32 v18, v248, v3
	v_lshl_add_u64 v[0:1], s[24:25], 0, v[210:211]
	v_lshl_add_u64 v[16:17], v[206:207], 1, v[0:1]
	v_cvt_pk_bf16_f32 v2, v4, v5
	v_cvt_pk_bf16_f32 v4, v14, v15
	s_waitcnt lgkmcnt(0)
	v_add_f32_e32 v0, v3, v18
	ds_bpermute_b32 v1, v249, v0
	v_cvt_pk_bf16_f32 v3, v6, v7
	v_cvt_pk_bf16_f32 v5, v12, v13
	global_store_dwordx4 v[16:17], v[8:11], off sc1
	global_store_dwordx4 v[16:17], v[2:5], off offset:256 sc1
	s_and_saveexec_b64 s[34:35], s[6:7]
	s_cbranch_execz .LBB0_972
	s_waitcnt lgkmcnt(0)
	v_add_f32_e32 v2, v0, v1
	v_lshlrev_b64 v[0:1], 6, v[208:209]
	v_lshl_add_u64 v[0:1], s[26:27], 0, v[0:1]
	v_lshl_add_u64 v[0:1], s[30:31], 2, v[0:1]
	s_lshl_b32 s16, s45, 2
	v_lshl_add_u64 v[0:1], v[0:1], 0, s[16:17]
	global_store_dword v[0:1], v2, off
	s_branch .LBB0_972

.LBB0_1238:
	v_add_u32_e32 v158, s37, v141
	v_lshl_or_b32 v156, s76, 8, v147
	ds_read2_b32 v[160:161], v148 offset1:16
	ds_read2_b32 v[162:163], v148 offset0:32 offset1:48
	ds_read2_b32 v[164:165], v148 offset0:64 offset1:80
	ds_read2_b32 v[142:143], v148 offset0:96 offset1:112
	v_ashrrev_i32_e32 v159, 31, v158
	v_ashrrev_i32_e32 v157, 31, v156
	v_lshlrev_b64 v[166:167], 11, v[158:159]
	s_waitcnt lgkmcnt(0)
	v_pk_mul_f32 v[154:155], v[126:127], v[160:161] op_sel_hi:[1,0]
	v_pk_mul_f32 v[152:153], v[124:125], v[160:161] op_sel_hi:[1,0]
	v_lshl_add_u64 v[124:125], s[14:15], 0, v[166:167]
	v_lshlrev_b64 v[126:127], 2, v[156:157]
	v_lshl_add_u64 v[124:125], v[124:125], 0, v[126:127]
	v_pk_mul_f32 v[110:111], v[110:111], v[160:161] op_sel_hi:[1,0]
	v_pk_mul_f32 v[108:109], v[108:109], v[160:161] op_sel_hi:[1,0]
	global_store_dwordx4 v[124:125], v[108:111], off offset:576 sc1
	v_pk_mul_f32 v[118:119], v[118:119], v[160:161] op_sel_hi:[1,0]
	v_pk_mul_f32 v[116:117], v[116:117], v[160:161] op_sel_hi:[1,0]
	v_or_b32_e32 v108, 16, v158
	v_ashrrev_i32_e32 v109, 31, v108
	global_store_dwordx4 v[124:125], v[116:119], off offset:512 sc1
	v_pk_mul_f32 v[78:79], v[78:79], v[162:163] op_sel_hi:[1,0]
	v_pk_mul_f32 v[76:77], v[76:77], v[162:163] op_sel_hi:[1,0]
	v_lshlrev_b64 v[116:117], 11, v[108:109]
	v_mov_b32_e32 v118, v161
	v_pk_mul_f32 v[108:109], v[112:113], v[118:119] op_sel_hi:[1,0]
	v_lshl_add_u64 v[112:113], s[14:15], 0, v[116:117]
	v_lshl_add_u64 v[112:113], v[112:113], 0, v[126:127]
	v_pk_mul_f32 v[94:95], v[94:95], v[118:119] op_sel_hi:[1,0]
	v_pk_mul_f32 v[92:93], v[92:93], v[118:119] op_sel_hi:[1,0]
	global_store_dwordx4 v[112:113], v[92:95], off offset:576 sc1
	v_pk_mul_f32 v[102:103], v[102:103], v[118:119] op_sel_hi:[1,0]
	v_pk_mul_f32 v[100:101], v[100:101], v[118:119] op_sel_hi:[1,0]
	v_or_b32_e32 v92, 32, v158
	v_ashrrev_i32_e32 v93, 31, v92
	global_store_dwordx4 v[112:113], v[100:103], off offset:512 sc1
	v_pk_mul_f32 v[86:87], v[86:87], v[162:163] op_sel_hi:[1,0]
	v_pk_mul_f32 v[84:85], v[84:85], v[162:163] op_sel_hi:[1,0]
	v_lshlrev_b64 v[100:101], 11, v[92:93]
	v_pk_mul_f32 v[92:93], v[96:97], v[162:163] op_sel_hi:[1,0]
	v_lshl_add_u64 v[96:97], s[14:15], 0, v[100:101]
	v_lshl_add_u64 v[96:97], v[96:97], 0, v[126:127]
	global_store_dwordx4 v[96:97], v[76:79], off offset:576 sc1
	global_store_dwordx4 v[96:97], v[84:87], off offset:512 sc1
	v_pk_mul_f32 v[50:51], v[50:51], v[164:165] op_sel_hi:[1,0]
	v_or_b32_e32 v76, 48, v158
	v_ashrrev_i32_e32 v77, 31, v76
	v_lshlrev_b64 v[84:85], 11, v[76:77]
	v_mov_b32_e32 v86, v163
	v_pk_mul_f32 v[76:77], v[80:81], v[86:87] op_sel_hi:[1,0]
	v_lshl_add_u64 v[80:81], s[14:15], 0, v[84:85]
	v_lshl_add_u64 v[80:81], v[80:81], 0, v[126:127]
	v_pk_mul_f32 v[66:67], v[66:67], v[86:87] op_sel_hi:[1,0]
	v_pk_mul_f32 v[64:65], v[64:65], v[86:87] op_sel_hi:[1,0]
	global_store_dwordx4 v[80:81], v[64:67], off offset:576 sc1
	v_pk_mul_f32 v[48:49], v[48:49], v[164:165] op_sel_hi:[1,0]
	v_pk_mul_f32 v[42:43], v[42:43], v[164:165] op_sel_hi:[1,0]
	v_lshl_add_u64 v[64:65], v[124:125], 0, s[12:13]
	v_add_co_u32_e32 v66, vcc, s71, v124
	global_store_dwordx4 v[64:65], v[48:51], off offset:512 sc1
	s_nop 0
	v_addc_co_u32_e32 v67, vcc, 0, v125, vcc
	v_pk_mul_f32 v[40:41], v[40:41], v[164:165] op_sel_hi:[1,0]
	v_mov_b32_e32 v48, v165
	global_store_dwordx4 v[64:65], v[40:43], off offset:576 sc1
	v_lshl_add_u64 v[50:51], v[124:125], 0, s[28:29]
	v_pk_mul_f32 v[34:35], v[34:35], v[48:49] op_sel_hi:[1,0]
	v_pk_mul_f32 v[40:41], v[52:53], v[48:49] op_sel_hi:[1,0]
	v_add_co_u32_e32 v52, vcc, s72, v124
	v_pk_mul_f32 v[32:33], v[32:33], v[48:49] op_sel_hi:[1,0]
	s_nop 0
	v_addc_co_u32_e32 v53, vcc, 0, v125, vcc
	global_store_dwordx4 v[50:51], v[32:35], off offset:512 sc1
	v_pk_mul_f32 v[18:19], v[18:19], v[142:143] op_sel_hi:[1,0]
	v_pk_mul_f32 v[16:17], v[16:17], v[142:143] op_sel_hi:[1,0]
	v_lshl_add_u64 v[32:33], v[124:125], 0, s[30:31]
	v_add_co_u32_e32 v34, vcc, s73, v124
	global_store_dwordx4 v[32:33], v[16:19], off offset:512 sc1
	s_nop 0
	v_addc_co_u32_e32 v35, vcc, 0, v125, vcc
	v_pk_mul_f32 v[10:11], v[10:11], v[142:143] op_sel_hi:[1,0]
	v_pk_mul_f32 v[8:9], v[8:9], v[142:143] op_sel_hi:[1,0]
	v_mov_b32_e32 v16, v143
	v_pk_mul_f32 v[26:27], v[26:27], v[48:49] op_sel_hi:[1,0]
	v_pk_mul_f32 v[24:25], v[24:25], v[48:49] op_sel_hi:[1,0]
	global_store_dwordx4 v[32:33], v[8:11], off offset:576 sc1
	v_pk_mul_f32 v[42:43], v[54:55], v[48:49] op_sel_hi:[1,0]
	global_store_dwordx4 v[50:51], v[24:27], off offset:576 sc1
	v_pk_mul_f32 v[8:9], v[20:21], v[16:17] op_sel_hi:[1,0]
	v_add_co_u32_e32 v20, vcc, s74, v124
	v_pk_mul_f32 v[26:27], v[38:39], v[142:143] op_sel_hi:[1,0]
	v_pk_mul_f32 v[24:25], v[36:37], v[142:143] op_sel_hi:[1,0]
	v_pk_mul_f32 v[10:11], v[22:23], v[16:17] op_sel_hi:[1,0]
	v_addc_co_u32_e32 v21, vcc, 0, v125, vcc
	v_pk_mul_f32 v[122:123], v[122:123], v[160:161] op_sel_hi:[1,0]
	v_pk_mul_f32 v[120:121], v[120:121], v[160:161] op_sel_hi:[1,0]
	v_pk_mul_f32 v[110:111], v[114:115], v[118:119] op_sel_hi:[1,0]
	v_pk_mul_f32 v[106:107], v[106:107], v[118:119] op_sel_hi:[1,0]
	v_pk_mul_f32 v[104:105], v[104:105], v[118:119] op_sel_hi:[1,0]
	v_pk_mul_f32 v[94:95], v[98:99], v[162:163] op_sel_hi:[1,0]
	v_pk_mul_f32 v[90:91], v[90:91], v[162:163] op_sel_hi:[1,0]
	v_pk_mul_f32 v[88:89], v[88:89], v[162:163] op_sel_hi:[1,0]
	v_pk_mul_f32 v[78:79], v[82:83], v[86:87] op_sel_hi:[1,0]
	v_pk_mul_f32 v[74:75], v[74:75], v[86:87] op_sel_hi:[1,0]
	v_pk_mul_f32 v[72:73], v[72:73], v[86:87] op_sel_hi:[1,0]
	v_pk_mul_f32 v[70:71], v[70:71], v[86:87] op_sel_hi:[1,0]
	v_pk_mul_f32 v[68:69], v[68:69], v[86:87] op_sel_hi:[1,0]
	v_pk_mul_f32 v[62:63], v[62:63], v[164:165] op_sel_hi:[1,0]
	v_pk_mul_f32 v[60:61], v[60:61], v[164:165] op_sel_hi:[1,0]
	v_pk_mul_f32 v[58:59], v[58:59], v[164:165] op_sel_hi:[1,0]
	v_pk_mul_f32 v[56:57], v[56:57], v[164:165] op_sel_hi:[1,0]
	global_store_dwordx4 v[52:53], v[40:43], off sc1
	global_store_dwordx4 v[34:35], v[24:27], off sc1
	v_lshl_add_u64 v[18:19], v[124:125], 0, s[34:35]
	v_pk_mul_f32 v[42:43], v[46:47], v[48:49] op_sel_hi:[1,0]
	v_pk_mul_f32 v[40:41], v[44:45], v[48:49] op_sel_hi:[1,0]
	v_pk_mul_f32 v[26:27], v[30:31], v[142:143] op_sel_hi:[1,0]
	v_pk_mul_f32 v[24:25], v[28:29], v[142:143] op_sel_hi:[1,0]
	global_store_dwordx4 v[20:21], v[8:11], off sc1
	v_pk_mul_f32 v[6:7], v[6:7], v[16:17] op_sel_hi:[1,0]
	v_pk_mul_f32 v[4:5], v[4:5], v[16:17] op_sel_hi:[1,0]
	v_pk_mul_f32 v[10:11], v[14:15], v[16:17] op_sel_hi:[1,0]
	v_pk_mul_f32 v[8:9], v[12:13], v[16:17] op_sel_hi:[1,0]
	v_pk_mul_f32 v[2:3], v[2:3], v[16:17] op_sel_hi:[1,0]
	v_pk_mul_f32 v[0:1], v[0:1], v[16:17] op_sel_hi:[1,0]
	s_and_b64 vcc, exec, s[6:7]
	s_mov_b32 s76, s36
	s_mov_b32 s44, s38
	s_mov_b64 s[46:47], s[42:43]
	s_mov_b64 s[8:9], s[40:41]
	global_store_dwordx4 v[124:125], v[152:155], off sc1
	global_store_dwordx4 v[124:125], v[120:123], off offset:64 sc1
	global_store_dwordx4 v[112:113], v[108:111], off sc1
	global_store_dwordx4 v[112:113], v[104:107], off offset:64 sc1
	global_store_dwordx4 v[96:97], v[92:95], off sc1
	global_store_dwordx4 v[96:97], v[88:91], off offset:64 sc1
	global_store_dwordx4 v[80:81], v[76:79], off sc1
	global_store_dwordx4 v[80:81], v[72:75], off offset:64 sc1
	global_store_dwordx4 v[80:81], v[68:71], off offset:512 sc1
	global_store_dwordx4 v[66:67], v[60:63], off sc1
	global_store_dwordx4 v[64:65], v[56:59], off offset:64 sc1
	global_store_dwordx4 v[50:51], v[40:43], off offset:64 sc1
	global_store_dwordx4 v[32:33], v[24:27], off offset:64 sc1
	global_store_dwordx4 v[18:19], v[8:11], off offset:64 sc1
	global_store_dwordx4 v[18:19], v[4:7], off offset:512 sc1
	global_store_dwordx4 v[18:19], v[0:3], off offset:576 sc1
	s_cbranch_vccnz .LBB0_1249

.LBB0_1409:
	s_or_b64 exec, exec, s[6:7]
	v_lshlrev_b32_e32 v155, 2, v148
	s_waitcnt lgkmcnt(0)
	v_or_b32_e32 v18, s48, v155
	v_lshlrev_b32_e32 v16, 2, v18
	s_waitcnt vmcnt(0)
	s_barrier
	global_load_dwordx4 v[156:159], v16, s[12:13]
	s_add_u32 s40, s36, 0x15000000
	ds_read_b128 v[20:23], v149
	ds_read_b128 v[138:141], v149 offset:16
	ds_read2_b64 v[142:145], v149 offset0:4 offset1:6
	s_addc_u32 s41, s37, 0
	s_add_u32 s36, s14, 0x15800000
	s_addc_u32 s37, s15, 0
	s_add_u32 s38, s10, 0x15c00000
	s_addc_u32 s39, s11, 0
	s_ashr_i32 s27, s26, 31
	s_waitcnt lgkmcnt(2)
	v_mov_b32_e32 v146, v20
	s_waitcnt lgkmcnt(0)
	v_mov_b32_e32 v147, v142
	v_mov_b32_e32 v142, v138
	v_mov_b32_e32 v143, v144
	v_mov_b32_e32 v129, 0
	v_pk_add_f32 v[20:21], v[20:21], v[138:139]
	v_add_f32_e32 v22, v22, v140
	s_lshl_b64 s[42:43], s[26:27], 8
	v_pk_add_f32 v[138:139], v[146:147], v[142:143]
	v_mov_b32_e32 v141, 0x358637bd
	s_mov_b32 s6, 0x3c800000
	v_mov_b32_e32 v17, v129
	v_mov_b32_e32 v19, v129
	v_pk_mov_b32 v[22:23], v[20:21], v[22:23] op_sel:[1,0]
	v_lshl_add_u64 v[20:21], s[42:43], 0, v[128:129]
	v_add_f32_e32 v129, v138, v139
	s_mov_b32 s49, 0x800000
	v_pk_mul_f32 v[22:23], v[22:23], s[6:7] op_sel_hi:[1,0]
	v_fmac_f32_e32 v141, 0x3c000000, v129
	v_fma_f32 v23, -v22, v22, v23
	v_mul_f32_e32 v129, 0x4b800000, v141
	v_cmp_gt_f32_e32 vcc, s49, v141
	s_cmp_lt_u32 s3, 2
	v_lshlrev_b64 v[138:139], 8, v[20:21]
	v_max_f32_e32 v23, 0, v23
	v_cndmask_b32_e32 v129, v141, v129, vcc
	v_lshlrev_b32_e32 v18, 1, v18
	s_cselect_b64 s[44:45], -1, 0
	s_cmp_gt_u32 s3, 1
	v_lshl_add_u64 v[138:139], s[40:41], 0, v[138:139]
	v_add_f32_e32 v23, 0x358637bd, v23
	v_rsq_f32_e32 v129, v129
	s_cselect_b64 s[14:15], -1, 0
	s_cmp_eq_u32 s3, 2
	v_lshl_add_u64 v[140:141], v[138:139], 0, v[18:19]
	v_mul_f32_e32 v138, 0x4b800000, v23
	v_cmp_gt_f32_e64 s[10:11], s49, v23
	s_cselect_b64 s[6:7], -1, 0
	v_cndmask_b32_e64 v19, 0, 1, s[6:7]
	v_cndmask_b32_e64 v23, v23, v138, s[10:11]
	v_rsq_f32_e32 v23, v23
	v_cmp_ne_u32_e64 s[6:7], 1, v19
	v_mul_f32_e32 v19, 0x45800000, v129
	v_cndmask_b32_e32 v144, v129, v19, vcc
	v_pk_mul_f32 v[146:147], v[136:137], v[144:145] op_sel_hi:[1,0]
	v_pk_mul_f32 v[160:161], v[134:135], v[144:145] op_sel_hi:[1,0]
	s_and_b64 s[8:9], exec, s[14:15]
	v_mul_f32_e32 v19, 0x45800000, v23
	s_mov_b64 s[46:47], -1
	v_lshlrev_b64 v[142:143], 7, v[20:21]
	v_cndmask_b32_e64 v138, v23, v19, s[10:11]
	s_mov_b64 vcc, s[8:9]
	s_waitcnt vmcnt(0)
	v_pk_mul_f32 v[158:159], v[158:159], v[160:161]
	v_pk_mul_f32 v[146:147], v[156:157], v[146:147]
	s_nop 0
	v_cvt_pk_bf16_f32 v146, v146, v147
	v_cvt_pk_bf16_f32 v147, v158, v159
	global_store_dwordx2 v[140:141], v[146:147], off
	s_cbranch_vccz .LBB0_1413
	s_and_b64 vcc, exec, s[6:7]
	s_cbranch_vccnz .LBB0_1412
	v_lshlrev_b64 v[20:21], 6, v[20:21]
	v_lshl_add_u64 v[20:21], s[38:39], 0, v[20:21]
	v_lshlrev_b32_e32 v146, 2, v155
	v_mov_b32_e32 v147, 0
	s_mov_b32 s8, 0x3d000000
	v_lshl_add_u64 v[20:21], v[20:21], 0, v[146:147]
	v_pk_mul_f32 v[158:159], v[124:125], s[8:9] op_sel_hi:[1,0]
	v_pk_mul_f32 v[156:157], v[126:127], s[8:9] op_sel_hi:[1,0]
	global_store_dwordx4 v[20:21], v[156:159], off sc1

.LBB0_1417:
	global_load_dwordx4 v[156:159], v[20:21], off
	v_or_b32_e32 v22, 16, v128
	v_mov_b32_e32 v23, 0
	v_lshl_add_u64 v[146:147], s[42:43], 0, v[22:23]
	v_lshl_add_u32 v22, v22, 6, 0
	ds_read_b128 v[138:141], v22
	ds_read_b128 v[160:163], v22 offset:16
	ds_read2_b64 v[164:167], v22 offset0:4 offset1:6
	v_cndmask_b32_e64 v129, 0, 1, s[14:15]
	v_mov_b32_e32 v17, 0x358637bd
	s_waitcnt lgkmcnt(2)
	v_mov_b32_e32 v142, v138
	s_waitcnt lgkmcnt(1)
	v_pk_add_f32 v[138:139], v[138:139], v[160:161]
	s_waitcnt lgkmcnt(0)
	v_mov_b32_e32 v143, v164
	v_mov_b32_e32 v164, v160
	v_mov_b32_e32 v165, v166
	v_add_f32_e32 v140, v140, v162
	v_pk_add_f32 v[142:143], v[142:143], v[164:165]
	s_mov_b32 s12, 0x3c800000
	v_cmp_ne_u32_e64 s[10:11], 1, v129
	v_pk_mov_b32 v[138:139], v[138:139], v[140:141] op_sel:[1,0]
	v_add_f32_e32 v129, v142, v143
	s_mov_b32 s27, 0x800000
	v_pk_mul_f32 v[138:139], v[138:139], s[12:13] op_sel_hi:[1,0]
	v_fmac_f32_e32 v17, 0x3c000000, v129
	v_fma_f32 v129, -v138, v138, v139
	v_mul_f32_e32 v139, 0x4b800000, v17
	v_cmp_gt_f32_e64 s[12:13], s27, v17
	v_max_f32_e32 v129, 0, v129
	v_add_f32_e32 v129, 0x358637bd, v129
	v_cndmask_b32_e64 v17, v17, v139, s[12:13]
	v_rsq_f32_e32 v17, v17
	s_andn2_b64 vcc, exec, s[14:15]
	v_mul_f32_e32 v139, 0x4b800000, v129
	v_cmp_gt_f32_e64 s[14:15], s27, v129
	v_mov_b32_e32 v19, v23
	v_lshlrev_b64 v[22:23], 8, v[146:147]
	v_cndmask_b32_e64 v129, v129, v139, s[14:15]
	v_lshl_add_u64 v[22:23], s[40:41], 0, v[22:23]
	v_rsq_f32_e32 v129, v129
	v_lshl_add_u64 v[140:141], v[22:23], 0, v[18:19]
	v_mul_f32_e32 v19, 0x45800000, v17
	v_cndmask_b32_e64 v142, v17, v19, s[12:13]
	v_pk_mul_f32 v[160:161], v[116:117], v[142:143] op_sel_hi:[1,0]
	v_pk_mul_f32 v[162:163], v[118:119], v[142:143] op_sel_hi:[1,0]
	v_mul_f32_e32 v17, 0x45800000, v129
	v_lshlrev_b64 v[144:145], 7, v[146:147]
	v_cndmask_b32_e64 v22, v129, v17, s[14:15]
	s_mov_b64 s[12:13], -1
	s_waitcnt vmcnt(0)
	v_pk_mul_f32 v[158:159], v[158:159], v[162:163]
	v_pk_mul_f32 v[156:157], v[156:157], v[160:161]
	s_nop 0
	v_cvt_pk_bf16_f32 v156, v156, v157
	v_cvt_pk_bf16_f32 v157, v158, v159
	global_store_dwordx2 v[140:141], v[156:157], off
	s_cbranch_vccnz .LBB0_1421
	s_and_b64 vcc, exec, s[6:7]
	s_cbranch_vccnz .LBB0_1420
	v_lshlrev_b64 v[146:147], 6, v[146:147]
	v_lshl_add_u64 v[146:147], s[38:39], 0, v[146:147]
	v_lshlrev_b32_e32 v156, 2, v155
	v_mov_b32_e32 v157, 0
	s_mov_b32 s12, 0x3d000000
	v_lshl_add_u64 v[146:147], v[146:147], 0, v[156:157]
	v_pk_mul_f32 v[158:159], v[108:109], s[12:13] op_sel_hi:[1,0]
	v_pk_mul_f32 v[156:157], v[110:111], s[12:13] op_sel_hi:[1,0]
	global_store_dwordx4 v[146:147], v[156:159], off sc1

.LBB0_1425:
	global_load_dwordx4 v[156:159], v[20:21], off
	v_or_b32_e32 v22, 32, v128
	v_mov_b32_e32 v23, 0
	v_lshl_add_u64 v[146:147], s[42:43], 0, v[22:23]
	v_lshl_add_u32 v22, v22, 6, 0
	ds_read_b128 v[138:141], v22
	ds_read_b128 v[160:163], v22 offset:16
	ds_read2_b64 v[164:167], v22 offset0:4 offset1:6
	v_mov_b32_e32 v17, 0x358637bd
	s_mov_b32 s12, 0x3c800000
	s_waitcnt lgkmcnt(2)
	v_mov_b32_e32 v142, v138
	s_waitcnt lgkmcnt(1)
	v_pk_add_f32 v[138:139], v[138:139], v[160:161]
	s_waitcnt lgkmcnt(0)
	v_mov_b32_e32 v143, v164
	v_mov_b32_e32 v164, v160
	v_mov_b32_e32 v165, v166
	v_add_f32_e32 v140, v140, v162
	v_pk_add_f32 v[142:143], v[142:143], v[164:165]
	v_pk_mov_b32 v[138:139], v[138:139], v[140:141] op_sel:[1,0]
	v_add_f32_e32 v129, v142, v143
	s_mov_b32 s14, 0x800000
	v_pk_mul_f32 v[138:139], v[138:139], s[12:13] op_sel_hi:[1,0]
	v_fmac_f32_e32 v17, 0x3c000000, v129
	v_fma_f32 v129, -v138, v138, v139
	v_mul_f32_e32 v139, 0x4b800000, v17
	v_cmp_gt_f32_e64 s[12:13], s14, v17
	v_max_f32_e32 v129, 0, v129
	v_add_f32_e32 v129, 0x358637bd, v129
	v_cndmask_b32_e64 v17, v17, v139, s[12:13]
	v_rsq_f32_e32 v17, v17
	v_mul_f32_e32 v139, 0x4b800000, v129
	v_cmp_gt_f32_e64 s[14:15], s14, v129
	v_mov_b32_e32 v19, v23
	v_lshlrev_b64 v[22:23], 8, v[146:147]
	v_cndmask_b32_e64 v129, v129, v139, s[14:15]
	v_lshl_add_u64 v[22:23], s[40:41], 0, v[22:23]
	v_rsq_f32_e32 v129, v129
	v_lshl_add_u64 v[140:141], v[22:23], 0, v[18:19]
	v_mul_f32_e32 v19, 0x45800000, v17
	v_cndmask_b32_e64 v142, v17, v19, s[12:13]
	v_pk_mul_f32 v[160:161], v[100:101], v[142:143] op_sel_hi:[1,0]
	v_pk_mul_f32 v[162:163], v[102:103], v[142:143] op_sel_hi:[1,0]
	v_mul_f32_e32 v17, 0x45800000, v129
	s_and_b64 vcc, exec, s[10:11]
	v_lshlrev_b64 v[144:145], 7, v[146:147]
	v_cndmask_b32_e64 v22, v129, v17, s[14:15]
	s_mov_b64 s[12:13], -1
	s_waitcnt vmcnt(0)
	v_pk_mul_f32 v[158:159], v[158:159], v[162:163]
	v_pk_mul_f32 v[156:157], v[156:157], v[160:161]
	s_nop 0
	v_cvt_pk_bf16_f32 v156, v156, v157
	v_cvt_pk_bf16_f32 v157, v158, v159
	global_store_dwordx2 v[140:141], v[156:157], off
	s_cbranch_vccnz .LBB0_1429
	s_and_b64 vcc, exec, s[6:7]
	s_cbranch_vccnz .LBB0_1428
	v_lshlrev_b64 v[146:147], 6, v[146:147]
	v_lshl_add_u64 v[146:147], s[38:39], 0, v[146:147]
	v_lshlrev_b32_e32 v156, 2, v155
	v_mov_b32_e32 v157, 0
	s_mov_b32 s12, 0x3d000000
	v_lshl_add_u64 v[146:147], v[146:147], 0, v[156:157]
	v_pk_mul_f32 v[158:159], v[92:93], s[12:13] op_sel_hi:[1,0]
	v_pk_mul_f32 v[156:157], v[94:95], s[12:13] op_sel_hi:[1,0]
	global_store_dwordx4 v[146:147], v[156:159], off sc1

.LBB0_1433:
	global_load_dwordx4 v[156:159], v[20:21], off
	v_or_b32_e32 v22, 48, v128
	v_mov_b32_e32 v23, 0
	v_lshl_add_u64 v[146:147], s[42:43], 0, v[22:23]
	v_lshl_add_u32 v22, v22, 6, 0
	ds_read_b128 v[138:141], v22
	ds_read_b128 v[160:163], v22 offset:16
	ds_read2_b64 v[164:167], v22 offset0:4 offset1:6
	v_mov_b32_e32 v17, 0x358637bd
	s_mov_b32 s12, 0x3c800000
	s_waitcnt lgkmcnt(2)
	v_mov_b32_e32 v142, v138
	s_waitcnt lgkmcnt(1)
	v_pk_add_f32 v[138:139], v[138:139], v[160:161]
	s_waitcnt lgkmcnt(0)
	v_mov_b32_e32 v143, v164
	v_mov_b32_e32 v164, v160
	v_mov_b32_e32 v165, v166
	v_add_f32_e32 v140, v140, v162
	v_pk_add_f32 v[142:143], v[142:143], v[164:165]
	v_pk_mov_b32 v[138:139], v[138:139], v[140:141] op_sel:[1,0]
	v_add_f32_e32 v129, v142, v143
	s_mov_b32 s14, 0x800000
	v_pk_mul_f32 v[138:139], v[138:139], s[12:13] op_sel_hi:[1,0]
	v_fmac_f32_e32 v17, 0x3c000000, v129
	v_fma_f32 v129, -v138, v138, v139
	v_mul_f32_e32 v139, 0x4b800000, v17
	v_cmp_gt_f32_e64 s[12:13], s14, v17
	v_max_f32_e32 v129, 0, v129
	v_add_f32_e32 v129, 0x358637bd, v129
	v_cndmask_b32_e64 v17, v17, v139, s[12:13]
	v_rsq_f32_e32 v17, v17
	v_mul_f32_e32 v139, 0x4b800000, v129
	v_cmp_gt_f32_e64 s[14:15], s14, v129
	v_mov_b32_e32 v19, v23
	v_lshlrev_b64 v[22:23], 8, v[146:147]
	v_cndmask_b32_e64 v129, v129, v139, s[14:15]
	v_lshl_add_u64 v[22:23], s[40:41], 0, v[22:23]
	v_rsq_f32_e32 v129, v129
	v_lshl_add_u64 v[140:141], v[22:23], 0, v[18:19]
	v_mul_f32_e32 v19, 0x45800000, v17
	v_cndmask_b32_e64 v142, v17, v19, s[12:13]
	v_pk_mul_f32 v[160:161], v[84:85], v[142:143] op_sel_hi:[1,0]
	v_pk_mul_f32 v[162:163], v[86:87], v[142:143] op_sel_hi:[1,0]
	v_mul_f32_e32 v17, 0x45800000, v129
	s_and_b64 vcc, exec, s[10:11]
	v_lshlrev_b64 v[144:145], 7, v[146:147]
	v_cndmask_b32_e64 v22, v129, v17, s[14:15]
	s_mov_b64 s[12:13], -1
	s_waitcnt vmcnt(0)
	v_pk_mul_f32 v[158:159], v[158:159], v[162:163]
	v_pk_mul_f32 v[156:157], v[156:157], v[160:161]
	s_nop 0
	v_cvt_pk_bf16_f32 v156, v156, v157
	v_cvt_pk_bf16_f32 v157, v158, v159
	global_store_dwordx2 v[140:141], v[156:157], off
	s_cbranch_vccnz .LBB0_1437
	s_and_b64 vcc, exec, s[6:7]
	s_cbranch_vccnz .LBB0_1436
	v_lshlrev_b64 v[146:147], 6, v[146:147]
	v_lshl_add_u64 v[146:147], s[38:39], 0, v[146:147]
	v_lshlrev_b32_e32 v156, 2, v155
	v_mov_b32_e32 v157, 0
	s_mov_b32 s12, 0x3d000000
	v_lshl_add_u64 v[146:147], v[146:147], 0, v[156:157]
	v_pk_mul_f32 v[158:159], v[76:77], s[12:13] op_sel_hi:[1,0]
	v_pk_mul_f32 v[156:157], v[78:79], s[12:13] op_sel_hi:[1,0]
	global_store_dwordx4 v[146:147], v[156:159], off sc1

.LBB0_1441:
	global_load_dwordx4 v[156:159], v[20:21], off
	v_add_u32_e32 v22, 0x80, v128
	v_mov_b32_e32 v23, 0
	v_lshl_add_u64 v[146:147], s[42:43], 0, v[22:23]
	v_lshl_add_u32 v22, v22, 6, 0
	ds_read_b128 v[138:141], v22
	ds_read_b128 v[160:163], v22 offset:16
	ds_read2_b64 v[164:167], v22 offset0:4 offset1:6
	v_mov_b32_e32 v17, 0x358637bd
	s_mov_b32 s12, 0x3c800000
	s_waitcnt lgkmcnt(2)
	v_mov_b32_e32 v142, v138
	s_waitcnt lgkmcnt(1)
	v_pk_add_f32 v[138:139], v[138:139], v[160:161]
	s_waitcnt lgkmcnt(0)
	v_mov_b32_e32 v143, v164
	v_mov_b32_e32 v164, v160
	v_mov_b32_e32 v165, v166
	v_add_f32_e32 v140, v140, v162
	v_pk_add_f32 v[142:143], v[142:143], v[164:165]
	v_pk_mov_b32 v[138:139], v[138:139], v[140:141] op_sel:[1,0]
	v_add_f32_e32 v129, v142, v143
	s_mov_b32 s14, 0x800000
	v_pk_mul_f32 v[138:139], v[138:139], s[12:13] op_sel_hi:[1,0]
	v_fmac_f32_e32 v17, 0x3c000000, v129
	v_fma_f32 v129, -v138, v138, v139
	v_mul_f32_e32 v139, 0x4b800000, v17
	v_cmp_gt_f32_e64 s[12:13], s14, v17
	v_max_f32_e32 v129, 0, v129
	v_add_f32_e32 v129, 0x358637bd, v129
	v_cndmask_b32_e64 v17, v17, v139, s[12:13]
	v_rsq_f32_e32 v17, v17
	v_mul_f32_e32 v139, 0x4b800000, v129
	v_cmp_gt_f32_e64 s[14:15], s14, v129
	v_mov_b32_e32 v19, v23
	v_lshlrev_b64 v[22:23], 8, v[146:147]
	v_cndmask_b32_e64 v129, v129, v139, s[14:15]
	v_lshl_add_u64 v[22:23], s[40:41], 0, v[22:23]
	v_rsq_f32_e32 v129, v129
	v_lshl_add_u64 v[140:141], v[22:23], 0, v[18:19]
	v_mul_f32_e32 v19, 0x45800000, v17
	v_cndmask_b32_e64 v142, v17, v19, s[12:13]
	v_pk_mul_f32 v[160:161], v[70:71], v[142:143] op_sel_hi:[1,0]
	v_pk_mul_f32 v[162:163], v[68:69], v[142:143] op_sel_hi:[1,0]
	v_mul_f32_e32 v17, 0x45800000, v129
	s_and_b64 vcc, exec, s[10:11]
	v_lshlrev_b64 v[144:145], 7, v[146:147]
	v_cndmask_b32_e64 v22, v129, v17, s[14:15]
	s_mov_b64 s[12:13], -1
	s_waitcnt vmcnt(0)
	v_pk_mul_f32 v[158:159], v[158:159], v[162:163]
	v_pk_mul_f32 v[156:157], v[156:157], v[160:161]
	s_nop 0
	v_cvt_pk_bf16_f32 v156, v156, v157
	v_cvt_pk_bf16_f32 v157, v158, v159
	global_store_dwordx2 v[140:141], v[156:157], off
	s_cbranch_vccnz .LBB0_1445
	s_and_b64 vcc, exec, s[6:7]
	s_cbranch_vccnz .LBB0_1444
	v_lshlrev_b64 v[146:147], 6, v[146:147]
	v_lshl_add_u64 v[146:147], s[38:39], 0, v[146:147]
	v_lshlrev_b32_e32 v156, 2, v155
	v_mov_b32_e32 v157, 0
	s_mov_b32 s12, 0x3d000000
	v_lshl_add_u64 v[146:147], v[146:147], 0, v[156:157]
	v_pk_mul_f32 v[158:159], v[60:61], s[12:13] op_sel_hi:[1,0]
	v_pk_mul_f32 v[156:157], v[62:63], s[12:13] op_sel_hi:[1,0]
	global_store_dwordx4 v[146:147], v[156:159], off sc1

.LBB0_1449:
	global_load_dwordx4 v[156:159], v[20:21], off
	v_add_u32_e32 v22, 0x90, v128
	v_mov_b32_e32 v23, 0
	v_lshl_add_u64 v[146:147], s[42:43], 0, v[22:23]
	v_lshl_add_u32 v22, v22, 6, 0
	ds_read_b128 v[138:141], v22
	ds_read_b128 v[160:163], v22 offset:16
	ds_read2_b64 v[164:167], v22 offset0:4 offset1:6
	v_mov_b32_e32 v17, 0x358637bd
	s_mov_b32 s12, 0x3c800000
	s_waitcnt lgkmcnt(2)
	v_mov_b32_e32 v142, v138
	s_waitcnt lgkmcnt(1)
	v_pk_add_f32 v[138:139], v[138:139], v[160:161]
	s_waitcnt lgkmcnt(0)
	v_mov_b32_e32 v143, v164
	v_mov_b32_e32 v164, v160
	v_mov_b32_e32 v165, v166
	v_add_f32_e32 v140, v140, v162
	v_pk_add_f32 v[142:143], v[142:143], v[164:165]
	v_pk_mov_b32 v[138:139], v[138:139], v[140:141] op_sel:[1,0]
	v_add_f32_e32 v129, v142, v143
	s_mov_b32 s14, 0x800000
	v_pk_mul_f32 v[138:139], v[138:139], s[12:13] op_sel_hi:[1,0]
	v_fmac_f32_e32 v17, 0x3c000000, v129
	v_fma_f32 v129, -v138, v138, v139
	v_mul_f32_e32 v139, 0x4b800000, v17
	v_cmp_gt_f32_e64 s[12:13], s14, v17
	v_max_f32_e32 v129, 0, v129
	v_add_f32_e32 v129, 0x358637bd, v129
	v_cndmask_b32_e64 v17, v17, v139, s[12:13]
	v_rsq_f32_e32 v17, v17
	v_mul_f32_e32 v139, 0x4b800000, v129
	v_cmp_gt_f32_e64 s[14:15], s14, v129
	v_mov_b32_e32 v19, v23
	v_lshlrev_b64 v[22:23], 8, v[146:147]
	v_cndmask_b32_e64 v129, v129, v139, s[14:15]
	v_lshl_add_u64 v[22:23], s[40:41], 0, v[22:23]
	v_rsq_f32_e32 v129, v129
	v_lshl_add_u64 v[140:141], v[22:23], 0, v[18:19]
	v_mul_f32_e32 v19, 0x45800000, v17
	v_cndmask_b32_e64 v142, v17, v19, s[12:13]
	v_pk_mul_f32 v[160:161], v[52:53], v[142:143] op_sel_hi:[1,0]
	v_pk_mul_f32 v[162:163], v[54:55], v[142:143] op_sel_hi:[1,0]
	v_mul_f32_e32 v17, 0x45800000, v129
	s_and_b64 vcc, exec, s[10:11]
	v_lshlrev_b64 v[144:145], 7, v[146:147]
	v_cndmask_b32_e64 v22, v129, v17, s[14:15]
	s_mov_b64 s[12:13], -1
	s_waitcnt vmcnt(0)
	v_pk_mul_f32 v[158:159], v[158:159], v[162:163]
	v_pk_mul_f32 v[156:157], v[156:157], v[160:161]
	s_nop 0
	v_cvt_pk_bf16_f32 v156, v156, v157
	v_cvt_pk_bf16_f32 v157, v158, v159
	global_store_dwordx2 v[140:141], v[156:157], off
	s_cbranch_vccnz .LBB0_1453
	s_and_b64 vcc, exec, s[6:7]
	s_cbranch_vccnz .LBB0_1452
	v_lshlrev_b64 v[146:147], 6, v[146:147]
	v_lshl_add_u64 v[146:147], s[38:39], 0, v[146:147]
	v_lshlrev_b32_e32 v156, 2, v155
	v_mov_b32_e32 v157, 0
	s_mov_b32 s12, 0x3d000000
	v_lshl_add_u64 v[146:147], v[146:147], 0, v[156:157]
	v_pk_mul_f32 v[158:159], v[44:45], s[12:13] op_sel_hi:[1,0]
	v_pk_mul_f32 v[156:157], v[46:47], s[12:13] op_sel_hi:[1,0]
	global_store_dwordx4 v[146:147], v[156:159], off sc1

.LBB0_1457:
	global_load_dwordx4 v[156:159], v[20:21], off
	v_add_u32_e32 v22, 0xa0, v128
	v_mov_b32_e32 v23, 0
	v_lshl_add_u64 v[146:147], s[42:43], 0, v[22:23]
	v_lshl_add_u32 v22, v22, 6, 0
	ds_read_b128 v[138:141], v22
	ds_read_b128 v[160:163], v22 offset:16
	ds_read2_b64 v[164:167], v22 offset0:4 offset1:6
	v_mov_b32_e32 v17, 0x358637bd
	s_mov_b32 s12, 0x3c800000
	s_waitcnt lgkmcnt(2)
	v_mov_b32_e32 v142, v138
	s_waitcnt lgkmcnt(1)
	v_pk_add_f32 v[138:139], v[138:139], v[160:161]
	s_waitcnt lgkmcnt(0)
	v_mov_b32_e32 v143, v164
	v_mov_b32_e32 v164, v160
	v_mov_b32_e32 v165, v166
	v_add_f32_e32 v140, v140, v162
	v_pk_add_f32 v[142:143], v[142:143], v[164:165]
	v_pk_mov_b32 v[138:139], v[138:139], v[140:141] op_sel:[1,0]
	v_add_f32_e32 v129, v142, v143
	s_mov_b32 s14, 0x800000
	v_pk_mul_f32 v[138:139], v[138:139], s[12:13] op_sel_hi:[1,0]
	v_fmac_f32_e32 v17, 0x3c000000, v129
	v_fma_f32 v129, -v138, v138, v139
	v_mul_f32_e32 v139, 0x4b800000, v17
	v_cmp_gt_f32_e64 s[12:13], s14, v17
	v_max_f32_e32 v129, 0, v129
	v_add_f32_e32 v129, 0x358637bd, v129
	v_cndmask_b32_e64 v17, v17, v139, s[12:13]
	v_rsq_f32_e32 v17, v17
	v_mul_f32_e32 v139, 0x4b800000, v129
	v_cmp_gt_f32_e64 s[14:15], s14, v129
	v_mov_b32_e32 v19, v23
	v_lshlrev_b64 v[22:23], 8, v[146:147]
	v_cndmask_b32_e64 v129, v129, v139, s[14:15]
	v_lshl_add_u64 v[22:23], s[40:41], 0, v[22:23]
	v_rsq_f32_e32 v129, v129
	v_lshl_add_u64 v[140:141], v[22:23], 0, v[18:19]
	v_mul_f32_e32 v19, 0x45800000, v17
	v_cndmask_b32_e64 v142, v17, v19, s[12:13]
	v_pk_mul_f32 v[160:161], v[36:37], v[142:143] op_sel_hi:[1,0]
	v_pk_mul_f32 v[162:163], v[38:39], v[142:143] op_sel_hi:[1,0]
	v_mul_f32_e32 v17, 0x45800000, v129
	s_and_b64 vcc, exec, s[10:11]
	v_lshlrev_b64 v[144:145], 7, v[146:147]
	v_cndmask_b32_e64 v22, v129, v17, s[14:15]
	s_mov_b64 s[12:13], -1
	s_waitcnt vmcnt(0)
	v_pk_mul_f32 v[158:159], v[158:159], v[162:163]
	v_pk_mul_f32 v[156:157], v[156:157], v[160:161]
	s_nop 0
	v_cvt_pk_bf16_f32 v156, v156, v157
	v_cvt_pk_bf16_f32 v157, v158, v159
	global_store_dwordx2 v[140:141], v[156:157], off
	s_cbranch_vccnz .LBB0_1461
	s_and_b64 vcc, exec, s[6:7]
	s_cbranch_vccnz .LBB0_1460
	v_lshlrev_b64 v[146:147], 6, v[146:147]
	v_lshl_add_u64 v[146:147], s[38:39], 0, v[146:147]
	v_lshlrev_b32_e32 v156, 2, v155
	v_mov_b32_e32 v157, 0
	s_mov_b32 s12, 0x3d000000
	v_lshl_add_u64 v[146:147], v[146:147], 0, v[156:157]
	v_pk_mul_f32 v[158:159], v[28:29], s[12:13] op_sel_hi:[1,0]
	v_pk_mul_f32 v[156:157], v[30:31], s[12:13] op_sel_hi:[1,0]
	global_store_dwordx4 v[146:147], v[156:159], off sc1

.LBB0_1465:
	global_load_dwordx4 v[156:159], v[20:21], off
	v_add_u32_e32 v22, 0xb0, v128
	v_mov_b32_e32 v23, 0
	v_lshl_add_u64 v[146:147], s[42:43], 0, v[22:23]
	v_lshl_add_u32 v22, v22, 6, 0
	ds_read_b128 v[138:141], v22
	ds_read_b128 v[160:163], v22 offset:16
	ds_read2_b64 v[164:167], v22 offset0:4 offset1:6
	v_mov_b32_e32 v17, 0x358637bd
	s_mov_b32 s13, 0x800000
	s_waitcnt lgkmcnt(2)
	v_mov_b32_e32 v142, v138
	s_waitcnt lgkmcnt(1)
	v_pk_add_f32 v[138:139], v[138:139], v[160:161]
	s_waitcnt lgkmcnt(0)
	v_mov_b32_e32 v143, v164
	v_mov_b32_e32 v164, v160
	v_mov_b32_e32 v165, v166
	v_add_f32_e32 v140, v140, v162
	v_pk_add_f32 v[142:143], v[142:143], v[164:165]
	s_mov_b32 s12, 0x3c800000
	v_pk_mov_b32 v[138:139], v[138:139], v[140:141] op_sel:[1,0]
	v_add_f32_e32 v129, v142, v143
	v_pk_mul_f32 v[138:139], v[138:139], s[12:13] op_sel_hi:[1,0]
	v_fmac_f32_e32 v17, 0x3c000000, v129
	s_and_b64 vcc, exec, s[10:11]
	v_fma_f32 v129, -v138, v138, v139
	v_mul_f32_e32 v139, 0x4b800000, v17
	v_cmp_gt_f32_e64 s[10:11], s13, v17
	v_max_f32_e32 v129, 0, v129
	v_add_f32_e32 v129, 0x358637bd, v129
	v_cndmask_b32_e64 v17, v17, v139, s[10:11]
	v_rsq_f32_e32 v17, v17
	v_mul_f32_e32 v139, 0x4b800000, v129
	v_cmp_gt_f32_e64 s[12:13], s13, v129
	v_mov_b32_e32 v19, v23
	v_lshlrev_b64 v[22:23], 8, v[146:147]
	v_cndmask_b32_e64 v129, v129, v139, s[12:13]
	v_lshl_add_u64 v[22:23], s[40:41], 0, v[22:23]
	v_rsq_f32_e32 v129, v129
	v_lshl_add_u64 v[140:141], v[22:23], 0, v[18:19]
	v_mul_f32_e32 v19, 0x45800000, v17
	v_cndmask_b32_e64 v142, v17, v19, s[10:11]
	v_pk_mul_f32 v[160:161], v[14:15], v[142:143] op_sel_hi:[1,0]
	v_pk_mul_f32 v[162:163], v[10:11], v[142:143] op_sel_hi:[1,0]
	v_mul_f32_e32 v17, 0x45800000, v129
	v_lshlrev_b64 v[144:145], 7, v[146:147]
	v_cndmask_b32_e64 v22, v129, v17, s[12:13]
	s_mov_b64 s[10:11], -1
	s_waitcnt vmcnt(0)
	v_pk_mul_f32 v[158:159], v[158:159], v[162:163]
	v_pk_mul_f32 v[156:157], v[156:157], v[160:161]
	s_nop 0
	v_cvt_pk_bf16_f32 v156, v156, v157
	v_cvt_pk_bf16_f32 v157, v158, v159
	global_store_dwordx2 v[140:141], v[156:157], off
	s_cbranch_vccnz .LBB0_1469
	s_and_b64 vcc, exec, s[6:7]
	s_cbranch_vccnz .LBB0_1468
	v_lshlrev_b64 v[146:147], 6, v[146:147]
	v_lshl_add_u64 v[146:147], s[38:39], 0, v[146:147]
	v_lshlrev_b32_e32 v156, 2, v155
	v_mov_b32_e32 v157, 0
	s_mov_b32 s6, 0x3d000000
	v_lshl_add_u64 v[146:147], v[146:147], 0, v[156:157]
	v_pk_mul_f32 v[158:159], v[6:7], s[6:7] op_sel_hi:[1,0]
	v_pk_mul_f32 v[156:157], v[4:5], s[6:7] op_sel_hi:[1,0]
	global_store_dwordx4 v[146:147], v[156:159], off sc1

.LBB0_1554:
	s_ashr_i32 s31, s30, 31
	s_lshl_b64 s[34:35], s[30:31], 17
	s_add_u32 s34, s45, s34
	s_addc_u32 s35, s46, s35
	ds_read_b128 v[18:21], v15
	ds_read_b128 v[22:25], v15 offset:1024
	ds_read_b128 v[26:29], v15 offset:2048
	ds_read_b128 v[30:33], v15 offset:3072
	s_and_b64 s[36:37], s[8:9], exec
	s_cselect_b32 s43, s35, s39
	s_cselect_b32 s42, s34, s38
	s_ashr_i32 s29, s28, 31
	s_lshl_b64 s[36:37], s[28:29], 17
	s_add_u32 s36, s47, s36
	s_addc_u32 s37, s48, s37
	s_and_b64 s[8:9], s[8:9], exec
	s_cselect_b32 s9, s37, s41
	s_cselect_b32 s8, s36, s40
	s_add_u32 s72, s38, 0x10080
	s_addc_u32 s73, s39, 0
	s_mov_b32 m0, s65
	v_lshl_add_u64 v[66:67], s[72:73], 0, v[6:7]
	ds_read_b128 v[34:37], v16
	ds_read_b128 v[38:41], v16 offset:1024
	ds_read_b128 v[42:45], v16 offset:2048
	ds_read_b128 v[46:49], v16 offset:3072
	ds_read_b128 v[50:53], v16 offset:4096
	ds_read_b128 v[54:57], v16 offset:5120
	ds_read_b128 v[58:61], v16 offset:6144
	ds_read_b128 v[62:65], v16 offset:7168
	global_load_lds_dwordx4 v[66:67], off
	v_lshl_add_u64 v[66:67], s[72:73], 0, v[2:3]
	s_mov_b32 m0, s66
	s_nop 0
	global_load_lds_dwordx4 v[66:67], off
	s_waitcnt lgkmcnt(8)
	s_barrier
	s_waitcnt lgkmcnt(0)
	s_setprio 1
	s_waitcnt lgkmcnt(0)
	v_mfma_f32_16x16x32_bf16 v[66:69], v[18:21], v[34:37], 0
	v_mfma_f32_16x16x32_bf16 v[70:73], v[26:29], v[34:37], 0
	v_mfma_f32_16x16x32_bf16 v[74:77], v[18:21], v[42:45], 0
	v_mfma_f32_16x16x32_bf16 v[78:81], v[26:29], v[42:45], 0
	v_mfma_f32_16x16x32_bf16 v[82:85], v[18:21], v[50:53], 0
	v_mfma_f32_16x16x32_bf16 v[86:89], v[26:29], v[50:53], 0
	v_mfma_f32_16x16x32_bf16 v[90:93], v[18:21], v[58:61], 0
	v_mfma_f32_16x16x32_bf16 v[94:97], v[26:29], v[58:61], 0
	v_mfma_f32_16x16x32_bf16 v[66:69], v[22:25], v[38:41], v[66:69]
	v_mfma_f32_16x16x32_bf16 v[70:73], v[30:33], v[38:41], v[70:73]
	v_mfma_f32_16x16x32_bf16 v[74:77], v[22:25], v[46:49], v[74:77]
	v_mfma_f32_16x16x32_bf16 v[78:81], v[30:33], v[46:49], v[78:81]
	v_mfma_f32_16x16x32_bf16 v[82:85], v[22:25], v[54:57], v[82:85]
	v_mfma_f32_16x16x32_bf16 v[86:89], v[30:33], v[54:57], v[86:89]
	v_mfma_f32_16x16x32_bf16 v[90:93], v[22:25], v[62:65], v[90:93]
	v_mfma_f32_16x16x32_bf16 v[94:97], v[30:33], v[62:65], v[94:97]
	s_setprio 0
	s_barrier
	v_lshl_add_u64 v[190:191], s[40:41], 0, v[4:5]
	s_mov_b32 m0, s67
	v_lshl_add_u64 v[114:115], v[190:191], 0, s[14:15]
	v_lshl_add_u64 v[214:215], s[40:41], 0, v[0:1]
	ds_read_b128 v[98:101], v17
	ds_read_b128 v[102:105], v17 offset:1024
	ds_read_b128 v[106:109], v17 offset:2048
	ds_read_b128 v[110:113], v17 offset:3072
	global_load_lds_dwordx4 v[114:115], off
	v_lshl_add_u64 v[114:115], v[214:215], 0, s[14:15]
	s_mov_b32 m0, s68
	s_nop 0
	global_load_lds_dwordx4 v[114:115], off
	s_barrier
	s_waitcnt lgkmcnt(0)
	s_setprio 1
	s_waitcnt lgkmcnt(0)
	v_mfma_f32_16x16x32_bf16 v[114:117], v[98:101], v[34:37], 0
	v_mfma_f32_16x16x32_bf16 v[34:37], v[106:109], v[34:37], 0
	v_mfma_f32_16x16x32_bf16 v[114:117], v[102:105], v[38:41], v[114:117]
	v_mfma_f32_16x16x32_bf16 v[34:37], v[110:113], v[38:41], v[34:37]
	v_mfma_f32_16x16x32_bf16 v[38:41], v[98:101], v[42:45], 0
	v_mfma_f32_16x16x32_bf16 v[42:45], v[106:109], v[42:45], 0
	v_mfma_f32_16x16x32_bf16 v[38:41], v[102:105], v[46:49], v[38:41]
	v_mfma_f32_16x16x32_bf16 v[42:45], v[110:113], v[46:49], v[42:45]
	v_mfma_f32_16x16x32_bf16 v[46:49], v[98:101], v[50:53], 0
	v_mfma_f32_16x16x32_bf16 v[50:53], v[106:109], v[50:53], 0
	v_mfma_f32_16x16x32_bf16 v[46:49], v[102:105], v[54:57], v[46:49]
	v_mfma_f32_16x16x32_bf16 v[50:53], v[110:113], v[54:57], v[50:53]
	v_mfma_f32_16x16x32_bf16 v[54:57], v[98:101], v[58:61], 0
	v_mfma_f32_16x16x32_bf16 v[58:61], v[106:109], v[58:61], 0
	v_mfma_f32_16x16x32_bf16 v[54:57], v[102:105], v[62:65], v[54:57]
	v_mfma_f32_16x16x32_bf16 v[58:61], v[110:113], v[62:65], v[58:61]
	s_setprio 0
	v_lshl_add_u64 v[216:217], s[38:39], 0, v[6:7]
	s_mov_b32 m0, s27
	v_lshl_add_u64 v[146:147], v[216:217], 0, s[14:15]
	v_lshl_add_u64 v[218:219], s[38:39], 0, v[2:3]
	s_barrier
	ds_read_b128 v[62:65], v16 offset:16384
	ds_read_b128 v[118:121], v16 offset:17408
	ds_read_b128 v[122:125], v16 offset:18432
	ds_read_b128 v[126:129], v16 offset:19456
	ds_read_b128 v[130:133], v16 offset:20480
	ds_read_b128 v[134:137], v16 offset:21504
	ds_read_b128 v[138:141], v16 offset:22528
	ds_read_b128 v[142:145], v16 offset:23552
	global_load_lds_dwordx4 v[146:147], off
	v_lshl_add_u64 v[146:147], v[218:219], 0, s[14:15]
	s_mov_b32 m0, s51
	s_nop 0
	global_load_lds_dwordx4 v[146:147], off
	s_barrier
	s_waitcnt lgkmcnt(0)
	s_setprio 1
	s_waitcnt lgkmcnt(0)
	v_mfma_f32_16x16x32_bf16 v[146:149], v[18:21], v[62:65], 0
	v_mfma_f32_16x16x32_bf16 v[154:157], v[18:21], v[122:125], 0
	v_mfma_f32_16x16x32_bf16 v[162:165], v[18:21], v[130:133], 0
	v_mfma_f32_16x16x32_bf16 v[18:21], v[18:21], v[138:141], 0
	v_mfma_f32_16x16x32_bf16 v[146:149], v[22:25], v[118:121], v[146:149]
	v_mfma_f32_16x16x32_bf16 v[150:153], v[26:29], v[62:65], 0
	v_mfma_f32_16x16x32_bf16 v[154:157], v[22:25], v[126:129], v[154:157]
	v_mfma_f32_16x16x32_bf16 v[158:161], v[26:29], v[122:125], 0
	v_mfma_f32_16x16x32_bf16 v[162:165], v[22:25], v[134:137], v[162:165]
	v_mfma_f32_16x16x32_bf16 v[166:169], v[26:29], v[130:133], 0
	v_mfma_f32_16x16x32_bf16 v[18:21], v[22:25], v[142:145], v[18:21]
	v_mfma_f32_16x16x32_bf16 v[22:25], v[26:29], v[138:141], 0
	v_mfma_f32_16x16x32_bf16 v[150:153], v[30:33], v[118:121], v[150:153]
	v_mfma_f32_16x16x32_bf16 v[158:161], v[30:33], v[126:129], v[158:161]
	v_mfma_f32_16x16x32_bf16 v[166:169], v[30:33], v[134:137], v[166:169]
	v_mfma_f32_16x16x32_bf16 v[22:25], v[30:33], v[142:145], v[22:25]
	s_setprio 0
	s_barrier
	s_add_u32 s72, s40, 0x10100
	s_addc_u32 s73, s41, 0
	s_mov_b32 m0, s69
	v_lshl_add_u64 v[26:27], s[72:73], 0, v[4:5]
	s_add_i32 s3, s69, 0x2000
	global_load_lds_dwordx4 v[26:27], off
	v_lshl_add_u64 v[26:27], s[72:73], 0, v[0:1]
	s_mov_b32 m0, s3
	s_nop 0
	global_load_lds_dwordx4 v[26:27], off
	s_waitcnt vmcnt(6)
	s_barrier
	s_setprio 1
	v_mfma_f32_16x16x32_bf16 v[26:29], v[98:101], v[62:65], 0
	v_mfma_f32_16x16x32_bf16 v[30:33], v[106:109], v[62:65], 0
	v_mfma_f32_16x16x32_bf16 v[26:29], v[102:105], v[118:121], v[26:29]
	v_mfma_f32_16x16x32_bf16 v[30:33], v[110:113], v[118:121], v[30:33]
	v_mfma_f32_16x16x32_bf16 v[62:65], v[98:101], v[122:125], 0
	v_mfma_f32_16x16x32_bf16 v[118:121], v[106:109], v[122:125], 0
	v_mfma_f32_16x16x32_bf16 v[122:125], v[98:101], v[130:133], 0
	v_mfma_f32_16x16x32_bf16 v[98:101], v[98:101], v[138:141], 0
	v_mfma_f32_16x16x32_bf16 v[62:65], v[102:105], v[126:129], v[62:65]
	v_mfma_f32_16x16x32_bf16 v[118:121], v[110:113], v[126:129], v[118:121]
	v_mfma_f32_16x16x32_bf16 v[122:125], v[102:105], v[134:137], v[122:125]
	v_mfma_f32_16x16x32_bf16 v[126:129], v[106:109], v[130:133], 0
	v_mfma_f32_16x16x32_bf16 v[98:101], v[102:105], v[142:145], v[98:101]
	v_mfma_f32_16x16x32_bf16 v[102:105], v[106:109], v[138:141], 0
	v_mfma_f32_16x16x32_bf16 v[126:129], v[110:113], v[134:137], v[126:129]
	v_mfma_f32_16x16x32_bf16 v[102:105], v[110:113], v[142:145], v[102:105]
	s_setprio 0
	s_add_i32 s71, 0, 0x18000
	v_add_u32_e32 v193, s71, v13
	s_barrier
	ds_read_b128 v[106:109], v193
	ds_read_b128 v[110:113], v193 offset:1024
	ds_read_b128 v[130:133], v193 offset:2048
	ds_read_b128 v[134:137], v193 offset:3072
	s_add_u32 s72, s38, 0x10100
	s_addc_u32 s73, s39, 0
	s_mov_b32 m0, s52
	v_lshl_add_u64 v[198:199], s[72:73], 0, v[6:7]
	ds_read_b128 v[138:141], v16 offset:32768
	ds_read_b128 v[142:145], v16 offset:33792
	ds_read_b128 v[170:173], v16 offset:34816
	ds_read_b128 v[174:177], v16 offset:35840
	ds_read_b128 v[178:181], v16 offset:36864
	ds_read_b128 v[182:185], v16 offset:37888
	ds_read_b128 v[186:189], v16 offset:38912
	ds_read_b128 v[194:197], v16 offset:39936
	global_load_lds_dwordx4 v[198:199], off
	v_lshl_add_u64 v[198:199], s[72:73], 0, v[2:3]
	s_mov_b32 m0, s53
	s_nop 0
	global_load_lds_dwordx4 v[198:199], off
	s_waitcnt lgkmcnt(8)
	s_barrier
	s_waitcnt lgkmcnt(0)
	s_setprio 1
	s_waitcnt lgkmcnt(0)
	v_mfma_f32_16x16x32_bf16 v[66:69], v[106:109], v[138:141], v[66:69]
	v_mfma_f32_16x16x32_bf16 v[70:73], v[130:133], v[138:141], v[70:73]
	v_mfma_f32_16x16x32_bf16 v[74:77], v[106:109], v[170:173], v[74:77]
	v_mfma_f32_16x16x32_bf16 v[78:81], v[130:133], v[170:173], v[78:81]
	v_mfma_f32_16x16x32_bf16 v[82:85], v[106:109], v[178:181], v[82:85]
	v_mfma_f32_16x16x32_bf16 v[86:89], v[130:133], v[178:181], v[86:89]
	v_mfma_f32_16x16x32_bf16 v[90:93], v[106:109], v[186:189], v[90:93]
	v_mfma_f32_16x16x32_bf16 v[94:97], v[130:133], v[186:189], v[94:97]
	v_mfma_f32_16x16x32_bf16 v[66:69], v[110:113], v[142:145], v[66:69]
	v_mfma_f32_16x16x32_bf16 v[70:73], v[134:137], v[142:145], v[70:73]
	v_mfma_f32_16x16x32_bf16 v[74:77], v[110:113], v[174:177], v[74:77]
	v_mfma_f32_16x16x32_bf16 v[78:81], v[134:137], v[174:177], v[78:81]
	v_mfma_f32_16x16x32_bf16 v[82:85], v[110:113], v[182:185], v[82:85]
	v_mfma_f32_16x16x32_bf16 v[86:89], v[134:137], v[182:185], v[86:89]
	v_mfma_f32_16x16x32_bf16 v[90:93], v[110:113], v[194:197], v[90:93]
	v_mfma_f32_16x16x32_bf16 v[94:97], v[134:137], v[194:197], v[94:97]
	s_setprio 0
	s_barrier
	s_add_i32 s31, 0, 0x1c000
	s_add_i32 s71, s71, s49
	v_add_u32_e32 v220, s31, v13
	v_lshl_add_u64 v[190:191], v[190:191], 0, s[16:17]
	s_mov_b32 m0, s71
	s_add_i32 s29, s71, 0x2000
	ds_read_b128 v[198:201], v220
	ds_read_b128 v[202:205], v220 offset:1024
	ds_read_b128 v[206:209], v220 offset:2048
	ds_read_b128 v[210:213], v220 offset:3072
	global_load_lds_dwordx4 v[190:191], off
	v_lshl_add_u64 v[190:191], v[214:215], 0, s[16:17]
	s_mov_b32 m0, s29
	s_nop 0
	global_load_lds_dwordx4 v[190:191], off
	s_barrier
	s_waitcnt lgkmcnt(0)
	s_setprio 1
	s_waitcnt lgkmcnt(0)
	v_mfma_f32_16x16x32_bf16 v[114:117], v[198:201], v[138:141], v[114:117]
	v_mfma_f32_16x16x32_bf16 v[34:37], v[206:209], v[138:141], v[34:37]
	v_mfma_f32_16x16x32_bf16 v[38:41], v[198:201], v[170:173], v[38:41]
	v_mfma_f32_16x16x32_bf16 v[42:45], v[206:209], v[170:173], v[42:45]
	v_mfma_f32_16x16x32_bf16 v[46:49], v[198:201], v[178:181], v[46:49]
	v_mfma_f32_16x16x32_bf16 v[50:53], v[206:209], v[178:181], v[50:53]
	v_mfma_f32_16x16x32_bf16 v[54:57], v[198:201], v[186:189], v[54:57]
	v_mfma_f32_16x16x32_bf16 v[58:61], v[206:209], v[186:189], v[58:61]
	v_mfma_f32_16x16x32_bf16 v[114:117], v[202:205], v[142:145], v[114:117]
	v_mfma_f32_16x16x32_bf16 v[34:37], v[210:213], v[142:145], v[34:37]
	v_mfma_f32_16x16x32_bf16 v[38:41], v[202:205], v[174:177], v[38:41]
	v_mfma_f32_16x16x32_bf16 v[42:45], v[210:213], v[174:177], v[42:45]
	v_mfma_f32_16x16x32_bf16 v[46:49], v[202:205], v[182:185], v[46:49]
	v_mfma_f32_16x16x32_bf16 v[50:53], v[210:213], v[182:185], v[50:53]
	v_mfma_f32_16x16x32_bf16 v[54:57], v[202:205], v[194:197], v[54:57]
	v_mfma_f32_16x16x32_bf16 v[58:61], v[210:213], v[194:197], v[58:61]
	s_setprio 0
	s_mov_b32 m0, s56
	v_lshl_add_u64 v[190:191], v[216:217], 0, s[16:17]
	s_barrier
	ds_read_b128 v[138:141], v16 offset:49152
	ds_read_b128 v[142:145], v16 offset:50176
	ds_read_b128 v[170:173], v16 offset:51200
	ds_read_b128 v[174:177], v16 offset:52224
	ds_read_b128 v[178:181], v16 offset:53248
	ds_read_b128 v[182:185], v16 offset:54272
	ds_read_b128 v[186:189], v16 offset:55296
	ds_read_b128 v[194:197], v16 offset:56320
	global_load_lds_dwordx4 v[190:191], off
	v_lshl_add_u64 v[190:191], v[218:219], 0, s[16:17]
	s_mov_b32 m0, s57
	s_nop 0
	global_load_lds_dwordx4 v[190:191], off
	s_barrier
	s_waitcnt lgkmcnt(0)
	s_setprio 1
	s_waitcnt lgkmcnt(0)
	v_mfma_f32_16x16x32_bf16 v[146:149], v[106:109], v[138:141], v[146:149]
	v_mfma_f32_16x16x32_bf16 v[150:153], v[130:133], v[138:141], v[150:153]
	v_mfma_f32_16x16x32_bf16 v[154:157], v[106:109], v[170:173], v[154:157]
	v_mfma_f32_16x16x32_bf16 v[158:161], v[130:133], v[170:173], v[158:161]
	v_mfma_f32_16x16x32_bf16 v[162:165], v[106:109], v[178:181], v[162:165]
	v_mfma_f32_16x16x32_bf16 v[166:169], v[130:133], v[178:181], v[166:169]
	v_mfma_f32_16x16x32_bf16 v[18:21], v[106:109], v[186:189], v[18:21]
	v_mfma_f32_16x16x32_bf16 v[22:25], v[130:133], v[186:189], v[22:25]
	v_mfma_f32_16x16x32_bf16 v[146:149], v[110:113], v[142:145], v[146:149]
	v_mfma_f32_16x16x32_bf16 v[150:153], v[134:137], v[142:145], v[150:153]
	v_mfma_f32_16x16x32_bf16 v[154:157], v[110:113], v[174:177], v[154:157]
	v_mfma_f32_16x16x32_bf16 v[158:161], v[134:137], v[174:177], v[158:161]
	v_mfma_f32_16x16x32_bf16 v[162:165], v[110:113], v[182:185], v[162:165]
	v_mfma_f32_16x16x32_bf16 v[166:169], v[134:137], v[182:185], v[166:169]
	v_mfma_f32_16x16x32_bf16 v[18:21], v[110:113], v[194:197], v[18:21]
	v_mfma_f32_16x16x32_bf16 v[22:25], v[134:137], v[194:197], v[22:25]
	s_setprio 0
	s_barrier
	s_add_u32 s72, s40, 0x10180
	s_addc_u32 s73, s41, 0
	s_add_i32 s40, s31, s49
	v_lshl_add_u64 v[106:107], s[72:73], 0, v[4:5]
	s_mov_b32 m0, s40
	s_add_i32 s31, s40, 0x2000
	global_load_lds_dwordx4 v[106:107], off
	v_lshl_add_u64 v[106:107], s[72:73], 0, v[0:1]
	s_mov_b32 m0, s31
	s_nop 0
	global_load_lds_dwordx4 v[106:107], off
	s_waitcnt vmcnt(6)
	s_barrier
	s_setprio 1
	v_mfma_f32_16x16x32_bf16 v[26:29], v[198:201], v[138:141], v[26:29]
	v_mfma_f32_16x16x32_bf16 v[30:33], v[206:209], v[138:141], v[30:33]
	v_mfma_f32_16x16x32_bf16 v[62:65], v[198:201], v[170:173], v[62:65]
	v_mfma_f32_16x16x32_bf16 v[106:109], v[206:209], v[170:173], v[118:121]
	v_mfma_f32_16x16x32_bf16 v[110:113], v[198:201], v[178:181], v[122:125]
	v_mfma_f32_16x16x32_bf16 v[118:121], v[206:209], v[178:181], v[126:129]
	v_mfma_f32_16x16x32_bf16 v[98:101], v[198:201], v[186:189], v[98:101]
	v_mfma_f32_16x16x32_bf16 v[102:105], v[206:209], v[186:189], v[102:105]
	v_mfma_f32_16x16x32_bf16 v[26:29], v[202:205], v[142:145], v[26:29]
	v_mfma_f32_16x16x32_bf16 v[30:33], v[210:213], v[142:145], v[30:33]
	v_mfma_f32_16x16x32_bf16 v[62:65], v[202:205], v[174:177], v[62:65]
	v_mfma_f32_16x16x32_bf16 v[106:109], v[210:213], v[174:177], v[106:109]
	v_mfma_f32_16x16x32_bf16 v[110:113], v[202:205], v[182:185], v[110:113]
	v_mfma_f32_16x16x32_bf16 v[118:121], v[210:213], v[182:185], v[118:121]
	v_mfma_f32_16x16x32_bf16 v[98:101], v[202:205], v[194:197], v[98:101]
	v_mfma_f32_16x16x32_bf16 v[102:105], v[210:213], v[194:197], v[102:105]
	s_setprio 0
	s_barrier
	ds_read_b128 v[122:125], v15
	ds_read_b128 v[126:129], v15 offset:1024
	ds_read_b128 v[130:133], v15 offset:2048
	ds_read_b128 v[134:137], v15 offset:3072
	s_add_u32 s38, s38, 0x10180
	s_addc_u32 s39, s39, 0
	s_mov_b32 m0, s65
	v_lshl_add_u64 v[190:191], s[38:39], 0, v[6:7]
	ds_read_b128 v[138:141], v16
	ds_read_b128 v[142:145], v16 offset:1024
	ds_read_b128 v[170:173], v16 offset:2048
	ds_read_b128 v[174:177], v16 offset:3072
	ds_read_b128 v[178:181], v16 offset:4096
	ds_read_b128 v[182:185], v16 offset:5120
	ds_read_b128 v[186:189], v16 offset:6144
	ds_read_b128 v[194:197], v16 offset:7168
	global_load_lds_dwordx4 v[190:191], off
	v_lshl_add_u64 v[190:191], s[38:39], 0, v[2:3]
	s_mov_b32 m0, s66
	s_nop 0
	global_load_lds_dwordx4 v[190:191], off
	s_waitcnt lgkmcnt(8)
	s_barrier
	s_waitcnt lgkmcnt(0)
	s_setprio 1
	s_waitcnt lgkmcnt(0)
	v_mfma_f32_16x16x32_bf16 v[66:69], v[122:125], v[138:141], v[66:69]
	v_mfma_f32_16x16x32_bf16 v[70:73], v[130:133], v[138:141], v[70:73]
	v_mfma_f32_16x16x32_bf16 v[74:77], v[122:125], v[170:173], v[74:77]
	v_mfma_f32_16x16x32_bf16 v[78:81], v[130:133], v[170:173], v[78:81]
	v_mfma_f32_16x16x32_bf16 v[82:85], v[122:125], v[178:181], v[82:85]
	v_mfma_f32_16x16x32_bf16 v[86:89], v[130:133], v[178:181], v[86:89]
	v_mfma_f32_16x16x32_bf16 v[90:93], v[122:125], v[186:189], v[90:93]
	v_mfma_f32_16x16x32_bf16 v[94:97], v[130:133], v[186:189], v[94:97]
	v_mfma_f32_16x16x32_bf16 v[66:69], v[126:129], v[142:145], v[66:69]
	v_mfma_f32_16x16x32_bf16 v[70:73], v[134:137], v[142:145], v[70:73]
	v_mfma_f32_16x16x32_bf16 v[74:77], v[126:129], v[174:177], v[74:77]
	v_mfma_f32_16x16x32_bf16 v[78:81], v[134:137], v[174:177], v[78:81]
	v_mfma_f32_16x16x32_bf16 v[82:85], v[126:129], v[182:185], v[82:85]
	v_mfma_f32_16x16x32_bf16 v[86:89], v[134:137], v[182:185], v[86:89]
	v_mfma_f32_16x16x32_bf16 v[90:93], v[126:129], v[194:197], v[90:93]
	v_mfma_f32_16x16x32_bf16 v[94:97], v[134:137], v[194:197], v[94:97]
	s_setprio 0
	s_barrier
	s_mov_b32 m0, s67
	v_lshl_add_u64 v[190:191], s[8:9], 0, v[4:5]
	ds_read_b128 v[198:201], v17
	ds_read_b128 v[202:205], v17 offset:1024
	ds_read_b128 v[206:209], v17 offset:2048
	ds_read_b128 v[210:213], v17 offset:3072
	global_load_lds_dwordx4 v[190:191], off
	v_lshl_add_u64 v[214:215], s[8:9], 0, v[0:1]
	s_mov_b32 m0, s68
	s_nop 0
	global_load_lds_dwordx4 v[214:215], off
	s_barrier
	s_waitcnt lgkmcnt(0)
	s_setprio 1
	s_waitcnt lgkmcnt(0)
	v_mfma_f32_16x16x32_bf16 v[114:117], v[198:201], v[138:141], v[114:117]
	v_mfma_f32_16x16x32_bf16 v[34:37], v[206:209], v[138:141], v[34:37]
	v_mfma_f32_16x16x32_bf16 v[38:41], v[198:201], v[170:173], v[38:41]
	v_mfma_f32_16x16x32_bf16 v[42:45], v[206:209], v[170:173], v[42:45]
	v_mfma_f32_16x16x32_bf16 v[46:49], v[198:201], v[178:181], v[46:49]
	v_mfma_f32_16x16x32_bf16 v[50:53], v[206:209], v[178:181], v[50:53]
	v_mfma_f32_16x16x32_bf16 v[54:57], v[198:201], v[186:189], v[54:57]
	v_mfma_f32_16x16x32_bf16 v[58:61], v[206:209], v[186:189], v[58:61]
	v_mfma_f32_16x16x32_bf16 v[114:117], v[202:205], v[142:145], v[114:117]
	v_mfma_f32_16x16x32_bf16 v[34:37], v[210:213], v[142:145], v[34:37]
	v_mfma_f32_16x16x32_bf16 v[38:41], v[202:205], v[174:177], v[38:41]
	v_mfma_f32_16x16x32_bf16 v[42:45], v[210:213], v[174:177], v[42:45]
	v_mfma_f32_16x16x32_bf16 v[46:49], v[202:205], v[182:185], v[46:49]
	v_mfma_f32_16x16x32_bf16 v[50:53], v[210:213], v[182:185], v[50:53]
	v_mfma_f32_16x16x32_bf16 v[54:57], v[202:205], v[194:197], v[54:57]
	v_mfma_f32_16x16x32_bf16 v[58:61], v[210:213], v[194:197], v[58:61]
	s_setprio 0
	s_mov_b32 m0, s27
	v_lshl_add_u64 v[216:217], s[42:43], 0, v[6:7]
	s_barrier
	ds_read_b128 v[138:141], v16 offset:16384
	ds_read_b128 v[142:145], v16 offset:17408
	ds_read_b128 v[170:173], v16 offset:18432
	ds_read_b128 v[174:177], v16 offset:19456
	ds_read_b128 v[178:181], v16 offset:20480
	ds_read_b128 v[182:185], v16 offset:21504
	ds_read_b128 v[186:189], v16 offset:22528
	ds_read_b128 v[194:197], v16 offset:23552
	global_load_lds_dwordx4 v[216:217], off
	v_lshl_add_u64 v[218:219], s[42:43], 0, v[2:3]
	s_mov_b32 m0, s51
	s_nop 0
	global_load_lds_dwordx4 v[218:219], off
	s_barrier
	s_waitcnt lgkmcnt(0)
	s_setprio 1
	s_waitcnt lgkmcnt(0)
	v_mfma_f32_16x16x32_bf16 v[146:149], v[122:125], v[138:141], v[146:149]
	v_mfma_f32_16x16x32_bf16 v[150:153], v[130:133], v[138:141], v[150:153]
	v_mfma_f32_16x16x32_bf16 v[154:157], v[122:125], v[170:173], v[154:157]
	v_mfma_f32_16x16x32_bf16 v[158:161], v[130:133], v[170:173], v[158:161]
	v_mfma_f32_16x16x32_bf16 v[162:165], v[122:125], v[178:181], v[162:165]
	v_mfma_f32_16x16x32_bf16 v[166:169], v[130:133], v[178:181], v[166:169]
	v_mfma_f32_16x16x32_bf16 v[18:21], v[122:125], v[186:189], v[18:21]
	v_mfma_f32_16x16x32_bf16 v[22:25], v[130:133], v[186:189], v[22:25]
	v_mfma_f32_16x16x32_bf16 v[146:149], v[126:129], v[142:145], v[146:149]
	v_mfma_f32_16x16x32_bf16 v[150:153], v[134:137], v[142:145], v[150:153]
	v_mfma_f32_16x16x32_bf16 v[154:157], v[126:129], v[174:177], v[154:157]
	v_mfma_f32_16x16x32_bf16 v[158:161], v[134:137], v[174:177], v[158:161]
	v_mfma_f32_16x16x32_bf16 v[162:165], v[126:129], v[182:185], v[162:165]
	v_mfma_f32_16x16x32_bf16 v[166:169], v[134:137], v[182:185], v[166:169]
	v_mfma_f32_16x16x32_bf16 v[18:21], v[126:129], v[194:197], v[18:21]
	v_mfma_f32_16x16x32_bf16 v[22:25], v[134:137], v[194:197], v[22:25]
	s_setprio 0
	s_barrier
	s_add_u32 s38, s8, 0x10000
	s_addc_u32 s39, s9, 0
	s_mov_b32 m0, s69
	v_lshl_add_u64 v[122:123], s[38:39], 0, v[4:5]
	global_load_lds_dwordx4 v[122:123], off
	v_lshl_add_u64 v[122:123], s[38:39], 0, v[0:1]
	s_mov_b32 m0, s3
	s_nop 0
	global_load_lds_dwordx4 v[122:123], off
	s_waitcnt vmcnt(6)
	s_barrier
	s_setprio 1
	v_mfma_f32_16x16x32_bf16 v[26:29], v[198:201], v[138:141], v[26:29]
	v_mfma_f32_16x16x32_bf16 v[30:33], v[206:209], v[138:141], v[30:33]
	v_mfma_f32_16x16x32_bf16 v[62:65], v[198:201], v[170:173], v[62:65]
	v_mfma_f32_16x16x32_bf16 v[106:109], v[206:209], v[170:173], v[106:109]
	v_mfma_f32_16x16x32_bf16 v[110:113], v[198:201], v[178:181], v[110:113]
	v_mfma_f32_16x16x32_bf16 v[118:121], v[206:209], v[178:181], v[118:121]
	v_mfma_f32_16x16x32_bf16 v[98:101], v[198:201], v[186:189], v[98:101]
	v_mfma_f32_16x16x32_bf16 v[102:105], v[206:209], v[186:189], v[102:105]
	v_mfma_f32_16x16x32_bf16 v[26:29], v[202:205], v[142:145], v[26:29]
	v_mfma_f32_16x16x32_bf16 v[30:33], v[210:213], v[142:145], v[30:33]
	v_mfma_f32_16x16x32_bf16 v[62:65], v[202:205], v[174:177], v[62:65]
	v_mfma_f32_16x16x32_bf16 v[106:109], v[210:213], v[174:177], v[106:109]
	v_mfma_f32_16x16x32_bf16 v[110:113], v[202:205], v[182:185], v[110:113]
	v_mfma_f32_16x16x32_bf16 v[118:121], v[210:213], v[182:185], v[118:121]
	v_mfma_f32_16x16x32_bf16 v[98:101], v[202:205], v[194:197], v[98:101]
	v_mfma_f32_16x16x32_bf16 v[102:105], v[210:213], v[194:197], v[102:105]
	s_setprio 0
	s_barrier
	ds_read_b128 v[122:125], v193
	ds_read_b128 v[126:129], v193 offset:1024
	ds_read_b128 v[130:133], v193 offset:2048
	ds_read_b128 v[134:137], v193 offset:3072
	s_add_u32 s38, s42, 0x10000
	s_addc_u32 s39, s43, 0
	s_mov_b32 m0, s52
	v_lshl_add_u64 v[198:199], s[38:39], 0, v[6:7]
	ds_read_b128 v[138:141], v16 offset:32768
	ds_read_b128 v[142:145], v16 offset:33792
	ds_read_b128 v[170:173], v16 offset:34816
	ds_read_b128 v[174:177], v16 offset:35840
	ds_read_b128 v[178:181], v16 offset:36864
	ds_read_b128 v[182:185], v16 offset:37888
	ds_read_b128 v[186:189], v16 offset:38912
	ds_read_b128 v[194:197], v16 offset:39936
	global_load_lds_dwordx4 v[198:199], off
	v_lshl_add_u64 v[198:199], s[38:39], 0, v[2:3]
	s_mov_b32 m0, s53
	s_nop 0
	global_load_lds_dwordx4 v[198:199], off
	s_waitcnt lgkmcnt(8)
	s_barrier
	s_waitcnt lgkmcnt(0)
	s_setprio 1
	s_waitcnt lgkmcnt(0)
	v_mfma_f32_16x16x32_bf16 v[66:69], v[122:125], v[138:141], v[66:69]
	v_mfma_f32_16x16x32_bf16 v[70:73], v[130:133], v[138:141], v[70:73]
	v_mfma_f32_16x16x32_bf16 v[74:77], v[122:125], v[170:173], v[74:77]
	v_mfma_f32_16x16x32_bf16 v[78:81], v[130:133], v[170:173], v[78:81]
	v_mfma_f32_16x16x32_bf16 v[82:85], v[122:125], v[178:181], v[82:85]
	v_mfma_f32_16x16x32_bf16 v[86:89], v[130:133], v[178:181], v[86:89]
	v_mfma_f32_16x16x32_bf16 v[90:93], v[122:125], v[186:189], v[90:93]
	v_mfma_f32_16x16x32_bf16 v[94:97], v[130:133], v[186:189], v[94:97]
	v_mfma_f32_16x16x32_bf16 v[66:69], v[126:129], v[142:145], v[66:69]
	v_mfma_f32_16x16x32_bf16 v[70:73], v[134:137], v[142:145], v[70:73]
	v_mfma_f32_16x16x32_bf16 v[74:77], v[126:129], v[174:177], v[74:77]
	v_mfma_f32_16x16x32_bf16 v[78:81], v[134:137], v[174:177], v[78:81]
	v_mfma_f32_16x16x32_bf16 v[82:85], v[126:129], v[182:185], v[82:85]
	v_mfma_f32_16x16x32_bf16 v[86:89], v[134:137], v[182:185], v[86:89]
	v_mfma_f32_16x16x32_bf16 v[90:93], v[126:129], v[194:197], v[90:93]
	v_mfma_f32_16x16x32_bf16 v[94:97], v[134:137], v[194:197], v[94:97]
	s_setprio 0
	s_barrier
	s_mov_b32 m0, s71
	v_lshl_add_u64 v[190:191], v[190:191], 0, s[12:13]
	ds_read_b128 v[198:201], v220
	ds_read_b128 v[202:205], v220 offset:1024
	ds_read_b128 v[206:209], v220 offset:2048
	ds_read_b128 v[210:213], v220 offset:3072
	global_load_lds_dwordx4 v[190:191], off
	v_lshl_add_u64 v[190:191], v[214:215], 0, s[12:13]
	s_mov_b32 m0, s29
	s_nop 0
	global_load_lds_dwordx4 v[190:191], off
	s_barrier
	s_waitcnt lgkmcnt(0)
	s_setprio 1
	s_waitcnt lgkmcnt(0)
	v_mfma_f32_16x16x32_bf16 v[114:117], v[198:201], v[138:141], v[114:117]
	v_mfma_f32_16x16x32_bf16 v[34:37], v[206:209], v[138:141], v[34:37]
	v_mfma_f32_16x16x32_bf16 v[38:41], v[198:201], v[170:173], v[38:41]
	v_mfma_f32_16x16x32_bf16 v[42:45], v[206:209], v[170:173], v[42:45]
	v_mfma_f32_16x16x32_bf16 v[46:49], v[198:201], v[178:181], v[46:49]
	v_mfma_f32_16x16x32_bf16 v[50:53], v[206:209], v[178:181], v[50:53]
	v_mfma_f32_16x16x32_bf16 v[54:57], v[198:201], v[186:189], v[54:57]
	v_mfma_f32_16x16x32_bf16 v[58:61], v[206:209], v[186:189], v[58:61]
	v_mfma_f32_16x16x32_bf16 v[114:117], v[202:205], v[142:145], v[114:117]
	v_mfma_f32_16x16x32_bf16 v[34:37], v[210:213], v[142:145], v[34:37]
	v_mfma_f32_16x16x32_bf16 v[38:41], v[202:205], v[174:177], v[38:41]
	v_mfma_f32_16x16x32_bf16 v[42:45], v[210:213], v[174:177], v[42:45]
	v_mfma_f32_16x16x32_bf16 v[46:49], v[202:205], v[182:185], v[46:49]
	v_mfma_f32_16x16x32_bf16 v[50:53], v[210:213], v[182:185], v[50:53]
	v_mfma_f32_16x16x32_bf16 v[54:57], v[202:205], v[194:197], v[54:57]
	v_mfma_f32_16x16x32_bf16 v[58:61], v[210:213], v[194:197], v[58:61]
	s_setprio 0
	s_mov_b32 m0, s56
	v_lshl_add_u64 v[190:191], v[216:217], 0, s[12:13]
	s_barrier
	ds_read_b128 v[138:141], v16 offset:49152
	ds_read_b128 v[142:145], v16 offset:50176
	ds_read_b128 v[170:173], v16 offset:51200
	ds_read_b128 v[174:177], v16 offset:52224
	ds_read_b128 v[178:181], v16 offset:53248
	ds_read_b128 v[182:185], v16 offset:54272
	ds_read_b128 v[186:189], v16 offset:55296
	ds_read_b128 v[194:197], v16 offset:56320
	global_load_lds_dwordx4 v[190:191], off
	v_lshl_add_u64 v[190:191], v[218:219], 0, s[12:13]
	s_mov_b32 m0, s57
	s_nop 0
	global_load_lds_dwordx4 v[190:191], off
	s_barrier
	s_waitcnt lgkmcnt(0)
	s_setprio 1
	s_waitcnt lgkmcnt(0)
	v_mfma_f32_16x16x32_bf16 v[146:149], v[122:125], v[138:141], v[146:149]
	v_mfma_f32_16x16x32_bf16 v[150:153], v[130:133], v[138:141], v[150:153]
	v_mfma_f32_16x16x32_bf16 v[154:157], v[122:125], v[170:173], v[154:157]
	v_mfma_f32_16x16x32_bf16 v[158:161], v[130:133], v[170:173], v[158:161]
	v_mfma_f32_16x16x32_bf16 v[162:165], v[122:125], v[178:181], v[162:165]
	v_mfma_f32_16x16x32_bf16 v[166:169], v[130:133], v[178:181], v[166:169]
	v_mfma_f32_16x16x32_bf16 v[18:21], v[122:125], v[186:189], v[18:21]
	v_mfma_f32_16x16x32_bf16 v[22:25], v[130:133], v[186:189], v[22:25]
	v_mfma_f32_16x16x32_bf16 v[146:149], v[126:129], v[142:145], v[146:149]
	v_mfma_f32_16x16x32_bf16 v[150:153], v[134:137], v[142:145], v[150:153]
	v_mfma_f32_16x16x32_bf16 v[154:157], v[126:129], v[174:177], v[154:157]
	v_mfma_f32_16x16x32_bf16 v[158:161], v[134:137], v[174:177], v[158:161]
	v_mfma_f32_16x16x32_bf16 v[162:165], v[126:129], v[182:185], v[162:165]
	v_mfma_f32_16x16x32_bf16 v[166:169], v[134:137], v[182:185], v[166:169]
	v_mfma_f32_16x16x32_bf16 v[18:21], v[126:129], v[194:197], v[18:21]
	v_mfma_f32_16x16x32_bf16 v[22:25], v[134:137], v[194:197], v[22:25]
	s_setprio 0
	s_barrier
	s_add_u32 s8, s8, 0x10080
	s_addc_u32 s9, s9, 0
	s_mov_b32 m0, s40
	v_lshl_add_u64 v[122:123], s[8:9], 0, v[4:5]
	global_load_lds_dwordx4 v[122:123], off
	v_lshl_add_u64 v[122:123], s[8:9], 0, v[0:1]
	s_mov_b32 m0, s31
	s_nop 0
	global_load_lds_dwordx4 v[122:123], off
	s_waitcnt vmcnt(6)
	s_barrier
	s_setprio 1
	v_mfma_f32_16x16x32_bf16 v[26:29], v[198:201], v[138:141], v[26:29]
	v_mfma_f32_16x16x32_bf16 v[30:33], v[206:209], v[138:141], v[30:33]
	v_mfma_f32_16x16x32_bf16 v[62:65], v[198:201], v[170:173], v[62:65]
	v_mfma_f32_16x16x32_bf16 v[106:109], v[206:209], v[170:173], v[106:109]
	v_mfma_f32_16x16x32_bf16 v[110:113], v[198:201], v[178:181], v[110:113]
	v_mfma_f32_16x16x32_bf16 v[118:121], v[206:209], v[178:181], v[118:121]
	v_mfma_f32_16x16x32_bf16 v[98:101], v[198:201], v[186:189], v[98:101]
	v_mfma_f32_16x16x32_bf16 v[102:105], v[206:209], v[186:189], v[102:105]
	v_mfma_f32_16x16x32_bf16 v[26:29], v[202:205], v[142:145], v[26:29]
	v_mfma_f32_16x16x32_bf16 v[30:33], v[210:213], v[142:145], v[30:33]
	v_mfma_f32_16x16x32_bf16 v[62:65], v[202:205], v[174:177], v[62:65]
	v_mfma_f32_16x16x32_bf16 v[106:109], v[210:213], v[174:177], v[106:109]
	v_mfma_f32_16x16x32_bf16 v[110:113], v[202:205], v[182:185], v[110:113]
	v_mfma_f32_16x16x32_bf16 v[118:121], v[210:213], v[182:185], v[118:121]
	v_mfma_f32_16x16x32_bf16 v[98:101], v[202:205], v[194:197], v[98:101]
	v_mfma_f32_16x16x32_bf16 v[102:105], v[210:213], v[194:197], v[102:105]
	s_setprio 0
	s_lshl_b32 s3, s70, 8
	s_add_i32 s8, s3, 0xfffff800
	s_cmp_lt_i32 s70, 8
	s_cselect_b32 s3, s3, s8
	v_lshl_add_u32 v122, s26, 8, v12
	s_cselect_b32 s9, s11, s55
	s_cselect_b32 s26, s10, s54
	v_or_b32_e32 v126, s3, v14
	v_mov_b32_e32 v124, s26
	v_mov_b32_e32 v125, s9
	v_ashrrev_i32_e32 v127, 31, v126
	v_ashrrev_i32_e32 v123, 31, v122
	s_cselect_b32 s3, 11, 10
	v_lshl_add_u64 v[124:125], v[126:127], 1, v[124:125]
	v_lshlrev_b64 v[126:127], s3, v[122:123]
	v_lshl_add_u64 v[126:127], v[126:127], 1, v[124:125]
	v_cvt_pk_bf16_f32 v66, v66, v67
	v_cvt_pk_bf16_f32 v67, v68, v69
	v_cvt_pk_bf16_f32 v68, v70, v71
	v_cvt_pk_bf16_f32 v69, v72, v73
	s_barrier
	global_store_dwordx4 v[126:127], v[66:69], off sc1
	v_cvt_pk_bf16_f32 v26, v26, v27
	v_cvt_pk_bf16_f32 v27, v28, v29
	v_cvt_pk_bf16_f32 v68, v34, v35
	v_or_b32_e32 v34, 16, v122
	v_ashrrev_i32_e32 v35, 31, v34
	v_cvt_pk_bf16_f32 v66, v114, v115
	v_cvt_pk_bf16_f32 v67, v116, v117
	v_cvt_pk_bf16_f32 v69, v36, v37
	v_lshlrev_b64 v[34:35], s3, v[34:35]
	global_store_dwordx4 v[126:127], v[66:69], off offset:256 sc1
	v_cvt_pk_bf16_f32 v36, v78, v79
	v_cvt_pk_bf16_f32 v37, v80, v81
	v_lshl_add_u64 v[66:67], v[34:35], 1, v[124:125]
	v_cvt_pk_bf16_f32 v34, v74, v75
	v_cvt_pk_bf16_f32 v35, v76, v77
	global_store_dwordx4 v[66:67], v[34:37], off sc1
	v_cvt_pk_bf16_f32 v28, v30, v31
	v_cvt_pk_bf16_f32 v29, v32, v33
	v_cvt_pk_bf16_f32 v34, v38, v39
	v_cvt_pk_bf16_f32 v35, v40, v41
	v_cvt_pk_bf16_f32 v36, v42, v43
	v_cvt_pk_bf16_f32 v37, v44, v45
	global_store_dwordx4 v[66:67], v[34:37], off offset:256 sc1
	v_cvt_pk_bf16_f32 v18, v18, v19
	v_cvt_pk_bf16_f32 v19, v20, v21
	v_or_b32_e32 v34, 32, v122
	v_ashrrev_i32_e32 v35, 31, v34
	v_lshlrev_b64 v[34:35], s3, v[34:35]
	v_lshl_add_u64 v[38:39], v[34:35], 1, v[124:125]
	v_cvt_pk_bf16_f32 v34, v82, v83
	v_cvt_pk_bf16_f32 v35, v84, v85
	v_cvt_pk_bf16_f32 v36, v86, v87
	v_cvt_pk_bf16_f32 v37, v88, v89
	global_store_dwordx4 v[38:39], v[34:37], off sc1
	v_cvt_pk_bf16_f32 v20, v22, v23
	v_cvt_pk_bf16_f32 v21, v24, v25
	v_cvt_pk_bf16_f32 v34, v46, v47
	v_cvt_pk_bf16_f32 v35, v48, v49
	v_cvt_pk_bf16_f32 v36, v50, v51
	v_cvt_pk_bf16_f32 v37, v52, v53
	global_store_dwordx4 v[38:39], v[34:37], off offset:256 sc1
	s_add_i32 s64, s64, s22
	s_andn2_b64 vcc, exec, s[6:7]
	v_or_b32_e32 v34, 48, v122
	v_ashrrev_i32_e32 v35, 31, v34
	v_lshlrev_b64 v[34:35], s3, v[34:35]
	v_lshl_add_u64 v[38:39], v[34:35], 1, v[124:125]
	v_cvt_pk_bf16_f32 v34, v90, v91
	v_cvt_pk_bf16_f32 v35, v92, v93
	v_cvt_pk_bf16_f32 v36, v94, v95
	v_cvt_pk_bf16_f32 v37, v96, v97
	global_store_dwordx4 v[38:39], v[34:37], off sc1
	s_mov_b32 s70, s28
	s_mov_b32 s26, s30
	v_cvt_pk_bf16_f32 v34, v54, v55
	v_cvt_pk_bf16_f32 v35, v56, v57
	v_cvt_pk_bf16_f32 v36, v58, v59
	v_cvt_pk_bf16_f32 v37, v60, v61
	global_store_dwordx4 v[38:39], v[34:37], off offset:256 sc1
	s_mov_b64 s[40:41], s[36:37]
	s_mov_b64 s[38:39], s[34:35]
	v_add_u32_e32 v34, 0x80, v122
	v_ashrrev_i32_e32 v35, 31, v34
	v_lshlrev_b64 v[34:35], s3, v[34:35]
	v_lshl_add_u64 v[38:39], v[34:35], 1, v[124:125]
	global_store_dwordx4 v[38:39], v[26:29], off offset:256 sc1
	v_cvt_pk_bf16_f32 v34, v146, v147
	v_cvt_pk_bf16_f32 v35, v148, v149
	v_add_u32_e32 v26, 0x90, v122
	v_ashrrev_i32_e32 v27, 31, v26
	v_lshlrev_b64 v[26:27], s3, v[26:27]
	v_cvt_pk_bf16_f32 v36, v150, v151
	v_cvt_pk_bf16_f32 v37, v152, v153
	v_lshl_add_u64 v[30:31], v[26:27], 1, v[124:125]
	v_cvt_pk_bf16_f32 v26, v154, v155
	v_cvt_pk_bf16_f32 v27, v156, v157
	v_cvt_pk_bf16_f32 v28, v158, v159
	v_cvt_pk_bf16_f32 v29, v160, v161
	global_store_dwordx4 v[38:39], v[34:37], off sc1
	global_store_dwordx4 v[30:31], v[26:29], off sc1
	s_nop 1
	v_cvt_pk_bf16_f32 v26, v62, v63
	v_cvt_pk_bf16_f32 v27, v64, v65
	v_cvt_pk_bf16_f32 v28, v106, v107
	v_cvt_pk_bf16_f32 v29, v108, v109
	global_store_dwordx4 v[30:31], v[26:29], off offset:256 sc1
	s_nop 1
	v_add_u32_e32 v26, 0xa0, v122
	v_ashrrev_i32_e32 v27, 31, v26
	v_lshlrev_b64 v[26:27], s3, v[26:27]
	v_lshl_add_u64 v[30:31], v[26:27], 1, v[124:125]
	v_cvt_pk_bf16_f32 v26, v162, v163
	v_cvt_pk_bf16_f32 v27, v164, v165
	v_cvt_pk_bf16_f32 v28, v166, v167
	v_cvt_pk_bf16_f32 v29, v168, v169
	global_store_dwordx4 v[30:31], v[26:29], off sc1
	s_nop 1
	v_cvt_pk_bf16_f32 v26, v110, v111
	v_cvt_pk_bf16_f32 v27, v112, v113
	v_cvt_pk_bf16_f32 v28, v118, v119
	v_cvt_pk_bf16_f32 v29, v120, v121
	global_store_dwordx4 v[30:31], v[26:29], off offset:256 sc1
	s_nop 1
	v_add_u32_e32 v26, 0xb0, v122
	v_ashrrev_i32_e32 v27, 31, v26
	v_lshlrev_b64 v[26:27], s3, v[26:27]
	v_lshl_add_u64 v[26:27], v[26:27], 1, v[124:125]
	global_store_dwordx4 v[26:27], v[18:21], off sc1
	s_nop 1
	v_cvt_pk_bf16_f32 v18, v98, v99
	v_cvt_pk_bf16_f32 v19, v100, v101
	v_cvt_pk_bf16_f32 v20, v102, v103
	v_cvt_pk_bf16_f32 v21, v104, v105
	global_store_dwordx4 v[26:27], v[18:21], off offset:256 sc1
	s_cbranch_vccz .LBB0_1557

.LBB0_2700:
	ds_read_b128 v[120:123], v244
	ds_read_b128 v[124:127], v244 offset:1024
	ds_read_b128 v[132:135], v244 offset:2048
	ds_read_b128 v[140:143], v244 offset:3072
	s_add_u32 s38, s36, 0xfff80080
	s_addc_u32 s39, s37, -1
	s_cmp_eq_u32 s66, 28
	s_cselect_b32 s41, s27, s39
	s_cselect_b32 s40, s35, s38
	s_cselect_b32 s39, s25, s65
	s_cselect_b32 s38, s63, s64
	v_lshl_add_u64 v[176:177], s[36:37], 0, v[202:203]
	s_add_i32 m0, s47, 0xc000
	ds_read_b128 v[144:147], v245
	ds_read_b128 v[148:151], v245 offset:1024
	ds_read_b128 v[152:155], v245 offset:2048
	ds_read_b128 v[156:159], v245 offset:3072
	ds_read_b128 v[160:163], v245 offset:4096
	ds_read_b128 v[164:167], v245 offset:5120
	ds_read_b128 v[168:171], v245 offset:6144
	ds_read_b128 v[172:175], v245 offset:7168
	global_load_lds_dwordx4 v[176:177], off
	v_lshl_add_u64 v[176:177], s[36:37], 0, v[204:205]
	s_add_i32 m0, s47, 0xe000
	s_nop 0
	global_load_lds_dwordx4 v[176:177], off
	s_waitcnt lgkmcnt(8)
	s_barrier
	s_waitcnt lgkmcnt(0)
	s_setprio 1
	s_waitcnt lgkmcnt(0)
	v_mfma_f32_16x16x32_bf16 v[136:139], v[120:123], v[144:147], v[136:139]
	v_mfma_f32_16x16x32_bf16 v[128:131], v[132:135], v[144:147], v[128:131]
	v_mfma_f32_16x16x32_bf16 v[108:111], v[120:123], v[152:155], v[108:111]
	v_mfma_f32_16x16x32_bf16 v[104:107], v[132:135], v[152:155], v[104:107]
	v_mfma_f32_16x16x32_bf16 v[92:95], v[120:123], v[160:163], v[92:95]
	v_mfma_f32_16x16x32_bf16 v[88:91], v[132:135], v[160:163], v[88:91]
	v_mfma_f32_16x16x32_bf16 v[76:79], v[120:123], v[168:171], v[76:79]
	v_mfma_f32_16x16x32_bf16 v[72:75], v[132:135], v[168:171], v[72:75]
	v_mfma_f32_16x16x32_bf16 v[136:139], v[124:127], v[148:151], v[136:139]
	v_mfma_f32_16x16x32_bf16 v[128:131], v[140:143], v[148:151], v[128:131]
	v_mfma_f32_16x16x32_bf16 v[108:111], v[124:127], v[156:159], v[108:111]
	v_mfma_f32_16x16x32_bf16 v[104:107], v[140:143], v[156:159], v[104:107]
	v_mfma_f32_16x16x32_bf16 v[92:95], v[124:127], v[164:167], v[92:95]
	v_mfma_f32_16x16x32_bf16 v[88:91], v[140:143], v[164:167], v[88:91]
	v_mfma_f32_16x16x32_bf16 v[76:79], v[124:127], v[172:175], v[76:79]
	v_mfma_f32_16x16x32_bf16 v[72:75], v[140:143], v[172:175], v[72:75]
	s_setprio 0
	s_barrier
	s_add_i32 s67, s57, s46
	v_lshl_add_u64 v[206:207], s[38:39], 0, v[196:197]
	s_mov_b32 m0, s67
	ds_read_b128 v[176:179], v246
	ds_read_b128 v[180:183], v246 offset:1024
	ds_read_b128 v[184:187], v246 offset:2048
	ds_read_b128 v[188:191], v246 offset:3072
	global_load_lds_dwordx4 v[206:207], off
	v_lshl_add_u64 v[208:209], s[38:39], 0, v[200:201]
	s_add_i32 m0, s67, 0x2000
	s_nop 0
	global_load_lds_dwordx4 v[208:209], off
	s_barrier
	s_waitcnt lgkmcnt(0)
	s_setprio 1
	s_waitcnt lgkmcnt(0)
	v_mfma_f32_16x16x32_bf16 v[116:119], v[176:179], v[144:147], v[116:119]
	v_mfma_f32_16x16x32_bf16 v[112:115], v[184:187], v[144:147], v[112:115]
	v_mfma_f32_16x16x32_bf16 v[100:103], v[176:179], v[152:155], v[100:103]
	v_mfma_f32_16x16x32_bf16 v[96:99], v[184:187], v[152:155], v[96:99]
	v_mfma_f32_16x16x32_bf16 v[84:87], v[176:179], v[160:163], v[84:87]
	v_mfma_f32_16x16x32_bf16 v[80:83], v[184:187], v[160:163], v[80:83]
	v_mfma_f32_16x16x32_bf16 v[68:71], v[176:179], v[168:171], v[68:71]
	v_mfma_f32_16x16x32_bf16 v[64:67], v[184:187], v[168:171], v[64:67]
	v_mfma_f32_16x16x32_bf16 v[116:119], v[180:183], v[148:151], v[116:119]
	v_mfma_f32_16x16x32_bf16 v[112:115], v[188:191], v[148:151], v[112:115]
	v_mfma_f32_16x16x32_bf16 v[100:103], v[180:183], v[156:159], v[100:103]
	v_mfma_f32_16x16x32_bf16 v[96:99], v[188:191], v[156:159], v[96:99]
	v_mfma_f32_16x16x32_bf16 v[84:87], v[180:183], v[164:167], v[84:87]
	v_mfma_f32_16x16x32_bf16 v[80:83], v[188:191], v[164:167], v[80:83]
	v_mfma_f32_16x16x32_bf16 v[68:71], v[180:183], v[172:175], v[68:71]
	v_mfma_f32_16x16x32_bf16 v[64:67], v[188:191], v[172:175], v[64:67]
	s_setprio 0
	s_mov_b32 m0, s47
	v_lshl_add_u64 v[210:211], s[40:41], 0, v[194:195]
	s_barrier
	ds_read_b128 v[144:147], v245 offset:16384
	ds_read_b128 v[148:151], v245 offset:17408
	ds_read_b128 v[152:155], v245 offset:18432
	ds_read_b128 v[156:159], v245 offset:19456
	ds_read_b128 v[160:163], v245 offset:20480
	ds_read_b128 v[164:167], v245 offset:21504
	ds_read_b128 v[168:171], v245 offset:22528
	ds_read_b128 v[172:175], v245 offset:23552
	global_load_lds_dwordx4 v[210:211], off
	v_lshl_add_u64 v[212:213], s[40:41], 0, v[198:199]
	s_mov_b32 m0, s48
	s_nop 0
	global_load_lds_dwordx4 v[212:213], off
	s_barrier
	s_waitcnt lgkmcnt(0)
	s_setprio 1
	s_waitcnt lgkmcnt(0)
	v_mfma_f32_16x16x32_bf16 v[60:63], v[120:123], v[144:147], v[60:63]
	v_mfma_f32_16x16x32_bf16 v[56:59], v[132:135], v[144:147], v[56:59]
	v_mfma_f32_16x16x32_bf16 v[44:47], v[120:123], v[152:155], v[44:47]
	v_mfma_f32_16x16x32_bf16 v[40:43], v[132:135], v[152:155], v[40:43]
	v_mfma_f32_16x16x32_bf16 v[28:31], v[120:123], v[160:163], v[28:31]
	v_mfma_f32_16x16x32_bf16 v[24:27], v[132:135], v[160:163], v[24:27]
	v_mfma_f32_16x16x32_bf16 v[12:15], v[120:123], v[168:171], v[12:15]
	v_mfma_f32_16x16x32_bf16 v[8:11], v[132:135], v[168:171], v[8:11]
	v_mfma_f32_16x16x32_bf16 v[60:63], v[124:127], v[148:151], v[60:63]
	v_mfma_f32_16x16x32_bf16 v[56:59], v[140:143], v[148:151], v[56:59]
	v_mfma_f32_16x16x32_bf16 v[44:47], v[124:127], v[156:159], v[44:47]
	v_mfma_f32_16x16x32_bf16 v[40:43], v[140:143], v[156:159], v[40:43]
	v_mfma_f32_16x16x32_bf16 v[28:31], v[124:127], v[164:167], v[28:31]
	v_mfma_f32_16x16x32_bf16 v[24:27], v[140:143], v[164:167], v[24:27]
	v_mfma_f32_16x16x32_bf16 v[12:15], v[124:127], v[172:175], v[12:15]
	v_mfma_f32_16x16x32_bf16 v[8:11], v[140:143], v[172:175], v[8:11]
	s_setprio 0
	s_barrier
	s_add_u32 s68, s38, 0x80000
	s_addc_u32 s69, s39, 0
	s_add_i32 s67, s58, s46
	v_lshl_add_u64 v[120:121], s[68:69], 0, v[196:197]
	s_mov_b32 m0, s67
	s_nop 0
	global_load_lds_dwordx4 v[120:121], off
	v_lshl_add_u64 v[120:121], s[68:69], 0, v[200:201]
	s_add_i32 m0, s67, 0x2000
	s_nop 0
	global_load_lds_dwordx4 v[120:121], off
	s_waitcnt vmcnt(6)
	s_barrier
	s_setprio 1
	v_mfma_f32_16x16x32_bf16 v[52:55], v[176:179], v[144:147], v[52:55]
	v_mfma_f32_16x16x32_bf16 v[48:51], v[184:187], v[144:147], v[48:51]
	v_mfma_f32_16x16x32_bf16 v[36:39], v[176:179], v[152:155], v[36:39]
	v_mfma_f32_16x16x32_bf16 v[32:35], v[184:187], v[152:155], v[32:35]
	v_mfma_f32_16x16x32_bf16 v[20:23], v[176:179], v[160:163], v[20:23]
	v_mfma_f32_16x16x32_bf16 v[16:19], v[184:187], v[160:163], v[16:19]
	v_mfma_f32_16x16x32_bf16 v[4:7], v[176:179], v[168:171], v[4:7]
	v_mfma_f32_16x16x32_bf16 v[0:3], v[184:187], v[168:171], v[0:3]
	v_mfma_f32_16x16x32_bf16 v[52:55], v[180:183], v[148:151], v[52:55]
	v_mfma_f32_16x16x32_bf16 v[48:51], v[188:191], v[148:151], v[48:51]
	v_mfma_f32_16x16x32_bf16 v[36:39], v[180:183], v[156:159], v[36:39]
	v_mfma_f32_16x16x32_bf16 v[32:35], v[188:191], v[156:159], v[32:35]
	v_mfma_f32_16x16x32_bf16 v[20:23], v[180:183], v[164:167], v[20:23]
	v_mfma_f32_16x16x32_bf16 v[16:19], v[188:191], v[164:167], v[16:19]
	v_mfma_f32_16x16x32_bf16 v[4:7], v[180:183], v[172:175], v[4:7]
	v_mfma_f32_16x16x32_bf16 v[0:3], v[188:191], v[172:175], v[0:3]
	s_setprio 0
	s_add_i32 s67, 0, 0x18000
	v_add_u32_e32 v140, s67, v242
	s_barrier
	ds_read_b128 v[120:123], v140
	ds_read_b128 v[124:127], v140 offset:1024
	ds_read_b128 v[132:135], v140 offset:2048
	ds_read_b128 v[140:143], v140 offset:3072
	s_add_u32 s40, s40, 0x80000
	s_addc_u32 s41, s41, 0
	s_mov_b32 m0, s49
	v_lshl_add_u64 v[176:177], s[40:41], 0, v[194:195]
	ds_read_b128 v[144:147], v245 offset:32768
	ds_read_b128 v[148:151], v245 offset:33792
	ds_read_b128 v[152:155], v245 offset:34816
	ds_read_b128 v[156:159], v245 offset:35840
	ds_read_b128 v[160:163], v245 offset:36864
	ds_read_b128 v[164:167], v245 offset:37888
	ds_read_b128 v[168:171], v245 offset:38912
	ds_read_b128 v[172:175], v245 offset:39936
	global_load_lds_dwordx4 v[176:177], off
	v_lshl_add_u64 v[176:177], s[40:41], 0, v[198:199]
	s_mov_b32 m0, s50
	s_nop 0
	global_load_lds_dwordx4 v[176:177], off
	s_waitcnt lgkmcnt(8)
	s_barrier
	s_waitcnt lgkmcnt(0)
	s_setprio 1
	s_waitcnt lgkmcnt(0)
	v_mfma_f32_16x16x32_bf16 v[136:139], v[120:123], v[144:147], v[136:139]
	v_mfma_f32_16x16x32_bf16 v[128:131], v[132:135], v[144:147], v[128:131]
	v_mfma_f32_16x16x32_bf16 v[108:111], v[120:123], v[152:155], v[108:111]
	v_mfma_f32_16x16x32_bf16 v[104:107], v[132:135], v[152:155], v[104:107]
	v_mfma_f32_16x16x32_bf16 v[92:95], v[120:123], v[160:163], v[92:95]
	v_mfma_f32_16x16x32_bf16 v[88:91], v[132:135], v[160:163], v[88:91]
	v_mfma_f32_16x16x32_bf16 v[76:79], v[120:123], v[168:171], v[76:79]
	v_mfma_f32_16x16x32_bf16 v[72:75], v[132:135], v[168:171], v[72:75]
	v_mfma_f32_16x16x32_bf16 v[136:139], v[124:127], v[148:151], v[136:139]
	v_mfma_f32_16x16x32_bf16 v[128:131], v[140:143], v[148:151], v[128:131]
	v_mfma_f32_16x16x32_bf16 v[108:111], v[124:127], v[156:159], v[108:111]
	v_mfma_f32_16x16x32_bf16 v[104:107], v[140:143], v[156:159], v[104:107]
	v_mfma_f32_16x16x32_bf16 v[92:95], v[124:127], v[164:167], v[92:95]
	v_mfma_f32_16x16x32_bf16 v[88:91], v[140:143], v[164:167], v[88:91]
	v_mfma_f32_16x16x32_bf16 v[76:79], v[124:127], v[172:175], v[76:79]
	v_mfma_f32_16x16x32_bf16 v[72:75], v[140:143], v[172:175], v[72:75]
	s_setprio 0
	s_barrier
	s_add_i32 s40, 0, 0x1c000
	s_add_i32 s41, s67, s46
	v_add_u32_e32 v188, s40, v242
	v_lshl_add_u64 v[206:207], v[206:207], 0, s[16:17]
	s_mov_b32 m0, s41
	ds_read_b128 v[176:179], v188
	ds_read_b128 v[180:183], v188 offset:1024
	ds_read_b128 v[184:187], v188 offset:2048
	ds_read_b128 v[188:191], v188 offset:3072
	global_load_lds_dwordx4 v[206:207], off
	v_lshl_add_u64 v[206:207], v[208:209], 0, s[16:17]
	s_add_i32 m0, s41, 0x2000
	s_nop 0
	global_load_lds_dwordx4 v[206:207], off
	s_barrier
	s_waitcnt lgkmcnt(0)
	s_setprio 1
	s_waitcnt lgkmcnt(0)
	v_mfma_f32_16x16x32_bf16 v[116:119], v[176:179], v[144:147], v[116:119]
	v_mfma_f32_16x16x32_bf16 v[112:115], v[184:187], v[144:147], v[112:115]
	v_mfma_f32_16x16x32_bf16 v[100:103], v[176:179], v[152:155], v[100:103]
	v_mfma_f32_16x16x32_bf16 v[96:99], v[184:187], v[152:155], v[96:99]
	v_mfma_f32_16x16x32_bf16 v[84:87], v[176:179], v[160:163], v[84:87]
	v_mfma_f32_16x16x32_bf16 v[80:83], v[184:187], v[160:163], v[80:83]
	v_mfma_f32_16x16x32_bf16 v[68:71], v[176:179], v[168:171], v[68:71]
	v_mfma_f32_16x16x32_bf16 v[64:67], v[184:187], v[168:171], v[64:67]
	v_mfma_f32_16x16x32_bf16 v[116:119], v[180:183], v[148:151], v[116:119]
	v_mfma_f32_16x16x32_bf16 v[112:115], v[188:191], v[148:151], v[112:115]
	v_mfma_f32_16x16x32_bf16 v[100:103], v[180:183], v[156:159], v[100:103]
	v_mfma_f32_16x16x32_bf16 v[96:99], v[188:191], v[156:159], v[96:99]
	v_mfma_f32_16x16x32_bf16 v[84:87], v[180:183], v[164:167], v[84:87]
	v_mfma_f32_16x16x32_bf16 v[80:83], v[188:191], v[164:167], v[80:83]
	v_mfma_f32_16x16x32_bf16 v[68:71], v[180:183], v[172:175], v[68:71]
	v_mfma_f32_16x16x32_bf16 v[64:67], v[188:191], v[172:175], v[64:67]
	s_setprio 0
	s_mov_b32 m0, s52
	v_lshl_add_u64 v[206:207], v[210:211], 0, s[16:17]
	s_barrier
	ds_read_b128 v[144:147], v245 offset:49152
	ds_read_b128 v[148:151], v245 offset:50176
	ds_read_b128 v[152:155], v245 offset:51200
	ds_read_b128 v[156:159], v245 offset:52224
	ds_read_b128 v[160:163], v245 offset:53248
	ds_read_b128 v[164:167], v245 offset:54272
	ds_read_b128 v[168:171], v245 offset:55296
	ds_read_b128 v[172:175], v245 offset:56320
	global_load_lds_dwordx4 v[206:207], off
	v_lshl_add_u64 v[206:207], v[212:213], 0, s[16:17]
	s_mov_b32 m0, s53
	s_nop 0
	global_load_lds_dwordx4 v[206:207], off
	s_barrier
	s_waitcnt lgkmcnt(0)
	s_setprio 1
	s_waitcnt lgkmcnt(0)
	v_mfma_f32_16x16x32_bf16 v[60:63], v[120:123], v[144:147], v[60:63]
	v_mfma_f32_16x16x32_bf16 v[56:59], v[132:135], v[144:147], v[56:59]
	v_mfma_f32_16x16x32_bf16 v[44:47], v[120:123], v[152:155], v[44:47]
	v_mfma_f32_16x16x32_bf16 v[40:43], v[132:135], v[152:155], v[40:43]
	v_mfma_f32_16x16x32_bf16 v[28:31], v[120:123], v[160:163], v[28:31]
	v_mfma_f32_16x16x32_bf16 v[24:27], v[132:135], v[160:163], v[24:27]
	v_mfma_f32_16x16x32_bf16 v[12:15], v[120:123], v[168:171], v[12:15]
	v_mfma_f32_16x16x32_bf16 v[8:11], v[132:135], v[168:171], v[8:11]
	v_mfma_f32_16x16x32_bf16 v[60:63], v[124:127], v[148:151], v[60:63]
	v_mfma_f32_16x16x32_bf16 v[56:59], v[140:143], v[148:151], v[56:59]
	v_mfma_f32_16x16x32_bf16 v[44:47], v[124:127], v[156:159], v[44:47]
	v_mfma_f32_16x16x32_bf16 v[40:43], v[140:143], v[156:159], v[40:43]
	v_mfma_f32_16x16x32_bf16 v[28:31], v[124:127], v[164:167], v[28:31]
	v_mfma_f32_16x16x32_bf16 v[24:27], v[140:143], v[164:167], v[24:27]
	v_mfma_f32_16x16x32_bf16 v[12:15], v[124:127], v[172:175], v[12:15]
	v_mfma_f32_16x16x32_bf16 v[8:11], v[140:143], v[172:175], v[8:11]
	s_setprio 0
	s_barrier
	s_add_u32 s38, s38, 0x80080
	s_addc_u32 s39, s39, 0
	s_add_i32 s40, s40, s46
	v_lshl_add_u64 v[120:121], s[38:39], 0, v[196:197]
	s_mov_b32 m0, s40
	s_nop 0
	global_load_lds_dwordx4 v[120:121], off
	v_lshl_add_u64 v[120:121], s[38:39], 0, v[200:201]
	s_add_i32 m0, s40, 0x2000
	s_nop 0
	global_load_lds_dwordx4 v[120:121], off
	s_waitcnt vmcnt(6)
	s_barrier
	s_setprio 1
	v_mfma_f32_16x16x32_bf16 v[52:55], v[176:179], v[144:147], v[52:55]
	v_mfma_f32_16x16x32_bf16 v[48:51], v[184:187], v[144:147], v[48:51]
	v_mfma_f32_16x16x32_bf16 v[36:39], v[176:179], v[152:155], v[36:39]
	v_mfma_f32_16x16x32_bf16 v[32:35], v[184:187], v[152:155], v[32:35]
	v_mfma_f32_16x16x32_bf16 v[20:23], v[176:179], v[160:163], v[20:23]
	v_mfma_f32_16x16x32_bf16 v[16:19], v[184:187], v[160:163], v[16:19]
	v_mfma_f32_16x16x32_bf16 v[4:7], v[176:179], v[168:171], v[4:7]
	v_mfma_f32_16x16x32_bf16 v[0:3], v[184:187], v[168:171], v[0:3]
	v_mfma_f32_16x16x32_bf16 v[52:55], v[180:183], v[148:151], v[52:55]
	v_mfma_f32_16x16x32_bf16 v[48:51], v[188:191], v[148:151], v[48:51]
	v_mfma_f32_16x16x32_bf16 v[36:39], v[180:183], v[156:159], v[36:39]
	v_mfma_f32_16x16x32_bf16 v[32:35], v[188:191], v[156:159], v[32:35]
	v_mfma_f32_16x16x32_bf16 v[20:23], v[180:183], v[164:167], v[20:23]
	v_mfma_f32_16x16x32_bf16 v[16:19], v[188:191], v[164:167], v[16:19]
	v_mfma_f32_16x16x32_bf16 v[4:7], v[180:183], v[172:175], v[4:7]
	v_mfma_f32_16x16x32_bf16 v[0:3], v[188:191], v[172:175], v[0:3]
	s_setprio 0
	s_add_i32 s66, s66, 2
	s_add_u32 s36, s36, 0x100
	s_addc_u32 s37, s37, 0
	s_add_u32 s64, s64, 0x100
	s_addc_u32 s65, s65, 0
	s_cmp_gt_u32 s66, 29
	s_barrier
	s_cbranch_scc0 .LBB0_2700
	v_lshl_or_b32 v206, s10, 8, v243
	v_lshl_add_u32 v236, s34, 8, v193
	v_ashrrev_i32_e32 v207, 31, v206
	v_lshlrev_b64 v[238:239], 1, v[206:207]
	v_ashrrev_i32_e32 v237, 31, v236
	v_lshl_add_u64 v[124:125], s[12:13], 0, v[238:239]
	v_lshlrev_b64 v[240:241], 11, v[236:237]
	v_lshl_add_u64 v[120:121], v[124:125], 0, v[240:241]
	global_load_dwordx4 v[188:191], v[120:121], off
	global_load_dwordx4 v[184:187], v[120:121], off offset:256
	v_or_b32_e32 v232, 16, v236
	v_ashrrev_i32_e32 v233, 31, v232
	v_or_b32_e32 v228, 32, v236
	v_lshlrev_b64 v[234:235], 11, v[232:233]
	v_ashrrev_i32_e32 v229, 31, v228
	v_or_b32_e32 v224, 48, v236
	v_lshl_add_u64 v[120:121], v[124:125], 0, v[234:235]
	v_lshlrev_b64 v[230:231], 11, v[228:229]
	v_ashrrev_i32_e32 v225, 31, v224
	v_add_u32_e32 v220, 0x80, v236
	global_load_dwordx4 v[180:183], v[120:121], off
	global_load_dwordx4 v[176:179], v[120:121], off offset:256
	v_lshl_add_u64 v[120:121], v[124:125], 0, v[230:231]
	v_lshlrev_b64 v[226:227], 11, v[224:225]
	v_ashrrev_i32_e32 v221, 31, v220
	v_add_u32_e32 v216, 0x90, v236
	global_load_dwordx4 v[172:175], v[120:121], off
	global_load_dwordx4 v[168:171], v[120:121], off offset:256
	v_lshl_add_u64 v[120:121], v[124:125], 0, v[226:227]
	v_lshlrev_b64 v[222:223], 11, v[220:221]
	v_ashrrev_i32_e32 v217, 31, v216
	v_add_u32_e32 v212, 0xa0, v236
	v_add_u32_e32 v208, 0xb0, v236
	global_load_dwordx4 v[164:167], v[120:121], off
	global_load_dwordx4 v[160:163], v[120:121], off offset:256
	v_lshl_add_u64 v[120:121], v[124:125], 0, v[222:223]
	v_lshlrev_b64 v[218:219], 11, v[216:217]
	v_ashrrev_i32_e32 v213, 31, v212
	v_ashrrev_i32_e32 v209, 31, v208
	global_load_dwordx4 v[156:159], v[120:121], off
	global_load_dwordx4 v[152:155], v[120:121], off offset:256
	v_lshl_add_u64 v[120:121], v[124:125], 0, v[218:219]
	v_lshlrev_b64 v[214:215], 11, v[212:213]
	v_lshlrev_b64 v[210:211], 11, v[208:209]
	global_load_dwordx4 v[148:151], v[120:121], off
	global_load_dwordx4 v[144:147], v[120:121], off offset:256
	v_lshl_add_u64 v[120:121], v[124:125], 0, v[214:215]
	v_lshl_add_u64 v[124:125], v[124:125], 0, v[210:211]
	global_load_dwordx4 v[132:135], v[120:121], off
	s_nop 0
	global_load_dwordx4 v[120:123], v[120:121], off offset:256
	s_nop 0
	global_load_dwordx4 v[140:143], v[124:125], off
	s_nop 0
	global_load_dwordx4 v[124:127], v[124:125], off offset:256
	v_and_b32_e32 v249, 64, v247
	v_xor_b32_e32 v248, 16, v247
	v_add_u32_e32 v249, 64, v249
	v_cmp_lt_i32_e32 vcc, v248, v249
	v_xor_b32_e32 v250, 32, v247
	s_lshl_b32 s34, s10, 2
	v_cndmask_b32_e32 v248, v247, v248, vcc
	v_cmp_lt_i32_e32 vcc, v250, v249
	v_lshlrev_b32_e32 v248, 2, v248
	s_ashr_i32 s35, s34, 31
	v_cndmask_b32_e32 v249, v247, v250, vcc
	v_lshlrev_b32_e32 v249, 2, v249
	s_waitcnt vmcnt(0)
	v_lshlrev_b32_e32 v250, 16, v188
	v_and_b32_e32 v251, 0xffff0000, v188
	v_lshlrev_b32_e32 v188, 16, v189
	v_and_b32_e32 v189, 0xffff0000, v189
	v_lshlrev_b32_e32 v252, 16, v190
	v_and_b32_e32 v253, 0xffff0000, v190
	v_lshlrev_b32_e32 v190, 16, v191
	v_and_b32_e32 v191, 0xffff0000, v191
	v_pk_add_f32 v[138:139], v[138:139], v[188:189]
	v_pk_add_f32 v[136:137], v[136:137], v[250:251]
	v_pk_add_f32 v[188:189], v[130:131], v[190:191]
	v_pk_add_f32 v[130:131], v[128:129], v[252:253]
	v_mul_f32_e32 v128, v137, v137
	v_mul_f32_e32 v129, v139, v139
	v_fmac_f32_e32 v128, v136, v136
	v_fmac_f32_e32 v129, v138, v138
	v_add_f32_e32 v128, v128, v129
	v_mul_f32_e32 v129, v131, v131
	v_mul_f32_e32 v190, v189, v189
	v_fmac_f32_e32 v129, v130, v130
	v_fmac_f32_e32 v190, v188, v188
	v_add_f32_e32 v129, v129, v190
	v_add_f32_e32 v190, v128, v129
	v_cvt_pk_bf16_f32 v128, v136, v137
	v_lshl_add_u64 v[136:137], s[12:13], 0, v[240:241]
	v_cvt_pk_bf16_f32 v129, v138, v139
	v_cvt_pk_bf16_f32 v130, v130, v131
	v_cvt_pk_bf16_f32 v131, v188, v189
	v_lshl_add_u64 v[136:137], v[136:137], 0, v[238:239]
	global_store_dwordx4 v[136:137], v[128:131], off sc1
	v_lshlrev_b32_e32 v138, 16, v186
	v_and_b32_e32 v139, 0xffff0000, v186
	v_lshlrev_b32_e32 v128, 16, v184
	v_and_b32_e32 v129, 0xffff0000, v184
	v_lshlrev_b32_e32 v130, 16, v185
	v_and_b32_e32 v131, 0xffff0000, v185
	v_lshlrev_b32_e32 v184, 16, v187
	v_and_b32_e32 v185, 0xffff0000, v187
	v_pk_add_f32 v[118:119], v[118:119], v[130:131]
	v_pk_add_f32 v[116:117], v[116:117], v[128:129]
	v_pk_add_f32 v[128:129], v[114:115], v[184:185]
	v_pk_add_f32 v[114:115], v[112:113], v[138:139]
	v_mul_f32_e32 v112, v117, v117
	v_mul_f32_e32 v113, v119, v119
	v_fmac_f32_e32 v112, v116, v116
	v_fmac_f32_e32 v113, v118, v118
	v_add_f32_e32 v112, v112, v113
	v_mul_f32_e32 v113, v115, v115
	v_mul_f32_e32 v130, v129, v129
	v_fmac_f32_e32 v113, v114, v114
	v_fmac_f32_e32 v130, v128, v128
	v_add_f32_e32 v113, v113, v130
	v_add_f32_e32 v112, v112, v113
	v_add_f32_e32 v130, v190, v112
	v_cvt_pk_bf16_f32 v112, v116, v117
	v_cvt_pk_bf16_f32 v113, v118, v119
	v_cvt_pk_bf16_f32 v114, v114, v115
	v_cvt_pk_bf16_f32 v115, v128, v129
	global_store_dwordx4 v[136:137], v[112:115], off offset:256 sc1
	ds_bpermute_b32 v112, v248, v130
	s_waitcnt lgkmcnt(0)
	v_add_f32_e32 v112, v130, v112
	ds_bpermute_b32 v113, v249, v112
	s_and_saveexec_b64 s[36:37], s[6:7]
	s_cbranch_execz .LBB0_2703
	v_lshlrev_b64 v[114:115], 6, v[236:237]
	v_lshl_add_u64 v[114:115], s[14:15], 0, v[114:115]
	v_lshl_add_u64 v[114:115], s[34:35], 2, v[114:115]
	s_lshl_b32 s10, s51, 2
	v_lshl_add_u64 v[114:115], v[114:115], 0, s[10:11]
	s_waitcnt lgkmcnt(0)
	v_add_f32_e32 v112, v112, v113
	global_store_dword v[114:115], v112, off
.LBB0_2703:
	s_or_b64 exec, exec, s[36:37]
	v_lshlrev_b32_e32 v112, 16, v180
	s_waitcnt lgkmcnt(0)
	v_and_b32_e32 v113, 0xffff0000, v180
	v_lshlrev_b32_e32 v114, 16, v181
	v_and_b32_e32 v115, 0xffff0000, v181
	v_lshlrev_b32_e32 v116, 16, v182
	v_and_b32_e32 v117, 0xffff0000, v182
	v_lshlrev_b32_e32 v118, 16, v183
	v_and_b32_e32 v119, 0xffff0000, v183
	v_pk_add_f32 v[110:111], v[110:111], v[114:115]
	v_pk_add_f32 v[108:109], v[108:109], v[112:113]
	v_pk_add_f32 v[112:113], v[106:107], v[118:119]
	v_pk_add_f32 v[106:107], v[104:105], v[116:117]
	v_mul_f32_e32 v104, v109, v109
	v_mul_f32_e32 v105, v111, v111
	v_fmac_f32_e32 v104, v108, v108
	v_fmac_f32_e32 v105, v110, v110
	v_add_f32_e32 v104, v104, v105
	v_mul_f32_e32 v105, v107, v107
	v_mul_f32_e32 v114, v113, v113
	v_fmac_f32_e32 v105, v106, v106
	v_fmac_f32_e32 v114, v112, v112
	v_add_f32_e32 v105, v105, v114
	v_add_f32_e32 v116, v104, v105
	v_cvt_pk_bf16_f32 v104, v108, v109
	v_cvt_pk_bf16_f32 v105, v110, v111
	v_lshlrev_b32_e32 v108, 16, v176
	v_and_b32_e32 v109, 0xffff0000, v176
	v_lshlrev_b32_e32 v110, 16, v177
	v_and_b32_e32 v111, 0xffff0000, v177
	v_cvt_pk_bf16_f32 v106, v106, v107
	v_cvt_pk_bf16_f32 v107, v112, v113
	v_lshlrev_b32_e32 v112, 16, v178
	v_and_b32_e32 v113, 0xffff0000, v178
	v_pk_add_f32 v[102:103], v[102:103], v[110:111]
	v_pk_add_f32 v[100:101], v[100:101], v[108:109]
	v_lshlrev_b32_e32 v114, 16, v179
	v_and_b32_e32 v115, 0xffff0000, v179
	v_pk_add_f32 v[110:111], v[96:97], v[112:113]
	v_mul_f32_e32 v96, v101, v101
	v_mul_f32_e32 v97, v103, v103
	v_pk_add_f32 v[108:109], v[98:99], v[114:115]
	v_fmac_f32_e32 v96, v100, v100
	v_fmac_f32_e32 v97, v102, v102
	v_add_f32_e32 v96, v96, v97
	v_mul_f32_e32 v97, v111, v111
	v_mul_f32_e32 v98, v109, v109
	v_fmac_f32_e32 v97, v110, v110
	v_fmac_f32_e32 v98, v108, v108
	v_add_f32_e32 v97, v97, v98
	v_add_f32_e32 v96, v96, v97
	v_add_f32_e32 v99, v116, v96
	ds_bpermute_b32 v114, v248, v99
	v_lshl_add_u64 v[96:97], s[12:13], 0, v[234:235]
	v_lshl_add_u64 v[112:113], v[206:207], 1, v[96:97]
	v_cvt_pk_bf16_f32 v98, v100, v101
	v_cvt_pk_bf16_f32 v100, v110, v111
	s_waitcnt lgkmcnt(0)
	v_add_f32_e32 v96, v99, v114
	ds_bpermute_b32 v97, v249, v96
	v_cvt_pk_bf16_f32 v99, v102, v103
	v_cvt_pk_bf16_f32 v101, v108, v109
	global_store_dwordx4 v[112:113], v[104:107], off sc1
	global_store_dwordx4 v[112:113], v[98:101], off offset:256 sc1
	s_and_saveexec_b64 s[36:37], s[6:7]
	s_cbranch_execz .LBB0_2705
	v_lshlrev_b64 v[98:99], 6, v[232:233]
	v_lshl_add_u64 v[98:99], s[14:15], 0, v[98:99]
	v_lshl_add_u64 v[98:99], s[34:35], 2, v[98:99]
	s_lshl_b32 s10, s51, 2
	v_lshl_add_u64 v[98:99], v[98:99], 0, s[10:11]
	s_waitcnt lgkmcnt(0)
	v_add_f32_e32 v96, v96, v97
	global_store_dword v[98:99], v96, off
.LBB0_2705:
	s_or_b64 exec, exec, s[36:37]
	v_lshlrev_b32_e32 v96, 16, v172
	s_waitcnt lgkmcnt(0)
	v_and_b32_e32 v97, 0xffff0000, v172
	v_lshlrev_b32_e32 v98, 16, v173
	v_and_b32_e32 v99, 0xffff0000, v173
	v_lshlrev_b32_e32 v100, 16, v174
	v_and_b32_e32 v101, 0xffff0000, v174
	v_lshlrev_b32_e32 v102, 16, v175
	v_and_b32_e32 v103, 0xffff0000, v175
	v_pk_add_f32 v[94:95], v[94:95], v[98:99]
	v_pk_add_f32 v[92:93], v[92:93], v[96:97]
	v_pk_add_f32 v[96:97], v[90:91], v[102:103]
	v_pk_add_f32 v[90:91], v[88:89], v[100:101]
	v_mul_f32_e32 v88, v93, v93
	v_mul_f32_e32 v89, v95, v95
	v_fmac_f32_e32 v88, v92, v92
	v_fmac_f32_e32 v89, v94, v94
	v_add_f32_e32 v88, v88, v89
	v_mul_f32_e32 v89, v91, v91
	v_mul_f32_e32 v98, v97, v97
	v_fmac_f32_e32 v89, v90, v90
	v_fmac_f32_e32 v98, v96, v96
	v_add_f32_e32 v89, v89, v98
	v_add_f32_e32 v100, v88, v89
	v_cvt_pk_bf16_f32 v88, v92, v93
	v_cvt_pk_bf16_f32 v89, v94, v95
	v_lshlrev_b32_e32 v92, 16, v168
	v_and_b32_e32 v93, 0xffff0000, v168
	v_lshlrev_b32_e32 v94, 16, v169
	v_and_b32_e32 v95, 0xffff0000, v169
	v_cvt_pk_bf16_f32 v90, v90, v91
	v_cvt_pk_bf16_f32 v91, v96, v97
	v_lshlrev_b32_e32 v96, 16, v170
	v_and_b32_e32 v97, 0xffff0000, v170
	v_pk_add_f32 v[86:87], v[86:87], v[94:95]
	v_pk_add_f32 v[84:85], v[84:85], v[92:93]
	v_lshlrev_b32_e32 v98, 16, v171
	v_and_b32_e32 v99, 0xffff0000, v171
	v_pk_add_f32 v[94:95], v[80:81], v[96:97]
	v_mul_f32_e32 v80, v85, v85
	v_mul_f32_e32 v81, v87, v87
	v_pk_add_f32 v[92:93], v[82:83], v[98:99]
	v_fmac_f32_e32 v80, v84, v84
	v_fmac_f32_e32 v81, v86, v86
	v_add_f32_e32 v80, v80, v81
	v_mul_f32_e32 v81, v95, v95
	v_mul_f32_e32 v82, v93, v93
	v_fmac_f32_e32 v81, v94, v94
	v_fmac_f32_e32 v82, v92, v92
	v_add_f32_e32 v81, v81, v82
	v_add_f32_e32 v80, v80, v81
	v_add_f32_e32 v83, v100, v80
	ds_bpermute_b32 v98, v248, v83
	v_lshl_add_u64 v[80:81], s[12:13], 0, v[230:231]
	v_lshl_add_u64 v[96:97], v[206:207], 1, v[80:81]
	v_cvt_pk_bf16_f32 v82, v84, v85
	v_cvt_pk_bf16_f32 v84, v94, v95
	s_waitcnt lgkmcnt(0)
	v_add_f32_e32 v80, v83, v98
	ds_bpermute_b32 v81, v249, v80
	v_cvt_pk_bf16_f32 v83, v86, v87
	v_cvt_pk_bf16_f32 v85, v92, v93
	global_store_dwordx4 v[96:97], v[88:91], off sc1
	global_store_dwordx4 v[96:97], v[82:85], off offset:256 sc1
	s_and_saveexec_b64 s[36:37], s[6:7]
	s_cbranch_execz .LBB0_2707
	v_lshlrev_b64 v[82:83], 6, v[228:229]
	v_lshl_add_u64 v[82:83], s[14:15], 0, v[82:83]
	v_lshl_add_u64 v[82:83], s[34:35], 2, v[82:83]
	s_lshl_b32 s10, s51, 2
	v_lshl_add_u64 v[82:83], v[82:83], 0, s[10:11]
	s_waitcnt lgkmcnt(0)
	v_add_f32_e32 v80, v80, v81
	global_store_dword v[82:83], v80, off
.LBB0_2707:
	s_or_b64 exec, exec, s[36:37]
	v_lshlrev_b32_e32 v80, 16, v164
	s_waitcnt lgkmcnt(0)
	v_and_b32_e32 v81, 0xffff0000, v164
	v_lshlrev_b32_e32 v82, 16, v165
	v_and_b32_e32 v83, 0xffff0000, v165
	v_lshlrev_b32_e32 v84, 16, v166
	v_and_b32_e32 v85, 0xffff0000, v166
	v_lshlrev_b32_e32 v86, 16, v167
	v_and_b32_e32 v87, 0xffff0000, v167
	v_pk_add_f32 v[78:79], v[78:79], v[82:83]
	v_pk_add_f32 v[76:77], v[76:77], v[80:81]
	v_pk_add_f32 v[80:81], v[74:75], v[86:87]
	v_pk_add_f32 v[74:75], v[72:73], v[84:85]
	v_mul_f32_e32 v72, v77, v77
	v_mul_f32_e32 v73, v79, v79
	v_fmac_f32_e32 v72, v76, v76
	v_fmac_f32_e32 v73, v78, v78
	v_add_f32_e32 v72, v72, v73
	v_mul_f32_e32 v73, v75, v75
	v_mul_f32_e32 v82, v81, v81
	v_fmac_f32_e32 v73, v74, v74
	v_fmac_f32_e32 v82, v80, v80
	v_add_f32_e32 v73, v73, v82
	v_add_f32_e32 v84, v72, v73
	v_cvt_pk_bf16_f32 v72, v76, v77
	v_cvt_pk_bf16_f32 v73, v78, v79
	v_lshlrev_b32_e32 v76, 16, v160
	v_and_b32_e32 v77, 0xffff0000, v160
	v_lshlrev_b32_e32 v78, 16, v161
	v_and_b32_e32 v79, 0xffff0000, v161
	v_cvt_pk_bf16_f32 v74, v74, v75
	v_cvt_pk_bf16_f32 v75, v80, v81
	v_lshlrev_b32_e32 v80, 16, v162
	v_and_b32_e32 v81, 0xffff0000, v162
	v_pk_add_f32 v[70:71], v[70:71], v[78:79]
	v_pk_add_f32 v[68:69], v[68:69], v[76:77]
	v_lshlrev_b32_e32 v82, 16, v163
	v_and_b32_e32 v83, 0xffff0000, v163
	v_pk_add_f32 v[78:79], v[64:65], v[80:81]
	v_mul_f32_e32 v64, v69, v69
	v_mul_f32_e32 v65, v71, v71
	v_pk_add_f32 v[76:77], v[66:67], v[82:83]
	v_fmac_f32_e32 v64, v68, v68
	v_fmac_f32_e32 v65, v70, v70
	v_add_f32_e32 v64, v64, v65
	v_mul_f32_e32 v65, v79, v79
	v_mul_f32_e32 v66, v77, v77
	v_fmac_f32_e32 v65, v78, v78
	v_fmac_f32_e32 v66, v76, v76
	v_add_f32_e32 v65, v65, v66
	v_add_f32_e32 v64, v64, v65
	v_add_f32_e32 v67, v84, v64
	ds_bpermute_b32 v82, v248, v67
	v_lshl_add_u64 v[64:65], s[12:13], 0, v[226:227]
	v_lshl_add_u64 v[80:81], v[206:207], 1, v[64:65]
	v_cvt_pk_bf16_f32 v66, v68, v69
	v_cvt_pk_bf16_f32 v68, v78, v79
	s_waitcnt lgkmcnt(0)
	v_add_f32_e32 v64, v67, v82
	ds_bpermute_b32 v65, v249, v64
	v_cvt_pk_bf16_f32 v67, v70, v71
	v_cvt_pk_bf16_f32 v69, v76, v77
	global_store_dwordx4 v[80:81], v[72:75], off sc1
	global_store_dwordx4 v[80:81], v[66:69], off offset:256 sc1
	s_and_saveexec_b64 s[36:37], s[6:7]
	s_cbranch_execz .LBB0_2709
	v_lshlrev_b64 v[66:67], 6, v[224:225]
	v_lshl_add_u64 v[66:67], s[14:15], 0, v[66:67]
	v_lshl_add_u64 v[66:67], s[34:35], 2, v[66:67]
	s_lshl_b32 s10, s51, 2
	v_lshl_add_u64 v[66:67], v[66:67], 0, s[10:11]
	s_waitcnt lgkmcnt(0)
	v_add_f32_e32 v64, v64, v65
	global_store_dword v[66:67], v64, off
.LBB0_2709:
	s_or_b64 exec, exec, s[36:37]
	v_lshlrev_b32_e32 v64, 16, v156
	s_waitcnt lgkmcnt(0)
	v_and_b32_e32 v65, 0xffff0000, v156
	v_lshlrev_b32_e32 v66, 16, v157
	v_and_b32_e32 v67, 0xffff0000, v157
	v_lshlrev_b32_e32 v68, 16, v158
	v_and_b32_e32 v69, 0xffff0000, v158
	v_lshlrev_b32_e32 v70, 16, v159
	v_and_b32_e32 v71, 0xffff0000, v159
	v_pk_add_f32 v[62:63], v[62:63], v[66:67]
	v_pk_add_f32 v[60:61], v[60:61], v[64:65]
	v_pk_add_f32 v[64:65], v[58:59], v[70:71]
	v_pk_add_f32 v[58:59], v[56:57], v[68:69]
	v_mul_f32_e32 v56, v61, v61
	v_mul_f32_e32 v57, v63, v63
	v_fmac_f32_e32 v56, v60, v60
	v_fmac_f32_e32 v57, v62, v62
	v_add_f32_e32 v56, v56, v57
	v_mul_f32_e32 v57, v59, v59
	v_mul_f32_e32 v66, v65, v65
	v_fmac_f32_e32 v57, v58, v58
	v_fmac_f32_e32 v66, v64, v64
	v_add_f32_e32 v57, v57, v66
	v_add_f32_e32 v68, v56, v57
	v_cvt_pk_bf16_f32 v56, v60, v61
	v_cvt_pk_bf16_f32 v57, v62, v63
	v_lshlrev_b32_e32 v60, 16, v152
	v_and_b32_e32 v61, 0xffff0000, v152
	v_lshlrev_b32_e32 v62, 16, v153
	v_and_b32_e32 v63, 0xffff0000, v153
	v_cvt_pk_bf16_f32 v58, v58, v59
	v_cvt_pk_bf16_f32 v59, v64, v65
	v_lshlrev_b32_e32 v64, 16, v154
	v_and_b32_e32 v65, 0xffff0000, v154
	v_pk_add_f32 v[54:55], v[54:55], v[62:63]
	v_pk_add_f32 v[52:53], v[52:53], v[60:61]
	v_lshlrev_b32_e32 v66, 16, v155
	v_and_b32_e32 v67, 0xffff0000, v155
	v_pk_add_f32 v[62:63], v[48:49], v[64:65]
	v_mul_f32_e32 v48, v53, v53
	v_mul_f32_e32 v49, v55, v55
	v_pk_add_f32 v[60:61], v[50:51], v[66:67]
	v_fmac_f32_e32 v48, v52, v52
	v_fmac_f32_e32 v49, v54, v54
	v_add_f32_e32 v48, v48, v49
	v_mul_f32_e32 v49, v63, v63
	v_mul_f32_e32 v50, v61, v61
	v_fmac_f32_e32 v49, v62, v62
	v_fmac_f32_e32 v50, v60, v60
	v_add_f32_e32 v49, v49, v50
	v_add_f32_e32 v48, v48, v49
	v_add_f32_e32 v51, v68, v48
	ds_bpermute_b32 v66, v248, v51
	v_lshl_add_u64 v[48:49], s[12:13], 0, v[222:223]
	v_lshl_add_u64 v[64:65], v[206:207], 1, v[48:49]
	v_cvt_pk_bf16_f32 v50, v52, v53
	v_cvt_pk_bf16_f32 v52, v62, v63
	s_waitcnt lgkmcnt(0)
	v_add_f32_e32 v48, v51, v66
	ds_bpermute_b32 v49, v249, v48
	v_cvt_pk_bf16_f32 v51, v54, v55
	v_cvt_pk_bf16_f32 v53, v60, v61
	global_store_dwordx4 v[64:65], v[56:59], off sc1
	global_store_dwordx4 v[64:65], v[50:53], off offset:256 sc1
	s_and_saveexec_b64 s[36:37], s[6:7]
	s_cbranch_execz .LBB0_2711
	v_lshlrev_b64 v[50:51], 6, v[220:221]
	v_lshl_add_u64 v[50:51], s[14:15], 0, v[50:51]
	v_lshl_add_u64 v[50:51], s[34:35], 2, v[50:51]
	s_lshl_b32 s10, s51, 2
	v_lshl_add_u64 v[50:51], v[50:51], 0, s[10:11]
	s_waitcnt lgkmcnt(0)
	v_add_f32_e32 v48, v48, v49
	global_store_dword v[50:51], v48, off
.LBB0_2711:
	s_or_b64 exec, exec, s[36:37]
	v_lshlrev_b32_e32 v48, 16, v148
	s_waitcnt lgkmcnt(0)
	v_and_b32_e32 v49, 0xffff0000, v148
	v_lshlrev_b32_e32 v50, 16, v149
	v_and_b32_e32 v51, 0xffff0000, v149
	v_lshlrev_b32_e32 v52, 16, v150
	v_and_b32_e32 v53, 0xffff0000, v150
	v_lshlrev_b32_e32 v54, 16, v151
	v_and_b32_e32 v55, 0xffff0000, v151
	v_pk_add_f32 v[46:47], v[46:47], v[50:51]
	v_pk_add_f32 v[44:45], v[44:45], v[48:49]
	v_pk_add_f32 v[48:49], v[42:43], v[54:55]
	v_pk_add_f32 v[42:43], v[40:41], v[52:53]
	v_mul_f32_e32 v40, v45, v45
	v_mul_f32_e32 v41, v47, v47
	v_fmac_f32_e32 v40, v44, v44
	v_fmac_f32_e32 v41, v46, v46
	v_add_f32_e32 v40, v40, v41
	v_mul_f32_e32 v41, v43, v43
	v_mul_f32_e32 v50, v49, v49
	v_fmac_f32_e32 v41, v42, v42
	v_fmac_f32_e32 v50, v48, v48
	v_add_f32_e32 v41, v41, v50
	v_add_f32_e32 v52, v40, v41
	v_cvt_pk_bf16_f32 v40, v44, v45
	v_cvt_pk_bf16_f32 v41, v46, v47
	v_lshlrev_b32_e32 v44, 16, v144
	v_and_b32_e32 v45, 0xffff0000, v144
	v_lshlrev_b32_e32 v46, 16, v145
	v_and_b32_e32 v47, 0xffff0000, v145
	v_cvt_pk_bf16_f32 v42, v42, v43
	v_cvt_pk_bf16_f32 v43, v48, v49
	v_lshlrev_b32_e32 v48, 16, v146
	v_and_b32_e32 v49, 0xffff0000, v146
	v_pk_add_f32 v[38:39], v[38:39], v[46:47]
	v_pk_add_f32 v[36:37], v[36:37], v[44:45]
	v_lshlrev_b32_e32 v50, 16, v147
	v_and_b32_e32 v51, 0xffff0000, v147
	v_pk_add_f32 v[46:47], v[32:33], v[48:49]
	v_mul_f32_e32 v32, v37, v37
	v_mul_f32_e32 v33, v39, v39
	v_pk_add_f32 v[44:45], v[34:35], v[50:51]
	v_fmac_f32_e32 v32, v36, v36
	v_fmac_f32_e32 v33, v38, v38
	v_add_f32_e32 v32, v32, v33
	v_mul_f32_e32 v33, v47, v47
	v_mul_f32_e32 v34, v45, v45
	v_fmac_f32_e32 v33, v46, v46
	v_fmac_f32_e32 v34, v44, v44
	v_add_f32_e32 v33, v33, v34
	v_add_f32_e32 v32, v32, v33
	v_add_f32_e32 v35, v52, v32
	ds_bpermute_b32 v50, v248, v35
	v_lshl_add_u64 v[32:33], s[12:13], 0, v[218:219]
	v_lshl_add_u64 v[48:49], v[206:207], 1, v[32:33]
	v_cvt_pk_bf16_f32 v34, v36, v37
	v_cvt_pk_bf16_f32 v36, v46, v47
	s_waitcnt lgkmcnt(0)
	v_add_f32_e32 v32, v35, v50
	ds_bpermute_b32 v33, v249, v32
	v_cvt_pk_bf16_f32 v35, v38, v39
	v_cvt_pk_bf16_f32 v37, v44, v45
	global_store_dwordx4 v[48:49], v[40:43], off sc1
	global_store_dwordx4 v[48:49], v[34:37], off offset:256 sc1
	s_and_saveexec_b64 s[36:37], s[6:7]
	s_cbranch_execz .LBB0_2713
	v_lshlrev_b64 v[34:35], 6, v[216:217]
	v_lshl_add_u64 v[34:35], s[14:15], 0, v[34:35]
	v_lshl_add_u64 v[34:35], s[34:35], 2, v[34:35]
	s_lshl_b32 s10, s51, 2
	v_lshl_add_u64 v[34:35], v[34:35], 0, s[10:11]
	s_waitcnt lgkmcnt(0)
	v_add_f32_e32 v32, v32, v33
	global_store_dword v[34:35], v32, off
.LBB0_2713:
	s_or_b64 exec, exec, s[36:37]
	v_lshlrev_b32_e32 v32, 16, v132
	s_waitcnt lgkmcnt(0)
	v_and_b32_e32 v33, 0xffff0000, v132
	v_lshlrev_b32_e32 v34, 16, v133
	v_and_b32_e32 v35, 0xffff0000, v133
	v_lshlrev_b32_e32 v36, 16, v134
	v_and_b32_e32 v37, 0xffff0000, v134
	v_lshlrev_b32_e32 v38, 16, v135
	v_and_b32_e32 v39, 0xffff0000, v135
	v_pk_add_f32 v[30:31], v[30:31], v[34:35]
	v_pk_add_f32 v[28:29], v[28:29], v[32:33]
	v_pk_add_f32 v[32:33], v[26:27], v[38:39]
	v_pk_add_f32 v[26:27], v[24:25], v[36:37]
	v_mul_f32_e32 v24, v29, v29
	v_mul_f32_e32 v25, v31, v31
	v_fmac_f32_e32 v24, v28, v28
	v_fmac_f32_e32 v25, v30, v30
	v_add_f32_e32 v24, v24, v25
	v_mul_f32_e32 v25, v27, v27
	v_mul_f32_e32 v34, v33, v33
	v_fmac_f32_e32 v25, v26, v26
	v_fmac_f32_e32 v34, v32, v32
	v_add_f32_e32 v25, v25, v34
	v_add_f32_e32 v36, v24, v25
	v_cvt_pk_bf16_f32 v24, v28, v29
	v_cvt_pk_bf16_f32 v25, v30, v31
	v_lshlrev_b32_e32 v28, 16, v120
	v_and_b32_e32 v29, 0xffff0000, v120
	v_lshlrev_b32_e32 v30, 16, v121
	v_and_b32_e32 v31, 0xffff0000, v121
	v_cvt_pk_bf16_f32 v26, v26, v27
	v_cvt_pk_bf16_f32 v27, v32, v33
	v_lshlrev_b32_e32 v32, 16, v122
	v_and_b32_e32 v33, 0xffff0000, v122
	v_pk_add_f32 v[22:23], v[22:23], v[30:31]
	v_pk_add_f32 v[20:21], v[20:21], v[28:29]
	v_lshlrev_b32_e32 v34, 16, v123
	v_and_b32_e32 v35, 0xffff0000, v123
	v_pk_add_f32 v[30:31], v[16:17], v[32:33]
	v_mul_f32_e32 v16, v21, v21
	v_mul_f32_e32 v17, v23, v23
	v_pk_add_f32 v[28:29], v[18:19], v[34:35]
	v_fmac_f32_e32 v16, v20, v20
	v_fmac_f32_e32 v17, v22, v22
	v_add_f32_e32 v16, v16, v17
	v_mul_f32_e32 v17, v31, v31
	v_mul_f32_e32 v18, v29, v29
	v_fmac_f32_e32 v17, v30, v30
	v_fmac_f32_e32 v18, v28, v28
	v_add_f32_e32 v17, v17, v18
	v_add_f32_e32 v16, v16, v17
	v_add_f32_e32 v19, v36, v16
	ds_bpermute_b32 v34, v248, v19
	v_lshl_add_u64 v[16:17], s[12:13], 0, v[214:215]
	v_lshl_add_u64 v[32:33], v[206:207], 1, v[16:17]
	v_cvt_pk_bf16_f32 v18, v20, v21
	v_cvt_pk_bf16_f32 v20, v30, v31
	s_waitcnt lgkmcnt(0)
	v_add_f32_e32 v16, v19, v34
	ds_bpermute_b32 v17, v249, v16
	v_cvt_pk_bf16_f32 v19, v22, v23
	v_cvt_pk_bf16_f32 v21, v28, v29
	global_store_dwordx4 v[32:33], v[24:27], off sc1
	global_store_dwordx4 v[32:33], v[18:21], off offset:256 sc1
	s_and_saveexec_b64 s[36:37], s[6:7]
	s_cbranch_execz .LBB0_2715
	v_lshlrev_b64 v[18:19], 6, v[212:213]
	v_lshl_add_u64 v[18:19], s[14:15], 0, v[18:19]
	v_lshl_add_u64 v[18:19], s[34:35], 2, v[18:19]
	s_lshl_b32 s10, s51, 2
	v_lshl_add_u64 v[18:19], v[18:19], 0, s[10:11]
	s_waitcnt lgkmcnt(0)
	v_add_f32_e32 v16, v16, v17
	global_store_dword v[18:19], v16, off
.LBB0_2715:
	s_or_b64 exec, exec, s[36:37]
	v_lshlrev_b32_e32 v16, 16, v140
	s_waitcnt lgkmcnt(0)
	v_and_b32_e32 v17, 0xffff0000, v140
	v_lshlrev_b32_e32 v18, 16, v141
	v_and_b32_e32 v19, 0xffff0000, v141
	v_lshlrev_b32_e32 v20, 16, v142
	v_and_b32_e32 v21, 0xffff0000, v142
	v_lshlrev_b32_e32 v22, 16, v143
	v_and_b32_e32 v23, 0xffff0000, v143
	v_pk_add_f32 v[14:15], v[14:15], v[18:19]
	v_pk_add_f32 v[12:13], v[12:13], v[16:17]
	v_pk_add_f32 v[16:17], v[10:11], v[22:23]
	v_pk_add_f32 v[10:11], v[8:9], v[20:21]
	v_mul_f32_e32 v8, v13, v13
	v_mul_f32_e32 v9, v15, v15
	v_fmac_f32_e32 v8, v12, v12
	v_fmac_f32_e32 v9, v14, v14
	v_add_f32_e32 v8, v8, v9
	v_mul_f32_e32 v9, v11, v11
	v_mul_f32_e32 v18, v17, v17
	v_fmac_f32_e32 v9, v10, v10
	v_fmac_f32_e32 v18, v16, v16
	v_add_f32_e32 v9, v9, v18
	v_add_f32_e32 v20, v8, v9
	v_cvt_pk_bf16_f32 v8, v12, v13
	v_cvt_pk_bf16_f32 v9, v14, v15
	v_lshlrev_b32_e32 v12, 16, v124
	v_and_b32_e32 v13, 0xffff0000, v124
	v_lshlrev_b32_e32 v14, 16, v125
	v_and_b32_e32 v15, 0xffff0000, v125
	v_cvt_pk_bf16_f32 v10, v10, v11
	v_cvt_pk_bf16_f32 v11, v16, v17
	v_lshlrev_b32_e32 v16, 16, v126
	v_and_b32_e32 v17, 0xffff0000, v126
	v_pk_add_f32 v[6:7], v[6:7], v[14:15]
	v_pk_add_f32 v[4:5], v[4:5], v[12:13]
	v_lshlrev_b32_e32 v18, 16, v127
	v_and_b32_e32 v19, 0xffff0000, v127
	v_pk_add_f32 v[14:15], v[0:1], v[16:17]
	v_mul_f32_e32 v0, v5, v5
	v_mul_f32_e32 v1, v7, v7
	v_pk_add_f32 v[12:13], v[2:3], v[18:19]
	v_fmac_f32_e32 v0, v4, v4
	v_fmac_f32_e32 v1, v6, v6
	v_add_f32_e32 v0, v0, v1
	v_mul_f32_e32 v1, v15, v15
	v_mul_f32_e32 v2, v13, v13
	v_fmac_f32_e32 v1, v14, v14
	v_fmac_f32_e32 v2, v12, v12
	v_add_f32_e32 v1, v1, v2
	v_add_f32_e32 v0, v0, v1
	v_add_f32_e32 v3, v20, v0
	ds_bpermute_b32 v18, v248, v3
	v_lshl_add_u64 v[0:1], s[12:13], 0, v[210:211]
	v_lshl_add_u64 v[16:17], v[206:207], 1, v[0:1]
	v_cvt_pk_bf16_f32 v2, v4, v5
	v_cvt_pk_bf16_f32 v4, v14, v15
	s_waitcnt lgkmcnt(0)
	v_add_f32_e32 v0, v3, v18
	ds_bpermute_b32 v1, v249, v0
	v_cvt_pk_bf16_f32 v3, v6, v7
	v_cvt_pk_bf16_f32 v5, v12, v13
	global_store_dwordx4 v[16:17], v[8:11], off sc1
	global_store_dwordx4 v[16:17], v[2:5], off offset:256 sc1
	s_and_saveexec_b64 s[36:37], s[6:7]
	s_cbranch_execz .LBB0_2692
	s_waitcnt lgkmcnt(0)
	v_add_f32_e32 v2, v0, v1
	v_lshlrev_b64 v[0:1], 6, v[208:209]
	v_lshl_add_u64 v[0:1], s[14:15], 0, v[0:1]
	v_lshl_add_u64 v[0:1], s[34:35], 2, v[0:1]
	s_lshl_b32 s10, s51, 2
	v_lshl_add_u64 v[0:1], v[0:1], 0, s[10:11]
	global_store_dword v[0:1], v2, off
	s_branch .LBB0_2692

.LBB0_2782:
	ds_read2_b32 v[164:165], v155 offset1:16
	ds_read2_b32 v[150:151], v155 offset0:32 offset1:48
	ds_read2_b32 v[148:149], v155 offset0:64 offset1:80
	ds_read2_b32 v[146:147], v155 offset0:96 offset1:112
	v_pk_mul_f32 v[120:121], v[124:125], v[120:121]
	s_waitcnt lgkmcnt(0)
	v_mul_f32_e32 v166, 0xbfb8aa3b, v164
	v_pk_mul_f32 v[168:169], v[124:125], v[166:167] op_sel_hi:[1,0]
	v_pk_mul_f32 v[170:171], v[126:127], v[166:167] op_sel_hi:[1,0]
	v_exp_f32_e32 v167, v169
	v_exp_f32_e32 v161, v168
	v_pk_mul_f32 v[122:123], v[126:127], v[122:123]
	v_exp_f32_e32 v171, v171
	v_add_f32_e32 v167, 1.0, v167
	v_pk_mul_f32 v[124:125], v[116:117], v[166:167] op_sel_hi:[1,0]
	v_add_f32_e32 v161, 1.0, v161
	v_exp_f32_e32 v124, v124
	v_pk_mul_f32 v[126:127], v[118:119], v[166:167] op_sel_hi:[1,0]
	v_exp_f32_e32 v125, v125
	v_rcp_f32_e32 v168, v161
	v_exp_f32_e32 v161, v170
	v_exp_f32_e32 v126, v126
	v_exp_f32_e32 v127, v127
	v_add_f32_e32 v124, 1.0, v124
	v_add_f32_e32 v125, 1.0, v125
	v_add_f32_e32 v161, 1.0, v161
	v_rcp_f32_e32 v124, v124
	v_rcp_f32_e32 v125, v125
	v_add_f32_e32 v126, 1.0, v126
	v_add_f32_e32 v127, 1.0, v127
	v_rcp_f32_e32 v169, v167
	v_rcp_f32_e32 v170, v161
	v_add_f32_e32 v161, 1.0, v171
	v_rcp_f32_e32 v126, v126
	v_rcp_f32_e32 v127, v127
	v_mul_f32_e32 v164, v164, v164
	v_rcp_f32_e32 v171, v161
	v_pk_mul_f32 v[112:113], v[116:117], v[112:113]
	v_pk_mul_f32 v[114:115], v[118:119], v[114:115]
	v_pk_mul_f32 v[112:113], v[112:113], v[164:165] op_sel_hi:[1,0]
	v_lshl_or_b32 v162, s63, 7, v156
	v_pk_mul_f32 v[120:121], v[120:121], v[164:165] op_sel_hi:[1,0]
	v_pk_mul_f32 v[112:113], v[112:113], v[124:125]
	v_pk_mul_f32 v[114:115], v[114:115], v[164:165] op_sel_hi:[1,0]
	v_add_u32_e32 v160, s25, v145
	v_ashrrev_i32_e32 v163, 31, v162
	v_pk_mul_f32 v[120:121], v[120:121], v[168:169]
	v_pk_mul_f32 v[122:123], v[122:123], v[164:165] op_sel_hi:[1,0]
	v_pk_mul_f32 v[114:115], v[114:115], v[126:127]
	v_cvt_pk_bf16_f32 v118, v112, v113
	v_mov_b64_e32 v[112:113], s[10:11]
	v_pk_mul_f32 v[122:123], v[122:123], v[170:171]
	v_cvt_pk_bf16_f32 v116, v120, v121
	v_cvt_pk_bf16_f32 v119, v114, v115
	v_mad_i64_i32 v[120:121], s[8:9], v160, s58, v[112:113]
	v_lshlrev_b64 v[114:115], 1, v[162:163]
	v_cvt_pk_bf16_f32 v117, v122, v123
	v_lshl_add_u64 v[120:121], v[120:121], 0, v[114:115]
	global_store_dwordx4 v[120:121], v[116:119], off sc1
	v_pk_mul_f32 v[104:105], v[108:109], v[104:105]
	v_pk_mul_f32 v[106:107], v[110:111], v[106:107]
	v_mul_f32_e32 v116, 0xbfb8aa3b, v165
	v_pk_mul_f32 v[118:119], v[108:109], v[116:117] op_sel_hi:[1,0]
	v_pk_mul_f32 v[96:97], v[100:101], v[96:97]
	v_exp_f32_e32 v117, v118
	v_exp_f32_e32 v119, v119
	v_mul_f32_e32 v118, v165, v165
	v_pk_mul_f32 v[98:99], v[102:103], v[98:99]
	v_pk_mul_f32 v[120:121], v[110:111], v[116:117] op_sel_hi:[1,0]
	v_add_f32_e32 v117, 1.0, v117
	v_rcp_f32_e32 v122, v117
	v_exp_f32_e32 v117, v120
	v_exp_f32_e32 v121, v121
	v_add_f32_e32 v119, 1.0, v119
	v_rcp_f32_e32 v123, v119
	v_add_f32_e32 v117, 1.0, v117
	v_rcp_f32_e32 v120, v117
	v_add_f32_e32 v117, 1.0, v121
	v_pk_mul_f32 v[108:109], v[100:101], v[116:117] op_sel_hi:[1,0]
	v_pk_mul_f32 v[110:111], v[102:103], v[116:117] op_sel_hi:[1,0]
	v_exp_f32_e32 v108, v108
	v_exp_f32_e32 v109, v109
	v_exp_f32_e32 v110, v110
	v_exp_f32_e32 v111, v111
	v_add_f32_e32 v108, 1.0, v108
	v_add_f32_e32 v109, 1.0, v109
	v_rcp_f32_e32 v108, v108
	v_rcp_f32_e32 v109, v109
	v_add_f32_e32 v110, 1.0, v110
	v_add_f32_e32 v111, 1.0, v111
	v_rcp_f32_e32 v121, v117
	v_rcp_f32_e32 v110, v110
	v_rcp_f32_e32 v111, v111
	v_pk_mul_f32 v[96:97], v[96:97], v[118:119] op_sel_hi:[1,0]
	v_pk_mul_f32 v[104:105], v[104:105], v[118:119] op_sel_hi:[1,0]
	v_pk_mul_f32 v[106:107], v[106:107], v[118:119] op_sel_hi:[1,0]
	v_pk_mul_f32 v[100:101], v[96:97], v[108:109]
	v_pk_mul_f32 v[96:97], v[98:99], v[118:119] op_sel_hi:[1,0]
	v_or_b32_e32 v108, 16, v160
	v_pk_mul_f32 v[104:105], v[104:105], v[122:123]
	v_pk_mul_f32 v[106:107], v[106:107], v[120:121]
	v_pk_mul_f32 v[102:103], v[96:97], v[110:111]
	v_cvt_pk_bf16_f32 v98, v100, v101
	v_mad_i64_i32 v[100:101], s[8:9], v108, s58, v[112:113]
	v_cvt_pk_bf16_f32 v96, v104, v105
	v_cvt_pk_bf16_f32 v97, v106, v107
	v_cvt_pk_bf16_f32 v99, v102, v103
	v_lshl_add_u64 v[100:101], v[100:101], 0, v[114:115]
	global_store_dwordx4 v[100:101], v[96:99], off sc1
	v_pk_mul_f32 v[88:89], v[92:93], v[88:89]
	v_pk_mul_f32 v[90:91], v[94:95], v[90:91]
	v_mul_f32_e32 v96, 0xbfb8aa3b, v150
	v_pk_mul_f32 v[98:99], v[92:93], v[96:97] op_sel_hi:[1,0]
	v_pk_mul_f32 v[80:81], v[84:85], v[80:81]
	v_exp_f32_e32 v97, v98
	v_exp_f32_e32 v99, v99
	v_mul_f32_e32 v98, v150, v150
	v_pk_mul_f32 v[82:83], v[86:87], v[82:83]
	v_pk_mul_f32 v[100:101], v[94:95], v[96:97] op_sel_hi:[1,0]
	v_add_f32_e32 v97, 1.0, v97
	v_rcp_f32_e32 v102, v97
	v_exp_f32_e32 v97, v100
	v_exp_f32_e32 v101, v101
	v_add_f32_e32 v99, 1.0, v99
	v_rcp_f32_e32 v103, v99
	v_add_f32_e32 v97, 1.0, v97
	v_rcp_f32_e32 v100, v97
	v_add_f32_e32 v97, 1.0, v101
	v_pk_mul_f32 v[92:93], v[84:85], v[96:97] op_sel_hi:[1,0]
	v_pk_mul_f32 v[94:95], v[86:87], v[96:97] op_sel_hi:[1,0]
	v_exp_f32_e32 v92, v92
	v_exp_f32_e32 v93, v93
	v_exp_f32_e32 v94, v94
	v_exp_f32_e32 v95, v95
	v_add_f32_e32 v92, 1.0, v92
	v_add_f32_e32 v93, 1.0, v93
	v_rcp_f32_e32 v92, v92
	v_rcp_f32_e32 v93, v93
	v_add_f32_e32 v94, 1.0, v94
	v_add_f32_e32 v95, 1.0, v95
	v_rcp_f32_e32 v101, v97
	v_rcp_f32_e32 v94, v94
	v_rcp_f32_e32 v95, v95
	v_pk_mul_f32 v[80:81], v[80:81], v[98:99] op_sel_hi:[1,0]
	v_pk_mul_f32 v[88:89], v[88:89], v[98:99] op_sel_hi:[1,0]
	v_pk_mul_f32 v[90:91], v[90:91], v[98:99] op_sel_hi:[1,0]
	v_pk_mul_f32 v[84:85], v[80:81], v[92:93]
	v_pk_mul_f32 v[80:81], v[82:83], v[98:99] op_sel_hi:[1,0]
	v_or_b32_e32 v92, 32, v160
	v_pk_mul_f32 v[88:89], v[88:89], v[102:103]
	v_pk_mul_f32 v[90:91], v[90:91], v[100:101]
	v_pk_mul_f32 v[86:87], v[80:81], v[94:95]
	v_cvt_pk_bf16_f32 v82, v84, v85
	v_mad_i64_i32 v[84:85], s[8:9], v92, s58, v[112:113]
	v_cvt_pk_bf16_f32 v80, v88, v89
	v_cvt_pk_bf16_f32 v81, v90, v91
	v_cvt_pk_bf16_f32 v83, v86, v87
	v_lshl_add_u64 v[84:85], v[84:85], 0, v[114:115]
	global_store_dwordx4 v[84:85], v[80:83], off sc1
	v_pk_mul_f32 v[72:73], v[76:77], v[72:73]
	v_pk_mul_f32 v[74:75], v[78:79], v[74:75]
	v_mul_f32_e32 v80, 0xbfb8aa3b, v151
	v_pk_mul_f32 v[82:83], v[76:77], v[80:81] op_sel_hi:[1,0]
	v_pk_mul_f32 v[64:65], v[68:69], v[64:65]
	v_exp_f32_e32 v81, v82
	v_exp_f32_e32 v83, v83
	v_mul_f32_e32 v82, v151, v151
	v_pk_mul_f32 v[66:67], v[70:71], v[66:67]
	v_pk_mul_f32 v[84:85], v[78:79], v[80:81] op_sel_hi:[1,0]
	v_add_f32_e32 v81, 1.0, v81
	v_rcp_f32_e32 v86, v81
	v_exp_f32_e32 v81, v84
	v_exp_f32_e32 v85, v85
	v_add_f32_e32 v83, 1.0, v83
	v_rcp_f32_e32 v87, v83
	v_add_f32_e32 v81, 1.0, v81
	v_rcp_f32_e32 v84, v81
	v_add_f32_e32 v81, 1.0, v85
	v_pk_mul_f32 v[76:77], v[68:69], v[80:81] op_sel_hi:[1,0]
	v_pk_mul_f32 v[78:79], v[70:71], v[80:81] op_sel_hi:[1,0]
	v_exp_f32_e32 v76, v76
	v_exp_f32_e32 v77, v77
	v_exp_f32_e32 v78, v78
	v_exp_f32_e32 v79, v79
	v_add_f32_e32 v76, 1.0, v76
	v_add_f32_e32 v77, 1.0, v77
	v_rcp_f32_e32 v76, v76
	v_rcp_f32_e32 v77, v77
	v_add_f32_e32 v78, 1.0, v78
	v_add_f32_e32 v79, 1.0, v79
	v_rcp_f32_e32 v85, v81
	v_rcp_f32_e32 v78, v78
	v_rcp_f32_e32 v79, v79
	v_pk_mul_f32 v[64:65], v[64:65], v[82:83] op_sel_hi:[1,0]
	v_pk_mul_f32 v[72:73], v[72:73], v[82:83] op_sel_hi:[1,0]
	v_pk_mul_f32 v[74:75], v[74:75], v[82:83] op_sel_hi:[1,0]
	v_pk_mul_f32 v[68:69], v[64:65], v[76:77]
	v_pk_mul_f32 v[64:65], v[66:67], v[82:83] op_sel_hi:[1,0]
	v_or_b32_e32 v76, 48, v160
	v_pk_mul_f32 v[72:73], v[72:73], v[86:87]
	v_pk_mul_f32 v[74:75], v[74:75], v[84:85]
	v_pk_mul_f32 v[70:71], v[64:65], v[78:79]
	v_cvt_pk_bf16_f32 v66, v68, v69
	v_mad_i64_i32 v[68:69], s[8:9], v76, s58, v[112:113]
	v_cvt_pk_bf16_f32 v64, v72, v73
	v_cvt_pk_bf16_f32 v65, v74, v75
	v_cvt_pk_bf16_f32 v67, v70, v71
	v_lshl_add_u64 v[68:69], v[68:69], 0, v[114:115]
	global_store_dwordx4 v[68:69], v[64:67], off sc1
	v_pk_mul_f32 v[56:57], v[60:61], v[56:57]
	v_pk_mul_f32 v[58:59], v[62:63], v[58:59]
	v_add_u32_e32 v65, 0x80, v160
	v_mul_f32_e32 v64, 0xbfb8aa3b, v148
	v_pk_mul_f32 v[66:67], v[60:61], v[64:65] op_sel_hi:[1,0]
	v_pk_mul_f32 v[68:69], v[62:63], v[64:65] op_sel_hi:[1,0]
	v_exp_f32_e32 v67, v67
	v_pk_mul_f32 v[60:61], v[52:53], v[64:65] op_sel_hi:[1,0]
	v_exp_f32_e32 v68, v68
	v_exp_f32_e32 v60, v60
	v_pk_mul_f32 v[62:63], v[54:55], v[64:65] op_sel_hi:[1,0]
	v_exp_f32_e32 v61, v61
	v_exp_f32_e32 v70, v66
	v_exp_f32_e32 v69, v69
	v_exp_f32_e32 v62, v62
	v_exp_f32_e32 v63, v63
	v_add_f32_e32 v67, 1.0, v67
	v_rcp_f32_e32 v71, v67
	v_add_f32_e32 v67, 1.0, v68
	v_add_f32_e32 v60, 1.0, v60
	v_add_f32_e32 v61, 1.0, v61
	v_add_f32_e32 v70, 1.0, v70
	v_rcp_f32_e32 v68, v67
	v_add_f32_e32 v67, 1.0, v69
	v_rcp_f32_e32 v60, v60
	v_rcp_f32_e32 v61, v61
	v_add_f32_e32 v62, 1.0, v62
	v_add_f32_e32 v63, 1.0, v63
	v_rcp_f32_e32 v70, v70
	v_rcp_f32_e32 v69, v67
	v_rcp_f32_e32 v62, v62
	v_rcp_f32_e32 v63, v63
	v_mul_f32_e32 v66, v148, v148
	v_pk_mul_f32 v[48:49], v[52:53], v[48:49]
	v_pk_mul_f32 v[50:51], v[54:55], v[50:51]
	v_pk_mul_f32 v[48:49], v[48:49], v[66:67] op_sel_hi:[1,0]
	v_pk_mul_f32 v[56:57], v[56:57], v[66:67] op_sel_hi:[1,0]
	v_pk_mul_f32 v[58:59], v[58:59], v[66:67] op_sel_hi:[1,0]
	v_pk_mul_f32 v[52:53], v[48:49], v[60:61]
	v_pk_mul_f32 v[48:49], v[50:51], v[66:67] op_sel_hi:[1,0]
	v_pk_mul_f32 v[56:57], v[56:57], v[70:71]
	v_pk_mul_f32 v[58:59], v[58:59], v[68:69]
	v_pk_mul_f32 v[54:55], v[48:49], v[62:63]
	v_cvt_pk_bf16_f32 v50, v52, v53
	v_mad_i64_i32 v[52:53], s[8:9], v65, s58, v[112:113]
	v_cvt_pk_bf16_f32 v48, v56, v57
	v_cvt_pk_bf16_f32 v49, v58, v59
	v_cvt_pk_bf16_f32 v51, v54, v55
	v_lshl_add_u64 v[52:53], v[52:53], 0, v[114:115]
	global_store_dwordx4 v[52:53], v[48:51], off sc1
	v_pk_mul_f32 v[40:41], v[44:45], v[40:41]
	v_pk_mul_f32 v[42:43], v[46:47], v[42:43]
	v_mul_f32_e32 v48, 0xbfb8aa3b, v149
	v_pk_mul_f32 v[50:51], v[44:45], v[48:49] op_sel_hi:[1,0]
	v_pk_mul_f32 v[32:33], v[36:37], v[32:33]
	v_exp_f32_e32 v49, v50
	v_exp_f32_e32 v51, v51
	v_mul_f32_e32 v50, v149, v149
	v_pk_mul_f32 v[34:35], v[38:39], v[34:35]
	v_pk_mul_f32 v[52:53], v[46:47], v[48:49] op_sel_hi:[1,0]
	v_add_f32_e32 v49, 1.0, v49
	v_rcp_f32_e32 v54, v49
	v_exp_f32_e32 v49, v52
	v_exp_f32_e32 v53, v53
	v_add_f32_e32 v51, 1.0, v51
	v_rcp_f32_e32 v55, v51
	v_add_f32_e32 v49, 1.0, v49
	v_rcp_f32_e32 v52, v49
	v_add_f32_e32 v49, 1.0, v53
	v_pk_mul_f32 v[44:45], v[36:37], v[48:49] op_sel_hi:[1,0]
	v_pk_mul_f32 v[46:47], v[38:39], v[48:49] op_sel_hi:[1,0]
	v_exp_f32_e32 v44, v44
	v_exp_f32_e32 v45, v45
	v_exp_f32_e32 v46, v46
	v_exp_f32_e32 v47, v47
	v_add_f32_e32 v44, 1.0, v44
	v_add_f32_e32 v45, 1.0, v45
	v_rcp_f32_e32 v44, v44
	v_rcp_f32_e32 v45, v45
	v_add_f32_e32 v46, 1.0, v46
	v_add_f32_e32 v47, 1.0, v47
	v_rcp_f32_e32 v53, v49
	v_rcp_f32_e32 v46, v46
	v_rcp_f32_e32 v47, v47
	v_pk_mul_f32 v[32:33], v[32:33], v[50:51] op_sel_hi:[1,0]
	v_pk_mul_f32 v[40:41], v[40:41], v[50:51] op_sel_hi:[1,0]
	v_pk_mul_f32 v[42:43], v[42:43], v[50:51] op_sel_hi:[1,0]
	v_pk_mul_f32 v[36:37], v[32:33], v[44:45]
	v_pk_mul_f32 v[32:33], v[34:35], v[50:51] op_sel_hi:[1,0]
	v_add_u32_e32 v44, 0x90, v160
	v_pk_mul_f32 v[40:41], v[40:41], v[54:55]
	v_pk_mul_f32 v[42:43], v[42:43], v[52:53]
	v_pk_mul_f32 v[38:39], v[32:33], v[46:47]
	v_cvt_pk_bf16_f32 v34, v36, v37
	v_mad_i64_i32 v[36:37], s[8:9], v44, s58, v[112:113]
	v_cvt_pk_bf16_f32 v32, v40, v41
	v_cvt_pk_bf16_f32 v33, v42, v43
	v_cvt_pk_bf16_f32 v35, v38, v39
	v_lshl_add_u64 v[36:37], v[36:37], 0, v[114:115]
	global_store_dwordx4 v[36:37], v[32:35], off sc1
	v_pk_mul_f32 v[24:25], v[28:29], v[24:25]
	v_pk_mul_f32 v[26:27], v[30:31], v[26:27]
	v_mul_f32_e32 v32, 0xbfb8aa3b, v146
	v_pk_mul_f32 v[34:35], v[28:29], v[32:33] op_sel_hi:[1,0]
	v_pk_mul_f32 v[16:17], v[20:21], v[16:17]
	v_exp_f32_e32 v33, v34
	v_exp_f32_e32 v35, v35
	v_mul_f32_e32 v34, v146, v146
	v_pk_mul_f32 v[18:19], v[22:23], v[18:19]
	v_pk_mul_f32 v[36:37], v[30:31], v[32:33] op_sel_hi:[1,0]
	v_add_f32_e32 v33, 1.0, v33
	v_rcp_f32_e32 v38, v33
	v_exp_f32_e32 v33, v36
	v_exp_f32_e32 v37, v37
	v_add_f32_e32 v35, 1.0, v35
	v_rcp_f32_e32 v39, v35
	v_add_f32_e32 v33, 1.0, v33
	v_rcp_f32_e32 v36, v33
	v_add_f32_e32 v33, 1.0, v37
	v_pk_mul_f32 v[28:29], v[20:21], v[32:33] op_sel_hi:[1,0]
	v_pk_mul_f32 v[30:31], v[22:23], v[32:33] op_sel_hi:[1,0]
	v_exp_f32_e32 v28, v28
	v_exp_f32_e32 v29, v29
	v_exp_f32_e32 v30, v30
	v_exp_f32_e32 v31, v31
	v_add_f32_e32 v28, 1.0, v28
	v_add_f32_e32 v29, 1.0, v29
	v_rcp_f32_e32 v28, v28
	v_rcp_f32_e32 v29, v29
	v_add_f32_e32 v30, 1.0, v30
	v_add_f32_e32 v31, 1.0, v31
	v_rcp_f32_e32 v37, v33
	v_rcp_f32_e32 v30, v30
	v_rcp_f32_e32 v31, v31
	v_pk_mul_f32 v[16:17], v[16:17], v[34:35] op_sel_hi:[1,0]
	v_pk_mul_f32 v[24:25], v[24:25], v[34:35] op_sel_hi:[1,0]
	v_pk_mul_f32 v[26:27], v[26:27], v[34:35] op_sel_hi:[1,0]
	v_pk_mul_f32 v[20:21], v[16:17], v[28:29]
	v_pk_mul_f32 v[16:17], v[18:19], v[34:35] op_sel_hi:[1,0]
	v_add_u32_e32 v28, 0xa0, v160
	v_pk_mul_f32 v[24:25], v[24:25], v[38:39]
	v_pk_mul_f32 v[26:27], v[26:27], v[36:37]
	v_pk_mul_f32 v[22:23], v[16:17], v[30:31]
	v_cvt_pk_bf16_f32 v18, v20, v21
	v_mad_i64_i32 v[20:21], s[8:9], v28, s58, v[112:113]
	v_cvt_pk_bf16_f32 v16, v24, v25
	v_cvt_pk_bf16_f32 v17, v26, v27
	v_cvt_pk_bf16_f32 v19, v22, v23
	v_lshl_add_u64 v[20:21], v[20:21], 0, v[114:115]
	global_store_dwordx4 v[20:21], v[16:19], off sc1
	v_pk_mul_f32 v[8:9], v[12:13], v[8:9]
	v_pk_mul_f32 v[10:11], v[14:15], v[10:11]
	v_mul_f32_e32 v16, 0xbfb8aa3b, v147
	v_pk_mul_f32 v[18:19], v[12:13], v[16:17] op_sel_hi:[1,0]
	v_pk_mul_f32 v[0:1], v[4:5], v[0:1]
	v_exp_f32_e32 v17, v18
	v_exp_f32_e32 v19, v19
	v_mul_f32_e32 v18, v147, v147
	v_pk_mul_f32 v[2:3], v[6:7], v[2:3]
	v_pk_mul_f32 v[20:21], v[14:15], v[16:17] op_sel_hi:[1,0]
	v_add_f32_e32 v17, 1.0, v17
	v_rcp_f32_e32 v22, v17
	v_exp_f32_e32 v17, v20
	v_exp_f32_e32 v21, v21
	v_add_f32_e32 v19, 1.0, v19
	v_rcp_f32_e32 v23, v19
	v_add_f32_e32 v17, 1.0, v17
	v_rcp_f32_e32 v20, v17
	v_add_f32_e32 v17, 1.0, v21
	v_pk_mul_f32 v[12:13], v[4:5], v[16:17] op_sel_hi:[1,0]
	v_pk_mul_f32 v[14:15], v[6:7], v[16:17] op_sel_hi:[1,0]
	v_exp_f32_e32 v12, v12
	v_exp_f32_e32 v13, v13
	v_exp_f32_e32 v14, v14
	v_exp_f32_e32 v15, v15
	v_add_f32_e32 v12, 1.0, v12
	v_add_f32_e32 v13, 1.0, v13
	v_rcp_f32_e32 v12, v12
	v_rcp_f32_e32 v13, v13
	v_add_f32_e32 v14, 1.0, v14
	v_add_f32_e32 v15, 1.0, v15
	v_rcp_f32_e32 v21, v17
	v_rcp_f32_e32 v14, v14
	v_rcp_f32_e32 v15, v15
	v_pk_mul_f32 v[0:1], v[0:1], v[18:19] op_sel_hi:[1,0]
	v_pk_mul_f32 v[8:9], v[8:9], v[18:19] op_sel_hi:[1,0]
	v_pk_mul_f32 v[10:11], v[10:11], v[18:19] op_sel_hi:[1,0]
	v_pk_mul_f32 v[4:5], v[0:1], v[12:13]
	v_pk_mul_f32 v[0:1], v[2:3], v[18:19] op_sel_hi:[1,0]
	v_add_u32_e32 v12, 0xb0, v160
	v_pk_mul_f32 v[8:9], v[8:9], v[22:23]
	v_pk_mul_f32 v[10:11], v[10:11], v[20:21]
	v_pk_mul_f32 v[6:7], v[0:1], v[14:15]
	v_cvt_pk_bf16_f32 v2, v4, v5
	v_mad_i64_i32 v[4:5], s[8:9], v12, s58, v[112:113]
	v_cvt_pk_bf16_f32 v0, v8, v9
	v_cvt_pk_bf16_f32 v1, v10, v11
	v_cvt_pk_bf16_f32 v3, v6, v7
	v_lshl_add_u64 v[4:5], v[4:5], 0, v[114:115]
	s_and_b64 vcc, exec, s[6:7]
	s_mov_b32 s63, s24
	s_mov_b32 s34, s26
	s_mov_b64 s[36:37], s[30:31]
	s_mov_b64 s[8:9], s[28:29]
	global_store_dwordx4 v[4:5], v[0:3], off sc1
	s_cbranch_vccnz .LBB0_2789

.LBB0_2866:
	ds_read_b128 v[120:123], v244
	ds_read_b128 v[124:127], v244 offset:1024
	ds_read_b128 v[132:135], v244 offset:2048
	ds_read_b128 v[140:143], v244 offset:3072
	s_add_u32 s34, s30, 0xfff50080
	s_addc_u32 s35, s31, -1
	s_cmp_eq_u32 s59, 40
	s_cselect_b32 s37, s11, s35
	s_cselect_b32 s36, s10, s34
	s_cselect_b32 s35, s13, s58
	s_cselect_b32 s34, s12, s57
	v_lshl_add_u64 v[176:177], s[30:31], 0, v[202:203]
	s_add_i32 m0, s41, 0xc000
	ds_read_b128 v[144:147], v245
	ds_read_b128 v[148:151], v245 offset:1024
	ds_read_b128 v[152:155], v245 offset:2048
	ds_read_b128 v[156:159], v245 offset:3072
	ds_read_b128 v[160:163], v245 offset:4096
	ds_read_b128 v[164:167], v245 offset:5120
	ds_read_b128 v[168:171], v245 offset:6144
	ds_read_b128 v[172:175], v245 offset:7168
	global_load_lds_dwordx4 v[176:177], off
	v_lshl_add_u64 v[176:177], s[30:31], 0, v[204:205]
	s_add_i32 m0, s41, 0xe000
	s_nop 0
	global_load_lds_dwordx4 v[176:177], off
	s_waitcnt lgkmcnt(8)
	s_barrier
	s_waitcnt lgkmcnt(0)
	s_setprio 1
	s_waitcnt lgkmcnt(0)
	v_mfma_f32_16x16x32_bf16 v[136:139], v[120:123], v[144:147], v[136:139]
	v_mfma_f32_16x16x32_bf16 v[128:131], v[132:135], v[144:147], v[128:131]
	v_mfma_f32_16x16x32_bf16 v[108:111], v[120:123], v[152:155], v[108:111]
	v_mfma_f32_16x16x32_bf16 v[104:107], v[132:135], v[152:155], v[104:107]
	v_mfma_f32_16x16x32_bf16 v[92:95], v[120:123], v[160:163], v[92:95]
	v_mfma_f32_16x16x32_bf16 v[88:91], v[132:135], v[160:163], v[88:91]
	v_mfma_f32_16x16x32_bf16 v[76:79], v[120:123], v[168:171], v[76:79]
	v_mfma_f32_16x16x32_bf16 v[72:75], v[132:135], v[168:171], v[72:75]
	v_mfma_f32_16x16x32_bf16 v[136:139], v[124:127], v[148:151], v[136:139]
	v_mfma_f32_16x16x32_bf16 v[128:131], v[140:143], v[148:151], v[128:131]
	v_mfma_f32_16x16x32_bf16 v[108:111], v[124:127], v[156:159], v[108:111]
	v_mfma_f32_16x16x32_bf16 v[104:107], v[140:143], v[156:159], v[104:107]
	v_mfma_f32_16x16x32_bf16 v[92:95], v[124:127], v[164:167], v[92:95]
	v_mfma_f32_16x16x32_bf16 v[88:91], v[140:143], v[164:167], v[88:91]
	v_mfma_f32_16x16x32_bf16 v[76:79], v[124:127], v[172:175], v[76:79]
	v_mfma_f32_16x16x32_bf16 v[72:75], v[140:143], v[172:175], v[72:75]
	s_setprio 0
	s_barrier
	s_add_i32 s63, s51, s40
	v_lshl_add_u64 v[206:207], s[34:35], 0, v[196:197]
	s_mov_b32 m0, s63
	ds_read_b128 v[176:179], v246
	ds_read_b128 v[180:183], v246 offset:1024
	ds_read_b128 v[184:187], v246 offset:2048
	ds_read_b128 v[188:191], v246 offset:3072
	global_load_lds_dwordx4 v[206:207], off
	v_lshl_add_u64 v[208:209], s[34:35], 0, v[200:201]
	s_add_i32 m0, s63, 0x2000
	s_nop 0
	global_load_lds_dwordx4 v[208:209], off
	s_barrier
	s_waitcnt lgkmcnt(0)
	s_setprio 1
	s_waitcnt lgkmcnt(0)
	v_mfma_f32_16x16x32_bf16 v[116:119], v[176:179], v[144:147], v[116:119]
	v_mfma_f32_16x16x32_bf16 v[112:115], v[184:187], v[144:147], v[112:115]
	v_mfma_f32_16x16x32_bf16 v[100:103], v[176:179], v[152:155], v[100:103]
	v_mfma_f32_16x16x32_bf16 v[96:99], v[184:187], v[152:155], v[96:99]
	v_mfma_f32_16x16x32_bf16 v[84:87], v[176:179], v[160:163], v[84:87]
	v_mfma_f32_16x16x32_bf16 v[80:83], v[184:187], v[160:163], v[80:83]
	v_mfma_f32_16x16x32_bf16 v[68:71], v[176:179], v[168:171], v[68:71]
	v_mfma_f32_16x16x32_bf16 v[64:67], v[184:187], v[168:171], v[64:67]
	v_mfma_f32_16x16x32_bf16 v[116:119], v[180:183], v[148:151], v[116:119]
	v_mfma_f32_16x16x32_bf16 v[112:115], v[188:191], v[148:151], v[112:115]
	v_mfma_f32_16x16x32_bf16 v[100:103], v[180:183], v[156:159], v[100:103]
	v_mfma_f32_16x16x32_bf16 v[96:99], v[188:191], v[156:159], v[96:99]
	v_mfma_f32_16x16x32_bf16 v[84:87], v[180:183], v[164:167], v[84:87]
	v_mfma_f32_16x16x32_bf16 v[80:83], v[188:191], v[164:167], v[80:83]
	v_mfma_f32_16x16x32_bf16 v[68:71], v[180:183], v[172:175], v[68:71]
	v_mfma_f32_16x16x32_bf16 v[64:67], v[188:191], v[172:175], v[64:67]
	s_setprio 0
	s_mov_b32 m0, s41
	v_lshl_add_u64 v[210:211], s[36:37], 0, v[194:195]
	s_barrier
	ds_read_b128 v[144:147], v245 offset:16384
	ds_read_b128 v[148:151], v245 offset:17408
	ds_read_b128 v[152:155], v245 offset:18432
	ds_read_b128 v[156:159], v245 offset:19456
	ds_read_b128 v[160:163], v245 offset:20480
	ds_read_b128 v[164:167], v245 offset:21504
	ds_read_b128 v[168:171], v245 offset:22528
	ds_read_b128 v[172:175], v245 offset:23552
	global_load_lds_dwordx4 v[210:211], off
	v_lshl_add_u64 v[212:213], s[36:37], 0, v[198:199]
	s_mov_b32 m0, s42
	s_nop 0
	global_load_lds_dwordx4 v[212:213], off
	s_barrier
	s_waitcnt lgkmcnt(0)
	s_setprio 1
	s_waitcnt lgkmcnt(0)
	v_mfma_f32_16x16x32_bf16 v[60:63], v[120:123], v[144:147], v[60:63]
	v_mfma_f32_16x16x32_bf16 v[56:59], v[132:135], v[144:147], v[56:59]
	v_mfma_f32_16x16x32_bf16 v[44:47], v[120:123], v[152:155], v[44:47]
	v_mfma_f32_16x16x32_bf16 v[40:43], v[132:135], v[152:155], v[40:43]
	v_mfma_f32_16x16x32_bf16 v[28:31], v[120:123], v[160:163], v[28:31]
	v_mfma_f32_16x16x32_bf16 v[24:27], v[132:135], v[160:163], v[24:27]
	v_mfma_f32_16x16x32_bf16 v[12:15], v[120:123], v[168:171], v[12:15]
	v_mfma_f32_16x16x32_bf16 v[8:11], v[132:135], v[168:171], v[8:11]
	v_mfma_f32_16x16x32_bf16 v[60:63], v[124:127], v[148:151], v[60:63]
	v_mfma_f32_16x16x32_bf16 v[56:59], v[140:143], v[148:151], v[56:59]
	v_mfma_f32_16x16x32_bf16 v[44:47], v[124:127], v[156:159], v[44:47]
	v_mfma_f32_16x16x32_bf16 v[40:43], v[140:143], v[156:159], v[40:43]
	v_mfma_f32_16x16x32_bf16 v[28:31], v[124:127], v[164:167], v[28:31]
	v_mfma_f32_16x16x32_bf16 v[24:27], v[140:143], v[164:167], v[24:27]
	v_mfma_f32_16x16x32_bf16 v[12:15], v[124:127], v[172:175], v[12:15]
	v_mfma_f32_16x16x32_bf16 v[8:11], v[140:143], v[172:175], v[8:11]
	s_setprio 0
	s_barrier
	s_add_u32 s64, s34, 0xb0000
	s_addc_u32 s65, s35, 0
	s_add_i32 s63, s52, s40
	v_lshl_add_u64 v[120:121], s[64:65], 0, v[196:197]
	s_mov_b32 m0, s63
	s_nop 0
	global_load_lds_dwordx4 v[120:121], off
	v_lshl_add_u64 v[120:121], s[64:65], 0, v[200:201]
	s_add_i32 m0, s63, 0x2000
	s_nop 0
	global_load_lds_dwordx4 v[120:121], off
	s_waitcnt vmcnt(6)
	s_barrier
	s_setprio 1
	v_mfma_f32_16x16x32_bf16 v[52:55], v[176:179], v[144:147], v[52:55]
	v_mfma_f32_16x16x32_bf16 v[48:51], v[184:187], v[144:147], v[48:51]
	v_mfma_f32_16x16x32_bf16 v[36:39], v[176:179], v[152:155], v[36:39]
	v_mfma_f32_16x16x32_bf16 v[32:35], v[184:187], v[152:155], v[32:35]
	v_mfma_f32_16x16x32_bf16 v[20:23], v[176:179], v[160:163], v[20:23]
	v_mfma_f32_16x16x32_bf16 v[16:19], v[184:187], v[160:163], v[16:19]
	v_mfma_f32_16x16x32_bf16 v[4:7], v[176:179], v[168:171], v[4:7]
	v_mfma_f32_16x16x32_bf16 v[0:3], v[184:187], v[168:171], v[0:3]
	v_mfma_f32_16x16x32_bf16 v[52:55], v[180:183], v[148:151], v[52:55]
	v_mfma_f32_16x16x32_bf16 v[48:51], v[188:191], v[148:151], v[48:51]
	v_mfma_f32_16x16x32_bf16 v[36:39], v[180:183], v[156:159], v[36:39]
	v_mfma_f32_16x16x32_bf16 v[32:35], v[188:191], v[156:159], v[32:35]
	v_mfma_f32_16x16x32_bf16 v[20:23], v[180:183], v[164:167], v[20:23]
	v_mfma_f32_16x16x32_bf16 v[16:19], v[188:191], v[164:167], v[16:19]
	v_mfma_f32_16x16x32_bf16 v[4:7], v[180:183], v[172:175], v[4:7]
	v_mfma_f32_16x16x32_bf16 v[0:3], v[188:191], v[172:175], v[0:3]
	s_setprio 0
	s_add_i32 s63, 0, 0x18000
	v_add_u32_e32 v140, s63, v242
	s_barrier
	ds_read_b128 v[120:123], v140
	ds_read_b128 v[124:127], v140 offset:1024
	ds_read_b128 v[132:135], v140 offset:2048
	ds_read_b128 v[140:143], v140 offset:3072
	s_add_u32 s36, s36, 0xb0000
	s_addc_u32 s37, s37, 0
	s_mov_b32 m0, s43
	v_lshl_add_u64 v[176:177], s[36:37], 0, v[194:195]
	ds_read_b128 v[144:147], v245 offset:32768
	ds_read_b128 v[148:151], v245 offset:33792
	ds_read_b128 v[152:155], v245 offset:34816
	ds_read_b128 v[156:159], v245 offset:35840
	ds_read_b128 v[160:163], v245 offset:36864
	ds_read_b128 v[164:167], v245 offset:37888
	ds_read_b128 v[168:171], v245 offset:38912
	ds_read_b128 v[172:175], v245 offset:39936
	global_load_lds_dwordx4 v[176:177], off
	v_lshl_add_u64 v[176:177], s[36:37], 0, v[198:199]
	s_mov_b32 m0, s44
	s_nop 0
	global_load_lds_dwordx4 v[176:177], off
	s_waitcnt lgkmcnt(8)
	s_barrier
	s_waitcnt lgkmcnt(0)
	s_setprio 1
	s_waitcnt lgkmcnt(0)
	v_mfma_f32_16x16x32_bf16 v[136:139], v[120:123], v[144:147], v[136:139]
	v_mfma_f32_16x16x32_bf16 v[128:131], v[132:135], v[144:147], v[128:131]
	v_mfma_f32_16x16x32_bf16 v[108:111], v[120:123], v[152:155], v[108:111]
	v_mfma_f32_16x16x32_bf16 v[104:107], v[132:135], v[152:155], v[104:107]
	v_mfma_f32_16x16x32_bf16 v[92:95], v[120:123], v[160:163], v[92:95]
	v_mfma_f32_16x16x32_bf16 v[88:91], v[132:135], v[160:163], v[88:91]
	v_mfma_f32_16x16x32_bf16 v[76:79], v[120:123], v[168:171], v[76:79]
	v_mfma_f32_16x16x32_bf16 v[72:75], v[132:135], v[168:171], v[72:75]
	v_mfma_f32_16x16x32_bf16 v[136:139], v[124:127], v[148:151], v[136:139]
	v_mfma_f32_16x16x32_bf16 v[128:131], v[140:143], v[148:151], v[128:131]
	v_mfma_f32_16x16x32_bf16 v[108:111], v[124:127], v[156:159], v[108:111]
	v_mfma_f32_16x16x32_bf16 v[104:107], v[140:143], v[156:159], v[104:107]
	v_mfma_f32_16x16x32_bf16 v[92:95], v[124:127], v[164:167], v[92:95]
	v_mfma_f32_16x16x32_bf16 v[88:91], v[140:143], v[164:167], v[88:91]
	v_mfma_f32_16x16x32_bf16 v[76:79], v[124:127], v[172:175], v[76:79]
	v_mfma_f32_16x16x32_bf16 v[72:75], v[140:143], v[172:175], v[72:75]
	s_setprio 0
	s_barrier
	s_add_i32 s36, 0, 0x1c000
	s_add_i32 s37, s63, s40
	v_add_u32_e32 v188, s36, v242
	v_lshl_add_u64 v[206:207], v[206:207], 0, s[28:29]
	s_mov_b32 m0, s37
	ds_read_b128 v[176:179], v188
	ds_read_b128 v[180:183], v188 offset:1024
	ds_read_b128 v[184:187], v188 offset:2048
	ds_read_b128 v[188:191], v188 offset:3072
	global_load_lds_dwordx4 v[206:207], off
	v_lshl_add_u64 v[206:207], v[208:209], 0, s[28:29]
	s_add_i32 m0, s37, 0x2000
	s_nop 0
	global_load_lds_dwordx4 v[206:207], off
	s_barrier
	s_waitcnt lgkmcnt(0)
	s_setprio 1
	s_waitcnt lgkmcnt(0)
	v_mfma_f32_16x16x32_bf16 v[116:119], v[176:179], v[144:147], v[116:119]
	v_mfma_f32_16x16x32_bf16 v[112:115], v[184:187], v[144:147], v[112:115]
	v_mfma_f32_16x16x32_bf16 v[100:103], v[176:179], v[152:155], v[100:103]
	v_mfma_f32_16x16x32_bf16 v[96:99], v[184:187], v[152:155], v[96:99]
	v_mfma_f32_16x16x32_bf16 v[84:87], v[176:179], v[160:163], v[84:87]
	v_mfma_f32_16x16x32_bf16 v[80:83], v[184:187], v[160:163], v[80:83]
	v_mfma_f32_16x16x32_bf16 v[68:71], v[176:179], v[168:171], v[68:71]
	v_mfma_f32_16x16x32_bf16 v[64:67], v[184:187], v[168:171], v[64:67]
	v_mfma_f32_16x16x32_bf16 v[116:119], v[180:183], v[148:151], v[116:119]
	v_mfma_f32_16x16x32_bf16 v[112:115], v[188:191], v[148:151], v[112:115]
	v_mfma_f32_16x16x32_bf16 v[100:103], v[180:183], v[156:159], v[100:103]
	v_mfma_f32_16x16x32_bf16 v[96:99], v[188:191], v[156:159], v[96:99]
	v_mfma_f32_16x16x32_bf16 v[84:87], v[180:183], v[164:167], v[84:87]
	v_mfma_f32_16x16x32_bf16 v[80:83], v[188:191], v[164:167], v[80:83]
	v_mfma_f32_16x16x32_bf16 v[68:71], v[180:183], v[172:175], v[68:71]
	v_mfma_f32_16x16x32_bf16 v[64:67], v[188:191], v[172:175], v[64:67]
	s_setprio 0
	s_mov_b32 m0, s46
	v_lshl_add_u64 v[206:207], v[210:211], 0, s[28:29]
	s_barrier
	ds_read_b128 v[144:147], v245 offset:49152
	ds_read_b128 v[148:151], v245 offset:50176
	ds_read_b128 v[152:155], v245 offset:51200
	ds_read_b128 v[156:159], v245 offset:52224
	ds_read_b128 v[160:163], v245 offset:53248
	ds_read_b128 v[164:167], v245 offset:54272
	ds_read_b128 v[168:171], v245 offset:55296
	ds_read_b128 v[172:175], v245 offset:56320
	global_load_lds_dwordx4 v[206:207], off
	v_lshl_add_u64 v[206:207], v[212:213], 0, s[28:29]
	s_mov_b32 m0, s47
	s_nop 0
	global_load_lds_dwordx4 v[206:207], off
	s_barrier
	s_waitcnt lgkmcnt(0)
	s_setprio 1
	s_waitcnt lgkmcnt(0)
	v_mfma_f32_16x16x32_bf16 v[60:63], v[120:123], v[144:147], v[60:63]
	v_mfma_f32_16x16x32_bf16 v[56:59], v[132:135], v[144:147], v[56:59]
	v_mfma_f32_16x16x32_bf16 v[44:47], v[120:123], v[152:155], v[44:47]
	v_mfma_f32_16x16x32_bf16 v[40:43], v[132:135], v[152:155], v[40:43]
	v_mfma_f32_16x16x32_bf16 v[28:31], v[120:123], v[160:163], v[28:31]
	v_mfma_f32_16x16x32_bf16 v[24:27], v[132:135], v[160:163], v[24:27]
	v_mfma_f32_16x16x32_bf16 v[12:15], v[120:123], v[168:171], v[12:15]
	v_mfma_f32_16x16x32_bf16 v[8:11], v[132:135], v[168:171], v[8:11]
	v_mfma_f32_16x16x32_bf16 v[60:63], v[124:127], v[148:151], v[60:63]
	v_mfma_f32_16x16x32_bf16 v[56:59], v[140:143], v[148:151], v[56:59]
	v_mfma_f32_16x16x32_bf16 v[44:47], v[124:127], v[156:159], v[44:47]
	v_mfma_f32_16x16x32_bf16 v[40:43], v[140:143], v[156:159], v[40:43]
	v_mfma_f32_16x16x32_bf16 v[28:31], v[124:127], v[164:167], v[28:31]
	v_mfma_f32_16x16x32_bf16 v[24:27], v[140:143], v[164:167], v[24:27]
	v_mfma_f32_16x16x32_bf16 v[12:15], v[124:127], v[172:175], v[12:15]
	v_mfma_f32_16x16x32_bf16 v[8:11], v[140:143], v[172:175], v[8:11]
	s_setprio 0
	s_barrier
	s_add_u32 s34, s34, 0xb0080
	s_addc_u32 s35, s35, 0
	s_add_i32 s36, s36, s40
	v_lshl_add_u64 v[120:121], s[34:35], 0, v[196:197]
	s_mov_b32 m0, s36
	s_nop 0
	global_load_lds_dwordx4 v[120:121], off
	v_lshl_add_u64 v[120:121], s[34:35], 0, v[200:201]
	s_add_i32 m0, s36, 0x2000
	s_nop 0
	global_load_lds_dwordx4 v[120:121], off
	s_waitcnt vmcnt(6)
	s_barrier
	s_setprio 1
	v_mfma_f32_16x16x32_bf16 v[52:55], v[176:179], v[144:147], v[52:55]
	v_mfma_f32_16x16x32_bf16 v[48:51], v[184:187], v[144:147], v[48:51]
	v_mfma_f32_16x16x32_bf16 v[36:39], v[176:179], v[152:155], v[36:39]
	v_mfma_f32_16x16x32_bf16 v[32:35], v[184:187], v[152:155], v[32:35]
	v_mfma_f32_16x16x32_bf16 v[20:23], v[176:179], v[160:163], v[20:23]
	v_mfma_f32_16x16x32_bf16 v[16:19], v[184:187], v[160:163], v[16:19]
	v_mfma_f32_16x16x32_bf16 v[4:7], v[176:179], v[168:171], v[4:7]
	v_mfma_f32_16x16x32_bf16 v[0:3], v[184:187], v[168:171], v[0:3]
	v_mfma_f32_16x16x32_bf16 v[52:55], v[180:183], v[148:151], v[52:55]
	v_mfma_f32_16x16x32_bf16 v[48:51], v[188:191], v[148:151], v[48:51]
	v_mfma_f32_16x16x32_bf16 v[36:39], v[180:183], v[156:159], v[36:39]
	v_mfma_f32_16x16x32_bf16 v[32:35], v[188:191], v[156:159], v[32:35]
	v_mfma_f32_16x16x32_bf16 v[20:23], v[180:183], v[164:167], v[20:23]
	v_mfma_f32_16x16x32_bf16 v[16:19], v[188:191], v[164:167], v[16:19]
	v_mfma_f32_16x16x32_bf16 v[4:7], v[180:183], v[172:175], v[4:7]
	v_mfma_f32_16x16x32_bf16 v[0:3], v[188:191], v[172:175], v[0:3]
	s_setprio 0
	s_add_i32 s59, s59, 2
	s_add_u32 s30, s30, 0x100
	s_addc_u32 s31, s31, 0
	s_add_u32 s57, s57, 0x100
	s_addc_u32 s58, s58, 0
	s_cmp_gt_u32 s59, 41
	s_barrier
	s_cbranch_scc0 .LBB0_2866
	v_lshl_or_b32 v206, s16, 8, v243
	v_lshl_add_u32 v236, s56, 8, v193
	v_ashrrev_i32_e32 v207, 31, v206
	v_lshlrev_b64 v[238:239], 1, v[206:207]
	v_ashrrev_i32_e32 v237, 31, v236
	v_lshl_add_u64 v[124:125], s[24:25], 0, v[238:239]
	v_lshlrev_b64 v[240:241], 11, v[236:237]
	v_lshl_add_u64 v[120:121], v[124:125], 0, v[240:241]
	global_load_dwordx4 v[188:191], v[120:121], off
	global_load_dwordx4 v[184:187], v[120:121], off offset:256
	v_or_b32_e32 v232, 16, v236
	v_ashrrev_i32_e32 v233, 31, v232
	v_or_b32_e32 v228, 32, v236
	v_lshlrev_b64 v[234:235], 11, v[232:233]
	v_ashrrev_i32_e32 v229, 31, v228
	v_or_b32_e32 v224, 48, v236
	v_lshl_add_u64 v[120:121], v[124:125], 0, v[234:235]
	v_lshlrev_b64 v[230:231], 11, v[228:229]
	v_ashrrev_i32_e32 v225, 31, v224
	v_add_u32_e32 v220, 0x80, v236
	global_load_dwordx4 v[180:183], v[120:121], off
	global_load_dwordx4 v[176:179], v[120:121], off offset:256
	v_lshl_add_u64 v[120:121], v[124:125], 0, v[230:231]
	v_lshlrev_b64 v[226:227], 11, v[224:225]
	v_ashrrev_i32_e32 v221, 31, v220
	v_add_u32_e32 v216, 0x90, v236
	global_load_dwordx4 v[172:175], v[120:121], off
	global_load_dwordx4 v[168:171], v[120:121], off offset:256
	v_lshl_add_u64 v[120:121], v[124:125], 0, v[226:227]
	v_lshlrev_b64 v[222:223], 11, v[220:221]
	v_ashrrev_i32_e32 v217, 31, v216
	v_add_u32_e32 v212, 0xa0, v236
	v_add_u32_e32 v208, 0xb0, v236
	global_load_dwordx4 v[164:167], v[120:121], off
	global_load_dwordx4 v[160:163], v[120:121], off offset:256
	v_lshl_add_u64 v[120:121], v[124:125], 0, v[222:223]
	v_lshlrev_b64 v[218:219], 11, v[216:217]
	v_ashrrev_i32_e32 v213, 31, v212
	v_ashrrev_i32_e32 v209, 31, v208
	global_load_dwordx4 v[156:159], v[120:121], off
	global_load_dwordx4 v[152:155], v[120:121], off offset:256
	v_lshl_add_u64 v[120:121], v[124:125], 0, v[218:219]
	v_lshlrev_b64 v[214:215], 11, v[212:213]
	v_lshlrev_b64 v[210:211], 11, v[208:209]
	global_load_dwordx4 v[148:151], v[120:121], off
	global_load_dwordx4 v[144:147], v[120:121], off offset:256
	v_lshl_add_u64 v[120:121], v[124:125], 0, v[214:215]
	v_lshl_add_u64 v[124:125], v[124:125], 0, v[210:211]
	global_load_dwordx4 v[132:135], v[120:121], off
	s_nop 0
	global_load_dwordx4 v[120:123], v[120:121], off offset:256
	s_nop 0
	global_load_dwordx4 v[140:143], v[124:125], off
	s_nop 0
	global_load_dwordx4 v[124:127], v[124:125], off offset:256
	v_and_b32_e32 v249, 64, v247
	v_xor_b32_e32 v248, 16, v247
	v_add_u32_e32 v249, 64, v249
	v_cmp_lt_i32_e32 vcc, v248, v249
	v_xor_b32_e32 v250, 32, v247
	s_lshl_b32 s30, s16, 2
	v_cndmask_b32_e32 v248, v247, v248, vcc
	v_cmp_lt_i32_e32 vcc, v250, v249
	v_lshlrev_b32_e32 v248, 2, v248
	s_ashr_i32 s31, s30, 31
	v_cndmask_b32_e32 v249, v247, v250, vcc
	v_lshlrev_b32_e32 v249, 2, v249
	s_waitcnt vmcnt(0)
	v_lshlrev_b32_e32 v250, 16, v188
	v_and_b32_e32 v251, 0xffff0000, v188
	v_lshlrev_b32_e32 v188, 16, v189
	v_and_b32_e32 v189, 0xffff0000, v189
	v_lshlrev_b32_e32 v252, 16, v190
	v_and_b32_e32 v253, 0xffff0000, v190
	v_lshlrev_b32_e32 v190, 16, v191
	v_and_b32_e32 v191, 0xffff0000, v191
	v_pk_add_f32 v[138:139], v[138:139], v[188:189]
	v_pk_add_f32 v[136:137], v[136:137], v[250:251]
	v_pk_add_f32 v[188:189], v[130:131], v[190:191]
	v_pk_add_f32 v[130:131], v[128:129], v[252:253]
	v_mul_f32_e32 v128, v137, v137
	v_mul_f32_e32 v129, v139, v139
	v_fmac_f32_e32 v128, v136, v136
	v_fmac_f32_e32 v129, v138, v138
	v_add_f32_e32 v128, v128, v129
	v_mul_f32_e32 v129, v131, v131
	v_mul_f32_e32 v190, v189, v189
	v_fmac_f32_e32 v129, v130, v130
	v_fmac_f32_e32 v190, v188, v188
	v_add_f32_e32 v129, v129, v190
	v_add_f32_e32 v190, v128, v129
	v_cvt_pk_bf16_f32 v128, v136, v137
	v_lshl_add_u64 v[136:137], s[24:25], 0, v[240:241]
	v_cvt_pk_bf16_f32 v129, v138, v139
	v_cvt_pk_bf16_f32 v130, v130, v131
	v_cvt_pk_bf16_f32 v131, v188, v189
	v_lshl_add_u64 v[136:137], v[136:137], 0, v[238:239]
	global_store_dwordx4 v[136:137], v[128:131], off sc1
	v_lshlrev_b32_e32 v138, 16, v186
	v_and_b32_e32 v139, 0xffff0000, v186
	v_lshlrev_b32_e32 v128, 16, v184
	v_and_b32_e32 v129, 0xffff0000, v184
	v_lshlrev_b32_e32 v130, 16, v185
	v_and_b32_e32 v131, 0xffff0000, v185
	v_lshlrev_b32_e32 v184, 16, v187
	v_and_b32_e32 v185, 0xffff0000, v187
	v_pk_add_f32 v[118:119], v[118:119], v[130:131]
	v_pk_add_f32 v[116:117], v[116:117], v[128:129]
	v_pk_add_f32 v[128:129], v[114:115], v[184:185]
	v_pk_add_f32 v[114:115], v[112:113], v[138:139]
	v_mul_f32_e32 v112, v117, v117
	v_mul_f32_e32 v113, v119, v119
	v_fmac_f32_e32 v112, v116, v116
	v_fmac_f32_e32 v113, v118, v118
	v_add_f32_e32 v112, v112, v113
	v_mul_f32_e32 v113, v115, v115
	v_mul_f32_e32 v130, v129, v129
	v_fmac_f32_e32 v113, v114, v114
	v_fmac_f32_e32 v130, v128, v128
	v_add_f32_e32 v113, v113, v130
	v_add_f32_e32 v112, v112, v113
	v_add_f32_e32 v130, v190, v112
	v_cvt_pk_bf16_f32 v112, v116, v117
	v_cvt_pk_bf16_f32 v113, v118, v119
	v_cvt_pk_bf16_f32 v114, v114, v115
	v_cvt_pk_bf16_f32 v115, v128, v129
	global_store_dwordx4 v[136:137], v[112:115], off offset:256 sc1
	ds_bpermute_b32 v112, v248, v130
	s_waitcnt lgkmcnt(0)
	v_add_f32_e32 v112, v130, v112
	ds_bpermute_b32 v113, v249, v112
	s_and_saveexec_b64 s[34:35], s[6:7]
	s_cbranch_execz .LBB0_2869
	v_lshlrev_b64 v[114:115], 6, v[236:237]
	v_lshl_add_u64 v[114:115], s[26:27], 0, v[114:115]
	v_lshl_add_u64 v[114:115], s[30:31], 2, v[114:115]
	s_lshl_b32 s16, s45, 2
	v_lshl_add_u64 v[114:115], v[114:115], 0, s[16:17]
	s_waitcnt lgkmcnt(0)
	v_add_f32_e32 v112, v112, v113
	global_store_dword v[114:115], v112, off

.Lfin_loop:
	v_lshrrev_b64 v[26:27], 8, v[0:1]
	v_lshlrev_b64 v[26:27], 12, v[26:27]
	v_lshl_add_u64 v[26:27], s[10:11], 0, v[26:27]
	v_lshl_add_u64 v[26:27], v[26:27], 0, v[62:63]
	v_lshl_add_u64 v[0:1], v[0:1], 0, s[14:15]
	v_cmp_lt_u64_e32 vcc, s[24:25], v[0:1]
	s_or_b64 s[16:17], vcc, s[16:17]
	s_waitcnt vmcnt(1)
	v_mov_b64_e32 v[6:7], v[40:41]
	v_mov_b64_e32 v[8:9], v[42:43]
	v_mov_b64_e32 v[10:11], v[44:45]
	v_mov_b64_e32 v[12:13], v[46:47]
	v_mov_b64_e32 v[14:15], v[48:49]
	v_mov_b64_e32 v[16:17], v[50:51]
	v_mov_b64_e32 v[18:19], v[52:53]
	v_mov_b64_e32 v[20:21], v[54:55]
	v_mov_b64_e32 v[30:31], v[56:57]
	v_lshrrev_b64 v[32:33], 8, v[0:1]
	v_min_u32_e32 v32, 0x7fff, v32
	v_lshlrev_b64 v[34:35], 6, v[32:33]
	v_lshl_add_u64 v[34:35], s[0:1], 0, v[34:35]
	global_load_dwordx4 v[40:43], v[34:35], off
	global_load_dwordx4 v[44:47], v[34:35], off offset:32
	global_load_dwordx4 v[48:51], v[34:35], off offset:16
	global_load_dwordx4 v[52:55], v[34:35], off offset:48
	v_lshlrev_b64 v[34:35], 11, v[32:33]
	v_lshl_add_u64 v[34:35], s[12:13], 0, v[34:35]
	v_lshl_add_u64 v[34:35], v[34:35], 0, v[60:61]
	global_load_dwordx2 v[56:57], v[34:35], off
	v_mov_b32_e32 v28, v6
	v_mov_b32_e32 v29, v10
	v_mov_b32_e32 v10, v7
	v_mov_b32_e32 v6, v8
	v_mov_b32_e32 v7, v12
	v_mov_b32_e32 v12, v9
	v_mov_b32_e32 v8, v14
	v_mov_b32_e32 v9, v18
	v_mov_b32_e32 v18, v15
	v_mov_b32_e32 v14, v16
	v_mov_b32_e32 v15, v20
	v_mov_b32_e32 v20, v17
	v_pk_add_f32 v[10:11], v[28:29], v[10:11]
	v_pk_add_f32 v[6:7], v[6:7], v[12:13]
	v_pk_add_f32 v[8:9], v[8:9], v[18:19]
	v_pk_add_f32 v[12:13], v[14:15], v[20:21]
	v_pk_add_f32 v[6:7], v[10:11], v[6:7]
	v_pk_add_f32 v[8:9], v[8:9], v[12:13]
	v_lshlrev_b32_e32 v14, 16, v30
	v_pk_add_f32 v[6:7], v[6:7], v[8:9]
	v_and_b32_e32 v15, 0xffff0000, v30
	v_add_f32_e32 v5, v6, v7
	v_fmamk_f32 v5, v5, 0x3a800000, v4
	v_mul_f32_e32 v6, 0x4b800000, v5
	v_cmp_gt_f32_e32 vcc, s26, v5
	v_lshlrev_b32_e32 v16, 16, v31
	v_and_b32_e32 v17, 0xffff0000, v31
	v_cndmask_b32_e32 v5, v5, v6, vcc
	v_rsq_f32_e32 v5, v5
	s_nop 0
	v_mul_f32_e32 v6, 0x45800000, v5
	v_cndmask_b32_e32 v6, v5, v6, vcc
	v_pk_mul_f32 v[10:11], v[6:7], v[14:15] op_sel_hi:[0,1]
	v_pk_mul_f32 v[6:7], v[6:7], v[16:17] op_sel_hi:[0,1]
	v_pk_mul_f32 v[8:9], v[66:67], v[6:7]
	v_pk_mul_f32 v[6:7], v[64:65], v[10:11]
	global_store_dwordx4 v[26:27], v[6:9], off sc1
	s_andn2_b64 exec, exec, s[16:17]
	s_cbranch_execnz .Lfin_loop
